# speedup vs baseline: 1.0196x; 1.0196x over previous
; template <int EPI, bool AF32>
; DEV void gemm_tile(const void* Ap, int lda, const u16* Bt, int ldb, int K, int m0, int n0, const Epi& ea, char* smem) {
;     ...
;   auto gload = [&](int kt) {
;     const int k0 = kt << 6;
; #pragma unroll
;     for (int i = 0; i < 4; i++) {
;       const int c = tid + i * 256, row = c >> 3, kc = c & 7;
;       if (AF32) {
;         const float* pa = (const float*)Ap + (size_t)(m0 + row) * lda + k0 + kc * 8;
;         rfa[2 * i] = *(const f32x4*)pa;
;         rfa[2 * i + 1] = *(const f32x4*)(pa + 4);
;       } else {
;         ra[i] = *(const u32x4*)((const u16*)Ap + (size_t)(m0 + row) * lda + k0 + kc * 8);
;       }
;       rb[i] = *(const u32x4*)(Bt + (size_t)(n0 + row) * ldb + k0 + kc * 8);
;     }
;   };
;   auto swrite = [&](int buf) {
; #pragma unroll
;     for (int i = 0; i < 4; i++) {
;       const int c = tid + i * 256, row = c >> 3, kc = c & 7;
;       u32x4 va;
;       if (AF32) {
;         va = (u32x4){pack2(rfa[2 * i][0], rfa[2 * i][1]), pack2(rfa[2 * i][2], rfa[2 * i][3]),
;                      pack2(rfa[2 * i + 1][0], rfa[2 * i + 1][1]), pack2(rfa[2 * i + 1][2], rfa[2 * i + 1][3])};
;       } else {
;         va = ra[i];
;       }
;       *(u32x4*)(sA + buf * 9216 + row * 72 + kc * 8) = va;
;       *(u32x4*)(sB + buf * 9216 + row * 72 + kc * 8) = rb[i];
;     }
;   };
;   gload(0);
;   swrite(0);
;   if (nk > 1) gload(1);
;   __syncthreads();
.LBB0_164:
	s_mul_hi_i32 s6, s8, 0x2aaaaaab
	s_lshr_b32 s7, s6, 31
	s_ashr_i32 s6, s6, 5
	s_add_i32 s6, s6, s7
	s_lshl_b32 s10, s6, 5
	s_mul_i32 s7, s6, 0xc0
	s_sub_i32 s6, 0x104, s10
	s_min_u32 s11, s6, 32
	s_sub_i32 s9, s8, s7
	v_cvt_f32_ubyte0_e32 v2, s11
	v_cvt_f32_i32_e32 v0, s9
	v_rcp_iflag_f32_e32 v3, v2
	s_ashr_i32 s6, s9, 30
	s_or_b32 s12, s6, 1
	s_waitcnt vmcnt(12)
	v_mov_b32_e32 v114, v157
	v_mul_f32_e32 v3, v0, v3
	v_trunc_f32_e32 v3, v3
	v_fma_f32 v0, -v3, v2, v0
	v_cvt_i32_f32_e32 v3, v3
	v_cmp_ge_f32_e64 s[6:7], |v0|, v2
	s_and_b64 s[6:7], s[6:7], exec
	s_cselect_b32 s6, s12, 0
	v_readfirstlane_b32 s7, v3
	s_add_i32 s6, s7, s6
	s_sext_i32_i16 s7, s6
	s_mul_i32 s6, s6, s11
	s_sub_i32 s6, s9, s6
	s_sext_i32_i16 s6, s6
	s_add_i32 s10, s10, s6
	s_lshl_b32 s9, s10, 7
	s_lshl_b32 s10, s7, 7
	v_ashrrev_i32_e32 v8, 3, v114
	v_add_u32_e32 v2, s9, v8
	v_ashrrev_i32_e32 v3, 31, v2
	v_lshlrev_b32_e32 v0, 3, v114
	v_add_u32_e32 v4, 0x100, v114
	v_lshlrev_b64 v[58:59], 11, v[2:3]
	v_and_b32_e32 v0, 56, v0
	v_ashrrev_i32_e32 v9, 3, v4
	v_lshl_add_u64 v[2:3], s[60:61], 0, v[58:59]
	v_lshlrev_b32_e32 v0, 1, v0
	v_add_u32_e32 v4, s9, v9
	v_add_u32_e32 v6, 0x200, v114
	v_lshl_add_u64 v[14:15], v[2:3], 0, v[0:1]
	v_add_u32_e32 v2, s10, v8
	v_ashrrev_i32_e32 v5, 31, v4
	v_ashrrev_i32_e32 v10, 3, v6
	v_ashrrev_i32_e32 v3, 31, v2
	v_lshlrev_b64 v[62:63], 11, v[4:5]
	v_add_u32_e32 v6, s9, v10
	v_lshlrev_b64 v[60:61], 11, v[2:3]
	v_lshl_add_u64 v[4:5], s[60:61], 0, v[62:63]
	v_ashrrev_i32_e32 v7, 31, v6
	v_lshl_add_u64 v[2:3], s[2:3], 0, v[60:61]
	v_lshl_add_u64 v[16:17], v[4:5], 0, v[0:1]
	v_add_u32_e32 v4, s10, v9
	v_lshlrev_b64 v[66:67], 11, v[6:7]
	v_lshl_add_u64 v[2:3], v[2:3], 0, v[0:1]
	v_ashrrev_i32_e32 v5, 31, v4
	v_lshl_add_u64 v[6:7], s[60:61], 0, v[66:67]
	global_load_dwordx4 v[30:33], v[2:3], off
	v_lshlrev_b64 v[64:65], 11, v[4:5]
	v_lshl_add_u64 v[68:69], v[6:7], 0, v[0:1]
	v_add_u32_e32 v6, s10, v10
	global_load_dwordx4 v[26:29], v[14:15], off
	global_load_dwordx4 v[34:37], v[16:17], off
	v_lshl_add_u64 v[4:5], s[2:3], 0, v[64:65]
	v_ashrrev_i32_e32 v7, 31, v6
	v_lshl_add_u64 v[4:5], v[4:5], 0, v[0:1]
	v_lshlrev_b64 v[70:71], 11, v[6:7]
	global_load_dwordx4 v[38:41], v[4:5], off
	v_lshl_add_u64 v[6:7], s[2:3], 0, v[70:71]
	global_load_dwordx4 v[42:45], v[68:69], off
	v_lshl_add_u64 v[18:19], v[6:7], 0, v[0:1]
	global_load_dwordx4 v[46:49], v[18:19], off
	v_add_u32_e32 v6, 0x300, v114
	v_ashrrev_i32_e32 v80, 3, v6
	v_add_u32_e32 v6, s9, v80
	v_ashrrev_i32_e32 v7, 31, v6
	v_lshlrev_b64 v[72:73], 11, v[6:7]
	v_lshl_add_u64 v[6:7], s[60:61], 0, v[72:73]
	v_lshl_add_u64 v[74:75], v[6:7], 0, v[0:1]
	v_add_u32_e32 v6, s10, v80
	v_ashrrev_i32_e32 v7, 31, v6
	v_lshlrev_b64 v[76:77], 11, v[6:7]
	v_lshl_add_u64 v[6:7], s[2:3], 0, v[76:77]
	v_lshl_add_u64 v[78:79], v[6:7], 0, v[0:1]
	global_load_dwordx4 v[50:53], v[74:75], off
	global_load_dwordx4 v[54:57], v[78:79], off
	s_waitcnt vmcnt(19)
	v_mul_lo_u32 v118, v8, s71
	v_mul_lo_u32 v119, v9, s71
	s_waitcnt vmcnt(18)
	v_mul_lo_u32 v123, v10, s71
	global_load_dwordx4 v[6:9], v[2:3], off offset:128
	global_load_dwordx4 v[10:13], v[4:5], off offset:128
	s_nop 0
	global_load_dwordx4 v[2:5], v[18:19], off offset:128
	global_load_dwordx4 v[22:25], v[14:15], off offset:128
	s_nop 0
	global_load_dwordx4 v[18:21], v[16:17], off offset:128
	s_nop 0
	global_load_dwordx4 v[14:17], v[68:69], off offset:128
	v_bfe_u32 v161, v157, 3, 4
	v_add_u32_e32 v161, 4, v161
	v_lshlrev_b32_e32 v161, 1, v161
	v_and_b32_e32 v161, 16, v161
	v_xor_b32_e32 v129, v0, v161
	v_lshl_add_u32 v122, v118, 1, v129
	v_lshl_add_u32 v121, v119, 1, v129
	v_lshl_add_u32 v120, v123, 1, v129
	v_and_b32_e32 v115, 15, v114
	s_waitcnt vmcnt(23)
	v_mul_lo_u32 v126, v80, s71
	v_bfe_u32 v116, v114, 4, 2
	v_lshl_add_u32 v124, v126, 1, v129
	s_mov_b32 s11, 0
	v_lshlrev_b32_e32 v125, 4, v116
	v_and_b32_e32 v161, 15, v157
	v_add_u32_e32 v161, 4, v161
	v_lshlrev_b32_e32 v161, 1, v161
	v_and_b32_e32 v161, 16, v161
	v_xor_b32_e32 v125, v125, v161
	s_mov_b64 s[6:7], 0
	s_waitcnt vmcnt(13)
	ds_write_b128 v122, v[30:33] offset:36864
	s_waitcnt vmcnt(12)
	ds_write_b128 v122, v[26:29]
	s_waitcnt vmcnt(11)
	ds_write_b128 v121, v[34:37]
	s_waitcnt vmcnt(10)
	ds_write_b128 v121, v[38:41] offset:36864
	s_waitcnt vmcnt(9)
	ds_write_b128 v120, v[42:45]
	s_waitcnt vmcnt(8)
	ds_write_b128 v120, v[46:49] offset:36864
	global_load_dwordx4 v[26:29], v[74:75], off offset:128
	global_load_dwordx4 v[30:33], v[78:79], off offset:128
	v_ashrrev_i32_e32 v34, 1, v114
	v_and_b32_e32 v117, 0xffffffc0, v34
	v_or_b32_e32 v34, v117, v115
	v_mul_lo_u32 v128, v34, s71
	v_lshlrev_b32_e32 v34, 4, v114
	v_and_b32_e32 v34, 0x70, v34
	v_and_b32_e32 v35, 0x4f, v114
	v_or_b32_e32 v76, v76, v34
	v_or_b32_e32 v72, v72, v34
	v_or_b32_e32 v70, v70, v34
	v_or_b32_e32 v66, v66, v34
	v_or_b32_e32 v64, v64, v34
	v_or_b32_e32 v62, v62, v34
	v_or_b32_e32 v60, v60, v34
	v_or_b32_e32 v58, v58, v34
	v_mov_b32_e32 v34, 0
	s_waitcnt vmcnt(9)
	ds_write_b128 v124, v[50:53]
	s_waitcnt vmcnt(8)
; template <int EPI, bool AF32>
; DEV void gemm_tile(const void* Ap, int lda, const u16* Bt, int ldb, int K, int m0, int n0, const Epi& ea, char* smem) {
;     ...
;   f32x4 acc[4][4];
; #pragma unroll
;   for (int m = 0; m < 4; m++)
; #pragma unroll
;     for (int n = 0; n < 4; n++) acc[m][n] = (f32x4){0.f, 0.f, 0.f, 0.f};
;   u32x4 ra[4], rb[4];
;   f32x4 rfa[8];
;   const int nk = K >> 6;
;   auto gload = [&](int kt) {
;     const int k0 = kt << 6;
; #pragma unroll
;     for (int i = 0; i < 4; i++) {
;       const int c = tid + i * 256, row = c >> 3, kc = c & 7;
;       if (AF32) {
;         const float* pa = (const float*)Ap + (size_t)(m0 + row) * lda + k0 + kc * 8;
;         rfa[2 * i] = *(const f32x4*)pa;
;         rfa[2 * i + 1] = *(const f32x4*)(pa + 4);
;       } else {
;         ra[i] = *(const u32x4*)((const u16*)Ap + (size_t)(m0 + row) * lda + k0 + kc * 8);
;       }
;       rb[i] = *(const u32x4*)(Bt + (size_t)(n0 + row) * ldb + k0 + kc * 8);
;     }
;   };
;   auto swrite = [&](int buf) {
; #pragma unroll
;     for (int i = 0; i < 4; i++) {
;       const int c = tid + i * 256, row = c >> 3, kc = c & 7;
;       u32x4 va;
;       if (AF32) {
;         va = (u32x4){pack2(rfa[2 * i][0], rfa[2 * i][1]), pack2(rfa[2 * i][2], rfa[2 * i][3]),
;                      pack2(rfa[2 * i + 1][0], rfa[2 * i + 1][1]), pack2(rfa[2 * i + 1][2], rfa[2 * i + 1][3])};
;       } else {
;         va = ra[i];
;       }
;       *(u32x4*)(sA + buf * 9216 + row * 72 + kc * 8) = va;
;       *(u32x4*)(sB + buf * 9216 + row * 72 + kc * 8) = rb[i];
;     }
;   };
;   gload(0);
;   swrite(0);
;   if (nk > 1) gload(1);
;   __syncthreads();
;   for (int kt = 0; kt < nk; kt++) {
;     const int buf = kt & 1;
;     if (kt + 1 < nk) swrite(buf ^ 1);
;     if (kt + 2 < nk) gload(kt + 2);
; #pragma unroll
;     for (int ks = 0; ks < 2; ks++) {
;       bf16x8 a[4], b[4];
; #pragma unroll
;       for (int m = 0; m < 4; m++) a[m] = *(const bf16x8*)(sA + buf * 9216 + (wr * 64 + m * 16 + fr) * 72 + ks * 32 + fq * 8);
; #pragma unroll
;       for (int n = 0; n < 4; n++) b[n] = *(const bf16x8*)(sB + buf * 9216 + (wc * 64 + n * 16 + fr) * 72 + ks * 32 + fq * 8);
;       __builtin_amdgcn_s_setprio(1);
; #pragma unroll
;       for (int m = 0; m < 4; m++)
; #pragma unroll
;         for (int n = 0; n < 4; n++) acc[m][n] = mfma16(a[m], b[n], acc[m][n]);
;       __builtin_amdgcn_s_setprio(0);
;     }
	ds_write_b128 v124, v[54:57] offset:36864
	v_mul_u32_u24_e32 v127, 0x48, v35
	v_lshl_add_u64 v[98:99], s[4:5], 0, v[76:77]
	v_lshl_add_u64 v[100:101], s[66:67], 0, v[72:73]
	v_lshl_add_u64 v[102:103], s[4:5], 0, v[70:71]
	v_lshl_add_u64 v[104:105], s[66:67], 0, v[66:67]
	v_lshl_add_u64 v[106:107], s[4:5], 0, v[64:65]
	v_lshl_add_u64 v[108:109], s[66:67], 0, v[62:63]
	v_lshl_add_u64 v[110:111], s[4:5], 0, v[60:61]
	v_lshl_add_u64 v[112:113], s[66:67], 0, v[58:59]
	global_load_dwordx4 v[222:225], v[112:113], off
	global_load_dwordx4 v[226:229], v[110:111], off
	global_load_dwordx4 v[230:233], v[108:109], off
	global_load_dwordx4 v[234:237], v[106:107], off
	global_load_dwordx4 v[238:241], v[104:105], off
	global_load_dwordx4 v[242:245], v[102:103], off
	global_load_dwordx4 v[246:249], v[100:101], off
	global_load_dwordx4 v[250:253], v[98:99], off
	v_mov_b32_e32 v35, v34
	v_mov_b32_e32 v36, v34
	v_mov_b32_e32 v37, v34
	v_mov_b32_e32 v38, v34
	v_mov_b32_e32 v39, v34
	v_mov_b32_e32 v40, v34
	v_mov_b32_e32 v41, v34
	v_mov_b32_e32 v42, v34
	v_mov_b32_e32 v43, v34
	v_mov_b32_e32 v44, v34
	v_mov_b32_e32 v45, v34
	v_mov_b32_e32 v46, v34
	v_mov_b32_e32 v47, v34
	v_mov_b32_e32 v48, v34
	v_mov_b32_e32 v49, v34
	v_mov_b32_e32 v50, v34
	v_mov_b32_e32 v51, v34
	v_mov_b32_e32 v52, v34
	v_mov_b32_e32 v53, v34
	v_mov_b32_e32 v54, v34
	v_mov_b32_e32 v55, v34
	v_mov_b32_e32 v56, v34
	v_mov_b32_e32 v57, v34
	v_mov_b32_e32 v58, v34
	v_mov_b32_e32 v59, v34
	v_mov_b32_e32 v60, v34
	v_mov_b32_e32 v61, v34
	v_mov_b32_e32 v62, v34
	v_mov_b32_e32 v63, v34
	v_mov_b32_e32 v64, v34
	v_mov_b32_e32 v65, v34
	v_mov_b32_e32 v66, v34
	v_mov_b32_e32 v67, v34
	v_mov_b32_e32 v68, v34
	v_mov_b32_e32 v69, v34
	v_mov_b32_e32 v70, v34
	v_mov_b32_e32 v71, v34
	v_mov_b32_e32 v72, v34
	v_mov_b32_e32 v73, v34
	v_mov_b32_e32 v74, v34
	v_mov_b32_e32 v75, v34
	v_mov_b32_e32 v76, v34
	v_mov_b32_e32 v77, v34
	v_mov_b32_e32 v78, v34
	v_mov_b32_e32 v79, v34
	v_mov_b32_e32 v80, v34
	v_mov_b32_e32 v81, v34
	v_mov_b32_e32 v82, v34
	v_mov_b32_e32 v83, v34
	v_mov_b32_e32 v84, v34
	v_mov_b32_e32 v85, v34
	v_mov_b32_e32 v86, v34
	v_mov_b32_e32 v87, v34
	v_mov_b32_e32 v88, v34
	v_mov_b32_e32 v89, v34
	v_mov_b32_e32 v90, v34
	v_mov_b32_e32 v91, v34
	v_mov_b32_e32 v92, v34
	v_mov_b32_e32 v93, v34
	v_mov_b32_e32 v94, v34
	v_mov_b32_e32 v95, v34
	v_mov_b32_e32 v96, v34
	v_mov_b32_e32 v97, v34
	s_waitcnt lgkmcnt(0)
	s_barrier
	v_lshl_add_u32 v161, v128, 1, v125
	v_lshl_add_u32 v129, v127, 1, v125
	s_mov_b32 s11, 0
	s_mov_b64 s[6:7], 0x100
.Lgk0_loop:
	v_lshl_add_u64 v[112:113], v[112:113], 0, s[6:7]
	v_lshl_add_u64 v[110:111], v[110:111], 0, s[6:7]
	v_lshl_add_u64 v[108:109], v[108:109], 0, s[6:7]
	v_lshl_add_u64 v[106:107], v[106:107], 0, s[6:7]
	v_lshl_add_u64 v[104:105], v[104:105], 0, s[6:7]
	v_lshl_add_u64 v[102:103], v[102:103], 0, s[6:7]
	v_lshl_add_u64 v[100:101], v[100:101], 0, s[6:7]
	v_lshl_add_u64 v[98:99], v[98:99], 0, s[6:7]
	ds_read_b128 v[130:133], v161
	ds_read_b128 v[134:137], v161 offset:2304
	ds_read_b128 v[138:141], v161 offset:4608
	ds_read_b128 v[142:145], v161 offset:6912
	ds_read_b128 v[146:149], v129 offset:36864
	ds_read_b128 v[150:153], v129 offset:39168
	ds_read_b128 v[162:165], v129 offset:41472
	ds_read_b128 v[166:169], v129 offset:43776
	s_setprio 1
	s_waitcnt lgkmcnt(3)
	v_mfma_f32_16x16x32_bf16 v[94:97], v[130:133], v[146:149], v[94:97]
	s_waitcnt lgkmcnt(2)
	v_mfma_f32_16x16x32_bf16 v[90:93], v[130:133], v[150:153], v[90:93]
	s_waitcnt lgkmcnt(1)
	v_mfma_f32_16x16x32_bf16 v[86:89], v[130:133], v[162:165], v[86:89]
	s_waitcnt lgkmcnt(0)
	v_mfma_f32_16x16x32_bf16 v[82:85], v[130:133], v[166:169], v[82:85]
	v_mfma_f32_16x16x32_bf16 v[78:81], v[134:137], v[146:149], v[78:81]
	v_mfma_f32_16x16x32_bf16 v[74:77], v[134:137], v[150:153], v[74:77]
	v_mfma_f32_16x16x32_bf16 v[70:73], v[134:137], v[162:165], v[70:73]
	v_mfma_f32_16x16x32_bf16 v[66:69], v[134:137], v[166:169], v[66:69]
	v_mfma_f32_16x16x32_bf16 v[62:65], v[138:141], v[146:149], v[62:65]
	v_mfma_f32_16x16x32_bf16 v[58:61], v[138:141], v[150:153], v[58:61]
	v_mfma_f32_16x16x32_bf16 v[54:57], v[138:141], v[162:165], v[54:57]
	v_mfma_f32_16x16x32_bf16 v[50:53], v[138:141], v[166:169], v[50:53]
	v_mfma_f32_16x16x32_bf16 v[46:49], v[142:145], v[146:149], v[46:49]
	v_mfma_f32_16x16x32_bf16 v[42:45], v[142:145], v[150:153], v[42:45]
	v_mfma_f32_16x16x32_bf16 v[38:41], v[142:145], v[162:165], v[38:41]
	v_mfma_f32_16x16x32_bf16 v[34:37], v[142:145], v[166:169], v[34:37]
	s_setprio 0
	ds_read_b128 v[130:133], v161 offset:64
	ds_read_b128 v[134:137], v161 offset:2368
	ds_read_b128 v[138:141], v161 offset:4672
	ds_read_b128 v[142:145], v161 offset:6976
	ds_read_b128 v[146:149], v129 offset:36928
	ds_read_b128 v[150:153], v129 offset:39232
	ds_read_b128 v[162:165], v129 offset:41536
	ds_read_b128 v[166:169], v129 offset:43840
	s_waitcnt vmcnt(8)
	ds_write_b128 v122, v[22:25] offset:18432
	ds_write_b128 v122, v[6:9] offset:55296
	ds_write_b128 v121, v[18:21] offset:18432
	ds_write_b128 v121, v[10:13] offset:55296
	ds_write_b128 v120, v[14:17] offset:18432
	ds_write_b128 v120, v[2:5] offset:55296
	ds_write_b128 v124, v[26:29] offset:18432
	ds_write_b128 v124, v[30:33] offset:55296
	global_load_dwordx4 v[22:25], v[112:113], off offset:-128
	global_load_dwordx4 v[6:9], v[110:111], off offset:-128
	global_load_dwordx4 v[18:21], v[108:109], off offset:-128
	global_load_dwordx4 v[10:13], v[106:107], off offset:-128
	global_load_dwordx4 v[14:17], v[104:105], off offset:-128
	global_load_dwordx4 v[2:5], v[102:103], off offset:-128
	global_load_dwordx4 v[26:29], v[100:101], off offset:-128
	global_load_dwordx4 v[30:33], v[98:99], off offset:-128
	s_setprio 1
	s_waitcnt lgkmcnt(11)
	v_mfma_f32_16x16x32_bf16 v[94:97], v[130:133], v[146:149], v[94:97]
	s_waitcnt lgkmcnt(10)
	v_mfma_f32_16x16x32_bf16 v[90:93], v[130:133], v[150:153], v[90:93]
	s_waitcnt lgkmcnt(9)
	v_mfma_f32_16x16x32_bf16 v[86:89], v[130:133], v[162:165], v[86:89]
	s_waitcnt lgkmcnt(8)
	v_mfma_f32_16x16x32_bf16 v[82:85], v[130:133], v[166:169], v[82:85]
	v_mfma_f32_16x16x32_bf16 v[78:81], v[134:137], v[146:149], v[78:81]
	v_mfma_f32_16x16x32_bf16 v[74:77], v[134:137], v[150:153], v[74:77]
	v_mfma_f32_16x16x32_bf16 v[70:73], v[134:137], v[162:165], v[70:73]
	v_mfma_f32_16x16x32_bf16 v[66:69], v[134:137], v[166:169], v[66:69]
	v_mfma_f32_16x16x32_bf16 v[62:65], v[138:141], v[146:149], v[62:65]
	v_mfma_f32_16x16x32_bf16 v[58:61], v[138:141], v[150:153], v[58:61]
	v_mfma_f32_16x16x32_bf16 v[54:57], v[138:141], v[162:165], v[54:57]
	v_mfma_f32_16x16x32_bf16 v[50:53], v[138:141], v[166:169], v[50:53]
	v_mfma_f32_16x16x32_bf16 v[46:49], v[142:145], v[146:149], v[46:49]
	v_mfma_f32_16x16x32_bf16 v[42:45], v[142:145], v[150:153], v[42:45]
	v_mfma_f32_16x16x32_bf16 v[38:41], v[142:145], v[162:165], v[38:41]
	v_mfma_f32_16x16x32_bf16 v[34:37], v[142:145], v[166:169], v[34:37]
	s_setprio 0
	s_waitcnt lgkmcnt(0)
	s_barrier
; DEV f32x4 mfma16(bf16x8 a, bf16x8 b, f32x4 c) { return __builtin_amdgcn_mfma_f32_16x16x32_bf16(a, b, c, 0, 0, 0); }
; template <int EPI, bool AF32>
; DEV void gemm_tile(const void* Ap, int lda, const u16* Bt, int ldb, int K, int m0, int n0, const Epi& ea, char* smem) {
;     ...
;   for (int kt = 0; kt < nk; kt++) {
;     const int buf = kt & 1;
;     if (kt + 1 < nk) swrite(buf ^ 1);
;     if (kt + 2 < nk) gload(kt + 2);
; #pragma unroll
;     for (int ks = 0; ks < 2; ks++) {
;       bf16x8 a[4], b[4];
; #pragma unroll
;       for (int m = 0; m < 4; m++) a[m] = *(const bf16x8*)(sA + buf * 9216 + (wr * 64 + m * 16 + fr) * 72 + ks * 32 + fq * 8);
; #pragma unroll
;       for (int n = 0; n < 4; n++) b[n] = *(const bf16x8*)(sB + buf * 9216 + (wc * 64 + n * 16 + fr) * 72 + ks * 32 + fq * 8);
;       __builtin_amdgcn_s_setprio(1);
; #pragma unroll
;       for (int m = 0; m < 4; m++)
; #pragma unroll
;         for (int n = 0; n < 4; n++) acc[m][n] = mfma16(a[m], b[n], acc[m][n]);
;       __builtin_amdgcn_s_setprio(0);
;     }
;     __syncthreads();
;   }
	ds_read_b128 v[130:133], v161 offset:18432
	ds_read_b128 v[134:137], v161 offset:20736
	ds_read_b128 v[138:141], v161 offset:23040
	ds_read_b128 v[142:145], v161 offset:25344
	ds_read_b128 v[146:149], v129 offset:55296
	ds_read_b128 v[150:153], v129 offset:57600
	ds_read_b128 v[162:165], v129 offset:59904
	ds_read_b128 v[166:169], v129 offset:62208
	s_setprio 1
	s_waitcnt lgkmcnt(3)
	v_mfma_f32_16x16x32_bf16 v[94:97], v[130:133], v[146:149], v[94:97]
	s_waitcnt lgkmcnt(2)
	v_mfma_f32_16x16x32_bf16 v[90:93], v[130:133], v[150:153], v[90:93]
	s_waitcnt lgkmcnt(1)
	v_mfma_f32_16x16x32_bf16 v[86:89], v[130:133], v[162:165], v[86:89]
	s_waitcnt lgkmcnt(0)
	v_mfma_f32_16x16x32_bf16 v[82:85], v[130:133], v[166:169], v[82:85]
	v_mfma_f32_16x16x32_bf16 v[78:81], v[134:137], v[146:149], v[78:81]
	v_mfma_f32_16x16x32_bf16 v[74:77], v[134:137], v[150:153], v[74:77]
	v_mfma_f32_16x16x32_bf16 v[70:73], v[134:137], v[162:165], v[70:73]
	v_mfma_f32_16x16x32_bf16 v[66:69], v[134:137], v[166:169], v[66:69]
	v_mfma_f32_16x16x32_bf16 v[62:65], v[138:141], v[146:149], v[62:65]
	v_mfma_f32_16x16x32_bf16 v[58:61], v[138:141], v[150:153], v[58:61]
	v_mfma_f32_16x16x32_bf16 v[54:57], v[138:141], v[162:165], v[54:57]
	v_mfma_f32_16x16x32_bf16 v[50:53], v[138:141], v[166:169], v[50:53]
	v_mfma_f32_16x16x32_bf16 v[46:49], v[142:145], v[146:149], v[46:49]
	v_mfma_f32_16x16x32_bf16 v[42:45], v[142:145], v[150:153], v[42:45]
	v_mfma_f32_16x16x32_bf16 v[38:41], v[142:145], v[162:165], v[38:41]
	v_mfma_f32_16x16x32_bf16 v[34:37], v[142:145], v[166:169], v[34:37]
	s_setprio 0
	ds_read_b128 v[130:133], v161 offset:18496
	ds_read_b128 v[134:137], v161 offset:20800
	ds_read_b128 v[138:141], v161 offset:23104
	ds_read_b128 v[142:145], v161 offset:25408
	ds_read_b128 v[146:149], v129 offset:55360
	ds_read_b128 v[150:153], v129 offset:57664
	ds_read_b128 v[162:165], v129 offset:59968
	ds_read_b128 v[166:169], v129 offset:62272
	s_waitcnt vmcnt(8)
	ds_write_b128 v122, v[222:225]
	ds_write_b128 v122, v[226:229] offset:36864
	ds_write_b128 v121, v[230:233]
	ds_write_b128 v121, v[234:237] offset:36864
	ds_write_b128 v120, v[238:241]
	ds_write_b128 v120, v[242:245] offset:36864
	ds_write_b128 v124, v[246:249]
	ds_write_b128 v124, v[250:253] offset:36864
	s_cmp_eq_u32 s11, 6
	s_cbranch_scc1 .Lgk0_nold
	global_load_dwordx4 v[222:225], v[112:113], off
	global_load_dwordx4 v[226:229], v[110:111], off
	global_load_dwordx4 v[230:233], v[108:109], off
	global_load_dwordx4 v[234:237], v[106:107], off
	global_load_dwordx4 v[238:241], v[104:105], off
	global_load_dwordx4 v[242:245], v[102:103], off
	global_load_dwordx4 v[246:249], v[100:101], off
	global_load_dwordx4 v[250:253], v[98:99], off
.Lgk0_nold:
	s_setprio 1
	s_waitcnt lgkmcnt(11)
	v_mfma_f32_16x16x32_bf16 v[94:97], v[130:133], v[146:149], v[94:97]
	s_waitcnt lgkmcnt(10)
	v_mfma_f32_16x16x32_bf16 v[90:93], v[130:133], v[150:153], v[90:93]
	s_waitcnt lgkmcnt(9)
	v_mfma_f32_16x16x32_bf16 v[86:89], v[130:133], v[162:165], v[86:89]
	s_waitcnt lgkmcnt(8)
	v_mfma_f32_16x16x32_bf16 v[82:85], v[130:133], v[166:169], v[82:85]
	v_mfma_f32_16x16x32_bf16 v[78:81], v[134:137], v[146:149], v[78:81]
	v_mfma_f32_16x16x32_bf16 v[74:77], v[134:137], v[150:153], v[74:77]
	v_mfma_f32_16x16x32_bf16 v[70:73], v[134:137], v[162:165], v[70:73]
	v_mfma_f32_16x16x32_bf16 v[66:69], v[134:137], v[166:169], v[66:69]
	v_mfma_f32_16x16x32_bf16 v[62:65], v[138:141], v[146:149], v[62:65]
	v_mfma_f32_16x16x32_bf16 v[58:61], v[138:141], v[150:153], v[58:61]
	v_mfma_f32_16x16x32_bf16 v[54:57], v[138:141], v[162:165], v[54:57]
	v_mfma_f32_16x16x32_bf16 v[50:53], v[138:141], v[166:169], v[50:53]
	v_mfma_f32_16x16x32_bf16 v[46:49], v[142:145], v[146:149], v[46:49]
	v_mfma_f32_16x16x32_bf16 v[42:45], v[142:145], v[150:153], v[42:45]
	v_mfma_f32_16x16x32_bf16 v[38:41], v[142:145], v[162:165], v[38:41]
	v_mfma_f32_16x16x32_bf16 v[34:37], v[142:145], v[166:169], v[34:37]
	s_setprio 0
	s_add_i32 s11, s11, 1
	s_cmp_lg_u32 s11, 7
	s_waitcnt lgkmcnt(0)
	s_barrier
	s_cbranch_scc1 .Lgk0_loop
	s_waitcnt vmcnt(7)
	ds_write_b128 v122, v[22:25] offset:18432
	s_waitcnt vmcnt(6)
	ds_write_b128 v122, v[6:9] offset:55296
	s_waitcnt vmcnt(5)
	ds_write_b128 v121, v[18:21] offset:18432
	s_waitcnt vmcnt(4)
	ds_write_b128 v121, v[10:13] offset:55296
	s_waitcnt vmcnt(3)
	ds_write_b128 v120, v[14:17] offset:18432
	s_waitcnt vmcnt(2)
	ds_write_b128 v120, v[2:5] offset:55296
	s_waitcnt vmcnt(1)
	ds_write_b128 v124, v[26:29] offset:18432
	s_waitcnt vmcnt(0)
	ds_write_b128 v124, v[30:33] offset:55296
	v_lshl_add_u32 v0, v128, 1, v125
	v_lshl_add_u32 v98, v127, 1, v125
	ds_read_b128 v[2:5], v0
	ds_read_b128 v[6:9], v0 offset:2304
	ds_read_b128 v[10:13], v0 offset:4608
	ds_read_b128 v[14:17], v0 offset:6912
	ds_read_b128 v[18:21], v98 offset:36864
	ds_read_b128 v[22:25], v98 offset:39168
	ds_read_b128 v[26:29], v98 offset:41472
	ds_read_b128 v[30:33], v98 offset:43776
	s_setprio 1
	s_waitcnt lgkmcnt(3)
	v_mfma_f32_16x16x32_bf16 v[94:97], v[2:5], v[18:21], v[94:97]
	s_waitcnt lgkmcnt(2)
	v_mfma_f32_16x16x32_bf16 v[90:93], v[2:5], v[22:25], v[90:93]
	s_waitcnt lgkmcnt(1)
	v_mfma_f32_16x16x32_bf16 v[86:89], v[2:5], v[26:29], v[86:89]
	s_waitcnt lgkmcnt(0)
; DEV f32x4 mfma16(bf16x8 a, bf16x8 b, f32x4 c) { return __builtin_amdgcn_mfma_f32_16x16x32_bf16(a, b, c, 0, 0, 0); }
; template <int EPI, bool AF32>
; DEV void gemm_tile(const void* Ap, int lda, const u16* Bt, int ldb, int K, int m0, int n0, const Epi& ea, char* smem) {
;     ...
;   for (int kt = 0; kt < nk; kt++) {
;     const int buf = kt & 1;
;     if (kt + 1 < nk) swrite(buf ^ 1);
;     if (kt + 2 < nk) gload(kt + 2);
; #pragma unroll
;     for (int ks = 0; ks < 2; ks++) {
;       bf16x8 a[4], b[4];
; #pragma unroll
;       for (int m = 0; m < 4; m++) a[m] = *(const bf16x8*)(sA + buf * 9216 + (wr * 64 + m * 16 + fr) * 72 + ks * 32 + fq * 8);
; #pragma unroll
;       for (int n = 0; n < 4; n++) b[n] = *(const bf16x8*)(sB + buf * 9216 + (wc * 64 + n * 16 + fr) * 72 + ks * 32 + fq * 8);
;       __builtin_amdgcn_s_setprio(1);
; #pragma unroll
;       for (int m = 0; m < 4; m++)
; #pragma unroll
;         for (int n = 0; n < 4; n++) acc[m][n] = mfma16(a[m], b[n], acc[m][n]);
;       __builtin_amdgcn_s_setprio(0);
;     }
;     __syncthreads();
;   }
;     ...
;   for (int m = 0; m < 4; m++) {
; #pragma unroll
;     for (int j = 0; j < 4; j++) {
;       const int row = m0 + wr * 64 + m * 16 + fq * 4 + j;
;       if (EPI == EP_F32) {
;         float* C = (float*)ea.p0;
; #pragma unroll
;         for (int n = 0; n < 4; n++) C[(size_t)row * ea.ld + cb + n * 16 + fr] = acc[m][n][j];
	v_mfma_f32_16x16x32_bf16 v[2:5], v[2:5], v[30:33], v[82:85]
	v_mfma_f32_16x16x32_bf16 v[78:81], v[6:9], v[18:21], v[78:81]
	v_mfma_f32_16x16x32_bf16 v[74:77], v[6:9], v[22:25], v[74:77]
	v_mfma_f32_16x16x32_bf16 v[70:73], v[6:9], v[26:29], v[70:73]
	v_mfma_f32_16x16x32_bf16 v[6:9], v[6:9], v[30:33], v[66:69]
	v_mfma_f32_16x16x32_bf16 v[62:65], v[10:13], v[18:21], v[62:65]
	v_mfma_f32_16x16x32_bf16 v[58:61], v[10:13], v[22:25], v[58:61]
	v_mfma_f32_16x16x32_bf16 v[54:57], v[10:13], v[26:29], v[54:57]
	v_mfma_f32_16x16x32_bf16 v[10:13], v[10:13], v[30:33], v[50:53]
	v_mfma_f32_16x16x32_bf16 v[18:21], v[14:17], v[18:21], v[46:49]
	v_mfma_f32_16x16x32_bf16 v[22:25], v[14:17], v[22:25], v[42:45]
	v_mfma_f32_16x16x32_bf16 v[26:29], v[14:17], v[26:29], v[38:41]
	v_mfma_f32_16x16x32_bf16 v[14:17], v[14:17], v[30:33], v[34:37]
	s_setprio 0
	ds_read_b128 v[30:33], v0 offset:64
	s_nop 0
	ds_read_b128 v[34:37], v0 offset:2368
	ds_read_b128 v[38:41], v0 offset:4672
	ds_read_b128 v[42:45], v0 offset:6976
	ds_read_b128 v[46:49], v98 offset:36928
	ds_read_b128 v[50:53], v98 offset:39232
	ds_read_b128 v[66:69], v98 offset:41536
	ds_read_b128 v[82:85], v98 offset:43840
	s_setprio 1
	s_waitcnt lgkmcnt(3)
	v_mfma_f32_16x16x32_bf16 v[94:97], v[30:33], v[46:49], v[94:97]
	s_waitcnt lgkmcnt(2)
	v_mfma_f32_16x16x32_bf16 v[90:93], v[30:33], v[50:53], v[90:93]
	s_waitcnt lgkmcnt(1)
	v_mfma_f32_16x16x32_bf16 v[86:89], v[30:33], v[66:69], v[86:89]
	s_waitcnt lgkmcnt(0)
	v_mfma_f32_16x16x32_bf16 v[2:5], v[30:33], v[82:85], v[2:5]
	v_mfma_f32_16x16x32_bf16 v[30:33], v[34:37], v[46:49], v[78:81]
	v_mfma_f32_16x16x32_bf16 v[74:77], v[34:37], v[50:53], v[74:77]
	v_mfma_f32_16x16x32_bf16 v[70:73], v[34:37], v[66:69], v[70:73]
	v_mfma_f32_16x16x32_bf16 v[6:9], v[34:37], v[82:85], v[6:9]
	v_mfma_f32_16x16x32_bf16 v[34:37], v[38:41], v[46:49], v[62:65]
	v_mfma_f32_16x16x32_bf16 v[58:61], v[38:41], v[50:53], v[58:61]
	v_mfma_f32_16x16x32_bf16 v[54:57], v[38:41], v[66:69], v[54:57]
	v_mfma_f32_16x16x32_bf16 v[10:13], v[38:41], v[82:85], v[10:13]
	v_mfma_f32_16x16x32_bf16 v[18:21], v[42:45], v[46:49], v[18:21]
	v_mfma_f32_16x16x32_bf16 v[22:25], v[42:45], v[50:53], v[22:25]
	v_mfma_f32_16x16x32_bf16 v[26:29], v[42:45], v[66:69], v[26:29]
	v_mfma_f32_16x16x32_bf16 v[14:17], v[42:45], v[82:85], v[14:17]
	s_setprio 0
	s_barrier
	ds_read_b128 v[38:41], v0 offset:18432
	ds_read_b128 v[42:45], v0 offset:20736
	ds_read_b128 v[46:49], v0 offset:23040
	ds_read_b128 v[50:53], v0 offset:25344
	ds_read_b128 v[62:65], v98 offset:55296
	ds_read_b128 v[66:69], v98 offset:57600
	ds_read_b128 v[78:81], v98 offset:59904
	ds_read_b128 v[82:85], v98 offset:62208
	s_setprio 1
	s_waitcnt lgkmcnt(3)
	v_mfma_f32_16x16x32_bf16 v[94:97], v[38:41], v[62:65], v[94:97]
	s_waitcnt lgkmcnt(2)
	v_mfma_f32_16x16x32_bf16 v[90:93], v[38:41], v[66:69], v[90:93]
	s_waitcnt lgkmcnt(1)
	v_mfma_f32_16x16x32_bf16 v[86:89], v[38:41], v[78:81], v[86:89]
	s_waitcnt lgkmcnt(0)
	v_mfma_f32_16x16x32_bf16 v[2:5], v[38:41], v[82:85], v[2:5]
	v_mfma_f32_16x16x32_bf16 v[30:33], v[42:45], v[62:65], v[30:33]
	v_mfma_f32_16x16x32_bf16 v[38:41], v[42:45], v[66:69], v[74:77]
	v_mfma_f32_16x16x32_bf16 v[70:73], v[42:45], v[78:81], v[70:73]
	v_mfma_f32_16x16x32_bf16 v[6:9], v[42:45], v[82:85], v[6:9]
	v_mfma_f32_16x16x32_bf16 v[34:37], v[46:49], v[62:65], v[34:37]
	v_mfma_f32_16x16x32_bf16 v[42:45], v[46:49], v[66:69], v[58:61]
	v_mfma_f32_16x16x32_bf16 v[54:57], v[46:49], v[78:81], v[54:57]
	v_mfma_f32_16x16x32_bf16 v[10:13], v[46:49], v[82:85], v[10:13]
	v_mfma_f32_16x16x32_bf16 v[18:21], v[50:53], v[62:65], v[18:21]
	v_mfma_f32_16x16x32_bf16 v[22:25], v[50:53], v[66:69], v[22:25]
	v_mfma_f32_16x16x32_bf16 v[26:29], v[50:53], v[78:81], v[26:29]
	v_mfma_f32_16x16x32_bf16 v[14:17], v[50:53], v[82:85], v[14:17]
	s_setprio 0
	ds_read_b128 v[46:49], v0 offset:18496
	ds_read_b128 v[50:53], v0 offset:20800
	ds_read_b128 v[58:61], v0 offset:23104
	ds_read_b128 v[62:65], v0 offset:25408
	ds_read_b128 v[66:69], v98 offset:55360
	ds_read_b128 v[74:77], v98 offset:57664
	ds_read_b128 v[78:81], v98 offset:59968
	ds_read_b128 v[82:85], v98 offset:62272
	s_setprio 1
	s_waitcnt lgkmcnt(3)
	v_mfma_f32_16x16x32_bf16 v[94:97], v[46:49], v[66:69], v[94:97]
	s_waitcnt lgkmcnt(2)
	v_mfma_f32_16x16x32_bf16 v[90:93], v[46:49], v[74:77], v[90:93]
	s_waitcnt lgkmcnt(1)
	v_mfma_f32_16x16x32_bf16 v[86:89], v[46:49], v[78:81], v[86:89]
	s_waitcnt lgkmcnt(0)
	v_mfma_f32_16x16x32_bf16 v[2:5], v[46:49], v[82:85], v[2:5]
	v_mfma_f32_16x16x32_bf16 v[30:33], v[50:53], v[66:69], v[30:33]
	v_mfma_f32_16x16x32_bf16 v[38:41], v[50:53], v[74:77], v[38:41]
	v_mfma_f32_16x16x32_bf16 v[46:49], v[50:53], v[78:81], v[70:73]
	v_mfma_f32_16x16x32_bf16 v[6:9], v[50:53], v[82:85], v[6:9]
	v_mfma_f32_16x16x32_bf16 v[34:37], v[58:61], v[66:69], v[34:37]
	v_mfma_f32_16x16x32_bf16 v[42:45], v[58:61], v[74:77], v[42:45]
	v_mfma_f32_16x16x32_bf16 v[50:53], v[58:61], v[78:81], v[54:57]
	v_mfma_f32_16x16x32_bf16 v[10:13], v[58:61], v[82:85], v[10:13]
	v_mfma_f32_16x16x32_bf16 v[18:21], v[62:65], v[66:69], v[18:21]
	v_mfma_f32_16x16x32_bf16 v[22:25], v[62:65], v[74:77], v[22:25]
	v_mfma_f32_16x16x32_bf16 v[26:29], v[62:65], v[78:81], v[26:29]
	v_mfma_f32_16x16x32_bf16 v[14:17], v[62:65], v[82:85], v[14:17]
	s_setprio 0
	v_and_or_b32 v54, v114, 64, s10
	v_add_u32_e32 v0, s9, v117
	v_ashrrev_i32_e32 v55, 31, v54
	v_lshl_or_b32 v58, v116, 2, v0
	v_lshl_add_u64 v[54:55], v[54:55], 2, s[0:1]
	v_lshlrev_b32_e32 v0, 2, v115
	v_lshl_add_u64 v[54:55], v[54:55], 0, v[0:1]
	v_mad_i64_i32 v[56:57], s[6:7], v58, s68, v[54:55]
	v_or_b32_e32 v0, 1, v58
	s_barrier
; DEV int bidx() { int b = __builtin_amdgcn_readfirstlane(blockIdx.x); asm volatile("" : "+s"(b)); return b; }
; DEV int gdim() { int g = __builtin_amdgcn_readfirstlane(gridDim.x); asm volatile("" : "+s"(g)); return g; }
; template <int EPI, bool AF32>
; DEV void gemm_tile(const void* Ap, int lda, const u16* Bt, int ldb, int K, int m0, int n0, const Epi& ea, char* smem) {
;     ...
;   for (int m = 0; m < 4; m++) {
; #pragma unroll
;     for (int j = 0; j < 4; j++) {
;       const int row = m0 + wr * 64 + m * 16 + fq * 4 + j;
;       if (EPI == EP_F32) {
;         float* C = (float*)ea.p0;
; #pragma unroll
;         for (int n = 0; n < 4; n++) C[(size_t)row * ea.ld + cb + n * 16 + fr] = acc[m][n][j];
; template <int EPI, bool AF32>
; DEV void gemm_phase(const void* A, int lda, const u16* Bt, int ldb, int M, int N, int K, const Epi& ea, char* smem) {
;     ...
;   for (int tile = bidx(); tile < ntm * ntn; tile += gdim()) {
;     int m, n;
;     tile_mn(tile, ntm, ntn, m, n);
;     gemm_tile<EPI, AF32>(A, lda, Bt, ldb, K, m << 7, n << 7, ea, smem);
;   }
	global_store_dword v[56:57], v94, off
	global_store_dword v[56:57], v90, off offset:64
	global_store_dword v[56:57], v86, off offset:128
	global_store_dword v[56:57], v2, off offset:192
	v_mad_i64_i32 v[56:57], s[6:7], v0, s68, v[54:55]
	v_or_b32_e32 v0, 2, v58
	global_store_dword v[56:57], v95, off
	global_store_dword v[56:57], v91, off offset:64
	global_store_dword v[56:57], v87, off offset:128
	global_store_dword v[56:57], v3, off offset:192
	v_mad_i64_i32 v[2:3], s[6:7], v0, s68, v[54:55]
	v_or_b32_e32 v0, 3, v58
	global_store_dword v[2:3], v96, off
	global_store_dword v[2:3], v92, off offset:64
	global_store_dword v[2:3], v88, off offset:128
	global_store_dword v[2:3], v4, off offset:192
	v_mad_i64_i32 v[2:3], s[6:7], v0, s68, v[54:55]
	v_or_b32_e32 v0, 16, v58
	global_store_dword v[2:3], v97, off
	global_store_dword v[2:3], v93, off offset:64
	global_store_dword v[2:3], v89, off offset:128
	global_store_dword v[2:3], v5, off offset:192
	v_mad_i64_i32 v[2:3], s[6:7], v0, s68, v[54:55]
	v_or_b32_e32 v0, 17, v58
	global_store_dword v[2:3], v30, off
	global_store_dword v[2:3], v38, off offset:64
	global_store_dword v[2:3], v46, off offset:128
	global_store_dword v[2:3], v6, off offset:192
	v_mad_i64_i32 v[2:3], s[6:7], v0, s68, v[54:55]
	v_or_b32_e32 v0, 18, v58
	global_store_dword v[2:3], v31, off
	global_store_dword v[2:3], v39, off offset:64
	global_store_dword v[2:3], v47, off offset:128
	global_store_dword v[2:3], v7, off offset:192
	v_mad_i64_i32 v[2:3], s[6:7], v0, s68, v[54:55]
	v_or_b32_e32 v0, 19, v58
	global_store_dword v[2:3], v32, off
	global_store_dword v[2:3], v40, off offset:64
	global_store_dword v[2:3], v48, off offset:128
	global_store_dword v[2:3], v8, off offset:192
	v_mad_i64_i32 v[2:3], s[6:7], v0, s68, v[54:55]
	v_or_b32_e32 v0, 32, v58
	global_store_dword v[2:3], v33, off
	global_store_dword v[2:3], v41, off offset:64
	global_store_dword v[2:3], v49, off offset:128
	global_store_dword v[2:3], v9, off offset:192
	v_mad_i64_i32 v[2:3], s[6:7], v0, s68, v[54:55]
	v_or_b32_e32 v0, 33, v58
	global_store_dword v[2:3], v34, off
	global_store_dword v[2:3], v42, off offset:64
	global_store_dword v[2:3], v50, off offset:128
	global_store_dword v[2:3], v10, off offset:192
	v_mad_i64_i32 v[2:3], s[6:7], v0, s68, v[54:55]
	v_or_b32_e32 v0, 34, v58
	global_store_dword v[2:3], v35, off
	global_store_dword v[2:3], v43, off offset:64
	global_store_dword v[2:3], v51, off offset:128
	global_store_dword v[2:3], v11, off offset:192
	v_mad_i64_i32 v[2:3], s[6:7], v0, s68, v[54:55]
	v_or_b32_e32 v0, 35, v58
	global_store_dword v[2:3], v36, off
	global_store_dword v[2:3], v44, off offset:64
	global_store_dword v[2:3], v52, off offset:128
	global_store_dword v[2:3], v12, off offset:192
	v_mad_i64_i32 v[2:3], s[6:7], v0, s68, v[54:55]
	v_or_b32_e32 v0, 48, v58
	global_store_dword v[2:3], v37, off
	global_store_dword v[2:3], v45, off offset:64
	global_store_dword v[2:3], v53, off offset:128
	global_store_dword v[2:3], v13, off offset:192
	v_mad_i64_i32 v[2:3], s[6:7], v0, s68, v[54:55]
	v_or_b32_e32 v0, 49, v58
	global_store_dword v[2:3], v18, off
	global_store_dword v[2:3], v22, off offset:64
	global_store_dword v[2:3], v26, off offset:128
	global_store_dword v[2:3], v14, off offset:192
	v_mad_i64_i32 v[2:3], s[6:7], v0, s68, v[54:55]
	v_or_b32_e32 v0, 50, v58
	global_store_dword v[2:3], v19, off
	global_store_dword v[2:3], v23, off offset:64
	global_store_dword v[2:3], v27, off offset:128
	global_store_dword v[2:3], v15, off offset:192
	v_mad_i64_i32 v[2:3], s[6:7], v0, s68, v[54:55]
	v_or_b32_e32 v0, 51, v58
	global_store_dword v[2:3], v20, off
	global_store_dword v[2:3], v24, off offset:64
	global_store_dword v[2:3], v28, off offset:128
	global_store_dword v[2:3], v16, off offset:192
	v_mad_i64_i32 v[2:3], s[6:7], v0, s68, v[54:55]
	v_readfirstlane_b32 s6, v198
	global_store_dword v[2:3], v21, off
	global_store_dword v[2:3], v25, off offset:64
	global_store_dword v[2:3], v29, off offset:128
	global_store_dword v[2:3], v17, off offset:192
	s_add_i32 s8, s6, s8
	s_cmpk_lt_i32 s8, 0x618
	s_cbranch_scc1 .LBB0_164

; template <int EPI, bool AF32>
; DEV void gemm_tile(const void* Ap, int lda, const u16* Bt, int ldb, int K, int m0, int n0, const Epi& ea, char* smem) {
;     ...
;   auto gload = [&](int kt) {
;     const int k0 = kt << 6;
; #pragma unroll
;     for (int i = 0; i < 4; i++) {
;       const int c = tid + i * 256, row = c >> 3, kc = c & 7;
;       if (AF32) {
;         const float* pa = (const float*)Ap + (size_t)(m0 + row) * lda + k0 + kc * 8;
;         rfa[2 * i] = *(const f32x4*)pa;
;         rfa[2 * i + 1] = *(const f32x4*)(pa + 4);
;       } else {
;         ra[i] = *(const u32x4*)((const u16*)Ap + (size_t)(m0 + row) * lda + k0 + kc * 8);
;       }
;       rb[i] = *(const u32x4*)(Bt + (size_t)(n0 + row) * ldb + k0 + kc * 8);
;     }
;   };
;   auto swrite = [&](int buf) {
; #pragma unroll
;     for (int i = 0; i < 4; i++) {
;       const int c = tid + i * 256, row = c >> 3, kc = c & 7;
;       u32x4 va;
;       if (AF32) {
;         va = (u32x4){pack2(rfa[2 * i][0], rfa[2 * i][1]), pack2(rfa[2 * i][2], rfa[2 * i][3]),
;                      pack2(rfa[2 * i + 1][0], rfa[2 * i + 1][1]), pack2(rfa[2 * i + 1][2], rfa[2 * i + 1][3])};
;       } else {
;         va = ra[i];
;       }
;       *(u32x4*)(sA + buf * 9216 + row * 72 + kc * 8) = va;
;       *(u32x4*)(sB + buf * 9216 + row * 72 + kc * 8) = rb[i];
;     }
;   };
;   gload(0);
;   swrite(0);
;   if (nk > 1) gload(1);
;   __syncthreads();
.LBB0_547:
	s_ashr_i32 s0, s26, 31
	s_lshr_b32 s0, s0, 22
	s_add_i32 s0, s26, s0
	s_ashr_i32 s1, s0, 10
	s_and_b32 s0, s0, 0xfffffc00
	s_lshl_b32 s3, s1, 5
	s_sub_i32 s2, s26, s0
	s_sub_i32 s0, 0x104, s3
	s_min_u32 s4, s0, 32
	v_cvt_f32_ubyte0_e32 v2, s4
	v_cvt_f32_i32_e32 v0, s2
	v_rcp_iflag_f32_e32 v3, v2
	s_ashr_i32 s0, s2, 30
	s_or_b32 s5, s0, 1
	s_waitcnt vmcnt(12)
	v_mov_b32_e32 v114, v157
	v_mul_f32_e32 v3, v0, v3
	v_trunc_f32_e32 v3, v3
	v_fma_f32 v0, -v3, v2, v0
	v_cvt_i32_f32_e32 v3, v3
	v_cmp_ge_f32_e64 s[0:1], |v0|, v2
	s_and_b64 s[0:1], s[0:1], exec
	s_cselect_b32 s0, s5, 0
	v_readfirstlane_b32 s1, v3
	s_add_i32 s0, s1, s0
	s_sext_i32_i16 s29, s0
	s_mul_i32 s0, s0, s4
	s_sub_i32 s0, s2, s0
	s_sext_i32_i16 s0, s0
	s_add_i32 s3, s3, s0
	s_lshl_b32 s2, s3, 7
	s_lshl_b32 s3, s29, 7
	v_ashrrev_i32_e32 v8, 3, v114
	v_add_u32_e32 v2, s2, v8
	v_ashrrev_i32_e32 v3, 31, v2
	v_lshlrev_b32_e32 v0, 3, v114
	v_add_u32_e32 v4, 0x100, v114
	v_lshlrev_b64 v[58:59], 11, v[2:3]
	v_and_b32_e32 v0, 56, v0
	v_ashrrev_i32_e32 v9, 3, v4
	v_lshl_add_u64 v[2:3], s[60:61], 0, v[58:59]
	v_lshlrev_b32_e32 v0, 1, v0
	v_add_u32_e32 v4, s2, v9
	v_add_u32_e32 v6, 0x200, v114
	v_lshl_add_u64 v[14:15], v[2:3], 0, v[0:1]
	v_add_u32_e32 v2, s3, v8
	v_ashrrev_i32_e32 v5, 31, v4
	v_ashrrev_i32_e32 v10, 3, v6
	v_ashrrev_i32_e32 v3, 31, v2
	v_lshlrev_b64 v[62:63], 11, v[4:5]
	v_add_u32_e32 v6, s2, v10
	v_lshlrev_b64 v[60:61], 11, v[2:3]
	v_lshl_add_u64 v[4:5], s[60:61], 0, v[62:63]
	v_ashrrev_i32_e32 v7, 31, v6
	v_lshl_add_u64 v[2:3], s[12:13], 0, v[60:61]
	v_lshl_add_u64 v[16:17], v[4:5], 0, v[0:1]
	v_add_u32_e32 v4, s3, v9
	v_lshlrev_b64 v[66:67], 11, v[6:7]
	v_lshl_add_u64 v[2:3], v[2:3], 0, v[0:1]
	v_ashrrev_i32_e32 v5, 31, v4
	v_lshl_add_u64 v[6:7], s[60:61], 0, v[66:67]
	global_load_dwordx4 v[30:33], v[2:3], off
	v_lshlrev_b64 v[64:65], 11, v[4:5]
	v_lshl_add_u64 v[68:69], v[6:7], 0, v[0:1]
	v_add_u32_e32 v6, s3, v10
	global_load_dwordx4 v[26:29], v[14:15], off
	global_load_dwordx4 v[34:37], v[16:17], off
	v_lshl_add_u64 v[4:5], s[12:13], 0, v[64:65]
	v_ashrrev_i32_e32 v7, 31, v6
	v_lshl_add_u64 v[4:5], v[4:5], 0, v[0:1]
	v_lshlrev_b64 v[70:71], 11, v[6:7]
	global_load_dwordx4 v[38:41], v[4:5], off
	v_lshl_add_u64 v[6:7], s[12:13], 0, v[70:71]
	global_load_dwordx4 v[42:45], v[68:69], off
	v_lshl_add_u64 v[18:19], v[6:7], 0, v[0:1]
	global_load_dwordx4 v[46:49], v[18:19], off
	v_add_u32_e32 v6, 0x300, v114
	v_ashrrev_i32_e32 v80, 3, v6
	v_add_u32_e32 v6, s2, v80
	v_ashrrev_i32_e32 v7, 31, v6
	v_lshlrev_b64 v[72:73], 11, v[6:7]
	v_lshl_add_u64 v[6:7], s[60:61], 0, v[72:73]
	v_lshl_add_u64 v[74:75], v[6:7], 0, v[0:1]
	v_add_u32_e32 v6, s3, v80
	v_ashrrev_i32_e32 v7, 31, v6
	v_lshlrev_b64 v[76:77], 11, v[6:7]
	v_lshl_add_u64 v[6:7], s[12:13], 0, v[76:77]
	v_lshl_add_u64 v[78:79], v[6:7], 0, v[0:1]
	global_load_dwordx4 v[50:53], v[74:75], off
	global_load_dwordx4 v[54:57], v[78:79], off
	s_waitcnt vmcnt(19)
	v_mul_lo_u32 v118, v8, s71
	v_mul_lo_u32 v119, v9, s71
	s_waitcnt vmcnt(18)
	v_mul_lo_u32 v123, v10, s71
	global_load_dwordx4 v[6:9], v[2:3], off offset:128
	global_load_dwordx4 v[10:13], v[4:5], off offset:128
	s_nop 0
	global_load_dwordx4 v[2:5], v[18:19], off offset:128
	global_load_dwordx4 v[22:25], v[14:15], off offset:128
	s_nop 0
	global_load_dwordx4 v[18:21], v[16:17], off offset:128
	s_nop 0
	global_load_dwordx4 v[14:17], v[68:69], off offset:128
	v_bfe_u32 v161, v157, 3, 4
	v_add_u32_e32 v161, 4, v161
	v_lshlrev_b32_e32 v161, 1, v161
	v_and_b32_e32 v161, 16, v161
	v_xor_b32_e32 v129, v0, v161
	v_lshl_add_u32 v122, v118, 1, v129
	v_lshl_add_u32 v121, v119, 1, v129
	v_lshl_add_u32 v120, v123, 1, v129
	v_and_b32_e32 v116, 15, v114
	s_waitcnt vmcnt(23)
	v_mul_lo_u32 v126, v80, s71
	v_bfe_u32 v115, v114, 4, 2
	v_lshl_add_u32 v124, v126, 1, v129
	s_mov_b32 s4, 0
	v_lshlrev_b32_e32 v125, 4, v115
	v_and_b32_e32 v161, 15, v157
	v_add_u32_e32 v161, 4, v161
	v_lshlrev_b32_e32 v161, 1, v161
	v_and_b32_e32 v161, 16, v161
	v_xor_b32_e32 v125, v125, v161
	s_mov_b64 s[0:1], 0
	s_waitcnt vmcnt(13)
	ds_write_b128 v122, v[30:33] offset:36864
	s_waitcnt vmcnt(12)
	ds_write_b128 v122, v[26:29]
	s_waitcnt vmcnt(11)
	ds_write_b128 v121, v[34:37]
	s_waitcnt vmcnt(10)
	ds_write_b128 v121, v[38:41] offset:36864
	s_waitcnt vmcnt(9)
	ds_write_b128 v120, v[42:45]
	s_waitcnt vmcnt(8)
	ds_write_b128 v120, v[46:49] offset:36864
	global_load_dwordx4 v[26:29], v[74:75], off offset:128
	global_load_dwordx4 v[30:33], v[78:79], off offset:128
	v_ashrrev_i32_e32 v34, 1, v114
	v_and_b32_e32 v117, 0xffffffc0, v34
	v_or_b32_e32 v34, v117, v116
	v_mul_lo_u32 v128, v34, s71
	v_lshlrev_b32_e32 v34, 4, v114
	v_and_b32_e32 v34, 0x70, v34
	v_and_b32_e32 v35, 0x4f, v114
	v_or_b32_e32 v76, v76, v34
	v_or_b32_e32 v72, v72, v34
	v_or_b32_e32 v70, v70, v34
	v_or_b32_e32 v66, v66, v34
	v_or_b32_e32 v64, v64, v34
	v_or_b32_e32 v62, v62, v34
	v_or_b32_e32 v60, v60, v34
	v_or_b32_e32 v58, v58, v34
	v_mov_b32_e32 v34, 0
	s_waitcnt vmcnt(9)
	ds_write_b128 v124, v[50:53]
	s_waitcnt vmcnt(8)
; template <int EPI, bool AF32>
; DEV void gemm_tile(const void* Ap, int lda, const u16* Bt, int ldb, int K, int m0, int n0, const Epi& ea, char* smem) {
;     ...
;   f32x4 acc[4][4];
; #pragma unroll
;   for (int m = 0; m < 4; m++)
; #pragma unroll
;     for (int n = 0; n < 4; n++) acc[m][n] = (f32x4){0.f, 0.f, 0.f, 0.f};
;   u32x4 ra[4], rb[4];
;   f32x4 rfa[8];
;   const int nk = K >> 6;
;   auto gload = [&](int kt) {
;     const int k0 = kt << 6;
; #pragma unroll
;     for (int i = 0; i < 4; i++) {
;       const int c = tid + i * 256, row = c >> 3, kc = c & 7;
;       if (AF32) {
;         const float* pa = (const float*)Ap + (size_t)(m0 + row) * lda + k0 + kc * 8;
;         rfa[2 * i] = *(const f32x4*)pa;
;         rfa[2 * i + 1] = *(const f32x4*)(pa + 4);
;       } else {
;         ra[i] = *(const u32x4*)((const u16*)Ap + (size_t)(m0 + row) * lda + k0 + kc * 8);
;       }
;       rb[i] = *(const u32x4*)(Bt + (size_t)(n0 + row) * ldb + k0 + kc * 8);
;     }
;   };
;   auto swrite = [&](int buf) {
; #pragma unroll
;     for (int i = 0; i < 4; i++) {
;       const int c = tid + i * 256, row = c >> 3, kc = c & 7;
;       u32x4 va;
;       if (AF32) {
;         va = (u32x4){pack2(rfa[2 * i][0], rfa[2 * i][1]), pack2(rfa[2 * i][2], rfa[2 * i][3]),
;                      pack2(rfa[2 * i + 1][0], rfa[2 * i + 1][1]), pack2(rfa[2 * i + 1][2], rfa[2 * i + 1][3])};
;       } else {
;         va = ra[i];
;       }
;       *(u32x4*)(sA + buf * 9216 + row * 72 + kc * 8) = va;
;       *(u32x4*)(sB + buf * 9216 + row * 72 + kc * 8) = rb[i];
;     }
;   };
;   gload(0);
;   swrite(0);
;   if (nk > 1) gload(1);
;   __syncthreads();
;   for (int kt = 0; kt < nk; kt++) {
;     const int buf = kt & 1;
;     if (kt + 1 < nk) swrite(buf ^ 1);
;     if (kt + 2 < nk) gload(kt + 2);
; #pragma unroll
;     for (int ks = 0; ks < 2; ks++) {
;       bf16x8 a[4], b[4];
; #pragma unroll
;       for (int m = 0; m < 4; m++) a[m] = *(const bf16x8*)(sA + buf * 9216 + (wr * 64 + m * 16 + fr) * 72 + ks * 32 + fq * 8);
; #pragma unroll
;       for (int n = 0; n < 4; n++) b[n] = *(const bf16x8*)(sB + buf * 9216 + (wc * 64 + n * 16 + fr) * 72 + ks * 32 + fq * 8);
;       __builtin_amdgcn_s_setprio(1);
; #pragma unroll
;       for (int m = 0; m < 4; m++)
; #pragma unroll
;         for (int n = 0; n < 4; n++) acc[m][n] = mfma16(a[m], b[n], acc[m][n]);
;       __builtin_amdgcn_s_setprio(0);
;     }
	ds_write_b128 v124, v[54:57] offset:36864
	v_mul_u32_u24_e32 v127, 0x48, v35
	v_lshl_add_u64 v[98:99], s[20:21], 0, v[76:77]
	v_lshl_add_u64 v[100:101], s[66:67], 0, v[72:73]
	v_lshl_add_u64 v[102:103], s[20:21], 0, v[70:71]
	v_lshl_add_u64 v[104:105], s[66:67], 0, v[66:67]
	v_lshl_add_u64 v[106:107], s[20:21], 0, v[64:65]
	v_lshl_add_u64 v[108:109], s[66:67], 0, v[62:63]
	v_lshl_add_u64 v[110:111], s[20:21], 0, v[60:61]
	v_lshl_add_u64 v[112:113], s[66:67], 0, v[58:59]
	global_load_dwordx4 v[222:225], v[112:113], off
	global_load_dwordx4 v[226:229], v[110:111], off
	global_load_dwordx4 v[230:233], v[108:109], off
	global_load_dwordx4 v[234:237], v[106:107], off
	global_load_dwordx4 v[238:241], v[104:105], off
	global_load_dwordx4 v[242:245], v[102:103], off
	global_load_dwordx4 v[246:249], v[100:101], off
	global_load_dwordx4 v[250:253], v[98:99], off
	v_mov_b32_e32 v35, v34
	v_mov_b32_e32 v36, v34
	v_mov_b32_e32 v37, v34
	v_mov_b32_e32 v38, v34
	v_mov_b32_e32 v39, v34
	v_mov_b32_e32 v40, v34
	v_mov_b32_e32 v41, v34
	v_mov_b32_e32 v42, v34
	v_mov_b32_e32 v43, v34
	v_mov_b32_e32 v44, v34
	v_mov_b32_e32 v45, v34
	v_mov_b32_e32 v46, v34
	v_mov_b32_e32 v47, v34
	v_mov_b32_e32 v48, v34
	v_mov_b32_e32 v49, v34
	v_mov_b32_e32 v50, v34
	v_mov_b32_e32 v51, v34
	v_mov_b32_e32 v52, v34
	v_mov_b32_e32 v53, v34
	v_mov_b32_e32 v54, v34
	v_mov_b32_e32 v55, v34
	v_mov_b32_e32 v56, v34
	v_mov_b32_e32 v57, v34
	v_mov_b32_e32 v58, v34
	v_mov_b32_e32 v59, v34
	v_mov_b32_e32 v60, v34
	v_mov_b32_e32 v61, v34
	v_mov_b32_e32 v62, v34
	v_mov_b32_e32 v63, v34
	v_mov_b32_e32 v64, v34
	v_mov_b32_e32 v65, v34
	v_mov_b32_e32 v66, v34
	v_mov_b32_e32 v67, v34
	v_mov_b32_e32 v68, v34
	v_mov_b32_e32 v69, v34
	v_mov_b32_e32 v70, v34
	v_mov_b32_e32 v71, v34
	v_mov_b32_e32 v72, v34
	v_mov_b32_e32 v73, v34
	v_mov_b32_e32 v74, v34
	v_mov_b32_e32 v75, v34
	v_mov_b32_e32 v76, v34
	v_mov_b32_e32 v77, v34
	v_mov_b32_e32 v78, v34
	v_mov_b32_e32 v79, v34
	v_mov_b32_e32 v80, v34
	v_mov_b32_e32 v81, v34
	v_mov_b32_e32 v82, v34
	v_mov_b32_e32 v83, v34
	v_mov_b32_e32 v84, v34
	v_mov_b32_e32 v85, v34
	v_mov_b32_e32 v86, v34
	v_mov_b32_e32 v87, v34
	v_mov_b32_e32 v88, v34
	v_mov_b32_e32 v89, v34
	v_mov_b32_e32 v90, v34
	v_mov_b32_e32 v91, v34
	v_mov_b32_e32 v92, v34
	v_mov_b32_e32 v93, v34
	v_mov_b32_e32 v94, v34
	v_mov_b32_e32 v95, v34
	v_mov_b32_e32 v96, v34
	v_mov_b32_e32 v97, v34
	s_waitcnt lgkmcnt(0)
	s_barrier
	v_lshl_add_u32 v161, v128, 1, v125
	v_lshl_add_u32 v129, v127, 1, v125
	s_mov_b32 s4, 0
	s_mov_b64 s[0:1], 0x100
.Lgk1_loop:
	v_lshl_add_u64 v[112:113], v[112:113], 0, s[0:1]
	v_lshl_add_u64 v[110:111], v[110:111], 0, s[0:1]
	v_lshl_add_u64 v[108:109], v[108:109], 0, s[0:1]
	v_lshl_add_u64 v[106:107], v[106:107], 0, s[0:1]
	v_lshl_add_u64 v[104:105], v[104:105], 0, s[0:1]
	v_lshl_add_u64 v[102:103], v[102:103], 0, s[0:1]
	v_lshl_add_u64 v[100:101], v[100:101], 0, s[0:1]
	v_lshl_add_u64 v[98:99], v[98:99], 0, s[0:1]
	ds_read_b128 v[130:133], v161
	ds_read_b128 v[134:137], v161 offset:2304
	ds_read_b128 v[138:141], v161 offset:4608
	ds_read_b128 v[142:145], v161 offset:6912
	ds_read_b128 v[146:149], v129 offset:36864
	ds_read_b128 v[150:153], v129 offset:39168
	ds_read_b128 v[162:165], v129 offset:41472
	ds_read_b128 v[166:169], v129 offset:43776
	s_setprio 1
	s_waitcnt lgkmcnt(3)
	v_mfma_f32_16x16x32_bf16 v[94:97], v[130:133], v[146:149], v[94:97]
	s_waitcnt lgkmcnt(2)
	v_mfma_f32_16x16x32_bf16 v[90:93], v[130:133], v[150:153], v[90:93]
	s_waitcnt lgkmcnt(1)
	v_mfma_f32_16x16x32_bf16 v[86:89], v[130:133], v[162:165], v[86:89]
	s_waitcnt lgkmcnt(0)
	v_mfma_f32_16x16x32_bf16 v[82:85], v[130:133], v[166:169], v[82:85]
	v_mfma_f32_16x16x32_bf16 v[78:81], v[134:137], v[146:149], v[78:81]
	v_mfma_f32_16x16x32_bf16 v[74:77], v[134:137], v[150:153], v[74:77]
	v_mfma_f32_16x16x32_bf16 v[70:73], v[134:137], v[162:165], v[70:73]
	v_mfma_f32_16x16x32_bf16 v[66:69], v[134:137], v[166:169], v[66:69]
	v_mfma_f32_16x16x32_bf16 v[62:65], v[138:141], v[146:149], v[62:65]
	v_mfma_f32_16x16x32_bf16 v[58:61], v[138:141], v[150:153], v[58:61]
	v_mfma_f32_16x16x32_bf16 v[54:57], v[138:141], v[162:165], v[54:57]
	v_mfma_f32_16x16x32_bf16 v[50:53], v[138:141], v[166:169], v[50:53]
	v_mfma_f32_16x16x32_bf16 v[46:49], v[142:145], v[146:149], v[46:49]
	v_mfma_f32_16x16x32_bf16 v[42:45], v[142:145], v[150:153], v[42:45]
	v_mfma_f32_16x16x32_bf16 v[38:41], v[142:145], v[162:165], v[38:41]
	v_mfma_f32_16x16x32_bf16 v[34:37], v[142:145], v[166:169], v[34:37]
	s_setprio 0
	ds_read_b128 v[130:133], v161 offset:64
	ds_read_b128 v[134:137], v161 offset:2368
	ds_read_b128 v[138:141], v161 offset:4672
	ds_read_b128 v[142:145], v161 offset:6976
	ds_read_b128 v[146:149], v129 offset:36928
	ds_read_b128 v[150:153], v129 offset:39232
	ds_read_b128 v[162:165], v129 offset:41536
	ds_read_b128 v[166:169], v129 offset:43840
	s_waitcnt vmcnt(8)
	ds_write_b128 v122, v[22:25] offset:18432
	ds_write_b128 v122, v[6:9] offset:55296
	ds_write_b128 v121, v[18:21] offset:18432
	ds_write_b128 v121, v[10:13] offset:55296
	ds_write_b128 v120, v[14:17] offset:18432
	ds_write_b128 v120, v[2:5] offset:55296
	ds_write_b128 v124, v[26:29] offset:18432
	ds_write_b128 v124, v[30:33] offset:55296
	global_load_dwordx4 v[22:25], v[112:113], off offset:-128
	global_load_dwordx4 v[6:9], v[110:111], off offset:-128
	global_load_dwordx4 v[18:21], v[108:109], off offset:-128
	global_load_dwordx4 v[10:13], v[106:107], off offset:-128
	global_load_dwordx4 v[14:17], v[104:105], off offset:-128
	global_load_dwordx4 v[2:5], v[102:103], off offset:-128
	global_load_dwordx4 v[26:29], v[100:101], off offset:-128
	global_load_dwordx4 v[30:33], v[98:99], off offset:-128
	s_setprio 1
	s_waitcnt lgkmcnt(11)
	v_mfma_f32_16x16x32_bf16 v[94:97], v[130:133], v[146:149], v[94:97]
	s_waitcnt lgkmcnt(10)
	v_mfma_f32_16x16x32_bf16 v[90:93], v[130:133], v[150:153], v[90:93]
	s_waitcnt lgkmcnt(9)
	v_mfma_f32_16x16x32_bf16 v[86:89], v[130:133], v[162:165], v[86:89]
	s_waitcnt lgkmcnt(8)
	v_mfma_f32_16x16x32_bf16 v[82:85], v[130:133], v[166:169], v[82:85]
	v_mfma_f32_16x16x32_bf16 v[78:81], v[134:137], v[146:149], v[78:81]
	v_mfma_f32_16x16x32_bf16 v[74:77], v[134:137], v[150:153], v[74:77]
	v_mfma_f32_16x16x32_bf16 v[70:73], v[134:137], v[162:165], v[70:73]
	v_mfma_f32_16x16x32_bf16 v[66:69], v[134:137], v[166:169], v[66:69]
	v_mfma_f32_16x16x32_bf16 v[62:65], v[138:141], v[146:149], v[62:65]
	v_mfma_f32_16x16x32_bf16 v[58:61], v[138:141], v[150:153], v[58:61]
	v_mfma_f32_16x16x32_bf16 v[54:57], v[138:141], v[162:165], v[54:57]
	v_mfma_f32_16x16x32_bf16 v[50:53], v[138:141], v[166:169], v[50:53]
	v_mfma_f32_16x16x32_bf16 v[46:49], v[142:145], v[146:149], v[46:49]
	v_mfma_f32_16x16x32_bf16 v[42:45], v[142:145], v[150:153], v[42:45]
	v_mfma_f32_16x16x32_bf16 v[38:41], v[142:145], v[162:165], v[38:41]
	v_mfma_f32_16x16x32_bf16 v[34:37], v[142:145], v[166:169], v[34:37]
	s_setprio 0
	s_waitcnt lgkmcnt(0)
	s_barrier
; DEV f32x4 mfma16(bf16x8 a, bf16x8 b, f32x4 c) { return __builtin_amdgcn_mfma_f32_16x16x32_bf16(a, b, c, 0, 0, 0); }
; template <int EPI, bool AF32>
; DEV void gemm_tile(const void* Ap, int lda, const u16* Bt, int ldb, int K, int m0, int n0, const Epi& ea, char* smem) {
;     ...
;   for (int kt = 0; kt < nk; kt++) {
;     const int buf = kt & 1;
;     if (kt + 1 < nk) swrite(buf ^ 1);
;     if (kt + 2 < nk) gload(kt + 2);
; #pragma unroll
;     for (int ks = 0; ks < 2; ks++) {
;       bf16x8 a[4], b[4];
; #pragma unroll
;       for (int m = 0; m < 4; m++) a[m] = *(const bf16x8*)(sA + buf * 9216 + (wr * 64 + m * 16 + fr) * 72 + ks * 32 + fq * 8);
; #pragma unroll
;       for (int n = 0; n < 4; n++) b[n] = *(const bf16x8*)(sB + buf * 9216 + (wc * 64 + n * 16 + fr) * 72 + ks * 32 + fq * 8);
;       __builtin_amdgcn_s_setprio(1);
; #pragma unroll
;       for (int m = 0; m < 4; m++)
; #pragma unroll
;         for (int n = 0; n < 4; n++) acc[m][n] = mfma16(a[m], b[n], acc[m][n]);
;       __builtin_amdgcn_s_setprio(0);
;     }
;     __syncthreads();
;   }
	ds_read_b128 v[130:133], v161 offset:18432
	ds_read_b128 v[134:137], v161 offset:20736
	ds_read_b128 v[138:141], v161 offset:23040
	ds_read_b128 v[142:145], v161 offset:25344
	ds_read_b128 v[146:149], v129 offset:55296
	ds_read_b128 v[150:153], v129 offset:57600
	ds_read_b128 v[162:165], v129 offset:59904
	ds_read_b128 v[166:169], v129 offset:62208
	s_setprio 1
	s_waitcnt lgkmcnt(3)
	v_mfma_f32_16x16x32_bf16 v[94:97], v[130:133], v[146:149], v[94:97]
	s_waitcnt lgkmcnt(2)
	v_mfma_f32_16x16x32_bf16 v[90:93], v[130:133], v[150:153], v[90:93]
	s_waitcnt lgkmcnt(1)
	v_mfma_f32_16x16x32_bf16 v[86:89], v[130:133], v[162:165], v[86:89]
	s_waitcnt lgkmcnt(0)
	v_mfma_f32_16x16x32_bf16 v[82:85], v[130:133], v[166:169], v[82:85]
	v_mfma_f32_16x16x32_bf16 v[78:81], v[134:137], v[146:149], v[78:81]
	v_mfma_f32_16x16x32_bf16 v[74:77], v[134:137], v[150:153], v[74:77]
	v_mfma_f32_16x16x32_bf16 v[70:73], v[134:137], v[162:165], v[70:73]
	v_mfma_f32_16x16x32_bf16 v[66:69], v[134:137], v[166:169], v[66:69]
	v_mfma_f32_16x16x32_bf16 v[62:65], v[138:141], v[146:149], v[62:65]
	v_mfma_f32_16x16x32_bf16 v[58:61], v[138:141], v[150:153], v[58:61]
	v_mfma_f32_16x16x32_bf16 v[54:57], v[138:141], v[162:165], v[54:57]
	v_mfma_f32_16x16x32_bf16 v[50:53], v[138:141], v[166:169], v[50:53]
	v_mfma_f32_16x16x32_bf16 v[46:49], v[142:145], v[146:149], v[46:49]
	v_mfma_f32_16x16x32_bf16 v[42:45], v[142:145], v[150:153], v[42:45]
	v_mfma_f32_16x16x32_bf16 v[38:41], v[142:145], v[162:165], v[38:41]
	v_mfma_f32_16x16x32_bf16 v[34:37], v[142:145], v[166:169], v[34:37]
	s_setprio 0
	ds_read_b128 v[130:133], v161 offset:18496
	ds_read_b128 v[134:137], v161 offset:20800
	ds_read_b128 v[138:141], v161 offset:23104
	ds_read_b128 v[142:145], v161 offset:25408
	ds_read_b128 v[146:149], v129 offset:55360
	ds_read_b128 v[150:153], v129 offset:57664
	ds_read_b128 v[162:165], v129 offset:59968
	ds_read_b128 v[166:169], v129 offset:62272
	s_waitcnt vmcnt(8)
	ds_write_b128 v122, v[222:225]
	ds_write_b128 v122, v[226:229] offset:36864
	ds_write_b128 v121, v[230:233]
	ds_write_b128 v121, v[234:237] offset:36864
	ds_write_b128 v120, v[238:241]
	ds_write_b128 v120, v[242:245] offset:36864
	ds_write_b128 v124, v[246:249]
	ds_write_b128 v124, v[250:253] offset:36864
	s_cmp_eq_u32 s4, 6
	s_cbranch_scc1 .Lgk1_nold
	global_load_dwordx4 v[222:225], v[112:113], off
	global_load_dwordx4 v[226:229], v[110:111], off
	global_load_dwordx4 v[230:233], v[108:109], off
	global_load_dwordx4 v[234:237], v[106:107], off
	global_load_dwordx4 v[238:241], v[104:105], off
	global_load_dwordx4 v[242:245], v[102:103], off
	global_load_dwordx4 v[246:249], v[100:101], off
	global_load_dwordx4 v[250:253], v[98:99], off
.Lgk1_nold:
	s_setprio 1
	s_waitcnt lgkmcnt(11)
	v_mfma_f32_16x16x32_bf16 v[94:97], v[130:133], v[146:149], v[94:97]
	s_waitcnt lgkmcnt(10)
	v_mfma_f32_16x16x32_bf16 v[90:93], v[130:133], v[150:153], v[90:93]
	s_waitcnt lgkmcnt(9)
	v_mfma_f32_16x16x32_bf16 v[86:89], v[130:133], v[162:165], v[86:89]
	s_waitcnt lgkmcnt(8)
	v_mfma_f32_16x16x32_bf16 v[82:85], v[130:133], v[166:169], v[82:85]
	v_mfma_f32_16x16x32_bf16 v[78:81], v[134:137], v[146:149], v[78:81]
	v_mfma_f32_16x16x32_bf16 v[74:77], v[134:137], v[150:153], v[74:77]
	v_mfma_f32_16x16x32_bf16 v[70:73], v[134:137], v[162:165], v[70:73]
	v_mfma_f32_16x16x32_bf16 v[66:69], v[134:137], v[166:169], v[66:69]
	v_mfma_f32_16x16x32_bf16 v[62:65], v[138:141], v[146:149], v[62:65]
	v_mfma_f32_16x16x32_bf16 v[58:61], v[138:141], v[150:153], v[58:61]
	v_mfma_f32_16x16x32_bf16 v[54:57], v[138:141], v[162:165], v[54:57]
	v_mfma_f32_16x16x32_bf16 v[50:53], v[138:141], v[166:169], v[50:53]
	v_mfma_f32_16x16x32_bf16 v[46:49], v[142:145], v[146:149], v[46:49]
	v_mfma_f32_16x16x32_bf16 v[42:45], v[142:145], v[150:153], v[42:45]
	v_mfma_f32_16x16x32_bf16 v[38:41], v[142:145], v[162:165], v[38:41]
	v_mfma_f32_16x16x32_bf16 v[34:37], v[142:145], v[166:169], v[34:37]
	s_setprio 0
	s_add_i32 s4, s4, 1
	s_cmp_lg_u32 s4, 7
	s_waitcnt lgkmcnt(0)
	s_barrier
	s_cbranch_scc1 .Lgk1_loop
	s_waitcnt vmcnt(7)
	ds_write_b128 v122, v[22:25] offset:18432
	s_waitcnt vmcnt(6)
	ds_write_b128 v122, v[6:9] offset:55296
	s_waitcnt vmcnt(5)
	ds_write_b128 v121, v[18:21] offset:18432
	s_waitcnt vmcnt(4)
	ds_write_b128 v121, v[10:13] offset:55296
	s_waitcnt vmcnt(3)
	ds_write_b128 v120, v[14:17] offset:18432
	s_waitcnt vmcnt(2)
	ds_write_b128 v120, v[2:5] offset:55296
	s_waitcnt vmcnt(1)
	ds_write_b128 v124, v[26:29] offset:18432
	s_waitcnt vmcnt(0)
	ds_write_b128 v124, v[30:33] offset:55296
	v_lshl_add_u32 v0, v128, 1, v125
	v_lshl_add_u32 v134, v127, 1, v125
	ds_read_b128 v[2:5], v0
	ds_read_b128 v[6:9], v0 offset:2304
	ds_read_b128 v[10:13], v0 offset:4608
	ds_read_b128 v[14:17], v0 offset:6912
	ds_read_b128 v[18:21], v134 offset:36864
	ds_read_b128 v[22:25], v134 offset:39168
	ds_read_b128 v[26:29], v134 offset:41472
	ds_read_b128 v[30:33], v134 offset:43776
	s_setprio 1
	s_waitcnt lgkmcnt(3)
	v_mfma_f32_16x16x32_bf16 v[94:97], v[2:5], v[18:21], v[94:97]
	s_waitcnt lgkmcnt(2)
	v_mfma_f32_16x16x32_bf16 v[90:93], v[2:5], v[22:25], v[90:93]
	s_waitcnt lgkmcnt(1)
	v_mfma_f32_16x16x32_bf16 v[86:89], v[2:5], v[26:29], v[86:89]
	s_waitcnt lgkmcnt(0)
; template <int EPI, bool AF32>
; DEV void gemm_tile(const void* Ap, int lda, const u16* Bt, int ldb, int K, int m0, int n0, const Epi& ea, char* smem) {
;     ...
;   for (int kt = 0; kt < nk; kt++) {
;     const int buf = kt & 1;
;     if (kt + 1 < nk) swrite(buf ^ 1);
;     if (kt + 2 < nk) gload(kt + 2);
; #pragma unroll
;     for (int ks = 0; ks < 2; ks++) {
;       bf16x8 a[4], b[4];
; #pragma unroll
;       for (int m = 0; m < 4; m++) a[m] = *(const bf16x8*)(sA + buf * 9216 + (wr * 64 + m * 16 + fr) * 72 + ks * 32 + fq * 8);
; #pragma unroll
;       for (int n = 0; n < 4; n++) b[n] = *(const bf16x8*)(sB + buf * 9216 + (wc * 64 + n * 16 + fr) * 72 + ks * 32 + fq * 8);
;       __builtin_amdgcn_s_setprio(1);
; #pragma unroll
;       for (int m = 0; m < 4; m++)
; #pragma unroll
;         for (int n = 0; n < 4; n++) acc[m][n] = mfma16(a[m], b[n], acc[m][n]);
;       __builtin_amdgcn_s_setprio(0);
;     }
;     __syncthreads();
;   }
;     ...
;       } else if (EPI == EP_GDNA) {
;         if (cb < 3072) {
;           u16* C = (u16*)ea.p0;
;           u16* H = (u16*)ea.p2;
;           float* O = (float*)ea.p3;
;           const int l = ea.layer;
; #pragma unroll
;           for (int n = 0; n < 4; n++) {
;             const int col = cb + n * 16 + fr;
;             const float v = acc[m][n][j];
;             const u16 hv = f2bf(v);
;             if (row < T_P) {
;               __builtin_nontemporal_store(hv, &C[((size_t)((row >> 6) * 8 + ((col >> 7) & 7)) * 3 + (col >> 10)) * 8192 + (row & 63) * 128 + (col & 127)]);
;               const int r = row & 63, ci = row >> 6;
;               if (r >= 61 && ((ci + 1) & 127) != 0) H[((size_t)(ci + 1) * 3 + (r - 61)) * 3072 + col] = hv;
;               const int pos = row & 8191;
;               if (pos >= 8189) O[O_PCONV + ((size_t)(l * 4 + (row >> 13)) * 3 + (pos - 8189)) * 3072 + col] = v;
;             } else {
;               const int ts = row - T_P, i = ts & 31;
;               ((u16*)ea.p2)[(size_t)(56590336 / 2) + (size_t)ts * 3072 + col] = hv;
;               if (i >= 29) O[O_SCONV + ((size_t)(l * 16 + (ts >> 5)) * 3 + (i - 29)) * 3072 + col] = v;
;             }
;           }
;         } else {
;           u16* Z = (u16*)ea.p1;
; #pragma unroll
;           for (int n = 0; n < 4; n++) Z[(size_t)row * 1024 + cb - 3072 + n * 16 + fr] = f2bf(acc[m][n][j]);
	v_mfma_f32_16x16x32_bf16 v[2:5], v[2:5], v[30:33], v[82:85]
	v_mfma_f32_16x16x32_bf16 v[78:81], v[6:9], v[18:21], v[78:81]
	v_mfma_f32_16x16x32_bf16 v[74:77], v[6:9], v[22:25], v[74:77]
	v_mfma_f32_16x16x32_bf16 v[70:73], v[6:9], v[26:29], v[70:73]
	v_mfma_f32_16x16x32_bf16 v[6:9], v[6:9], v[30:33], v[66:69]
	v_mfma_f32_16x16x32_bf16 v[62:65], v[10:13], v[18:21], v[62:65]
	v_mfma_f32_16x16x32_bf16 v[58:61], v[10:13], v[22:25], v[58:61]
	v_mfma_f32_16x16x32_bf16 v[54:57], v[10:13], v[26:29], v[54:57]
	v_mfma_f32_16x16x32_bf16 v[10:13], v[10:13], v[30:33], v[50:53]
	v_mfma_f32_16x16x32_bf16 v[18:21], v[14:17], v[18:21], v[46:49]
	v_mfma_f32_16x16x32_bf16 v[22:25], v[14:17], v[22:25], v[42:45]
	v_mfma_f32_16x16x32_bf16 v[26:29], v[14:17], v[26:29], v[38:41]
	v_mfma_f32_16x16x32_bf16 v[14:17], v[14:17], v[30:33], v[34:37]
	s_setprio 0
	ds_read_b128 v[30:33], v0 offset:64
	s_nop 0
	ds_read_b128 v[34:37], v0 offset:2368
	ds_read_b128 v[38:41], v0 offset:4672
	ds_read_b128 v[42:45], v0 offset:6976
	ds_read_b128 v[46:49], v134 offset:36928
	ds_read_b128 v[50:53], v134 offset:39232
	ds_read_b128 v[66:69], v134 offset:41536
	ds_read_b128 v[82:85], v134 offset:43840
	s_setprio 1
	s_waitcnt lgkmcnt(3)
	v_mfma_f32_16x16x32_bf16 v[94:97], v[30:33], v[46:49], v[94:97]
	s_waitcnt lgkmcnt(2)
	v_mfma_f32_16x16x32_bf16 v[90:93], v[30:33], v[50:53], v[90:93]
	s_waitcnt lgkmcnt(1)
	v_mfma_f32_16x16x32_bf16 v[86:89], v[30:33], v[66:69], v[86:89]
	s_waitcnt lgkmcnt(0)
	v_mfma_f32_16x16x32_bf16 v[2:5], v[30:33], v[82:85], v[2:5]
	v_mfma_f32_16x16x32_bf16 v[30:33], v[34:37], v[46:49], v[78:81]
	v_mfma_f32_16x16x32_bf16 v[74:77], v[34:37], v[50:53], v[74:77]
	v_mfma_f32_16x16x32_bf16 v[70:73], v[34:37], v[66:69], v[70:73]
	v_mfma_f32_16x16x32_bf16 v[6:9], v[34:37], v[82:85], v[6:9]
	v_mfma_f32_16x16x32_bf16 v[34:37], v[38:41], v[46:49], v[62:65]
	v_mfma_f32_16x16x32_bf16 v[58:61], v[38:41], v[50:53], v[58:61]
	v_mfma_f32_16x16x32_bf16 v[54:57], v[38:41], v[66:69], v[54:57]
	v_mfma_f32_16x16x32_bf16 v[10:13], v[38:41], v[82:85], v[10:13]
	v_mfma_f32_16x16x32_bf16 v[18:21], v[42:45], v[46:49], v[18:21]
	v_mfma_f32_16x16x32_bf16 v[22:25], v[42:45], v[50:53], v[22:25]
	v_mfma_f32_16x16x32_bf16 v[26:29], v[42:45], v[66:69], v[26:29]
	v_mfma_f32_16x16x32_bf16 v[14:17], v[42:45], v[82:85], v[14:17]
	s_setprio 0
	s_barrier
	ds_read_b128 v[38:41], v0 offset:18432
	ds_read_b128 v[42:45], v0 offset:20736
	ds_read_b128 v[46:49], v0 offset:23040
	ds_read_b128 v[50:53], v0 offset:25344
	ds_read_b128 v[62:65], v134 offset:55296
	ds_read_b128 v[66:69], v134 offset:57600
	ds_read_b128 v[78:81], v134 offset:59904
	ds_read_b128 v[82:85], v134 offset:62208
	s_setprio 1
	s_waitcnt lgkmcnt(3)
	v_mfma_f32_16x16x32_bf16 v[94:97], v[38:41], v[62:65], v[94:97]
	s_waitcnt lgkmcnt(2)
	v_mfma_f32_16x16x32_bf16 v[90:93], v[38:41], v[66:69], v[90:93]
	s_waitcnt lgkmcnt(1)
	v_mfma_f32_16x16x32_bf16 v[86:89], v[38:41], v[78:81], v[86:89]
	s_waitcnt lgkmcnt(0)
	v_mfma_f32_16x16x32_bf16 v[2:5], v[38:41], v[82:85], v[2:5]
	v_mfma_f32_16x16x32_bf16 v[30:33], v[42:45], v[62:65], v[30:33]
	v_mfma_f32_16x16x32_bf16 v[38:41], v[42:45], v[66:69], v[74:77]
	v_mfma_f32_16x16x32_bf16 v[70:73], v[42:45], v[78:81], v[70:73]
	v_mfma_f32_16x16x32_bf16 v[6:9], v[42:45], v[82:85], v[6:9]
	v_mfma_f32_16x16x32_bf16 v[98:101], v[46:49], v[66:69], v[58:61]
	v_mfma_f32_16x16x32_bf16 v[102:105], v[46:49], v[78:81], v[54:57]
	v_mfma_f32_16x16x32_bf16 v[10:13], v[46:49], v[82:85], v[10:13]
	v_mfma_f32_16x16x32_bf16 v[66:69], v[50:53], v[66:69], v[22:25]
	v_mfma_f32_16x16x32_bf16 v[78:81], v[50:53], v[78:81], v[26:29]
	v_mfma_f32_16x16x32_bf16 v[74:77], v[46:49], v[62:65], v[34:37]
	v_mfma_f32_16x16x32_bf16 v[106:109], v[50:53], v[62:65], v[18:21]
	v_mfma_f32_16x16x32_bf16 v[82:85], v[50:53], v[82:85], v[14:17]
	s_setprio 0
	s_nop 1
	ds_read_b128 v[14:17], v0 offset:18496
	ds_read_b128 v[18:21], v0 offset:20800
	ds_read_b128 v[110:113], v0 offset:23104
	ds_read_b128 v[118:121], v0 offset:25408
	ds_read_b128 v[122:125], v134 offset:55360
	ds_read_b128 v[126:129], v134 offset:57664
	ds_read_b128 v[130:133], v134 offset:59968
	ds_read_b128 v[134:137], v134 offset:62272
	s_setprio 1
	s_waitcnt lgkmcnt(3)
	v_mfma_f32_16x16x32_bf16 v[62:65], v[14:17], v[122:125], v[94:97]
	s_waitcnt lgkmcnt(2)
	v_mfma_f32_16x16x32_bf16 v[58:61], v[14:17], v[126:129], v[90:93]
	s_waitcnt lgkmcnt(1)
	v_mfma_f32_16x16x32_bf16 v[54:57], v[14:17], v[130:133], v[86:89]
	s_waitcnt lgkmcnt(0)
	v_mfma_f32_16x16x32_bf16 v[50:53], v[14:17], v[134:137], v[2:5]
	v_mfma_f32_16x16x32_bf16 v[46:49], v[18:21], v[122:125], v[30:33]
	v_mfma_f32_16x16x32_bf16 v[42:45], v[18:21], v[126:129], v[38:41]
	v_mfma_f32_16x16x32_bf16 v[38:41], v[18:21], v[130:133], v[70:73]
	v_mfma_f32_16x16x32_bf16 v[34:37], v[18:21], v[134:137], v[6:9]
	v_mfma_f32_16x16x32_bf16 v[30:33], v[110:113], v[122:125], v[74:77]
	v_mfma_f32_16x16x32_bf16 v[26:29], v[110:113], v[126:129], v[98:101]
	v_mfma_f32_16x16x32_bf16 v[22:25], v[110:113], v[130:133], v[102:105]
	v_mfma_f32_16x16x32_bf16 v[18:21], v[110:113], v[134:137], v[10:13]
	v_mfma_f32_16x16x32_bf16 v[14:17], v[118:121], v[122:125], v[106:109]
	v_mfma_f32_16x16x32_bf16 v[10:13], v[118:121], v[126:129], v[66:69]
	v_mfma_f32_16x16x32_bf16 v[6:9], v[118:121], v[130:133], v[78:81]
	v_mfma_f32_16x16x32_bf16 v[2:5], v[118:121], v[134:137], v[82:85]
	s_setprio 0
	v_and_or_b32 v0, v114, 64, s3
	v_add_u32_e32 v80, s2, v117
	s_movk_i32 s0, 0xbff
	v_lshl_or_b32 v68, v115, 2, v80
	v_cmp_lt_i32_e64 s[2:3], s0, v0
	v_lshl_add_u64 v[72:73], v[0:1], 1, s[16:17]
	v_lshlrev_b32_e32 v70, 1, v116
	s_barrier
	s_and_saveexec_b64 s[0:1], s[2:3]
	s_xor_b64 s[0:1], exec, s[0:1]
	s_cbranch_execz .LBB0_551
	v_ashrrev_i32_e32 v69, 31, v68
	v_lshlrev_b64 v[66:67], 11, v[68:69]
	v_lshl_add_u64 v[66:67], v[72:73], 0, v[66:67]
	v_mov_b32_e32 v71, v1
	v_lshl_add_u64 v[66:67], v[66:67], 0, v[70:71]
	v_lshl_add_u64 v[74:75], v[66:67], 0, s[36:37]
	v_add_co_u32_e32 v66, vcc, 0xfffff000, v66
	v_cvt_pk_bf16_f32 v69, v62, s0
	s_nop 0
	v_addc_co_u32_e32 v67, vcc, -1, v67, vcc
	global_store_short v[66:67], v69, off offset:-2048
	v_cvt_pk_bf16_f32 v66, v58, s0
	global_store_short v[74:75], v66, off offset:32
	v_cvt_pk_bf16_f32 v66, v54, s0
	global_store_short v[74:75], v66, off offset:64
	v_cvt_pk_bf16_f32 v66, v50, s0
	global_store_short v[74:75], v66, off offset:96

; template <int EPI, bool AF32>
; DEV void gemm_tile(const void* Ap, int lda, const u16* Bt, int ldb, int K, int m0, int n0, const Epi& ea, char* smem) {
;     ...
;   auto gload = [&](int kt) {
;     const int k0 = kt << 6;
; #pragma unroll
;     for (int i = 0; i < 4; i++) {
;       const int c = tid + i * 256, row = c >> 3, kc = c & 7;
;       if (AF32) {
;         const float* pa = (const float*)Ap + (size_t)(m0 + row) * lda + k0 + kc * 8;
;         rfa[2 * i] = *(const f32x4*)pa;
;         rfa[2 * i + 1] = *(const f32x4*)(pa + 4);
;       } else {
;         ra[i] = *(const u32x4*)((const u16*)Ap + (size_t)(m0 + row) * lda + k0 + kc * 8);
;       }
;       rb[i] = *(const u32x4*)(Bt + (size_t)(n0 + row) * ldb + k0 + kc * 8);
;     }
;   };
;   auto swrite = [&](int buf) {
; #pragma unroll
;     for (int i = 0; i < 4; i++) {
;       const int c = tid + i * 256, row = c >> 3, kc = c & 7;
;       u32x4 va;
;       if (AF32) {
;         va = (u32x4){pack2(rfa[2 * i][0], rfa[2 * i][1]), pack2(rfa[2 * i][2], rfa[2 * i][3]),
;                      pack2(rfa[2 * i + 1][0], rfa[2 * i + 1][1]), pack2(rfa[2 * i + 1][2], rfa[2 * i + 1][3])};
;       } else {
;         va = ra[i];
;       }
;       *(u32x4*)(sA + buf * 9216 + row * 72 + kc * 8) = va;
;       *(u32x4*)(sB + buf * 9216 + row * 72 + kc * 8) = rb[i];
;     }
;   };
;   gload(0);
;   swrite(0);
;   if (nk > 1) gload(1);
;   __syncthreads();
.LBB0_1262:
	s_ashr_i32 s0, s8, 31
	s_lshr_b32 s0, s0, 23
	s_add_i32 s0, s8, s0
	s_ashr_i32 s1, s0, 9
	s_and_b32 s0, s0, 0xfffffe00
	s_lshl_b32 s10, s1, 5
	s_sub_i32 s9, s8, s0
	s_sub_i32 s0, 0x104, s10
	s_min_u32 s11, s0, 32
	v_cvt_f32_ubyte0_e32 v2, s11
	v_cvt_f32_i32_e32 v0, s9
	v_rcp_iflag_f32_e32 v3, v2
	s_ashr_i32 s0, s9, 30
	s_or_b32 s12, s0, 1
	s_waitcnt vmcnt(12)
	v_mov_b32_e32 v114, v157
	v_mul_f32_e32 v3, v0, v3
	v_trunc_f32_e32 v3, v3
	v_fma_f32 v0, -v3, v2, v0
	v_cvt_i32_f32_e32 v3, v3
	v_cmp_ge_f32_e64 s[0:1], |v0|, v2
	s_and_b64 s[0:1], s[0:1], exec
	s_cselect_b32 s0, s12, 0
	v_readfirstlane_b32 s1, v3
	s_add_i32 s0, s1, s0
	s_sext_i32_i16 s1, s0
	s_mul_i32 s0, s0, s11
	s_sub_i32 s0, s9, s0
	s_sext_i32_i16 s0, s0
	s_add_i32 s10, s10, s0
	s_lshl_b32 s9, s10, 7
	s_lshl_b32 s10, s1, 7
	v_ashrrev_i32_e32 v8, 3, v114
	v_add_u32_e32 v2, s9, v8
	v_ashrrev_i32_e32 v3, 31, v2
	v_lshlrev_b32_e32 v0, 3, v114
	v_add_u32_e32 v4, 0x100, v114
	v_lshlrev_b64 v[58:59], 11, v[2:3]
	v_and_b32_e32 v0, 56, v0
	v_ashrrev_i32_e32 v9, 3, v4
	v_lshl_add_u64 v[2:3], s[60:61], 0, v[58:59]
	v_lshlrev_b32_e32 v0, 1, v0
	v_add_u32_e32 v4, s9, v9
	v_add_u32_e32 v6, 0x200, v114
	v_lshl_add_u64 v[14:15], v[2:3], 0, v[0:1]
	v_add_u32_e32 v2, s10, v8
	v_ashrrev_i32_e32 v5, 31, v4
	v_ashrrev_i32_e32 v10, 3, v6
	v_ashrrev_i32_e32 v3, 31, v2
	v_lshlrev_b64 v[62:63], 11, v[4:5]
	v_add_u32_e32 v6, s9, v10
	v_lshlrev_b64 v[60:61], 11, v[2:3]
	v_lshl_add_u64 v[4:5], s[60:61], 0, v[62:63]
	v_ashrrev_i32_e32 v7, 31, v6
	v_lshl_add_u64 v[2:3], s[4:5], 0, v[60:61]
	v_lshl_add_u64 v[16:17], v[4:5], 0, v[0:1]
	v_add_u32_e32 v4, s10, v9
	v_lshlrev_b64 v[66:67], 11, v[6:7]
	v_lshl_add_u64 v[2:3], v[2:3], 0, v[0:1]
	v_ashrrev_i32_e32 v5, 31, v4
	v_lshl_add_u64 v[6:7], s[60:61], 0, v[66:67]
	global_load_dwordx4 v[30:33], v[2:3], off
	v_lshlrev_b64 v[64:65], 11, v[4:5]
	v_lshl_add_u64 v[68:69], v[6:7], 0, v[0:1]
	v_add_u32_e32 v6, s10, v10
	global_load_dwordx4 v[26:29], v[14:15], off
	global_load_dwordx4 v[34:37], v[16:17], off
	v_lshl_add_u64 v[4:5], s[4:5], 0, v[64:65]
	v_ashrrev_i32_e32 v7, 31, v6
	v_lshl_add_u64 v[4:5], v[4:5], 0, v[0:1]
	v_lshlrev_b64 v[70:71], 11, v[6:7]
	global_load_dwordx4 v[38:41], v[4:5], off
	v_lshl_add_u64 v[6:7], s[4:5], 0, v[70:71]
	global_load_dwordx4 v[42:45], v[68:69], off
	v_lshl_add_u64 v[18:19], v[6:7], 0, v[0:1]
	global_load_dwordx4 v[46:49], v[18:19], off
	v_add_u32_e32 v6, 0x300, v114
	v_ashrrev_i32_e32 v80, 3, v6
	v_add_u32_e32 v6, s9, v80
	v_ashrrev_i32_e32 v7, 31, v6
	v_lshlrev_b64 v[72:73], 11, v[6:7]
	v_lshl_add_u64 v[6:7], s[60:61], 0, v[72:73]
	v_lshl_add_u64 v[74:75], v[6:7], 0, v[0:1]
	v_add_u32_e32 v6, s10, v80
	v_ashrrev_i32_e32 v7, 31, v6
	v_lshlrev_b64 v[76:77], 11, v[6:7]
	v_lshl_add_u64 v[6:7], s[4:5], 0, v[76:77]
	v_lshl_add_u64 v[78:79], v[6:7], 0, v[0:1]
	global_load_dwordx4 v[50:53], v[74:75], off
	global_load_dwordx4 v[54:57], v[78:79], off
	s_waitcnt vmcnt(19)
	v_mul_lo_u32 v118, v8, s71
	v_mul_lo_u32 v119, v9, s71
	s_waitcnt vmcnt(18)
	v_mul_lo_u32 v123, v10, s71
	global_load_dwordx4 v[6:9], v[2:3], off offset:128
	global_load_dwordx4 v[10:13], v[4:5], off offset:128
	s_nop 0
	global_load_dwordx4 v[2:5], v[18:19], off offset:128
	global_load_dwordx4 v[22:25], v[14:15], off offset:128
	s_nop 0
	global_load_dwordx4 v[18:21], v[16:17], off offset:128
	s_nop 0
	global_load_dwordx4 v[14:17], v[68:69], off offset:128
	v_bfe_u32 v161, v157, 3, 4
	v_add_u32_e32 v161, 4, v161
	v_lshlrev_b32_e32 v161, 1, v161
	v_and_b32_e32 v161, 16, v161
	v_xor_b32_e32 v129, v0, v161
	v_lshl_add_u32 v122, v118, 1, v129
	v_lshl_add_u32 v121, v119, 1, v129
	v_lshl_add_u32 v120, v123, 1, v129
	v_and_b32_e32 v115, 15, v114
	s_waitcnt vmcnt(23)
	v_mul_lo_u32 v126, v80, s71
	v_bfe_u32 v116, v114, 4, 2
	v_lshl_add_u32 v124, v126, 1, v129
	s_mov_b32 s11, 0
	v_lshlrev_b32_e32 v125, 4, v116
	v_and_b32_e32 v161, 15, v157
	v_add_u32_e32 v161, 4, v161
	v_lshlrev_b32_e32 v161, 1, v161
	v_and_b32_e32 v161, 16, v161
	v_xor_b32_e32 v125, v125, v161
	s_mov_b64 s[0:1], 0
	s_waitcnt vmcnt(13)
	ds_write_b128 v122, v[30:33] offset:36864
	s_waitcnt vmcnt(12)
	ds_write_b128 v122, v[26:29]
	s_waitcnt vmcnt(11)
	ds_write_b128 v121, v[34:37]
	s_waitcnt vmcnt(10)
	ds_write_b128 v121, v[38:41] offset:36864
	s_waitcnt vmcnt(9)
	ds_write_b128 v120, v[42:45]
	s_waitcnt vmcnt(8)
	ds_write_b128 v120, v[46:49] offset:36864
	global_load_dwordx4 v[26:29], v[74:75], off offset:128
	global_load_dwordx4 v[30:33], v[78:79], off offset:128
	v_ashrrev_i32_e32 v34, 1, v114
	v_and_b32_e32 v117, 0xffffffc0, v34
	v_or_b32_e32 v34, v117, v115
	v_mul_lo_u32 v128, v34, s71
	v_lshlrev_b32_e32 v34, 4, v114
	v_and_b32_e32 v34, 0x70, v34
	v_and_b32_e32 v35, 0x4f, v114
	v_or_b32_e32 v76, v76, v34
	v_or_b32_e32 v72, v72, v34
	v_or_b32_e32 v70, v70, v34
	v_or_b32_e32 v66, v66, v34
	v_or_b32_e32 v64, v64, v34
	v_or_b32_e32 v62, v62, v34
	v_or_b32_e32 v60, v60, v34
	v_or_b32_e32 v58, v58, v34
	v_mov_b32_e32 v34, 0
	s_waitcnt vmcnt(9)
	ds_write_b128 v124, v[50:53]
	s_waitcnt vmcnt(8)
; template <int EPI, bool AF32>
; DEV void gemm_tile(const void* Ap, int lda, const u16* Bt, int ldb, int K, int m0, int n0, const Epi& ea, char* smem) {
;     ...
;   f32x4 acc[4][4];
; #pragma unroll
;   for (int m = 0; m < 4; m++)
; #pragma unroll
;     for (int n = 0; n < 4; n++) acc[m][n] = (f32x4){0.f, 0.f, 0.f, 0.f};
;   u32x4 ra[4], rb[4];
;   f32x4 rfa[8];
;   const int nk = K >> 6;
;   auto gload = [&](int kt) {
;     const int k0 = kt << 6;
; #pragma unroll
;     for (int i = 0; i < 4; i++) {
;       const int c = tid + i * 256, row = c >> 3, kc = c & 7;
;       if (AF32) {
;         const float* pa = (const float*)Ap + (size_t)(m0 + row) * lda + k0 + kc * 8;
;         rfa[2 * i] = *(const f32x4*)pa;
;         rfa[2 * i + 1] = *(const f32x4*)(pa + 4);
;       } else {
;         ra[i] = *(const u32x4*)((const u16*)Ap + (size_t)(m0 + row) * lda + k0 + kc * 8);
;       }
;       rb[i] = *(const u32x4*)(Bt + (size_t)(n0 + row) * ldb + k0 + kc * 8);
;     }
;   };
;   auto swrite = [&](int buf) {
; #pragma unroll
;     for (int i = 0; i < 4; i++) {
;       const int c = tid + i * 256, row = c >> 3, kc = c & 7;
;       u32x4 va;
;       if (AF32) {
;         va = (u32x4){pack2(rfa[2 * i][0], rfa[2 * i][1]), pack2(rfa[2 * i][2], rfa[2 * i][3]),
;                      pack2(rfa[2 * i + 1][0], rfa[2 * i + 1][1]), pack2(rfa[2 * i + 1][2], rfa[2 * i + 1][3])};
;       } else {
;         va = ra[i];
;       }
;       *(u32x4*)(sA + buf * 9216 + row * 72 + kc * 8) = va;
;       *(u32x4*)(sB + buf * 9216 + row * 72 + kc * 8) = rb[i];
;     }
;   };
;   gload(0);
;   swrite(0);
;   if (nk > 1) gload(1);
;   __syncthreads();
;   for (int kt = 0; kt < nk; kt++) {
;     const int buf = kt & 1;
;     if (kt + 1 < nk) swrite(buf ^ 1);
;     if (kt + 2 < nk) gload(kt + 2);
; #pragma unroll
;     for (int ks = 0; ks < 2; ks++) {
;       bf16x8 a[4], b[4];
; #pragma unroll
;       for (int m = 0; m < 4; m++) a[m] = *(const bf16x8*)(sA + buf * 9216 + (wr * 64 + m * 16 + fr) * 72 + ks * 32 + fq * 8);
; #pragma unroll
;       for (int n = 0; n < 4; n++) b[n] = *(const bf16x8*)(sB + buf * 9216 + (wc * 64 + n * 16 + fr) * 72 + ks * 32 + fq * 8);
;       __builtin_amdgcn_s_setprio(1);
; #pragma unroll
;       for (int m = 0; m < 4; m++)
; #pragma unroll
;         for (int n = 0; n < 4; n++) acc[m][n] = mfma16(a[m], b[n], acc[m][n]);
;       __builtin_amdgcn_s_setprio(0);
;     }
	ds_write_b128 v124, v[54:57] offset:36864
	v_mul_u32_u24_e32 v127, 0x48, v35
	v_lshl_add_u64 v[98:99], s[6:7], 0, v[76:77]
	v_lshl_add_u64 v[100:101], s[66:67], 0, v[72:73]
	v_lshl_add_u64 v[102:103], s[6:7], 0, v[70:71]
	v_lshl_add_u64 v[104:105], s[66:67], 0, v[66:67]
	v_lshl_add_u64 v[106:107], s[6:7], 0, v[64:65]
	v_lshl_add_u64 v[108:109], s[66:67], 0, v[62:63]
	v_lshl_add_u64 v[110:111], s[6:7], 0, v[60:61]
	v_lshl_add_u64 v[112:113], s[66:67], 0, v[58:59]
	global_load_dwordx4 v[222:225], v[112:113], off
	global_load_dwordx4 v[226:229], v[110:111], off
	global_load_dwordx4 v[230:233], v[108:109], off
	global_load_dwordx4 v[234:237], v[106:107], off
	global_load_dwordx4 v[238:241], v[104:105], off
	global_load_dwordx4 v[242:245], v[102:103], off
	global_load_dwordx4 v[246:249], v[100:101], off
	global_load_dwordx4 v[250:253], v[98:99], off
	v_mov_b32_e32 v35, v34
	v_mov_b32_e32 v36, v34
	v_mov_b32_e32 v37, v34
	v_mov_b32_e32 v38, v34
	v_mov_b32_e32 v39, v34
	v_mov_b32_e32 v40, v34
	v_mov_b32_e32 v41, v34
	v_mov_b32_e32 v42, v34
	v_mov_b32_e32 v43, v34
	v_mov_b32_e32 v44, v34
	v_mov_b32_e32 v45, v34
	v_mov_b32_e32 v46, v34
	v_mov_b32_e32 v47, v34
	v_mov_b32_e32 v48, v34
	v_mov_b32_e32 v49, v34
	v_mov_b32_e32 v50, v34
	v_mov_b32_e32 v51, v34
	v_mov_b32_e32 v52, v34
	v_mov_b32_e32 v53, v34
	v_mov_b32_e32 v54, v34
	v_mov_b32_e32 v55, v34
	v_mov_b32_e32 v56, v34
	v_mov_b32_e32 v57, v34
	v_mov_b32_e32 v58, v34
	v_mov_b32_e32 v59, v34
	v_mov_b32_e32 v60, v34
	v_mov_b32_e32 v61, v34
	v_mov_b32_e32 v62, v34
	v_mov_b32_e32 v63, v34
	v_mov_b32_e32 v64, v34
	v_mov_b32_e32 v65, v34
	v_mov_b32_e32 v66, v34
	v_mov_b32_e32 v67, v34
	v_mov_b32_e32 v68, v34
	v_mov_b32_e32 v69, v34
	v_mov_b32_e32 v70, v34
	v_mov_b32_e32 v71, v34
	v_mov_b32_e32 v72, v34
	v_mov_b32_e32 v73, v34
	v_mov_b32_e32 v74, v34
	v_mov_b32_e32 v75, v34
	v_mov_b32_e32 v76, v34
	v_mov_b32_e32 v77, v34
	v_mov_b32_e32 v78, v34
	v_mov_b32_e32 v79, v34
	v_mov_b32_e32 v80, v34
	v_mov_b32_e32 v81, v34
	v_mov_b32_e32 v82, v34
	v_mov_b32_e32 v83, v34
	v_mov_b32_e32 v84, v34
	v_mov_b32_e32 v85, v34
	v_mov_b32_e32 v86, v34
	v_mov_b32_e32 v87, v34
	v_mov_b32_e32 v88, v34
	v_mov_b32_e32 v89, v34
	v_mov_b32_e32 v90, v34
	v_mov_b32_e32 v91, v34
	v_mov_b32_e32 v92, v34
	v_mov_b32_e32 v93, v34
	v_mov_b32_e32 v94, v34
	v_mov_b32_e32 v95, v34
	v_mov_b32_e32 v96, v34
	v_mov_b32_e32 v97, v34
	s_waitcnt lgkmcnt(0)
	s_barrier
	v_lshl_add_u32 v161, v128, 1, v125
	v_lshl_add_u32 v129, v127, 1, v125
	s_mov_b32 s11, 0
	s_mov_b64 s[0:1], 0x100
.Lgk2_loop:
	v_lshl_add_u64 v[112:113], v[112:113], 0, s[0:1]
	v_lshl_add_u64 v[110:111], v[110:111], 0, s[0:1]
	v_lshl_add_u64 v[108:109], v[108:109], 0, s[0:1]
	v_lshl_add_u64 v[106:107], v[106:107], 0, s[0:1]
	v_lshl_add_u64 v[104:105], v[104:105], 0, s[0:1]
	v_lshl_add_u64 v[102:103], v[102:103], 0, s[0:1]
	v_lshl_add_u64 v[100:101], v[100:101], 0, s[0:1]
	v_lshl_add_u64 v[98:99], v[98:99], 0, s[0:1]
	ds_read_b128 v[130:133], v161
	ds_read_b128 v[134:137], v161 offset:2304
	ds_read_b128 v[138:141], v161 offset:4608
	ds_read_b128 v[142:145], v161 offset:6912
	ds_read_b128 v[146:149], v129 offset:36864
	ds_read_b128 v[150:153], v129 offset:39168
	ds_read_b128 v[162:165], v129 offset:41472
	ds_read_b128 v[166:169], v129 offset:43776
	s_setprio 1
	s_waitcnt lgkmcnt(3)
	v_mfma_f32_16x16x32_bf16 v[94:97], v[130:133], v[146:149], v[94:97]
	s_waitcnt lgkmcnt(2)
	v_mfma_f32_16x16x32_bf16 v[90:93], v[130:133], v[150:153], v[90:93]
	s_waitcnt lgkmcnt(1)
	v_mfma_f32_16x16x32_bf16 v[86:89], v[130:133], v[162:165], v[86:89]
	s_waitcnt lgkmcnt(0)
	v_mfma_f32_16x16x32_bf16 v[82:85], v[130:133], v[166:169], v[82:85]
	v_mfma_f32_16x16x32_bf16 v[78:81], v[134:137], v[146:149], v[78:81]
	v_mfma_f32_16x16x32_bf16 v[74:77], v[134:137], v[150:153], v[74:77]
	v_mfma_f32_16x16x32_bf16 v[70:73], v[134:137], v[162:165], v[70:73]
	v_mfma_f32_16x16x32_bf16 v[66:69], v[134:137], v[166:169], v[66:69]
	v_mfma_f32_16x16x32_bf16 v[62:65], v[138:141], v[146:149], v[62:65]
	v_mfma_f32_16x16x32_bf16 v[58:61], v[138:141], v[150:153], v[58:61]
	v_mfma_f32_16x16x32_bf16 v[54:57], v[138:141], v[162:165], v[54:57]
	v_mfma_f32_16x16x32_bf16 v[50:53], v[138:141], v[166:169], v[50:53]
	v_mfma_f32_16x16x32_bf16 v[46:49], v[142:145], v[146:149], v[46:49]
	v_mfma_f32_16x16x32_bf16 v[42:45], v[142:145], v[150:153], v[42:45]
	v_mfma_f32_16x16x32_bf16 v[38:41], v[142:145], v[162:165], v[38:41]
	v_mfma_f32_16x16x32_bf16 v[34:37], v[142:145], v[166:169], v[34:37]
	s_setprio 0
	ds_read_b128 v[130:133], v161 offset:64
	ds_read_b128 v[134:137], v161 offset:2368
	ds_read_b128 v[138:141], v161 offset:4672
	ds_read_b128 v[142:145], v161 offset:6976
	ds_read_b128 v[146:149], v129 offset:36928
	ds_read_b128 v[150:153], v129 offset:39232
	ds_read_b128 v[162:165], v129 offset:41536
	ds_read_b128 v[166:169], v129 offset:43840
	s_waitcnt vmcnt(8)
	ds_write_b128 v122, v[22:25] offset:18432
	ds_write_b128 v122, v[6:9] offset:55296
	ds_write_b128 v121, v[18:21] offset:18432
	ds_write_b128 v121, v[10:13] offset:55296
	ds_write_b128 v120, v[14:17] offset:18432
	ds_write_b128 v120, v[2:5] offset:55296
	ds_write_b128 v124, v[26:29] offset:18432
	ds_write_b128 v124, v[30:33] offset:55296
	global_load_dwordx4 v[22:25], v[112:113], off offset:-128
	global_load_dwordx4 v[6:9], v[110:111], off offset:-128
	global_load_dwordx4 v[18:21], v[108:109], off offset:-128
	global_load_dwordx4 v[10:13], v[106:107], off offset:-128
	global_load_dwordx4 v[14:17], v[104:105], off offset:-128
	global_load_dwordx4 v[2:5], v[102:103], off offset:-128
	global_load_dwordx4 v[26:29], v[100:101], off offset:-128
	global_load_dwordx4 v[30:33], v[98:99], off offset:-128
	s_setprio 1
	s_waitcnt lgkmcnt(11)
	v_mfma_f32_16x16x32_bf16 v[94:97], v[130:133], v[146:149], v[94:97]
	s_waitcnt lgkmcnt(10)
	v_mfma_f32_16x16x32_bf16 v[90:93], v[130:133], v[150:153], v[90:93]
	s_waitcnt lgkmcnt(9)
	v_mfma_f32_16x16x32_bf16 v[86:89], v[130:133], v[162:165], v[86:89]
	s_waitcnt lgkmcnt(8)
	v_mfma_f32_16x16x32_bf16 v[82:85], v[130:133], v[166:169], v[82:85]
	v_mfma_f32_16x16x32_bf16 v[78:81], v[134:137], v[146:149], v[78:81]
	v_mfma_f32_16x16x32_bf16 v[74:77], v[134:137], v[150:153], v[74:77]
	v_mfma_f32_16x16x32_bf16 v[70:73], v[134:137], v[162:165], v[70:73]
	v_mfma_f32_16x16x32_bf16 v[66:69], v[134:137], v[166:169], v[66:69]
	v_mfma_f32_16x16x32_bf16 v[62:65], v[138:141], v[146:149], v[62:65]
	v_mfma_f32_16x16x32_bf16 v[58:61], v[138:141], v[150:153], v[58:61]
	v_mfma_f32_16x16x32_bf16 v[54:57], v[138:141], v[162:165], v[54:57]
	v_mfma_f32_16x16x32_bf16 v[50:53], v[138:141], v[166:169], v[50:53]
	v_mfma_f32_16x16x32_bf16 v[46:49], v[142:145], v[146:149], v[46:49]
	v_mfma_f32_16x16x32_bf16 v[42:45], v[142:145], v[150:153], v[42:45]
	v_mfma_f32_16x16x32_bf16 v[38:41], v[142:145], v[162:165], v[38:41]
	v_mfma_f32_16x16x32_bf16 v[34:37], v[142:145], v[166:169], v[34:37]
	s_setprio 0
	s_waitcnt lgkmcnt(0)
	s_barrier
; DEV f32x4 mfma16(bf16x8 a, bf16x8 b, f32x4 c) { return __builtin_amdgcn_mfma_f32_16x16x32_bf16(a, b, c, 0, 0, 0); }
; template <int EPI, bool AF32>
; DEV void gemm_tile(const void* Ap, int lda, const u16* Bt, int ldb, int K, int m0, int n0, const Epi& ea, char* smem) {
;     ...
;   for (int kt = 0; kt < nk; kt++) {
;     const int buf = kt & 1;
;     if (kt + 1 < nk) swrite(buf ^ 1);
;     if (kt + 2 < nk) gload(kt + 2);
; #pragma unroll
;     for (int ks = 0; ks < 2; ks++) {
;       bf16x8 a[4], b[4];
; #pragma unroll
;       for (int m = 0; m < 4; m++) a[m] = *(const bf16x8*)(sA + buf * 9216 + (wr * 64 + m * 16 + fr) * 72 + ks * 32 + fq * 8);
; #pragma unroll
;       for (int n = 0; n < 4; n++) b[n] = *(const bf16x8*)(sB + buf * 9216 + (wc * 64 + n * 16 + fr) * 72 + ks * 32 + fq * 8);
;       __builtin_amdgcn_s_setprio(1);
; #pragma unroll
;       for (int m = 0; m < 4; m++)
; #pragma unroll
;         for (int n = 0; n < 4; n++) acc[m][n] = mfma16(a[m], b[n], acc[m][n]);
;       __builtin_amdgcn_s_setprio(0);
;     }
;     __syncthreads();
;   }
	ds_read_b128 v[130:133], v161 offset:18432
	ds_read_b128 v[134:137], v161 offset:20736
	ds_read_b128 v[138:141], v161 offset:23040
	ds_read_b128 v[142:145], v161 offset:25344
	ds_read_b128 v[146:149], v129 offset:55296
	ds_read_b128 v[150:153], v129 offset:57600
	ds_read_b128 v[162:165], v129 offset:59904
	ds_read_b128 v[166:169], v129 offset:62208
	s_setprio 1
	s_waitcnt lgkmcnt(3)
	v_mfma_f32_16x16x32_bf16 v[94:97], v[130:133], v[146:149], v[94:97]
	s_waitcnt lgkmcnt(2)
	v_mfma_f32_16x16x32_bf16 v[90:93], v[130:133], v[150:153], v[90:93]
	s_waitcnt lgkmcnt(1)
	v_mfma_f32_16x16x32_bf16 v[86:89], v[130:133], v[162:165], v[86:89]
	s_waitcnt lgkmcnt(0)
	v_mfma_f32_16x16x32_bf16 v[82:85], v[130:133], v[166:169], v[82:85]
	v_mfma_f32_16x16x32_bf16 v[78:81], v[134:137], v[146:149], v[78:81]
	v_mfma_f32_16x16x32_bf16 v[74:77], v[134:137], v[150:153], v[74:77]
	v_mfma_f32_16x16x32_bf16 v[70:73], v[134:137], v[162:165], v[70:73]
	v_mfma_f32_16x16x32_bf16 v[66:69], v[134:137], v[166:169], v[66:69]
	v_mfma_f32_16x16x32_bf16 v[62:65], v[138:141], v[146:149], v[62:65]
	v_mfma_f32_16x16x32_bf16 v[58:61], v[138:141], v[150:153], v[58:61]
	v_mfma_f32_16x16x32_bf16 v[54:57], v[138:141], v[162:165], v[54:57]
	v_mfma_f32_16x16x32_bf16 v[50:53], v[138:141], v[166:169], v[50:53]
	v_mfma_f32_16x16x32_bf16 v[46:49], v[142:145], v[146:149], v[46:49]
	v_mfma_f32_16x16x32_bf16 v[42:45], v[142:145], v[150:153], v[42:45]
	v_mfma_f32_16x16x32_bf16 v[38:41], v[142:145], v[162:165], v[38:41]
	v_mfma_f32_16x16x32_bf16 v[34:37], v[142:145], v[166:169], v[34:37]
	s_setprio 0
	ds_read_b128 v[130:133], v161 offset:18496
	ds_read_b128 v[134:137], v161 offset:20800
	ds_read_b128 v[138:141], v161 offset:23104
	ds_read_b128 v[142:145], v161 offset:25408
	ds_read_b128 v[146:149], v129 offset:55360
	ds_read_b128 v[150:153], v129 offset:57664
	ds_read_b128 v[162:165], v129 offset:59968
	ds_read_b128 v[166:169], v129 offset:62272
	s_waitcnt vmcnt(8)
	ds_write_b128 v122, v[222:225]
	ds_write_b128 v122, v[226:229] offset:36864
	ds_write_b128 v121, v[230:233]
	ds_write_b128 v121, v[234:237] offset:36864
	ds_write_b128 v120, v[238:241]
	ds_write_b128 v120, v[242:245] offset:36864
	ds_write_b128 v124, v[246:249]
	ds_write_b128 v124, v[250:253] offset:36864
	s_cmp_eq_u32 s11, 6
	s_cbranch_scc1 .Lgk2_nold
	global_load_dwordx4 v[222:225], v[112:113], off
	global_load_dwordx4 v[226:229], v[110:111], off
	global_load_dwordx4 v[230:233], v[108:109], off
	global_load_dwordx4 v[234:237], v[106:107], off
	global_load_dwordx4 v[238:241], v[104:105], off
	global_load_dwordx4 v[242:245], v[102:103], off
	global_load_dwordx4 v[246:249], v[100:101], off
	global_load_dwordx4 v[250:253], v[98:99], off
.Lgk2_nold:
	s_setprio 1
	s_waitcnt lgkmcnt(11)
	v_mfma_f32_16x16x32_bf16 v[94:97], v[130:133], v[146:149], v[94:97]
	s_waitcnt lgkmcnt(10)
	v_mfma_f32_16x16x32_bf16 v[90:93], v[130:133], v[150:153], v[90:93]
	s_waitcnt lgkmcnt(9)
	v_mfma_f32_16x16x32_bf16 v[86:89], v[130:133], v[162:165], v[86:89]
	s_waitcnt lgkmcnt(8)
	v_mfma_f32_16x16x32_bf16 v[82:85], v[130:133], v[166:169], v[82:85]
	v_mfma_f32_16x16x32_bf16 v[78:81], v[134:137], v[146:149], v[78:81]
	v_mfma_f32_16x16x32_bf16 v[74:77], v[134:137], v[150:153], v[74:77]
	v_mfma_f32_16x16x32_bf16 v[70:73], v[134:137], v[162:165], v[70:73]
	v_mfma_f32_16x16x32_bf16 v[66:69], v[134:137], v[166:169], v[66:69]
	v_mfma_f32_16x16x32_bf16 v[62:65], v[138:141], v[146:149], v[62:65]
	v_mfma_f32_16x16x32_bf16 v[58:61], v[138:141], v[150:153], v[58:61]
	v_mfma_f32_16x16x32_bf16 v[54:57], v[138:141], v[162:165], v[54:57]
	v_mfma_f32_16x16x32_bf16 v[50:53], v[138:141], v[166:169], v[50:53]
	v_mfma_f32_16x16x32_bf16 v[46:49], v[142:145], v[146:149], v[46:49]
	v_mfma_f32_16x16x32_bf16 v[42:45], v[142:145], v[150:153], v[42:45]
	v_mfma_f32_16x16x32_bf16 v[38:41], v[142:145], v[162:165], v[38:41]
	v_mfma_f32_16x16x32_bf16 v[34:37], v[142:145], v[166:169], v[34:37]
	s_setprio 0
	s_add_i32 s11, s11, 1
	s_cmp_lg_u32 s11, 7
	s_waitcnt lgkmcnt(0)
	s_barrier
	s_cbranch_scc1 .Lgk2_loop
	s_waitcnt vmcnt(7)
	ds_write_b128 v122, v[22:25] offset:18432
	s_waitcnt vmcnt(6)
	ds_write_b128 v122, v[6:9] offset:55296
	s_waitcnt vmcnt(5)
	ds_write_b128 v121, v[18:21] offset:18432
	s_waitcnt vmcnt(4)
	ds_write_b128 v121, v[10:13] offset:55296
	s_waitcnt vmcnt(3)
	ds_write_b128 v120, v[14:17] offset:18432
	s_waitcnt vmcnt(2)
	ds_write_b128 v120, v[2:5] offset:55296
	s_waitcnt vmcnt(1)
	ds_write_b128 v124, v[26:29] offset:18432
	s_waitcnt vmcnt(0)
	ds_write_b128 v124, v[30:33] offset:55296
	v_lshl_add_u32 v0, v128, 1, v125
	v_lshl_add_u32 v118, v127, 1, v125
	ds_read_b128 v[2:5], v0
	ds_read_b128 v[6:9], v0 offset:2304
	ds_read_b128 v[10:13], v0 offset:4608
	ds_read_b128 v[14:17], v0 offset:6912
	ds_read_b128 v[18:21], v118 offset:36864
	ds_read_b128 v[22:25], v118 offset:39168
	ds_read_b128 v[26:29], v118 offset:41472
	ds_read_b128 v[30:33], v118 offset:43776
	s_setprio 1
	s_waitcnt lgkmcnt(3)
	v_mfma_f32_16x16x32_bf16 v[94:97], v[2:5], v[18:21], v[94:97]
	s_waitcnt lgkmcnt(2)
	v_mfma_f32_16x16x32_bf16 v[90:93], v[2:5], v[22:25], v[90:93]
	s_waitcnt lgkmcnt(1)
	v_mfma_f32_16x16x32_bf16 v[86:89], v[2:5], v[26:29], v[86:89]
	s_waitcnt lgkmcnt(0)
; DEV float sigmf(float x) { return __builtin_amdgcn_rcpf(1.f + __expf(-x)); }
; DEV f32x4 mfma16(bf16x8 a, bf16x8 b, f32x4 c) { return __builtin_amdgcn_mfma_f32_16x16x32_bf16(a, b, c, 0, 0, 0); }
; template <int EPI, bool AF32>
; DEV void gemm_tile(const void* Ap, int lda, const u16* Bt, int ldb, int K, int m0, int n0, const Epi& ea, char* smem) {
;     ...
;   for (int kt = 0; kt < nk; kt++) {
;     const int buf = kt & 1;
;     if (kt + 1 < nk) swrite(buf ^ 1);
;     if (kt + 2 < nk) gload(kt + 2);
; #pragma unroll
;     for (int ks = 0; ks < 2; ks++) {
;       bf16x8 a[4], b[4];
; #pragma unroll
;       for (int m = 0; m < 4; m++) a[m] = *(const bf16x8*)(sA + buf * 9216 + (wr * 64 + m * 16 + fr) * 72 + ks * 32 + fq * 8);
; #pragma unroll
;       for (int n = 0; n < 4; n++) b[n] = *(const bf16x8*)(sB + buf * 9216 + (wc * 64 + n * 16 + fr) * 72 + ks * 32 + fq * 8);
;       __builtin_amdgcn_s_setprio(1);
; #pragma unroll
;       for (int m = 0; m < 4; m++)
; #pragma unroll
;         for (int n = 0; n < 4; n++) acc[m][n] = mfma16(a[m], b[n], acc[m][n]);
;       __builtin_amdgcn_s_setprio(0);
;     }
;     __syncthreads();
;   }
;     ...
;       } else if (EPI == EP_SIG) {
;         u16* C = (u16*)ea.p0;
; #pragma unroll
;         for (int n = 0; n < 4; n++) C[(size_t)row * ea.ld + cb + n * 16 + fr] = f2bf(sigmf(acc[m][n][j]));
	v_mfma_f32_16x16x32_bf16 v[2:5], v[2:5], v[30:33], v[82:85]
	v_mfma_f32_16x16x32_bf16 v[78:81], v[6:9], v[18:21], v[78:81]
	v_mfma_f32_16x16x32_bf16 v[74:77], v[6:9], v[22:25], v[74:77]
	v_mfma_f32_16x16x32_bf16 v[70:73], v[6:9], v[26:29], v[70:73]
	v_mfma_f32_16x16x32_bf16 v[6:9], v[6:9], v[30:33], v[66:69]
	v_mfma_f32_16x16x32_bf16 v[62:65], v[10:13], v[18:21], v[62:65]
	v_mfma_f32_16x16x32_bf16 v[58:61], v[10:13], v[22:25], v[58:61]
	v_mfma_f32_16x16x32_bf16 v[54:57], v[10:13], v[26:29], v[54:57]
	v_mfma_f32_16x16x32_bf16 v[10:13], v[10:13], v[30:33], v[50:53]
	v_mfma_f32_16x16x32_bf16 v[18:21], v[14:17], v[18:21], v[46:49]
	v_mfma_f32_16x16x32_bf16 v[22:25], v[14:17], v[22:25], v[42:45]
	v_mfma_f32_16x16x32_bf16 v[26:29], v[14:17], v[26:29], v[38:41]
	v_mfma_f32_16x16x32_bf16 v[14:17], v[14:17], v[30:33], v[34:37]
	s_setprio 0
	ds_read_b128 v[30:33], v0 offset:64
	s_nop 0
	ds_read_b128 v[34:37], v0 offset:2368
	ds_read_b128 v[38:41], v0 offset:4672
	ds_read_b128 v[42:45], v0 offset:6976
	ds_read_b128 v[46:49], v118 offset:36928
	ds_read_b128 v[50:53], v118 offset:39232
	ds_read_b128 v[66:69], v118 offset:41536
	ds_read_b128 v[82:85], v118 offset:43840
	s_setprio 1
	s_waitcnt lgkmcnt(3)
	v_mfma_f32_16x16x32_bf16 v[94:97], v[30:33], v[46:49], v[94:97]
	s_waitcnt lgkmcnt(2)
	v_mfma_f32_16x16x32_bf16 v[90:93], v[30:33], v[50:53], v[90:93]
	s_waitcnt lgkmcnt(1)
	v_mfma_f32_16x16x32_bf16 v[86:89], v[30:33], v[66:69], v[86:89]
	s_waitcnt lgkmcnt(0)
	v_mfma_f32_16x16x32_bf16 v[2:5], v[30:33], v[82:85], v[2:5]
	v_mfma_f32_16x16x32_bf16 v[30:33], v[34:37], v[46:49], v[78:81]
	v_mfma_f32_16x16x32_bf16 v[74:77], v[34:37], v[50:53], v[74:77]
	v_mfma_f32_16x16x32_bf16 v[70:73], v[34:37], v[66:69], v[70:73]
	v_mfma_f32_16x16x32_bf16 v[6:9], v[34:37], v[82:85], v[6:9]
	v_mfma_f32_16x16x32_bf16 v[34:37], v[38:41], v[46:49], v[62:65]
	v_mfma_f32_16x16x32_bf16 v[58:61], v[38:41], v[50:53], v[58:61]
	v_mfma_f32_16x16x32_bf16 v[54:57], v[38:41], v[66:69], v[54:57]
	v_mfma_f32_16x16x32_bf16 v[10:13], v[38:41], v[82:85], v[10:13]
	v_mfma_f32_16x16x32_bf16 v[18:21], v[42:45], v[46:49], v[18:21]
	v_mfma_f32_16x16x32_bf16 v[22:25], v[42:45], v[50:53], v[22:25]
	v_mfma_f32_16x16x32_bf16 v[26:29], v[42:45], v[66:69], v[26:29]
	v_mfma_f32_16x16x32_bf16 v[14:17], v[42:45], v[82:85], v[14:17]
	s_setprio 0
	s_barrier
	ds_read_b128 v[38:41], v0 offset:18432
	ds_read_b128 v[42:45], v0 offset:20736
	ds_read_b128 v[46:49], v0 offset:23040
	ds_read_b128 v[50:53], v0 offset:25344
	ds_read_b128 v[62:65], v118 offset:55296
	ds_read_b128 v[66:69], v118 offset:57600
	ds_read_b128 v[78:81], v118 offset:59904
	ds_read_b128 v[82:85], v118 offset:62208
	s_setprio 1
	s_waitcnt lgkmcnt(3)
	v_mfma_f32_16x16x32_bf16 v[94:97], v[38:41], v[62:65], v[94:97]
	s_waitcnt lgkmcnt(2)
	v_mfma_f32_16x16x32_bf16 v[90:93], v[38:41], v[66:69], v[90:93]
	s_waitcnt lgkmcnt(1)
	v_mfma_f32_16x16x32_bf16 v[86:89], v[38:41], v[78:81], v[86:89]
	s_waitcnt lgkmcnt(0)
	v_mfma_f32_16x16x32_bf16 v[2:5], v[38:41], v[82:85], v[2:5]
	v_mfma_f32_16x16x32_bf16 v[30:33], v[42:45], v[62:65], v[30:33]
	v_mfma_f32_16x16x32_bf16 v[38:41], v[42:45], v[66:69], v[74:77]
	v_mfma_f32_16x16x32_bf16 v[70:73], v[42:45], v[78:81], v[70:73]
	v_mfma_f32_16x16x32_bf16 v[6:9], v[42:45], v[82:85], v[6:9]
	v_mfma_f32_16x16x32_bf16 v[74:77], v[46:49], v[62:65], v[34:37]
	v_mfma_f32_16x16x32_bf16 v[58:61], v[46:49], v[66:69], v[58:61]
	v_mfma_f32_16x16x32_bf16 v[54:57], v[46:49], v[78:81], v[54:57]
	v_mfma_f32_16x16x32_bf16 v[10:13], v[46:49], v[82:85], v[10:13]
	v_mfma_f32_16x16x32_bf16 v[62:65], v[50:53], v[62:65], v[18:21]
	v_mfma_f32_16x16x32_bf16 v[66:69], v[50:53], v[66:69], v[22:25]
	v_mfma_f32_16x16x32_bf16 v[78:81], v[50:53], v[78:81], v[26:29]
	v_mfma_f32_16x16x32_bf16 v[50:53], v[50:53], v[82:85], v[14:17]
	s_setprio 0
	s_nop 1
	ds_read_b128 v[14:17], v0 offset:18496
	ds_read_b128 v[18:21], v0 offset:20800
	ds_read_b128 v[82:85], v0 offset:23104
	ds_read_b128 v[98:101], v0 offset:25408
	ds_read_b128 v[102:105], v118 offset:55360
	ds_read_b128 v[106:109], v118 offset:57664
	ds_read_b128 v[110:113], v118 offset:59968
	ds_read_b128 v[118:121], v118 offset:62272
	s_setprio 1
	s_waitcnt lgkmcnt(3)
	v_mfma_f32_16x16x32_bf16 v[94:97], v[14:17], v[102:105], v[94:97]
	s_waitcnt lgkmcnt(2)
	v_mfma_f32_16x16x32_bf16 v[90:93], v[14:17], v[106:109], v[90:93]
	s_waitcnt lgkmcnt(1)
	v_mfma_f32_16x16x32_bf16 v[86:89], v[14:17], v[110:113], v[86:89]
	s_waitcnt lgkmcnt(0)
	v_mfma_f32_16x16x32_bf16 v[122:125], v[14:17], v[118:121], v[2:5]
	v_mfma_f32_16x16x32_bf16 v[46:49], v[18:21], v[102:105], v[30:33]
	v_mfma_f32_16x16x32_bf16 v[42:45], v[18:21], v[106:109], v[38:41]
	v_mfma_f32_16x16x32_bf16 v[38:41], v[18:21], v[110:113], v[70:73]
	v_mfma_f32_16x16x32_bf16 v[34:37], v[18:21], v[118:121], v[6:9]
	v_mfma_f32_16x16x32_bf16 v[30:33], v[82:85], v[102:105], v[74:77]
	v_mfma_f32_16x16x32_bf16 v[26:29], v[82:85], v[106:109], v[58:61]
	v_mfma_f32_16x16x32_bf16 v[22:25], v[82:85], v[110:113], v[54:57]
	v_mfma_f32_16x16x32_bf16 v[18:21], v[82:85], v[118:121], v[10:13]
	v_mfma_f32_16x16x32_bf16 v[14:17], v[98:101], v[102:105], v[62:65]
	v_mfma_f32_16x16x32_bf16 v[10:13], v[98:101], v[106:109], v[66:69]
	v_mfma_f32_16x16x32_bf16 v[6:9], v[98:101], v[110:113], v[78:81]
	v_mfma_f32_16x16x32_bf16 v[2:5], v[98:101], v[118:121], v[50:53]
	s_setprio 0
	s_nop 1
	v_mul_f32_e32 v51, 0xbfb8aa3b, v94
	v_exp_f32_e32 v56, v51
	v_and_or_b32 v52, v114, 64, s10
	v_add_u32_e32 v0, s9, v117
	v_ashrrev_i32_e32 v53, 31, v52
	v_lshl_or_b32 v50, v116, 2, v0
	v_lshl_add_u64 v[52:53], v[52:53], 1, s[2:3]
	v_lshlrev_b32_e32 v0, 1, v115
	v_lshl_add_u64 v[52:53], v[52:53], 0, v[0:1]
	v_ashrrev_i32_e32 v51, 31, v50
	v_add_f32_e32 v0, 1.0, v56
	v_lshlrev_b64 v[54:55], 12, v[50:51]
	v_rcp_f32_e32 v0, v0
	v_mul_f32_e32 v51, 0xbfb8aa3b, v90
	v_exp_f32_e32 v51, v51
	v_lshl_add_u64 v[54:55], v[52:53], 0, v[54:55]
	v_cvt_pk_bf16_f32 v0, v0, s0
	s_barrier
; DEV float sigmf(float x) { return __builtin_amdgcn_rcpf(1.f + __expf(-x)); }
; template <int EPI, bool AF32>
; DEV void gemm_tile(const void* Ap, int lda, const u16* Bt, int ldb, int K, int m0, int n0, const Epi& ea, char* smem) {
;     ...
;       } else if (EPI == EP_SIG) {
;         u16* C = (u16*)ea.p0;
; #pragma unroll
;         for (int n = 0; n < 4; n++) C[(size_t)row * ea.ld + cb + n * 16 + fr] = f2bf(sigmf(acc[m][n][j]));
	global_store_short v[54:55], v0, off
	v_add_f32_e32 v0, 1.0, v51
	v_mul_f32_e32 v51, 0xbfb8aa3b, v86
	v_exp_f32_e32 v51, v51
	v_mul_f32_e32 v56, 0xbfb8aa3b, v122
	v_exp_f32_e32 v56, v56
	v_rcp_f32_e32 v0, v0
	v_add_f32_e32 v51, 1.0, v51
	v_rcp_f32_e32 v51, v51
	v_add_f32_e32 v56, 1.0, v56
	v_rcp_f32_e32 v56, v56
	v_cvt_pk_bf16_f32 v0, v0, s0
	global_store_short v[54:55], v0, off offset:32
	v_cvt_pk_bf16_f32 v0, v51, s0
	global_store_short v[54:55], v0, off offset:64
	v_cvt_pk_bf16_f32 v0, v56, s0
	global_store_short v[54:55], v0, off offset:96
	v_mul_f32_e32 v0, 0xbfb8aa3b, v95
	v_exp_f32_e32 v0, v0
	v_mul_f32_e32 v51, 0xbfb8aa3b, v91
	v_or_b32_e32 v54, 1, v50
	v_exp_f32_e32 v51, v51
	v_add_f32_e32 v0, 1.0, v0
	v_rcp_f32_e32 v0, v0
	v_ashrrev_i32_e32 v55, 31, v54
	v_lshlrev_b64 v[54:55], 12, v[54:55]
	v_lshl_add_u64 v[54:55], v[52:53], 0, v[54:55]
	v_cvt_pk_bf16_f32 v0, v0, s0
	global_store_short v[54:55], v0, off
	v_add_f32_e32 v0, 1.0, v51
	v_mul_f32_e32 v51, 0xbfb8aa3b, v87
	v_exp_f32_e32 v51, v51
	v_mul_f32_e32 v56, 0xbfb8aa3b, v123
	v_exp_f32_e32 v56, v56
	v_rcp_f32_e32 v0, v0
	v_add_f32_e32 v51, 1.0, v51
	v_rcp_f32_e32 v51, v51
	v_add_f32_e32 v56, 1.0, v56
	v_rcp_f32_e32 v56, v56
	v_cvt_pk_bf16_f32 v0, v0, s0
	global_store_short v[54:55], v0, off offset:32
	v_cvt_pk_bf16_f32 v0, v51, s0
	global_store_short v[54:55], v0, off offset:64
	v_cvt_pk_bf16_f32 v0, v56, s0
	global_store_short v[54:55], v0, off offset:96
	v_mul_f32_e32 v0, 0xbfb8aa3b, v96
	v_exp_f32_e32 v0, v0
	v_mul_f32_e32 v51, 0xbfb8aa3b, v92
	v_or_b32_e32 v54, 2, v50
	v_exp_f32_e32 v51, v51
	v_add_f32_e32 v0, 1.0, v0
	v_rcp_f32_e32 v0, v0
	v_ashrrev_i32_e32 v55, 31, v54
	v_lshlrev_b64 v[54:55], 12, v[54:55]
	v_lshl_add_u64 v[54:55], v[52:53], 0, v[54:55]
	v_cvt_pk_bf16_f32 v0, v0, s0
	global_store_short v[54:55], v0, off
	v_add_f32_e32 v0, 1.0, v51
	v_mul_f32_e32 v51, 0xbfb8aa3b, v88
	v_exp_f32_e32 v51, v51
	v_mul_f32_e32 v56, 0xbfb8aa3b, v124
	v_exp_f32_e32 v56, v56
	v_rcp_f32_e32 v0, v0
	v_add_f32_e32 v51, 1.0, v51
	v_rcp_f32_e32 v51, v51
	v_add_f32_e32 v56, 1.0, v56
	v_rcp_f32_e32 v56, v56
	v_cvt_pk_bf16_f32 v0, v0, s0
	global_store_short v[54:55], v0, off offset:32
	v_cvt_pk_bf16_f32 v0, v51, s0
	global_store_short v[54:55], v0, off offset:64
	v_cvt_pk_bf16_f32 v0, v56, s0
	global_store_short v[54:55], v0, off offset:96
	v_mul_f32_e32 v0, 0xbfb8aa3b, v97
	v_exp_f32_e32 v0, v0
	v_mul_f32_e32 v51, 0xbfb8aa3b, v93
	v_or_b32_e32 v54, 3, v50
	v_exp_f32_e32 v51, v51
	v_add_f32_e32 v0, 1.0, v0
	v_rcp_f32_e32 v0, v0
	v_ashrrev_i32_e32 v55, 31, v54
	v_lshlrev_b64 v[54:55], 12, v[54:55]
	v_lshl_add_u64 v[54:55], v[52:53], 0, v[54:55]
	v_cvt_pk_bf16_f32 v0, v0, s0
	global_store_short v[54:55], v0, off
	v_add_f32_e32 v0, 1.0, v51
	v_mul_f32_e32 v51, 0xbfb8aa3b, v89
	v_exp_f32_e32 v51, v51
	v_mul_f32_e32 v56, 0xbfb8aa3b, v125
	v_exp_f32_e32 v56, v56
	v_rcp_f32_e32 v0, v0
	v_add_f32_e32 v51, 1.0, v51
	v_rcp_f32_e32 v51, v51
	v_add_f32_e32 v56, 1.0, v56
	v_rcp_f32_e32 v56, v56
	v_cvt_pk_bf16_f32 v0, v0, s0
	global_store_short v[54:55], v0, off offset:32
	v_cvt_pk_bf16_f32 v0, v51, s0
	global_store_short v[54:55], v0, off offset:64
	v_cvt_pk_bf16_f32 v0, v56, s0
	global_store_short v[54:55], v0, off offset:96
	v_mul_f32_e32 v0, 0xbfb8aa3b, v46
	v_exp_f32_e32 v0, v0
	v_mul_f32_e32 v42, 0xbfb8aa3b, v42
	v_or_b32_e32 v54, 16, v50
	v_exp_f32_e32 v42, v42
	v_add_f32_e32 v0, 1.0, v0
	v_rcp_f32_e32 v0, v0
	v_mul_f32_e32 v38, 0xbfb8aa3b, v38
	v_ashrrev_i32_e32 v55, 31, v54
	v_exp_f32_e32 v38, v38
	v_mul_f32_e32 v34, 0xbfb8aa3b, v34
	v_lshlrev_b64 v[54:55], 12, v[54:55]
	v_exp_f32_e32 v34, v34
	v_lshl_add_u64 v[54:55], v[52:53], 0, v[54:55]
	v_cvt_pk_bf16_f32 v0, v0, s0
	global_store_short v[54:55], v0, off
	v_add_f32_e32 v0, 1.0, v42
	v_rcp_f32_e32 v0, v0
	v_add_f32_e32 v38, 1.0, v38
	v_rcp_f32_e32 v38, v38
	v_add_f32_e32 v34, 1.0, v34
	v_rcp_f32_e32 v34, v34
	v_cvt_pk_bf16_f32 v0, v0, s0
	global_store_short v[54:55], v0, off offset:32
	v_cvt_pk_bf16_f32 v0, v38, s0
	global_store_short v[54:55], v0, off offset:64
	v_cvt_pk_bf16_f32 v0, v34, s0
	global_store_short v[54:55], v0, off offset:96
	v_mul_f32_e32 v0, 0xbfb8aa3b, v47
	v_exp_f32_e32 v0, v0
	v_mul_f32_e32 v34, 0xbfb8aa3b, v43
	v_or_b32_e32 v46, 17, v50
	v_exp_f32_e32 v34, v34
	v_add_f32_e32 v0, 1.0, v0
	v_rcp_f32_e32 v0, v0
	v_ashrrev_i32_e32 v47, 31, v46
	v_lshlrev_b64 v[46:47], 12, v[46:47]
	v_lshl_add_u64 v[42:43], v[52:53], 0, v[46:47]
	v_cvt_pk_bf16_f32 v0, v0, s0
	global_store_short v[42:43], v0, off
	v_add_f32_e32 v0, 1.0, v34
	v_mul_f32_e32 v34, 0xbfb8aa3b, v39
	v_exp_f32_e32 v34, v34
	v_mul_f32_e32 v35, 0xbfb8aa3b, v35
	v_exp_f32_e32 v35, v35
	v_rcp_f32_e32 v0, v0
	v_add_f32_e32 v34, 1.0, v34
	v_rcp_f32_e32 v34, v34
	v_add_f32_e32 v35, 1.0, v35
	v_rcp_f32_e32 v35, v35
	v_cvt_pk_bf16_f32 v0, v0, s0
	global_store_short v[42:43], v0, off offset:32
	v_cvt_pk_bf16_f32 v0, v34, s0
	global_store_short v[42:43], v0, off offset:64
	v_cvt_pk_bf16_f32 v0, v35, s0
	global_store_short v[42:43], v0, off offset:96
	v_mul_f32_e32 v0, 0xbfb8aa3b, v48
	v_exp_f32_e32 v0, v0
	v_mul_f32_e32 v38, 0xbfb8aa3b, v44
	v_or_b32_e32 v34, 18, v50
	v_exp_f32_e32 v38, v38
	v_add_f32_e32 v0, 1.0, v0
	v_rcp_f32_e32 v0, v0
	v_ashrrev_i32_e32 v35, 31, v34
	v_lshlrev_b64 v[34:35], 12, v[34:35]
	v_lshl_add_u64 v[34:35], v[52:53], 0, v[34:35]
	v_cvt_pk_bf16_f32 v0, v0, s0
	global_store_short v[34:35], v0, off
	v_add_f32_e32 v0, 1.0, v38
	v_mul_f32_e32 v38, 0xbfb8aa3b, v40
	v_exp_f32_e32 v38, v38
	v_mul_f32_e32 v36, 0xbfb8aa3b, v36
	v_exp_f32_e32 v36, v36
	v_rcp_f32_e32 v0, v0
	v_add_f32_e32 v38, 1.0, v38
	v_rcp_f32_e32 v38, v38
	v_add_f32_e32 v36, 1.0, v36
; DEV float sigmf(float x) { return __builtin_amdgcn_rcpf(1.f + __expf(-x)); }
; template <int EPI, bool AF32>
; DEV void gemm_tile(const void* Ap, int lda, const u16* Bt, int ldb, int K, int m0, int n0, const Epi& ea, char* smem) {
;     ...
;       } else if (EPI == EP_SIG) {
;         u16* C = (u16*)ea.p0;
; #pragma unroll
;         for (int n = 0; n < 4; n++) C[(size_t)row * ea.ld + cb + n * 16 + fr] = f2bf(sigmf(acc[m][n][j]));
	v_rcp_f32_e32 v36, v36
	v_cvt_pk_bf16_f32 v0, v0, s0
	global_store_short v[34:35], v0, off offset:32
	v_cvt_pk_bf16_f32 v0, v38, s0
	global_store_short v[34:35], v0, off offset:64
	v_cvt_pk_bf16_f32 v0, v36, s0
	global_store_short v[34:35], v0, off offset:96
	v_mul_f32_e32 v0, 0xbfb8aa3b, v49
	v_exp_f32_e32 v0, v0
	v_mul_f32_e32 v36, 0xbfb8aa3b, v45
	v_or_b32_e32 v34, 19, v50
	v_exp_f32_e32 v36, v36
	v_add_f32_e32 v0, 1.0, v0
	v_rcp_f32_e32 v0, v0
	v_ashrrev_i32_e32 v35, 31, v34
	v_lshlrev_b64 v[34:35], 12, v[34:35]
	v_lshl_add_u64 v[34:35], v[52:53], 0, v[34:35]
	v_cvt_pk_bf16_f32 v0, v0, s0
	global_store_short v[34:35], v0, off
	v_add_f32_e32 v0, 1.0, v36
	v_mul_f32_e32 v36, 0xbfb8aa3b, v41
	v_exp_f32_e32 v36, v36
	v_mul_f32_e32 v37, 0xbfb8aa3b, v37
	v_exp_f32_e32 v37, v37
	v_rcp_f32_e32 v0, v0
	v_add_f32_e32 v36, 1.0, v36
	v_rcp_f32_e32 v36, v36
	v_add_f32_e32 v37, 1.0, v37
	v_rcp_f32_e32 v37, v37
	v_cvt_pk_bf16_f32 v0, v0, s0
	global_store_short v[34:35], v0, off offset:32
	v_cvt_pk_bf16_f32 v0, v36, s0
	global_store_short v[34:35], v0, off offset:64
	v_cvt_pk_bf16_f32 v0, v37, s0
	global_store_short v[34:35], v0, off offset:96
	v_mul_f32_e32 v0, 0xbfb8aa3b, v30
	v_exp_f32_e32 v0, v0
	v_mul_f32_e32 v26, 0xbfb8aa3b, v26
	v_or_b32_e32 v34, 32, v50
	v_exp_f32_e32 v26, v26
	v_add_f32_e32 v0, 1.0, v0
	v_rcp_f32_e32 v0, v0
	v_mul_f32_e32 v22, 0xbfb8aa3b, v22
	v_ashrrev_i32_e32 v35, 31, v34
	v_exp_f32_e32 v22, v22
	v_mul_f32_e32 v18, 0xbfb8aa3b, v18
	v_lshlrev_b64 v[34:35], 12, v[34:35]
	v_exp_f32_e32 v18, v18
	v_lshl_add_u64 v[34:35], v[52:53], 0, v[34:35]
	v_cvt_pk_bf16_f32 v0, v0, s0
	global_store_short v[34:35], v0, off
	v_add_f32_e32 v0, 1.0, v26
	v_rcp_f32_e32 v0, v0
	v_add_f32_e32 v22, 1.0, v22
	v_rcp_f32_e32 v22, v22
	v_add_f32_e32 v18, 1.0, v18
	v_rcp_f32_e32 v18, v18
	v_cvt_pk_bf16_f32 v0, v0, s0
	global_store_short v[34:35], v0, off offset:32
	v_cvt_pk_bf16_f32 v0, v22, s0
	global_store_short v[34:35], v0, off offset:64
	v_cvt_pk_bf16_f32 v0, v18, s0
	global_store_short v[34:35], v0, off offset:96
	v_mul_f32_e32 v0, 0xbfb8aa3b, v31
	v_exp_f32_e32 v0, v0
	v_mul_f32_e32 v18, 0xbfb8aa3b, v27
	v_or_b32_e32 v30, 33, v50
	v_exp_f32_e32 v18, v18
	v_add_f32_e32 v0, 1.0, v0
	v_rcp_f32_e32 v0, v0
	v_ashrrev_i32_e32 v31, 31, v30
	v_lshlrev_b64 v[30:31], 12, v[30:31]
	v_lshl_add_u64 v[26:27], v[52:53], 0, v[30:31]
	v_cvt_pk_bf16_f32 v0, v0, s0
	global_store_short v[26:27], v0, off
	v_add_f32_e32 v0, 1.0, v18
	v_mul_f32_e32 v18, 0xbfb8aa3b, v23
	v_exp_f32_e32 v18, v18
	v_mul_f32_e32 v19, 0xbfb8aa3b, v19
	v_exp_f32_e32 v19, v19
	v_rcp_f32_e32 v0, v0
	v_add_f32_e32 v18, 1.0, v18
	v_rcp_f32_e32 v18, v18
	v_add_f32_e32 v19, 1.0, v19
	v_rcp_f32_e32 v19, v19
	v_cvt_pk_bf16_f32 v0, v0, s0
	global_store_short v[26:27], v0, off offset:32
	v_cvt_pk_bf16_f32 v0, v18, s0
	global_store_short v[26:27], v0, off offset:64
	v_cvt_pk_bf16_f32 v0, v19, s0
	global_store_short v[26:27], v0, off offset:96
	v_mul_f32_e32 v0, 0xbfb8aa3b, v32
	v_exp_f32_e32 v0, v0
	v_mul_f32_e32 v22, 0xbfb8aa3b, v28
	v_or_b32_e32 v18, 34, v50
	v_exp_f32_e32 v22, v22
	v_add_f32_e32 v0, 1.0, v0
	v_rcp_f32_e32 v0, v0
	v_ashrrev_i32_e32 v19, 31, v18
	v_lshlrev_b64 v[18:19], 12, v[18:19]
	v_lshl_add_u64 v[18:19], v[52:53], 0, v[18:19]
	v_cvt_pk_bf16_f32 v0, v0, s0
	global_store_short v[18:19], v0, off
	v_add_f32_e32 v0, 1.0, v22
	v_mul_f32_e32 v22, 0xbfb8aa3b, v24
	v_exp_f32_e32 v22, v22
	v_mul_f32_e32 v20, 0xbfb8aa3b, v20
	v_exp_f32_e32 v20, v20
	v_rcp_f32_e32 v0, v0
	v_add_f32_e32 v22, 1.0, v22
	v_rcp_f32_e32 v22, v22
	v_add_f32_e32 v20, 1.0, v20
	v_rcp_f32_e32 v20, v20
	v_cvt_pk_bf16_f32 v0, v0, s0
	global_store_short v[18:19], v0, off offset:32
	v_cvt_pk_bf16_f32 v0, v22, s0
	global_store_short v[18:19], v0, off offset:64
	v_cvt_pk_bf16_f32 v0, v20, s0
	global_store_short v[18:19], v0, off offset:96
	v_mul_f32_e32 v0, 0xbfb8aa3b, v33
	v_exp_f32_e32 v0, v0
	v_mul_f32_e32 v20, 0xbfb8aa3b, v29
	v_or_b32_e32 v18, 35, v50
	v_exp_f32_e32 v20, v20
	v_add_f32_e32 v0, 1.0, v0
	v_rcp_f32_e32 v0, v0
	v_ashrrev_i32_e32 v19, 31, v18
	v_lshlrev_b64 v[18:19], 12, v[18:19]
	v_lshl_add_u64 v[18:19], v[52:53], 0, v[18:19]
; DEV int bidx() { int b = __builtin_amdgcn_readfirstlane(blockIdx.x); asm volatile("" : "+s"(b)); return b; }
; DEV int gdim() { int g = __builtin_amdgcn_readfirstlane(gridDim.x); asm volatile("" : "+s"(g)); return g; }
; DEV float sigmf(float x) { return __builtin_amdgcn_rcpf(1.f + __expf(-x)); }
; template <int EPI, bool AF32>
; DEV void gemm_tile(const void* Ap, int lda, const u16* Bt, int ldb, int K, int m0, int n0, const Epi& ea, char* smem) {
;     ...
;       } else if (EPI == EP_SIG) {
;         u16* C = (u16*)ea.p0;
; #pragma unroll
;         for (int n = 0; n < 4; n++) C[(size_t)row * ea.ld + cb + n * 16 + fr] = f2bf(sigmf(acc[m][n][j]));
; template <int EPI, bool AF32>
; DEV void gemm_phase(const void* A, int lda, const u16* Bt, int ldb, int M, int N, int K, const Epi& ea, char* smem) {
;     ...
;   for (int tile = bidx(); tile < ntm * ntn; tile += gdim()) {
;     int m, n;
;     tile_mn(tile, ntm, ntn, m, n);
;     gemm_tile<EPI, AF32>(A, lda, Bt, ldb, K, m << 7, n << 7, ea, smem);
;   }
	v_cvt_pk_bf16_f32 v0, v0, s0
	global_store_short v[18:19], v0, off
	v_add_f32_e32 v0, 1.0, v20
	v_mul_f32_e32 v20, 0xbfb8aa3b, v25
	v_exp_f32_e32 v20, v20
	v_mul_f32_e32 v21, 0xbfb8aa3b, v21
	v_exp_f32_e32 v21, v21
	v_rcp_f32_e32 v0, v0
	v_add_f32_e32 v20, 1.0, v20
	v_rcp_f32_e32 v20, v20
	v_add_f32_e32 v21, 1.0, v21
	v_rcp_f32_e32 v21, v21
	v_cvt_pk_bf16_f32 v0, v0, s0
	global_store_short v[18:19], v0, off offset:32
	v_cvt_pk_bf16_f32 v0, v20, s0
	global_store_short v[18:19], v0, off offset:64
	v_cvt_pk_bf16_f32 v0, v21, s0
	global_store_short v[18:19], v0, off offset:96
	v_mul_f32_e32 v0, 0xbfb8aa3b, v14
	v_exp_f32_e32 v0, v0
	v_mul_f32_e32 v10, 0xbfb8aa3b, v10
	v_or_b32_e32 v18, 48, v50
	v_exp_f32_e32 v10, v10
	v_add_f32_e32 v0, 1.0, v0
	v_rcp_f32_e32 v0, v0
	v_mul_f32_e32 v6, 0xbfb8aa3b, v6
	v_ashrrev_i32_e32 v19, 31, v18
	v_exp_f32_e32 v6, v6
	v_mul_f32_e32 v2, 0xbfb8aa3b, v2
	v_lshlrev_b64 v[18:19], 12, v[18:19]
	v_exp_f32_e32 v2, v2
	v_lshl_add_u64 v[18:19], v[52:53], 0, v[18:19]
	v_cvt_pk_bf16_f32 v0, v0, s0
	global_store_short v[18:19], v0, off
	v_add_f32_e32 v0, 1.0, v10
	v_rcp_f32_e32 v0, v0
	v_add_f32_e32 v6, 1.0, v6
	v_rcp_f32_e32 v6, v6
	v_add_f32_e32 v2, 1.0, v2
	v_rcp_f32_e32 v2, v2
	v_cvt_pk_bf16_f32 v0, v0, s0
	global_store_short v[18:19], v0, off offset:32
	v_cvt_pk_bf16_f32 v0, v6, s0
	global_store_short v[18:19], v0, off offset:64
	v_cvt_pk_bf16_f32 v0, v2, s0
	global_store_short v[18:19], v0, off offset:96
	v_mul_f32_e32 v0, 0xbfb8aa3b, v15
	v_exp_f32_e32 v0, v0
	v_mul_f32_e32 v2, 0xbfb8aa3b, v11
	v_or_b32_e32 v14, 49, v50
	v_exp_f32_e32 v2, v2
	v_add_f32_e32 v0, 1.0, v0
	v_rcp_f32_e32 v0, v0
	v_ashrrev_i32_e32 v15, 31, v14
	v_lshlrev_b64 v[14:15], 12, v[14:15]
	v_lshl_add_u64 v[10:11], v[52:53], 0, v[14:15]
	v_cvt_pk_bf16_f32 v0, v0, s0
	global_store_short v[10:11], v0, off
	v_add_f32_e32 v0, 1.0, v2
	v_mul_f32_e32 v2, 0xbfb8aa3b, v7
	v_exp_f32_e32 v2, v2
	v_mul_f32_e32 v3, 0xbfb8aa3b, v3
	v_exp_f32_e32 v3, v3
	v_rcp_f32_e32 v0, v0
	v_add_f32_e32 v2, 1.0, v2
	v_rcp_f32_e32 v2, v2
	v_add_f32_e32 v3, 1.0, v3
	v_rcp_f32_e32 v3, v3
	v_cvt_pk_bf16_f32 v0, v0, s0
	global_store_short v[10:11], v0, off offset:32
	v_cvt_pk_bf16_f32 v0, v2, s0
	global_store_short v[10:11], v0, off offset:64
	v_cvt_pk_bf16_f32 v0, v3, s0
	global_store_short v[10:11], v0, off offset:96
	v_mul_f32_e32 v0, 0xbfb8aa3b, v16
	v_exp_f32_e32 v0, v0
	v_mul_f32_e32 v6, 0xbfb8aa3b, v12
	v_or_b32_e32 v2, 50, v50
	v_exp_f32_e32 v6, v6
	v_add_f32_e32 v0, 1.0, v0
	v_rcp_f32_e32 v0, v0
	v_ashrrev_i32_e32 v3, 31, v2
	v_lshlrev_b64 v[2:3], 12, v[2:3]
	v_lshl_add_u64 v[2:3], v[52:53], 0, v[2:3]
	v_cvt_pk_bf16_f32 v0, v0, s0
	global_store_short v[2:3], v0, off
	v_add_f32_e32 v0, 1.0, v6
	v_mul_f32_e32 v6, 0xbfb8aa3b, v8
	v_exp_f32_e32 v6, v6
	v_mul_f32_e32 v4, 0xbfb8aa3b, v4
	v_exp_f32_e32 v4, v4
	v_rcp_f32_e32 v0, v0
	v_add_f32_e32 v6, 1.0, v6
	v_rcp_f32_e32 v6, v6
	v_add_f32_e32 v4, 1.0, v4
	v_rcp_f32_e32 v4, v4
	v_cvt_pk_bf16_f32 v0, v0, s0
	global_store_short v[2:3], v0, off offset:32
	v_cvt_pk_bf16_f32 v0, v6, s0
	global_store_short v[2:3], v0, off offset:64
	v_cvt_pk_bf16_f32 v0, v4, s0
	global_store_short v[2:3], v0, off offset:96
	v_mul_f32_e32 v0, 0xbfb8aa3b, v17
	v_exp_f32_e32 v0, v0
	v_mul_f32_e32 v4, 0xbfb8aa3b, v13
	v_or_b32_e32 v2, 51, v50
	v_exp_f32_e32 v4, v4
	v_add_f32_e32 v0, 1.0, v0
	v_rcp_f32_e32 v0, v0
	v_ashrrev_i32_e32 v3, 31, v2
	v_lshlrev_b64 v[2:3], 12, v[2:3]
	v_lshl_add_u64 v[2:3], v[52:53], 0, v[2:3]
	v_cvt_pk_bf16_f32 v0, v0, s0
	global_store_short v[2:3], v0, off
	v_add_f32_e32 v0, 1.0, v4
	v_mul_f32_e32 v4, 0xbfb8aa3b, v9
	v_exp_f32_e32 v4, v4
	v_mul_f32_e32 v5, 0xbfb8aa3b, v5
	v_exp_f32_e32 v5, v5
	v_rcp_f32_e32 v0, v0
	v_add_f32_e32 v4, 1.0, v4
	v_rcp_f32_e32 v4, v4
	v_add_f32_e32 v5, 1.0, v5
	v_rcp_f32_e32 v5, v5
	v_cvt_pk_bf16_f32 v0, v0, s0
	global_store_short v[2:3], v0, off offset:32
	v_cvt_pk_bf16_f32 v0, v4, s0
	global_store_short v[2:3], v0, off offset:64
	v_cvt_pk_bf16_f32 v0, v5, s0
	v_readfirstlane_b32 s0, v198
	global_store_short v[2:3], v0, off offset:96
	s_add_i32 s8, s0, s8
	s_cmpk_lt_i32 s8, 0x1040
	s_cbranch_scc1 .LBB0_1262

; template <int EPI, bool AF32>
; DEV void gemm_tile(const void* Ap, int lda, const u16* Bt, int ldb, int K, int m0, int n0, const Epi& ea, char* smem) {
;     ...
;   auto gload = [&](int kt) {
;     const int k0 = kt << 6;
; #pragma unroll
;     for (int i = 0; i < 4; i++) {
;       const int c = tid + i * 256, row = c >> 3, kc = c & 7;
;       if (AF32) {
;         const float* pa = (const float*)Ap + (size_t)(m0 + row) * lda + k0 + kc * 8;
;         rfa[2 * i] = *(const f32x4*)pa;
;         rfa[2 * i + 1] = *(const f32x4*)(pa + 4);
;       } else {
;         ra[i] = *(const u32x4*)((const u16*)Ap + (size_t)(m0 + row) * lda + k0 + kc * 8);
;       }
;       rb[i] = *(const u32x4*)(Bt + (size_t)(n0 + row) * ldb + k0 + kc * 8);
;     }
;   };
;   auto swrite = [&](int buf) {
; #pragma unroll
;     for (int i = 0; i < 4; i++) {
;       const int c = tid + i * 256, row = c >> 3, kc = c & 7;
;       u32x4 va;
;       if (AF32) {
;         va = (u32x4){pack2(rfa[2 * i][0], rfa[2 * i][1]), pack2(rfa[2 * i][2], rfa[2 * i][3]),
;                      pack2(rfa[2 * i + 1][0], rfa[2 * i + 1][1]), pack2(rfa[2 * i + 1][2], rfa[2 * i + 1][3])};
;       } else {
;         va = ra[i];
;       }
;       *(u32x4*)(sA + buf * 9216 + row * 72 + kc * 8) = va;
;       *(u32x4*)(sB + buf * 9216 + row * 72 + kc * 8) = rb[i];
;     }
;   };
;   gload(0);
;   swrite(0);
;   if (nk > 1) gload(1);
;   __syncthreads();
.LBB0_1304:
	s_ashr_i32 s0, s16, 31
	s_lshr_b32 s0, s0, 24
	s_add_i32 s0, s16, s0
	s_ashr_i32 s1, s0, 8
	s_and_b32 s0, s0, 0xffffff00
	s_lshl_b32 s18, s1, 5
	s_sub_i32 s17, s16, s0
	s_sub_i32 s0, 0x104, s18
	s_min_u32 s19, s0, 32
	v_cvt_f32_ubyte0_e32 v2, s19
	v_cvt_f32_i32_e32 v0, s17
	v_rcp_iflag_f32_e32 v3, v2
	s_ashr_i32 s0, s17, 30
	s_or_b32 s20, s0, 1
	s_waitcnt vmcnt(12)
	v_mov_b32_e32 v114, v157
	v_mul_f32_e32 v3, v0, v3
	v_trunc_f32_e32 v3, v3
	v_fma_f32 v0, -v3, v2, v0
	v_cvt_i32_f32_e32 v3, v3
	v_cmp_ge_f32_e64 s[0:1], |v0|, v2
	s_and_b64 s[0:1], s[0:1], exec
	s_cselect_b32 s0, s20, 0
	v_readfirstlane_b32 s1, v3
	s_add_i32 s0, s1, s0
	s_sext_i32_i16 s1, s0
	s_mul_i32 s0, s0, s19
	s_sub_i32 s0, s17, s0
	s_sext_i32_i16 s0, s0
	s_add_i32 s18, s18, s0
	s_lshl_b32 s18, s18, 7
	s_lshl_b32 s17, s1, 7
	v_ashrrev_i32_e32 v8, 3, v114
	v_add_u32_e32 v2, s18, v8
	v_ashrrev_i32_e32 v3, 31, v2
	v_lshlrev_b32_e32 v0, 3, v114
	v_add_u32_e32 v4, 0x100, v114
	v_lshlrev_b64 v[58:59], 11, v[2:3]
	v_and_b32_e32 v0, 56, v0
	v_ashrrev_i32_e32 v9, 3, v4
	v_lshl_add_u64 v[2:3], s[6:7], 0, v[58:59]
	v_lshlrev_b32_e32 v0, 1, v0
	v_add_u32_e32 v4, s18, v9
	v_add_u32_e32 v6, 0x200, v114
	v_lshl_add_u64 v[14:15], v[2:3], 0, v[0:1]
	v_add_u32_e32 v2, s17, v8
	v_ashrrev_i32_e32 v5, 31, v4
	v_ashrrev_i32_e32 v10, 3, v6
	v_ashrrev_i32_e32 v3, 31, v2
	v_lshlrev_b64 v[62:63], 11, v[4:5]
	v_add_u32_e32 v6, s18, v10
	v_lshlrev_b64 v[60:61], 11, v[2:3]
	v_lshl_add_u64 v[4:5], s[6:7], 0, v[62:63]
	v_ashrrev_i32_e32 v7, 31, v6
	v_lshl_add_u64 v[2:3], s[10:11], 0, v[60:61]
	v_lshl_add_u64 v[16:17], v[4:5], 0, v[0:1]
	v_add_u32_e32 v4, s17, v9
	v_lshlrev_b64 v[66:67], 11, v[6:7]
	v_lshl_add_u64 v[2:3], v[2:3], 0, v[0:1]
	v_ashrrev_i32_e32 v5, 31, v4
	v_lshl_add_u64 v[6:7], s[6:7], 0, v[66:67]
	global_load_dwordx4 v[30:33], v[2:3], off
	v_lshlrev_b64 v[64:65], 11, v[4:5]
	v_lshl_add_u64 v[68:69], v[6:7], 0, v[0:1]
	v_add_u32_e32 v6, s17, v10
	global_load_dwordx4 v[26:29], v[14:15], off
	global_load_dwordx4 v[34:37], v[16:17], off
	v_lshl_add_u64 v[4:5], s[10:11], 0, v[64:65]
	v_ashrrev_i32_e32 v7, 31, v6
	v_lshl_add_u64 v[4:5], v[4:5], 0, v[0:1]
	v_lshlrev_b64 v[70:71], 11, v[6:7]
	global_load_dwordx4 v[38:41], v[4:5], off
	v_lshl_add_u64 v[6:7], s[10:11], 0, v[70:71]
	global_load_dwordx4 v[42:45], v[68:69], off
	v_lshl_add_u64 v[18:19], v[6:7], 0, v[0:1]
	global_load_dwordx4 v[46:49], v[18:19], off
	v_add_u32_e32 v6, 0x300, v114
	v_ashrrev_i32_e32 v80, 3, v6
	v_add_u32_e32 v6, s18, v80
	v_ashrrev_i32_e32 v7, 31, v6
	v_lshlrev_b64 v[72:73], 11, v[6:7]
	v_lshl_add_u64 v[6:7], s[6:7], 0, v[72:73]
	v_lshl_add_u64 v[74:75], v[6:7], 0, v[0:1]
	v_add_u32_e32 v6, s17, v80
	v_ashrrev_i32_e32 v7, 31, v6
	v_lshlrev_b64 v[76:77], 11, v[6:7]
	v_lshl_add_u64 v[6:7], s[10:11], 0, v[76:77]
	v_lshl_add_u64 v[78:79], v[6:7], 0, v[0:1]
	global_load_dwordx4 v[50:53], v[74:75], off
	global_load_dwordx4 v[54:57], v[78:79], off
	s_waitcnt vmcnt(19)
	v_mul_lo_u32 v118, v8, s71
	v_mul_lo_u32 v119, v9, s71
	s_waitcnt vmcnt(18)
	v_mul_lo_u32 v123, v10, s71
	global_load_dwordx4 v[6:9], v[2:3], off offset:128
	global_load_dwordx4 v[10:13], v[4:5], off offset:128
	s_nop 0
	global_load_dwordx4 v[2:5], v[18:19], off offset:128
	global_load_dwordx4 v[22:25], v[14:15], off offset:128
	s_nop 0
	global_load_dwordx4 v[18:21], v[16:17], off offset:128
	s_nop 0
	global_load_dwordx4 v[14:17], v[68:69], off offset:128
	v_bfe_u32 v161, v157, 3, 4
	v_add_u32_e32 v161, 4, v161
	v_lshlrev_b32_e32 v161, 1, v161
	v_and_b32_e32 v161, 16, v161
	v_xor_b32_e32 v129, v0, v161
	v_lshl_add_u32 v122, v118, 1, v129
	v_lshl_add_u32 v121, v119, 1, v129
	v_lshl_add_u32 v120, v123, 1, v129
	v_and_b32_e32 v115, 15, v114
	s_waitcnt vmcnt(23)
	v_mul_lo_u32 v126, v80, s71
	v_bfe_u32 v116, v114, 4, 2
	v_lshl_add_u32 v124, v126, 1, v129
	s_mov_b32 s19, 0
	v_lshlrev_b32_e32 v125, 4, v116
	v_and_b32_e32 v161, 15, v157
	v_add_u32_e32 v161, 4, v161
	v_lshlrev_b32_e32 v161, 1, v161
	v_and_b32_e32 v161, 16, v161
	v_xor_b32_e32 v125, v125, v161
	s_mov_b64 s[0:1], 0
	s_waitcnt vmcnt(13)
	ds_write_b128 v122, v[30:33] offset:36864
	s_waitcnt vmcnt(12)
	ds_write_b128 v122, v[26:29]
	s_waitcnt vmcnt(11)
	ds_write_b128 v121, v[34:37]
	s_waitcnt vmcnt(10)
	ds_write_b128 v121, v[38:41] offset:36864
	s_waitcnt vmcnt(9)
	ds_write_b128 v120, v[42:45]
	s_waitcnt vmcnt(8)
	ds_write_b128 v120, v[46:49] offset:36864
	global_load_dwordx4 v[26:29], v[74:75], off offset:128
	global_load_dwordx4 v[30:33], v[78:79], off offset:128
	v_ashrrev_i32_e32 v34, 1, v114
	v_and_b32_e32 v117, 0xffffffc0, v34
	v_or_b32_e32 v34, v117, v115
	v_mul_lo_u32 v128, v34, s71
	v_lshlrev_b32_e32 v34, 4, v114
	v_and_b32_e32 v34, 0x70, v34
	v_and_b32_e32 v35, 0x4f, v114
	v_or_b32_e32 v76, v76, v34
	v_or_b32_e32 v72, v72, v34
	v_or_b32_e32 v70, v70, v34
	v_or_b32_e32 v66, v66, v34
	v_or_b32_e32 v64, v64, v34
	v_or_b32_e32 v62, v62, v34
	v_or_b32_e32 v60, v60, v34
	v_or_b32_e32 v58, v58, v34
	v_mov_b32_e32 v34, 0
	s_waitcnt vmcnt(9)
	ds_write_b128 v124, v[50:53]
	s_waitcnt vmcnt(8)
; template <int EPI, bool AF32>
; DEV void gemm_tile(const void* Ap, int lda, const u16* Bt, int ldb, int K, int m0, int n0, const Epi& ea, char* smem) {
;     ...
;   f32x4 acc[4][4];
; #pragma unroll
;   for (int m = 0; m < 4; m++)
; #pragma unroll
;     for (int n = 0; n < 4; n++) acc[m][n] = (f32x4){0.f, 0.f, 0.f, 0.f};
;   u32x4 ra[4], rb[4];
;   f32x4 rfa[8];
;   const int nk = K >> 6;
;   auto gload = [&](int kt) {
;     const int k0 = kt << 6;
; #pragma unroll
;     for (int i = 0; i < 4; i++) {
;       const int c = tid + i * 256, row = c >> 3, kc = c & 7;
;       if (AF32) {
;         const float* pa = (const float*)Ap + (size_t)(m0 + row) * lda + k0 + kc * 8;
;         rfa[2 * i] = *(const f32x4*)pa;
;         rfa[2 * i + 1] = *(const f32x4*)(pa + 4);
;       } else {
;         ra[i] = *(const u32x4*)((const u16*)Ap + (size_t)(m0 + row) * lda + k0 + kc * 8);
;       }
;       rb[i] = *(const u32x4*)(Bt + (size_t)(n0 + row) * ldb + k0 + kc * 8);
;     }
;   };
;   auto swrite = [&](int buf) {
; #pragma unroll
;     for (int i = 0; i < 4; i++) {
;       const int c = tid + i * 256, row = c >> 3, kc = c & 7;
;       u32x4 va;
;       if (AF32) {
;         va = (u32x4){pack2(rfa[2 * i][0], rfa[2 * i][1]), pack2(rfa[2 * i][2], rfa[2 * i][3]),
;                      pack2(rfa[2 * i + 1][0], rfa[2 * i + 1][1]), pack2(rfa[2 * i + 1][2], rfa[2 * i + 1][3])};
;       } else {
;         va = ra[i];
;       }
;       *(u32x4*)(sA + buf * 9216 + row * 72 + kc * 8) = va;
;       *(u32x4*)(sB + buf * 9216 + row * 72 + kc * 8) = rb[i];
;     }
;   };
;   gload(0);
;   swrite(0);
;   if (nk > 1) gload(1);
;   __syncthreads();
;   for (int kt = 0; kt < nk; kt++) {
;     const int buf = kt & 1;
;     if (kt + 1 < nk) swrite(buf ^ 1);
;     if (kt + 2 < nk) gload(kt + 2);
; #pragma unroll
;     for (int ks = 0; ks < 2; ks++) {
;       bf16x8 a[4], b[4];
; #pragma unroll
;       for (int m = 0; m < 4; m++) a[m] = *(const bf16x8*)(sA + buf * 9216 + (wr * 64 + m * 16 + fr) * 72 + ks * 32 + fq * 8);
; #pragma unroll
;       for (int n = 0; n < 4; n++) b[n] = *(const bf16x8*)(sB + buf * 9216 + (wc * 64 + n * 16 + fr) * 72 + ks * 32 + fq * 8);
;       __builtin_amdgcn_s_setprio(1);
; #pragma unroll
;       for (int m = 0; m < 4; m++)
; #pragma unroll
;         for (int n = 0; n < 4; n++) acc[m][n] = mfma16(a[m], b[n], acc[m][n]);
;       __builtin_amdgcn_s_setprio(0);
;     }
	ds_write_b128 v124, v[54:57] offset:36864
	v_mul_u32_u24_e32 v127, 0x48, v35
	v_lshl_add_u64 v[98:99], s[12:13], 0, v[76:77]
	v_lshl_add_u64 v[100:101], s[14:15], 0, v[72:73]
	v_lshl_add_u64 v[102:103], s[12:13], 0, v[70:71]
	v_lshl_add_u64 v[104:105], s[14:15], 0, v[66:67]
	v_lshl_add_u64 v[106:107], s[12:13], 0, v[64:65]
	v_lshl_add_u64 v[108:109], s[14:15], 0, v[62:63]
	v_lshl_add_u64 v[110:111], s[12:13], 0, v[60:61]
	v_lshl_add_u64 v[112:113], s[14:15], 0, v[58:59]
	global_load_dwordx4 v[222:225], v[112:113], off
	global_load_dwordx4 v[226:229], v[110:111], off
	global_load_dwordx4 v[230:233], v[108:109], off
	global_load_dwordx4 v[234:237], v[106:107], off
	global_load_dwordx4 v[238:241], v[104:105], off
	global_load_dwordx4 v[242:245], v[102:103], off
	global_load_dwordx4 v[246:249], v[100:101], off
	global_load_dwordx4 v[250:253], v[98:99], off
	v_mov_b32_e32 v35, v34
	v_mov_b32_e32 v36, v34
	v_mov_b32_e32 v37, v34
	v_mov_b32_e32 v38, v34
	v_mov_b32_e32 v39, v34
	v_mov_b32_e32 v40, v34
	v_mov_b32_e32 v41, v34
	v_mov_b32_e32 v42, v34
	v_mov_b32_e32 v43, v34
	v_mov_b32_e32 v44, v34
	v_mov_b32_e32 v45, v34
	v_mov_b32_e32 v46, v34
	v_mov_b32_e32 v47, v34
	v_mov_b32_e32 v48, v34
	v_mov_b32_e32 v49, v34
	v_mov_b32_e32 v50, v34
	v_mov_b32_e32 v51, v34
	v_mov_b32_e32 v52, v34
	v_mov_b32_e32 v53, v34
	v_mov_b32_e32 v54, v34
	v_mov_b32_e32 v55, v34
	v_mov_b32_e32 v56, v34
	v_mov_b32_e32 v57, v34
	v_mov_b32_e32 v58, v34
	v_mov_b32_e32 v59, v34
	v_mov_b32_e32 v60, v34
	v_mov_b32_e32 v61, v34
	v_mov_b32_e32 v62, v34
	v_mov_b32_e32 v63, v34
	v_mov_b32_e32 v64, v34
	v_mov_b32_e32 v65, v34
	v_mov_b32_e32 v66, v34
	v_mov_b32_e32 v67, v34
	v_mov_b32_e32 v68, v34
	v_mov_b32_e32 v69, v34
	v_mov_b32_e32 v70, v34
	v_mov_b32_e32 v71, v34
	v_mov_b32_e32 v72, v34
	v_mov_b32_e32 v73, v34
	v_mov_b32_e32 v74, v34
	v_mov_b32_e32 v75, v34
	v_mov_b32_e32 v76, v34
	v_mov_b32_e32 v77, v34
	v_mov_b32_e32 v78, v34
	v_mov_b32_e32 v79, v34
	v_mov_b32_e32 v80, v34
	v_mov_b32_e32 v81, v34
	v_mov_b32_e32 v82, v34
	v_mov_b32_e32 v83, v34
	v_mov_b32_e32 v84, v34
	v_mov_b32_e32 v85, v34
	v_mov_b32_e32 v86, v34
	v_mov_b32_e32 v87, v34
	v_mov_b32_e32 v88, v34
	v_mov_b32_e32 v89, v34
	v_mov_b32_e32 v90, v34
	v_mov_b32_e32 v91, v34
	v_mov_b32_e32 v92, v34
	v_mov_b32_e32 v93, v34
	v_mov_b32_e32 v94, v34
	v_mov_b32_e32 v95, v34
	v_mov_b32_e32 v96, v34
	v_mov_b32_e32 v97, v34
	s_waitcnt lgkmcnt(0)
	s_barrier
	v_lshl_add_u32 v161, v128, 1, v125
	v_lshl_add_u32 v129, v127, 1, v125
	s_mov_b32 s19, 0
	s_mov_b64 s[0:1], 0x100
.Lgk3_loop:
	v_lshl_add_u64 v[112:113], v[112:113], 0, s[0:1]
	v_lshl_add_u64 v[110:111], v[110:111], 0, s[0:1]
	v_lshl_add_u64 v[108:109], v[108:109], 0, s[0:1]
	v_lshl_add_u64 v[106:107], v[106:107], 0, s[0:1]
	v_lshl_add_u64 v[104:105], v[104:105], 0, s[0:1]
	v_lshl_add_u64 v[102:103], v[102:103], 0, s[0:1]
	v_lshl_add_u64 v[100:101], v[100:101], 0, s[0:1]
	v_lshl_add_u64 v[98:99], v[98:99], 0, s[0:1]
	ds_read_b128 v[130:133], v161
	ds_read_b128 v[134:137], v161 offset:2304
	ds_read_b128 v[138:141], v161 offset:4608
	ds_read_b128 v[142:145], v161 offset:6912
	ds_read_b128 v[146:149], v129 offset:36864
	ds_read_b128 v[150:153], v129 offset:39168
	ds_read_b128 v[162:165], v129 offset:41472
	ds_read_b128 v[166:169], v129 offset:43776
	s_setprio 1
	s_waitcnt lgkmcnt(3)
	v_mfma_f32_16x16x32_bf16 v[34:37], v[130:133], v[146:149], v[34:37]
	s_waitcnt lgkmcnt(2)
	v_mfma_f32_16x16x32_bf16 v[38:41], v[130:133], v[150:153], v[38:41]
	s_waitcnt lgkmcnt(1)
	v_mfma_f32_16x16x32_bf16 v[42:45], v[130:133], v[162:165], v[42:45]
	s_waitcnt lgkmcnt(0)
	v_mfma_f32_16x16x32_bf16 v[46:49], v[130:133], v[166:169], v[46:49]
	v_mfma_f32_16x16x32_bf16 v[50:53], v[134:137], v[146:149], v[50:53]
	v_mfma_f32_16x16x32_bf16 v[54:57], v[134:137], v[150:153], v[54:57]
	v_mfma_f32_16x16x32_bf16 v[58:61], v[134:137], v[162:165], v[58:61]
	v_mfma_f32_16x16x32_bf16 v[62:65], v[134:137], v[166:169], v[62:65]
	v_mfma_f32_16x16x32_bf16 v[66:69], v[138:141], v[146:149], v[66:69]
	v_mfma_f32_16x16x32_bf16 v[70:73], v[138:141], v[150:153], v[70:73]
	v_mfma_f32_16x16x32_bf16 v[74:77], v[138:141], v[162:165], v[74:77]
	v_mfma_f32_16x16x32_bf16 v[78:81], v[138:141], v[166:169], v[78:81]
	v_mfma_f32_16x16x32_bf16 v[82:85], v[142:145], v[146:149], v[82:85]
	v_mfma_f32_16x16x32_bf16 v[86:89], v[142:145], v[150:153], v[86:89]
	v_mfma_f32_16x16x32_bf16 v[90:93], v[142:145], v[162:165], v[90:93]
	v_mfma_f32_16x16x32_bf16 v[94:97], v[142:145], v[166:169], v[94:97]
	s_setprio 0
	ds_read_b128 v[130:133], v161 offset:64
	ds_read_b128 v[134:137], v161 offset:2368
	ds_read_b128 v[138:141], v161 offset:4672
	ds_read_b128 v[142:145], v161 offset:6976
	ds_read_b128 v[146:149], v129 offset:36928
	ds_read_b128 v[150:153], v129 offset:39232
	ds_read_b128 v[162:165], v129 offset:41536
	ds_read_b128 v[166:169], v129 offset:43840
	s_waitcnt vmcnt(8)
	ds_write_b128 v122, v[22:25] offset:18432
	ds_write_b128 v122, v[6:9] offset:55296
	ds_write_b128 v121, v[18:21] offset:18432
	ds_write_b128 v121, v[10:13] offset:55296
	ds_write_b128 v120, v[14:17] offset:18432
	ds_write_b128 v120, v[2:5] offset:55296
	ds_write_b128 v124, v[26:29] offset:18432
	ds_write_b128 v124, v[30:33] offset:55296
	global_load_dwordx4 v[22:25], v[112:113], off offset:-128
	global_load_dwordx4 v[6:9], v[110:111], off offset:-128
	global_load_dwordx4 v[18:21], v[108:109], off offset:-128
	global_load_dwordx4 v[10:13], v[106:107], off offset:-128
	global_load_dwordx4 v[14:17], v[104:105], off offset:-128
	global_load_dwordx4 v[2:5], v[102:103], off offset:-128
	global_load_dwordx4 v[26:29], v[100:101], off offset:-128
	global_load_dwordx4 v[30:33], v[98:99], off offset:-128
	s_setprio 1
	s_waitcnt lgkmcnt(11)
	v_mfma_f32_16x16x32_bf16 v[34:37], v[130:133], v[146:149], v[34:37]
	s_waitcnt lgkmcnt(10)
	v_mfma_f32_16x16x32_bf16 v[38:41], v[130:133], v[150:153], v[38:41]
	s_waitcnt lgkmcnt(9)
	v_mfma_f32_16x16x32_bf16 v[42:45], v[130:133], v[162:165], v[42:45]
	s_waitcnt lgkmcnt(8)
	v_mfma_f32_16x16x32_bf16 v[46:49], v[130:133], v[166:169], v[46:49]
	v_mfma_f32_16x16x32_bf16 v[50:53], v[134:137], v[146:149], v[50:53]
	v_mfma_f32_16x16x32_bf16 v[54:57], v[134:137], v[150:153], v[54:57]
	v_mfma_f32_16x16x32_bf16 v[58:61], v[134:137], v[162:165], v[58:61]
	v_mfma_f32_16x16x32_bf16 v[62:65], v[134:137], v[166:169], v[62:65]
	v_mfma_f32_16x16x32_bf16 v[66:69], v[138:141], v[146:149], v[66:69]
	v_mfma_f32_16x16x32_bf16 v[70:73], v[138:141], v[150:153], v[70:73]
	v_mfma_f32_16x16x32_bf16 v[74:77], v[138:141], v[162:165], v[74:77]
	v_mfma_f32_16x16x32_bf16 v[78:81], v[138:141], v[166:169], v[78:81]
	v_mfma_f32_16x16x32_bf16 v[82:85], v[142:145], v[146:149], v[82:85]
	v_mfma_f32_16x16x32_bf16 v[86:89], v[142:145], v[150:153], v[86:89]
	v_mfma_f32_16x16x32_bf16 v[90:93], v[142:145], v[162:165], v[90:93]
	v_mfma_f32_16x16x32_bf16 v[94:97], v[142:145], v[166:169], v[94:97]
	s_setprio 0
	s_waitcnt lgkmcnt(0)
	s_barrier
; DEV f32x4 mfma16(bf16x8 a, bf16x8 b, f32x4 c) { return __builtin_amdgcn_mfma_f32_16x16x32_bf16(a, b, c, 0, 0, 0); }
; template <int EPI, bool AF32>
; DEV void gemm_tile(const void* Ap, int lda, const u16* Bt, int ldb, int K, int m0, int n0, const Epi& ea, char* smem) {
;     ...
;   for (int kt = 0; kt < nk; kt++) {
;     const int buf = kt & 1;
;     if (kt + 1 < nk) swrite(buf ^ 1);
;     if (kt + 2 < nk) gload(kt + 2);
; #pragma unroll
;     for (int ks = 0; ks < 2; ks++) {
;       bf16x8 a[4], b[4];
; #pragma unroll
;       for (int m = 0; m < 4; m++) a[m] = *(const bf16x8*)(sA + buf * 9216 + (wr * 64 + m * 16 + fr) * 72 + ks * 32 + fq * 8);
; #pragma unroll
;       for (int n = 0; n < 4; n++) b[n] = *(const bf16x8*)(sB + buf * 9216 + (wc * 64 + n * 16 + fr) * 72 + ks * 32 + fq * 8);
;       __builtin_amdgcn_s_setprio(1);
; #pragma unroll
;       for (int m = 0; m < 4; m++)
; #pragma unroll
;         for (int n = 0; n < 4; n++) acc[m][n] = mfma16(a[m], b[n], acc[m][n]);
;       __builtin_amdgcn_s_setprio(0);
;     }
;     __syncthreads();
;   }
	ds_read_b128 v[130:133], v161 offset:18432
	ds_read_b128 v[134:137], v161 offset:20736
	ds_read_b128 v[138:141], v161 offset:23040
	ds_read_b128 v[142:145], v161 offset:25344
	ds_read_b128 v[146:149], v129 offset:55296
	ds_read_b128 v[150:153], v129 offset:57600
	ds_read_b128 v[162:165], v129 offset:59904
	ds_read_b128 v[166:169], v129 offset:62208
	s_setprio 1
	s_waitcnt lgkmcnt(3)
	v_mfma_f32_16x16x32_bf16 v[34:37], v[130:133], v[146:149], v[34:37]
	s_waitcnt lgkmcnt(2)
	v_mfma_f32_16x16x32_bf16 v[38:41], v[130:133], v[150:153], v[38:41]
	s_waitcnt lgkmcnt(1)
	v_mfma_f32_16x16x32_bf16 v[42:45], v[130:133], v[162:165], v[42:45]
	s_waitcnt lgkmcnt(0)
	v_mfma_f32_16x16x32_bf16 v[46:49], v[130:133], v[166:169], v[46:49]
	v_mfma_f32_16x16x32_bf16 v[50:53], v[134:137], v[146:149], v[50:53]
	v_mfma_f32_16x16x32_bf16 v[54:57], v[134:137], v[150:153], v[54:57]
	v_mfma_f32_16x16x32_bf16 v[58:61], v[134:137], v[162:165], v[58:61]
	v_mfma_f32_16x16x32_bf16 v[62:65], v[134:137], v[166:169], v[62:65]
	v_mfma_f32_16x16x32_bf16 v[66:69], v[138:141], v[146:149], v[66:69]
	v_mfma_f32_16x16x32_bf16 v[70:73], v[138:141], v[150:153], v[70:73]
	v_mfma_f32_16x16x32_bf16 v[74:77], v[138:141], v[162:165], v[74:77]
	v_mfma_f32_16x16x32_bf16 v[78:81], v[138:141], v[166:169], v[78:81]
	v_mfma_f32_16x16x32_bf16 v[82:85], v[142:145], v[146:149], v[82:85]
	v_mfma_f32_16x16x32_bf16 v[86:89], v[142:145], v[150:153], v[86:89]
	v_mfma_f32_16x16x32_bf16 v[90:93], v[142:145], v[162:165], v[90:93]
	v_mfma_f32_16x16x32_bf16 v[94:97], v[142:145], v[166:169], v[94:97]
	s_setprio 0
	ds_read_b128 v[130:133], v161 offset:18496
	ds_read_b128 v[134:137], v161 offset:20800
	ds_read_b128 v[138:141], v161 offset:23104
	ds_read_b128 v[142:145], v161 offset:25408
	ds_read_b128 v[146:149], v129 offset:55360
	ds_read_b128 v[150:153], v129 offset:57664
	ds_read_b128 v[162:165], v129 offset:59968
	ds_read_b128 v[166:169], v129 offset:62272
	s_waitcnt vmcnt(8)
	ds_write_b128 v122, v[222:225]
	ds_write_b128 v122, v[226:229] offset:36864
	ds_write_b128 v121, v[230:233]
	ds_write_b128 v121, v[234:237] offset:36864
	ds_write_b128 v120, v[238:241]
	ds_write_b128 v120, v[242:245] offset:36864
	ds_write_b128 v124, v[246:249]
	ds_write_b128 v124, v[250:253] offset:36864
	s_cmp_eq_u32 s19, 6
	s_cbranch_scc1 .Lgk3_nold
	global_load_dwordx4 v[222:225], v[112:113], off
	global_load_dwordx4 v[226:229], v[110:111], off
	global_load_dwordx4 v[230:233], v[108:109], off
	global_load_dwordx4 v[234:237], v[106:107], off
	global_load_dwordx4 v[238:241], v[104:105], off
	global_load_dwordx4 v[242:245], v[102:103], off
	global_load_dwordx4 v[246:249], v[100:101], off
	global_load_dwordx4 v[250:253], v[98:99], off
.Lgk3_nold:
	s_setprio 1
	s_waitcnt lgkmcnt(11)
	v_mfma_f32_16x16x32_bf16 v[34:37], v[130:133], v[146:149], v[34:37]
	s_waitcnt lgkmcnt(10)
	v_mfma_f32_16x16x32_bf16 v[38:41], v[130:133], v[150:153], v[38:41]
	s_waitcnt lgkmcnt(9)
	v_mfma_f32_16x16x32_bf16 v[42:45], v[130:133], v[162:165], v[42:45]
	s_waitcnt lgkmcnt(8)
	v_mfma_f32_16x16x32_bf16 v[46:49], v[130:133], v[166:169], v[46:49]
	v_mfma_f32_16x16x32_bf16 v[50:53], v[134:137], v[146:149], v[50:53]
	v_mfma_f32_16x16x32_bf16 v[54:57], v[134:137], v[150:153], v[54:57]
	v_mfma_f32_16x16x32_bf16 v[58:61], v[134:137], v[162:165], v[58:61]
	v_mfma_f32_16x16x32_bf16 v[62:65], v[134:137], v[166:169], v[62:65]
	v_mfma_f32_16x16x32_bf16 v[66:69], v[138:141], v[146:149], v[66:69]
	v_mfma_f32_16x16x32_bf16 v[70:73], v[138:141], v[150:153], v[70:73]
	v_mfma_f32_16x16x32_bf16 v[74:77], v[138:141], v[162:165], v[74:77]
	v_mfma_f32_16x16x32_bf16 v[78:81], v[138:141], v[166:169], v[78:81]
	v_mfma_f32_16x16x32_bf16 v[82:85], v[142:145], v[146:149], v[82:85]
	v_mfma_f32_16x16x32_bf16 v[86:89], v[142:145], v[150:153], v[86:89]
	v_mfma_f32_16x16x32_bf16 v[90:93], v[142:145], v[162:165], v[90:93]
	v_mfma_f32_16x16x32_bf16 v[94:97], v[142:145], v[166:169], v[94:97]
	s_setprio 0
	s_add_i32 s19, s19, 1
	s_cmp_lg_u32 s19, 7
	s_waitcnt lgkmcnt(0)
	s_barrier
	s_cbranch_scc1 .Lgk3_loop
	s_waitcnt vmcnt(7)
	ds_write_b128 v122, v[22:25] offset:18432
	s_waitcnt vmcnt(6)
	ds_write_b128 v122, v[6:9] offset:55296
	s_waitcnt vmcnt(5)
	ds_write_b128 v121, v[18:21] offset:18432
	s_waitcnt vmcnt(4)
	ds_write_b128 v121, v[10:13] offset:55296
	s_waitcnt vmcnt(3)
	ds_write_b128 v120, v[14:17] offset:18432
	s_waitcnt vmcnt(2)
	ds_write_b128 v120, v[2:5] offset:55296
	s_waitcnt vmcnt(1)
	ds_write_b128 v124, v[26:29] offset:18432
	s_waitcnt vmcnt(0)
	ds_write_b128 v124, v[30:33] offset:55296
	v_lshl_add_u32 v0, v128, 1, v125
	v_lshl_add_u32 v110, v127, 1, v125
	ds_read_b128 v[2:5], v0
	ds_read_b128 v[6:9], v0 offset:2304
	ds_read_b128 v[10:13], v0 offset:4608
	ds_read_b128 v[14:17], v0 offset:6912
	ds_read_b128 v[18:21], v110 offset:36864
	ds_read_b128 v[22:25], v110 offset:39168
	ds_read_b128 v[26:29], v110 offset:41472
	ds_read_b128 v[30:33], v110 offset:43776
	s_setprio 1
	s_waitcnt lgkmcnt(3)
	v_mfma_f32_16x16x32_bf16 v[34:37], v[2:5], v[18:21], v[34:37]
	s_waitcnt lgkmcnt(2)
	v_mfma_f32_16x16x32_bf16 v[38:41], v[2:5], v[22:25], v[38:41]
	s_waitcnt lgkmcnt(1)
	v_mfma_f32_16x16x32_bf16 v[42:45], v[2:5], v[26:29], v[42:45]
	s_waitcnt lgkmcnt(0)
; DEV f32x4 mfma16(bf16x8 a, bf16x8 b, f32x4 c) { return __builtin_amdgcn_mfma_f32_16x16x32_bf16(a, b, c, 0, 0, 0); }
; template <int EPI, bool AF32>
; DEV void gemm_tile(const void* Ap, int lda, const u16* Bt, int ldb, int K, int m0, int n0, const Epi& ea, char* smem) {
;     ...
;   for (int kt = 0; kt < nk; kt++) {
;     const int buf = kt & 1;
;     if (kt + 1 < nk) swrite(buf ^ 1);
;     if (kt + 2 < nk) gload(kt + 2);
; #pragma unroll
;     for (int ks = 0; ks < 2; ks++) {
;       bf16x8 a[4], b[4];
; #pragma unroll
;       for (int m = 0; m < 4; m++) a[m] = *(const bf16x8*)(sA + buf * 9216 + (wr * 64 + m * 16 + fr) * 72 + ks * 32 + fq * 8);
; #pragma unroll
;       for (int n = 0; n < 4; n++) b[n] = *(const bf16x8*)(sB + buf * 9216 + (wc * 64 + n * 16 + fr) * 72 + ks * 32 + fq * 8);
;       __builtin_amdgcn_s_setprio(1);
; #pragma unroll
;       for (int m = 0; m < 4; m++)
; #pragma unroll
;         for (int n = 0; n < 4; n++) acc[m][n] = mfma16(a[m], b[n], acc[m][n]);
;       __builtin_amdgcn_s_setprio(0);
;     }
;     __syncthreads();
;   }
	v_mfma_f32_16x16x32_bf16 v[2:5], v[2:5], v[30:33], v[46:49]
	v_mfma_f32_16x16x32_bf16 v[46:49], v[6:9], v[18:21], v[50:53]
	v_mfma_f32_16x16x32_bf16 v[50:53], v[6:9], v[22:25], v[54:57]
	v_mfma_f32_16x16x32_bf16 v[54:57], v[6:9], v[26:29], v[58:61]
	v_mfma_f32_16x16x32_bf16 v[6:9], v[6:9], v[30:33], v[62:65]
	v_mfma_f32_16x16x32_bf16 v[58:61], v[10:13], v[18:21], v[66:69]
	v_mfma_f32_16x16x32_bf16 v[62:65], v[10:13], v[22:25], v[70:73]
	v_mfma_f32_16x16x32_bf16 v[66:69], v[10:13], v[26:29], v[74:77]
	v_mfma_f32_16x16x32_bf16 v[10:13], v[10:13], v[30:33], v[78:81]
	v_mfma_f32_16x16x32_bf16 v[18:21], v[14:17], v[18:21], v[82:85]
	v_mfma_f32_16x16x32_bf16 v[22:25], v[14:17], v[22:25], v[86:89]
	v_mfma_f32_16x16x32_bf16 v[26:29], v[14:17], v[26:29], v[90:93]
	v_mfma_f32_16x16x32_bf16 v[14:17], v[14:17], v[30:33], v[94:97]
	s_setprio 0
	ds_read_b128 v[30:33], v0 offset:64
	ds_read_b128 v[70:73], v0 offset:2368
	ds_read_b128 v[74:77], v0 offset:4672
	ds_read_b128 v[78:81], v0 offset:6976
	ds_read_b128 v[82:85], v110 offset:36928
	ds_read_b128 v[86:89], v110 offset:39232
	ds_read_b128 v[90:93], v110 offset:41536
	ds_read_b128 v[94:97], v110 offset:43840
	s_setprio 1
	s_waitcnt lgkmcnt(3)
	v_mfma_f32_16x16x32_bf16 v[34:37], v[30:33], v[82:85], v[34:37]
	s_waitcnt lgkmcnt(2)
	v_mfma_f32_16x16x32_bf16 v[38:41], v[30:33], v[86:89], v[38:41]
	s_waitcnt lgkmcnt(1)
	v_mfma_f32_16x16x32_bf16 v[42:45], v[30:33], v[90:93], v[42:45]
	s_waitcnt lgkmcnt(0)
	v_mfma_f32_16x16x32_bf16 v[2:5], v[30:33], v[94:97], v[2:5]
	v_mfma_f32_16x16x32_bf16 v[30:33], v[70:73], v[82:85], v[46:49]
	v_mfma_f32_16x16x32_bf16 v[46:49], v[70:73], v[86:89], v[50:53]
	v_mfma_f32_16x16x32_bf16 v[50:53], v[70:73], v[90:93], v[54:57]
	v_mfma_f32_16x16x32_bf16 v[6:9], v[70:73], v[94:97], v[6:9]
	v_mfma_f32_16x16x32_bf16 v[54:57], v[74:77], v[82:85], v[58:61]
	v_mfma_f32_16x16x32_bf16 v[58:61], v[74:77], v[86:89], v[62:65]
	v_mfma_f32_16x16x32_bf16 v[62:65], v[74:77], v[90:93], v[66:69]
	v_mfma_f32_16x16x32_bf16 v[10:13], v[74:77], v[94:97], v[10:13]
	v_mfma_f32_16x16x32_bf16 v[18:21], v[78:81], v[82:85], v[18:21]
	v_mfma_f32_16x16x32_bf16 v[22:25], v[78:81], v[86:89], v[22:25]
	v_mfma_f32_16x16x32_bf16 v[26:29], v[78:81], v[90:93], v[26:29]
	v_mfma_f32_16x16x32_bf16 v[14:17], v[78:81], v[94:97], v[14:17]
	s_setprio 0
	s_barrier
	ds_read_b128 v[66:69], v0 offset:18432
	ds_read_b128 v[70:73], v0 offset:20736
	ds_read_b128 v[74:77], v0 offset:23040
	ds_read_b128 v[78:81], v0 offset:25344
	ds_read_b128 v[82:85], v110 offset:55296
	ds_read_b128 v[86:89], v110 offset:57600
	ds_read_b128 v[90:93], v110 offset:59904
	ds_read_b128 v[94:97], v110 offset:62208
	v_and_b32_e32 v114, 64, v114
	s_setprio 1
	s_waitcnt lgkmcnt(3)
	v_mfma_f32_16x16x32_bf16 v[34:37], v[66:69], v[82:85], v[34:37]
	s_waitcnt lgkmcnt(2)
	v_mfma_f32_16x16x32_bf16 v[38:41], v[66:69], v[86:89], v[38:41]
	s_waitcnt lgkmcnt(1)
	v_mfma_f32_16x16x32_bf16 v[42:45], v[66:69], v[90:93], v[42:45]
	s_waitcnt lgkmcnt(0)
	v_mfma_f32_16x16x32_bf16 v[2:5], v[66:69], v[94:97], v[2:5]
	v_mfma_f32_16x16x32_bf16 v[30:33], v[70:73], v[82:85], v[30:33]
	v_mfma_f32_16x16x32_bf16 v[66:69], v[70:73], v[86:89], v[46:49]
	v_mfma_f32_16x16x32_bf16 v[98:101], v[70:73], v[90:93], v[50:53]
	v_mfma_f32_16x16x32_bf16 v[6:9], v[70:73], v[94:97], v[6:9]
	v_mfma_f32_16x16x32_bf16 v[54:57], v[74:77], v[82:85], v[54:57]
	v_mfma_f32_16x16x32_bf16 v[58:61], v[74:77], v[86:89], v[58:61]
	v_mfma_f32_16x16x32_bf16 v[62:65], v[74:77], v[90:93], v[62:65]
	v_mfma_f32_16x16x32_bf16 v[10:13], v[74:77], v[94:97], v[10:13]
	v_mfma_f32_16x16x32_bf16 v[70:73], v[78:81], v[82:85], v[18:21]
	v_mfma_f32_16x16x32_bf16 v[74:77], v[78:81], v[86:89], v[22:25]
	v_mfma_f32_16x16x32_bf16 v[82:85], v[78:81], v[90:93], v[26:29]
	v_mfma_f32_16x16x32_bf16 v[78:81], v[78:81], v[94:97], v[14:17]
	s_setprio 0
	s_nop 1
	ds_read_b128 v[14:17], v0 offset:18496
	ds_read_b128 v[18:21], v0 offset:20800
	ds_read_b128 v[86:89], v0 offset:23104
	ds_read_b128 v[90:93], v0 offset:25408
	ds_read_b128 v[94:97], v110 offset:55360
	ds_read_b128 v[102:105], v110 offset:57664
	ds_read_b128 v[106:109], v110 offset:59968
	ds_read_b128 v[110:113], v110 offset:62272
	s_setprio 1
	s_waitcnt lgkmcnt(3)
	v_mfma_f32_16x16x32_bf16 v[118:121], v[14:17], v[94:97], v[34:37]
	s_waitcnt lgkmcnt(2)
	v_mfma_f32_16x16x32_bf16 v[122:125], v[14:17], v[102:105], v[38:41]
	s_waitcnt lgkmcnt(1)
	v_mfma_f32_16x16x32_bf16 v[126:129], v[14:17], v[106:109], v[42:45]
	s_waitcnt lgkmcnt(0)
; template <int EPI, bool AF32>
; DEV void gemm_tile(const void* Ap, int lda, const u16* Bt, int ldb, int K, int m0, int n0, const Epi& ea, char* smem) {
;     ...
;   if (EPI == EP_RES || EPI == EP_MERGE1 || EPI == EP_MERGE2) {
;     const int rbase = m0 + wr * 64 + fq * 4, cbase = cb + fr;
;     if (EPI == EP_RES) {
;       float* C = (float*)ea.p0;
;       const float* R = (const float*)ea.p1;
;       float rv[4][4][4];
; #pragma unroll
;       for (int m = 0; m < 4; m++)
; #pragma unroll
;         for (int j = 0; j < 4; j++)
; #pragma unroll
;           for (int n = 0; n < 4; n++) rv[m][j][n] = R[(size_t)(rbase + m * 16 + j) * 1024 + cbase + n * 16];
;       __builtin_amdgcn_sched_barrier(0);
; #pragma unroll
;       for (int m = 0; m < 4; m++)
; #pragma unroll
;         for (int j = 0; j < 4; j++)
; #pragma unroll
;           for (int n = 0; n < 4; n++)
;             C[(size_t)(rbase + m * 16 + j) * 1024 + cbase + n * 16] = ALPHA_ * rv[m][j][n] + acc[m][n][j];
;     } else {
;       u16* C = (u16*)ea.p0;
;       const u16* G = (const u16*)ea.p1 + (EPI == EP_MERGE2 ? 1024 : 0);
;       u16 gv[4][4][4], cv[4][4][4];
; #pragma unroll
;       for (int m = 0; m < 4; m++)
; #pragma unroll
;         for (int j = 0; j < 4; j++)
; #pragma unroll
;           for (int n = 0; n < 4; n++) {
;             gv[m][j][n] = G[(size_t)(rbase + m * 16 + j) * 2048 + cbase + n * 16];
;             if (EPI == EP_MERGE2) cv[m][j][n] = C[(size_t)(rbase + m * 16 + j) * 1024 + cbase + n * 16];
;           }
	v_mfma_f32_16x16x32_bf16 v[50:53], v[14:17], v[110:113], v[2:5]
	v_mfma_f32_16x16x32_bf16 v[46:49], v[18:21], v[94:97], v[30:33]
	v_mfma_f32_16x16x32_bf16 v[42:45], v[18:21], v[102:105], v[66:69]
	v_mfma_f32_16x16x32_bf16 v[38:41], v[18:21], v[106:109], v[98:101]
	v_mfma_f32_16x16x32_bf16 v[34:37], v[18:21], v[110:113], v[6:9]
	v_mfma_f32_16x16x32_bf16 v[30:33], v[86:89], v[94:97], v[54:57]
	v_mfma_f32_16x16x32_bf16 v[26:29], v[86:89], v[102:105], v[58:61]
	v_mfma_f32_16x16x32_bf16 v[22:25], v[86:89], v[106:109], v[62:65]
	v_mfma_f32_16x16x32_bf16 v[18:21], v[86:89], v[110:113], v[10:13]
	v_mfma_f32_16x16x32_bf16 v[14:17], v[90:93], v[94:97], v[70:73]
	v_mfma_f32_16x16x32_bf16 v[10:13], v[90:93], v[102:105], v[74:77]
	v_mfma_f32_16x16x32_bf16 v[6:9], v[90:93], v[106:109], v[82:85]
	v_mfma_f32_16x16x32_bf16 v[2:5], v[90:93], v[110:113], v[78:81]
	s_setprio 0
	v_add_u32_e32 v0, s18, v117
	v_or3_b32 v54, v114, s17, v115
	v_lshl_or_b32 v72, v116, 2, v0
	v_ashrrev_i32_e32 v55, 31, v54
	v_lshlrev_b64 v[66:67], 1, v[54:55]
	v_ashrrev_i32_e32 v73, 31, v72
	v_or_b32_e32 v78, 1, v72
	v_lshl_add_u64 v[74:75], s[4:5], 0, v[66:67]
	v_lshlrev_b64 v[54:55], 12, v[72:73]
	v_ashrrev_i32_e32 v79, 31, v78
	v_or_b32_e32 v82, 2, v72
	v_lshl_add_u64 v[76:77], v[74:75], 0, v[54:55]
	v_lshlrev_b64 v[54:55], 12, v[78:79]
	v_ashrrev_i32_e32 v83, 31, v82
	v_or_b32_e32 v86, 3, v72
	v_lshl_add_u64 v[80:81], v[74:75], 0, v[54:55]
	v_lshlrev_b64 v[54:55], 12, v[82:83]
	v_ashrrev_i32_e32 v87, 31, v86
	v_or_b32_e32 v90, 16, v72
	v_lshl_add_u64 v[84:85], v[74:75], 0, v[54:55]
	v_lshlrev_b64 v[54:55], 12, v[86:87]
	v_ashrrev_i32_e32 v91, 31, v90
	v_or_b32_e32 v94, 17, v72
	v_lshl_add_u64 v[88:89], v[74:75], 0, v[54:55]
	v_lshlrev_b64 v[54:55], 12, v[90:91]
	v_ashrrev_i32_e32 v95, 31, v94
	v_or_b32_e32 v98, 18, v72
	v_lshl_add_u64 v[92:93], v[74:75], 0, v[54:55]
	v_lshlrev_b64 v[54:55], 12, v[94:95]
	v_ashrrev_i32_e32 v99, 31, v98
	v_or_b32_e32 v102, 19, v72
	v_lshl_add_u64 v[96:97], v[74:75], 0, v[54:55]
	v_lshlrev_b64 v[54:55], 12, v[98:99]
	v_ashrrev_i32_e32 v103, 31, v102
	v_or_b32_e32 v70, 32, v72
	v_lshl_add_u64 v[100:101], v[74:75], 0, v[54:55]
	v_lshlrev_b64 v[54:55], 12, v[102:103]
	v_ashrrev_i32_e32 v71, 31, v70
	v_or_b32_e32 v68, 33, v72
	v_lshl_add_u64 v[104:105], v[74:75], 0, v[54:55]
	v_lshlrev_b64 v[54:55], 12, v[70:71]
	v_ashrrev_i32_e32 v69, 31, v68
	v_or_b32_e32 v64, 34, v72
	v_lshl_add_u64 v[106:107], v[74:75], 0, v[54:55]
	v_lshlrev_b64 v[54:55], 12, v[68:69]
	v_ashrrev_i32_e32 v65, 31, v64
	v_or_b32_e32 v62, 35, v72
	v_lshl_add_u64 v[108:109], v[74:75], 0, v[54:55]
	v_lshlrev_b64 v[54:55], 12, v[64:65]
	v_ashrrev_i32_e32 v63, 31, v62
	v_or_b32_e32 v60, 48, v72
	v_lshl_add_u64 v[110:111], v[74:75], 0, v[54:55]
	v_lshlrev_b64 v[54:55], 12, v[62:63]
	v_ashrrev_i32_e32 v61, 31, v60
	v_or_b32_e32 v58, 49, v72
	v_lshl_add_u64 v[112:113], v[74:75], 0, v[54:55]
	v_lshlrev_b64 v[54:55], 12, v[60:61]
	v_ashrrev_i32_e32 v59, 31, v58
	v_or_b32_e32 v56, 50, v72
	v_lshl_add_u64 v[114:115], v[74:75], 0, v[54:55]
	v_lshlrev_b64 v[54:55], 12, v[58:59]
	v_ashrrev_i32_e32 v57, 31, v56
	v_lshl_add_u64 v[116:117], v[74:75], 0, v[54:55]
	v_lshlrev_b64 v[54:55], 12, v[56:57]
	v_lshl_add_u64 v[130:131], v[74:75], 0, v[54:55]
	v_or_b32_e32 v54, 51, v72
	v_ashrrev_i32_e32 v55, 31, v54
	v_lshlrev_b64 v[132:133], 12, v[54:55]
	v_lshl_add_u64 v[74:75], v[74:75], 0, v[132:133]
	s_barrier
	global_load_ushort v0, v[76:77], off
	global_load_ushort v132, v[76:77], off offset:32
	global_load_ushort v133, v[76:77], off offset:64
	s_nop 0
	global_load_ushort v76, v[76:77], off offset:96
	s_nop 0
	global_load_ushort v77, v[80:81], off
	global_load_ushort v134, v[80:81], off offset:32
	global_load_ushort v135, v[80:81], off offset:64
	s_nop 0
	global_load_ushort v80, v[80:81], off offset:96
	s_nop 0
	global_load_ushort v81, v[84:85], off
	global_load_ushort v136, v[84:85], off offset:32
	global_load_ushort v137, v[84:85], off offset:64
	s_nop 0
	global_load_ushort v84, v[84:85], off offset:96
	s_nop 0
	global_load_ushort v85, v[88:89], off
	global_load_ushort v138, v[88:89], off offset:32
	global_load_ushort v139, v[88:89], off offset:64
	s_nop 0
	global_load_ushort v88, v[88:89], off offset:96
	s_nop 0
	global_load_ushort v89, v[92:93], off
	global_load_ushort v140, v[92:93], off offset:32
	global_load_ushort v141, v[92:93], off offset:64
	s_nop 0
	global_load_ushort v92, v[92:93], off offset:96
	s_nop 0
	global_load_ushort v93, v[96:97], off
	global_load_ushort v142, v[96:97], off offset:32
	global_load_ushort v143, v[96:97], off offset:64
	s_nop 0
	global_load_ushort v96, v[96:97], off offset:96
	s_nop 0
	global_load_ushort v97, v[100:101], off
	global_load_ushort v144, v[100:101], off offset:32
	global_load_ushort v145, v[100:101], off offset:64
	s_nop 0
	global_load_ushort v100, v[100:101], off offset:96
	s_nop 0
	global_load_ushort v101, v[104:105], off
	global_load_ushort v146, v[104:105], off offset:32
	global_load_ushort v147, v[104:105], off offset:64
	s_nop 0
	global_load_ushort v104, v[104:105], off offset:96
	s_nop 0
	global_load_ushort v105, v[106:107], off
	global_load_ushort v148, v[106:107], off offset:32
	global_load_ushort v149, v[106:107], off offset:64
	s_nop 0
	global_load_ushort v106, v[106:107], off offset:96
	s_nop 0
	global_load_ushort v107, v[108:109], off
	global_load_ushort v150, v[108:109], off offset:32
	global_load_ushort v151, v[108:109], off offset:64
	s_nop 0
	global_load_ushort v108, v[108:109], off offset:96
	s_nop 0
	global_load_ushort v109, v[110:111], off
	global_load_ushort v152, v[110:111], off offset:32
	global_load_ushort v153, v[110:111], off offset:64
	s_nop 0
	global_load_ushort v110, v[110:111], off offset:96
	s_nop 0
	global_load_ushort v111, v[112:113], off
	global_load_ushort v161, v[112:113], off offset:32
	global_load_ushort v162, v[112:113], off offset:64
	s_nop 0
	global_load_ushort v112, v[112:113], off offset:96
	s_nop 0
	global_load_ushort v113, v[114:115], off
	global_load_ushort v163, v[114:115], off offset:32
	global_load_ushort v164, v[114:115], off offset:64
	s_nop 0
	global_load_ushort v114, v[114:115], off offset:96
	s_nop 0
	global_load_ushort v115, v[116:117], off
	global_load_ushort v165, v[116:117], off offset:32
	global_load_ushort v166, v[116:117], off offset:64
	s_nop 0
	global_load_ushort v116, v[116:117], off offset:96
	s_nop 0
	global_load_ushort v117, v[130:131], off
	global_load_ushort v167, v[130:131], off offset:32
	global_load_ushort v168, v[130:131], off offset:64
	s_nop 0
	global_load_ushort v130, v[130:131], off offset:96
	s_nop 0
	global_load_ushort v131, v[74:75], off
	global_load_ushort v169, v[74:75], off offset:32
	global_load_ushort v170, v[74:75], off offset:64
	s_nop 0
	global_load_ushort v74, v[74:75], off offset:96
	s_waitcnt vmcnt(62)
; DEV float bf2f(u16 h) { return __uint_as_float(((unsigned)h) << 16); }
; template <int EPI, bool AF32>
; DEV void gemm_tile(const void* Ap, int lda, const u16* Bt, int ldb, int K, int m0, int n0, const Epi& ea, char* smem) {
;     ...
; #pragma unroll
;       for (int m = 0; m < 4; m++)
; #pragma unroll
;         for (int j = 0; j < 4; j++)
; #pragma unroll
;           for (int n = 0; n < 4; n++) {
;             float v = bf2f(gv[m][j][n]) * acc[m][n][j];
;             if (EPI == EP_MERGE2) v += bf2f(cv[m][j][n]);
;             C[(size_t)(rbase + m * 16 + j) * 1024 + cbase + n * 16] = f2bf(v);
;           }
	v_lshlrev_b32_e32 v0, 16, v0
	v_lshl_add_u64 v[66:67], s[2:3], 0, v[66:67]
	v_lshlrev_b64 v[72:73], 11, v[72:73]
	v_mul_f32_e32 v0, v118, v0
	v_lshl_add_u64 v[72:73], v[66:67], 0, v[72:73]
	v_cvt_pk_bf16_f32 v0, v0, s0
	global_store_short v[72:73], v0, off
	v_lshlrev_b32_e32 v0, 16, v132
	v_mul_f32_e32 v0, v122, v0
	v_cvt_pk_bf16_f32 v0, v0, s0
	global_store_short v[72:73], v0, off offset:32
	s_waitcnt vmcnt(62)
	v_lshlrev_b32_e32 v0, 16, v133
	v_mul_f32_e32 v0, v126, v0
	v_cvt_pk_bf16_f32 v0, v0, s0
	global_store_short v[72:73], v0, off offset:64
	v_lshlrev_b32_e32 v0, 16, v76
	v_mul_f32_e32 v0, v50, v0
	v_cvt_pk_bf16_f32 v0, v0, s0
	global_store_short v[72:73], v0, off offset:96
	s_waitcnt vmcnt(62)
	v_lshlrev_b32_e32 v0, 16, v77
	v_lshlrev_b64 v[72:73], 11, v[78:79]
	v_mul_f32_e32 v0, v119, v0
	v_lshl_add_u64 v[72:73], v[66:67], 0, v[72:73]
	v_cvt_pk_bf16_f32 v0, v0, s0
	global_store_short v[72:73], v0, off
	v_lshlrev_b32_e32 v0, 16, v134
	v_mul_f32_e32 v0, v123, v0
	v_cvt_pk_bf16_f32 v0, v0, s0
	global_store_short v[72:73], v0, off offset:32
	s_waitcnt vmcnt(62)
	v_lshlrev_b32_e32 v0, 16, v135
	v_mul_f32_e32 v0, v127, v0
	v_cvt_pk_bf16_f32 v0, v0, s0
	global_store_short v[72:73], v0, off offset:64
	v_lshlrev_b32_e32 v0, 16, v80
	v_mul_f32_e32 v0, v51, v0
	v_cvt_pk_bf16_f32 v0, v0, s0
	global_store_short v[72:73], v0, off offset:96
	s_waitcnt vmcnt(62)
	v_lshlrev_b32_e32 v0, 16, v81
	v_lshlrev_b64 v[50:51], 11, v[82:83]
	v_mul_f32_e32 v0, v120, v0
	v_lshl_add_u64 v[50:51], v[66:67], 0, v[50:51]
	v_cvt_pk_bf16_f32 v0, v0, s0
	global_store_short v[50:51], v0, off
	v_lshlrev_b32_e32 v0, 16, v136
	v_mul_f32_e32 v0, v124, v0
	v_cvt_pk_bf16_f32 v0, v0, s0
	global_store_short v[50:51], v0, off offset:32
	s_waitcnt vmcnt(62)
	v_lshlrev_b32_e32 v0, 16, v137
	v_mul_f32_e32 v0, v128, v0
	v_cvt_pk_bf16_f32 v0, v0, s0
	global_store_short v[50:51], v0, off offset:64
	v_lshlrev_b32_e32 v0, 16, v84
	v_mul_f32_e32 v0, v52, v0
	v_cvt_pk_bf16_f32 v0, v0, s0
	global_store_short v[50:51], v0, off offset:96
	s_waitcnt vmcnt(62)
	v_lshlrev_b32_e32 v0, 16, v85
	v_lshlrev_b64 v[50:51], 11, v[86:87]
	v_mul_f32_e32 v0, v121, v0
	v_lshl_add_u64 v[50:51], v[66:67], 0, v[50:51]
	v_cvt_pk_bf16_f32 v0, v0, s0
	global_store_short v[50:51], v0, off
	v_lshlrev_b32_e32 v0, 16, v138
	v_mul_f32_e32 v0, v125, v0
	v_cvt_pk_bf16_f32 v0, v0, s0
	global_store_short v[50:51], v0, off offset:32
	s_waitcnt vmcnt(62)
	v_lshlrev_b32_e32 v0, 16, v139
	v_mul_f32_e32 v0, v129, v0
	v_cvt_pk_bf16_f32 v0, v0, s0
	global_store_short v[50:51], v0, off offset:64
	v_lshlrev_b32_e32 v0, 16, v88
	v_mul_f32_e32 v0, v53, v0
	v_cvt_pk_bf16_f32 v0, v0, s0
	global_store_short v[50:51], v0, off offset:96
	s_waitcnt vmcnt(62)
	v_lshlrev_b32_e32 v0, 16, v89
	v_lshlrev_b64 v[50:51], 11, v[90:91]
	v_mul_f32_e32 v0, v46, v0
	v_lshl_add_u64 v[50:51], v[66:67], 0, v[50:51]
	v_cvt_pk_bf16_f32 v0, v0, s0
	global_store_short v[50:51], v0, off
	v_lshlrev_b32_e32 v0, 16, v140
	v_mul_f32_e32 v0, v42, v0
	v_cvt_pk_bf16_f32 v0, v0, s0
	global_store_short v[50:51], v0, off offset:32
	s_waitcnt vmcnt(62)
	v_lshlrev_b32_e32 v0, 16, v141
	v_mul_f32_e32 v0, v38, v0
	v_cvt_pk_bf16_f32 v0, v0, s0
	global_store_short v[50:51], v0, off offset:64
	v_lshlrev_b32_e32 v0, 16, v92
	v_mul_f32_e32 v0, v34, v0
	v_cvt_pk_bf16_f32 v0, v0, s0
	global_store_short v[50:51], v0, off offset:96
	s_waitcnt vmcnt(62)
	v_lshlrev_b32_e32 v0, 16, v93
	v_lshlrev_b64 v[50:51], 11, v[94:95]
	v_mul_f32_e32 v0, v47, v0
	v_lshl_add_u64 v[50:51], v[66:67], 0, v[50:51]
	v_cvt_pk_bf16_f32 v0, v0, s0
	global_store_short v[50:51], v0, off
	v_lshlrev_b32_e32 v0, 16, v142
	v_mul_f32_e32 v0, v43, v0
	v_cvt_pk_bf16_f32 v0, v0, s0
	global_store_short v[50:51], v0, off offset:32
	s_waitcnt vmcnt(62)
	v_lshlrev_b32_e32 v0, 16, v143
	v_mul_f32_e32 v0, v39, v0
	v_cvt_pk_bf16_f32 v0, v0, s0
	global_store_short v[50:51], v0, off offset:64
	v_lshlrev_b32_e32 v0, 16, v96
	v_mul_f32_e32 v0, v35, v0
	v_cvt_pk_bf16_f32 v0, v0, s0
	global_store_short v[50:51], v0, off offset:96
	s_waitcnt vmcnt(62)
	v_lshlrev_b32_e32 v0, 16, v97
	v_lshlrev_b64 v[34:35], 11, v[98:99]
	v_mul_f32_e32 v0, v48, v0
	v_lshl_add_u64 v[34:35], v[66:67], 0, v[34:35]
	v_cvt_pk_bf16_f32 v0, v0, s0
	global_store_short v[34:35], v0, off
	v_lshlrev_b32_e32 v0, 16, v144
	v_mul_f32_e32 v0, v44, v0
	v_cvt_pk_bf16_f32 v0, v0, s0
	global_store_short v[34:35], v0, off offset:32
	s_waitcnt vmcnt(62)
	v_lshlrev_b32_e32 v0, 16, v145
	v_mul_f32_e32 v0, v40, v0
	v_cvt_pk_bf16_f32 v0, v0, s0
	global_store_short v[34:35], v0, off offset:64
	v_lshlrev_b32_e32 v0, 16, v100
	v_mul_f32_e32 v0, v36, v0
	v_cvt_pk_bf16_f32 v0, v0, s0
	global_store_short v[34:35], v0, off offset:96
	s_waitcnt vmcnt(62)
	v_lshlrev_b32_e32 v0, 16, v101
	v_lshlrev_b64 v[34:35], 11, v[102:103]
	v_mul_f32_e32 v0, v49, v0
	v_lshl_add_u64 v[34:35], v[66:67], 0, v[34:35]
	v_cvt_pk_bf16_f32 v0, v0, s0
	global_store_short v[34:35], v0, off
	v_lshlrev_b32_e32 v0, 16, v146
	v_mul_f32_e32 v0, v45, v0
	v_cvt_pk_bf16_f32 v0, v0, s0
	global_store_short v[34:35], v0, off offset:32
	s_waitcnt vmcnt(62)
	v_lshlrev_b32_e32 v0, 16, v147
	v_mul_f32_e32 v0, v41, v0
	v_cvt_pk_bf16_f32 v0, v0, s0
	global_store_short v[34:35], v0, off offset:64
	v_lshlrev_b32_e32 v0, 16, v104
	v_mul_f32_e32 v0, v37, v0
	v_cvt_pk_bf16_f32 v0, v0, s0
	global_store_short v[34:35], v0, off offset:96
	s_waitcnt vmcnt(62)
; DEV float bf2f(u16 h) { return __uint_as_float(((unsigned)h) << 16); }
; template <int EPI, bool AF32>
; DEV void gemm_tile(const void* Ap, int lda, const u16* Bt, int ldb, int K, int m0, int n0, const Epi& ea, char* smem) {
;     ...
; #pragma unroll
;       for (int m = 0; m < 4; m++)
; #pragma unroll
;         for (int j = 0; j < 4; j++)
; #pragma unroll
;           for (int n = 0; n < 4; n++) {
;             float v = bf2f(gv[m][j][n]) * acc[m][n][j];
;             if (EPI == EP_MERGE2) v += bf2f(cv[m][j][n]);
;             C[(size_t)(rbase + m * 16 + j) * 1024 + cbase + n * 16] = f2bf(v);
;           }
	v_lshlrev_b32_e32 v0, 16, v105
	v_lshlrev_b64 v[34:35], 11, v[70:71]
	v_mul_f32_e32 v0, v30, v0
	v_lshl_add_u64 v[34:35], v[66:67], 0, v[34:35]
	v_cvt_pk_bf16_f32 v0, v0, s0
	global_store_short v[34:35], v0, off
	v_lshlrev_b32_e32 v0, 16, v148
	v_mul_f32_e32 v0, v26, v0
	v_cvt_pk_bf16_f32 v0, v0, s0
	global_store_short v[34:35], v0, off offset:32
	s_waitcnt vmcnt(62)
	v_lshlrev_b32_e32 v0, 16, v149
	v_mul_f32_e32 v0, v22, v0
	v_cvt_pk_bf16_f32 v0, v0, s0
	global_store_short v[34:35], v0, off offset:64
	v_lshlrev_b32_e32 v0, 16, v106
	v_mul_f32_e32 v0, v18, v0
	v_cvt_pk_bf16_f32 v0, v0, s0
	global_store_short v[34:35], v0, off offset:96
	s_waitcnt vmcnt(62)
	v_lshlrev_b32_e32 v0, 16, v107
	v_lshlrev_b64 v[34:35], 11, v[68:69]
	v_mul_f32_e32 v0, v31, v0
	v_lshl_add_u64 v[34:35], v[66:67], 0, v[34:35]
	v_cvt_pk_bf16_f32 v0, v0, s0
	global_store_short v[34:35], v0, off
	v_lshlrev_b32_e32 v0, 16, v150
	v_mul_f32_e32 v0, v27, v0
	v_cvt_pk_bf16_f32 v0, v0, s0
	global_store_short v[34:35], v0, off offset:32
	s_waitcnt vmcnt(62)
	v_lshlrev_b32_e32 v0, 16, v151
	v_mul_f32_e32 v0, v23, v0
	v_cvt_pk_bf16_f32 v0, v0, s0
	global_store_short v[34:35], v0, off offset:64
	v_lshlrev_b32_e32 v0, 16, v108
	v_mul_f32_e32 v0, v19, v0
	v_cvt_pk_bf16_f32 v0, v0, s0
	global_store_short v[34:35], v0, off offset:96
	s_waitcnt vmcnt(62)
	v_lshlrev_b32_e32 v0, 16, v109
	v_lshlrev_b64 v[18:19], 11, v[64:65]
	v_mul_f32_e32 v0, v32, v0
	v_lshl_add_u64 v[18:19], v[66:67], 0, v[18:19]
	v_cvt_pk_bf16_f32 v0, v0, s0
	global_store_short v[18:19], v0, off
	v_lshlrev_b32_e32 v0, 16, v152
	v_mul_f32_e32 v0, v28, v0
	v_cvt_pk_bf16_f32 v0, v0, s0
	global_store_short v[18:19], v0, off offset:32
	s_waitcnt vmcnt(62)
	v_lshlrev_b32_e32 v0, 16, v153
	v_mul_f32_e32 v0, v24, v0
	v_cvt_pk_bf16_f32 v0, v0, s0
	global_store_short v[18:19], v0, off offset:64
	v_lshlrev_b32_e32 v0, 16, v110
	v_mul_f32_e32 v0, v20, v0
	v_cvt_pk_bf16_f32 v0, v0, s0
	global_store_short v[18:19], v0, off offset:96
	s_waitcnt vmcnt(62)
	v_lshlrev_b32_e32 v0, 16, v111
	v_lshlrev_b64 v[18:19], 11, v[62:63]
	v_mul_f32_e32 v0, v33, v0
	v_lshl_add_u64 v[18:19], v[66:67], 0, v[18:19]
	v_cvt_pk_bf16_f32 v0, v0, s0
	global_store_short v[18:19], v0, off
	v_lshlrev_b32_e32 v0, 16, v161
	v_mul_f32_e32 v0, v29, v0
	v_cvt_pk_bf16_f32 v0, v0, s0
	global_store_short v[18:19], v0, off offset:32
	s_waitcnt vmcnt(62)
	v_lshlrev_b32_e32 v0, 16, v162
	v_mul_f32_e32 v0, v25, v0
	v_cvt_pk_bf16_f32 v0, v0, s0
	global_store_short v[18:19], v0, off offset:64
	v_lshlrev_b32_e32 v0, 16, v112
	v_mul_f32_e32 v0, v21, v0
	v_cvt_pk_bf16_f32 v0, v0, s0
	global_store_short v[18:19], v0, off offset:96
	s_waitcnt vmcnt(62)
	v_lshlrev_b32_e32 v0, 16, v113
	v_lshlrev_b64 v[18:19], 11, v[60:61]
	v_mul_f32_e32 v0, v14, v0
	v_lshl_add_u64 v[18:19], v[66:67], 0, v[18:19]
	v_cvt_pk_bf16_f32 v0, v0, s0
	global_store_short v[18:19], v0, off
	v_lshlrev_b32_e32 v0, 16, v163
	v_mul_f32_e32 v0, v10, v0
	v_cvt_pk_bf16_f32 v0, v0, s0
	global_store_short v[18:19], v0, off offset:32
	s_waitcnt vmcnt(62)
	v_lshlrev_b32_e32 v0, 16, v164
	v_mul_f32_e32 v0, v6, v0
	v_cvt_pk_bf16_f32 v0, v0, s0
	global_store_short v[18:19], v0, off offset:64
	v_lshlrev_b32_e32 v0, 16, v114
	v_mul_f32_e32 v0, v2, v0
	v_cvt_pk_bf16_f32 v0, v0, s0
	global_store_short v[18:19], v0, off offset:96
	s_waitcnt vmcnt(62)
	v_lshlrev_b32_e32 v0, 16, v115
	v_lshlrev_b64 v[18:19], 11, v[58:59]
	v_mul_f32_e32 v0, v15, v0
	v_lshl_add_u64 v[18:19], v[66:67], 0, v[18:19]
	v_cvt_pk_bf16_f32 v0, v0, s0
	global_store_short v[18:19], v0, off
	v_lshlrev_b32_e32 v0, 16, v165
	v_mul_f32_e32 v0, v11, v0
	v_cvt_pk_bf16_f32 v0, v0, s0
	global_store_short v[18:19], v0, off offset:32
	s_waitcnt vmcnt(62)
	v_lshlrev_b32_e32 v0, 16, v166
	v_mul_f32_e32 v0, v7, v0
	v_cvt_pk_bf16_f32 v0, v0, s0
	global_store_short v[18:19], v0, off offset:64
	v_lshlrev_b32_e32 v0, 16, v116
	v_mul_f32_e32 v0, v3, v0
	v_cvt_pk_bf16_f32 v0, v0, s0
	global_store_short v[18:19], v0, off offset:96
	s_waitcnt vmcnt(62)
	v_lshlrev_b32_e32 v0, 16, v117
	v_lshlrev_b64 v[2:3], 11, v[56:57]
	v_mul_f32_e32 v0, v16, v0
	v_lshl_add_u64 v[2:3], v[66:67], 0, v[2:3]
	v_cvt_pk_bf16_f32 v0, v0, s0
	global_store_short v[2:3], v0, off
	v_lshlrev_b32_e32 v0, 16, v167
	v_mul_f32_e32 v0, v12, v0
	v_cvt_pk_bf16_f32 v0, v0, s0
	global_store_short v[2:3], v0, off offset:32
	s_waitcnt vmcnt(62)
	v_lshlrev_b32_e32 v0, 16, v168
	v_mul_f32_e32 v0, v8, v0
	v_cvt_pk_bf16_f32 v0, v0, s0
	global_store_short v[2:3], v0, off offset:64
	v_lshlrev_b32_e32 v0, 16, v130
	v_mul_f32_e32 v0, v4, v0
	v_cvt_pk_bf16_f32 v0, v0, s0
	global_store_short v[2:3], v0, off offset:96
	s_waitcnt vmcnt(62)
	v_lshlrev_b32_e32 v0, 16, v131
	v_lshlrev_b64 v[2:3], 11, v[54:55]
	v_mul_f32_e32 v0, v17, v0
	v_lshl_add_u64 v[2:3], v[66:67], 0, v[2:3]
	v_cvt_pk_bf16_f32 v0, v0, s0
	global_store_short v[2:3], v0, off
	v_lshlrev_b32_e32 v0, 16, v169
	v_mul_f32_e32 v0, v13, v0
	v_cvt_pk_bf16_f32 v0, v0, s0
	global_store_short v[2:3], v0, off offset:32
	s_waitcnt vmcnt(62)
	v_lshlrev_b32_e32 v0, 16, v170
	v_mul_f32_e32 v0, v9, v0
	v_cvt_pk_bf16_f32 v0, v0, s0
	global_store_short v[2:3], v0, off offset:64
	v_lshlrev_b32_e32 v0, 16, v74
	v_mul_f32_e32 v0, v5, v0
	v_cvt_pk_bf16_f32 v0, v0, s0
	v_readfirstlane_b32 s0, v198
	global_store_short v[2:3], v0, off offset:96
	s_add_i32 s16, s0, s16
	s_cmpk_lt_i32 s16, 0x820
	s_cbranch_scc1 .LBB0_1304

; template <int EPI, bool AF32>
; DEV void gemm_tile(const void* Ap, int lda, const u16* Bt, int ldb, int K, int m0, int n0, const Epi& ea, char* smem) {
;     ...
;   auto gload = [&](int kt) {
;     const int k0 = kt << 6;
; #pragma unroll
;     for (int i = 0; i < 4; i++) {
;       const int c = tid + i * 256, row = c >> 3, kc = c & 7;
;       if (AF32) {
;         const float* pa = (const float*)Ap + (size_t)(m0 + row) * lda + k0 + kc * 8;
;         rfa[2 * i] = *(const f32x4*)pa;
;         rfa[2 * i + 1] = *(const f32x4*)(pa + 4);
;       } else {
;         ra[i] = *(const u32x4*)((const u16*)Ap + (size_t)(m0 + row) * lda + k0 + kc * 8);
;       }
;       rb[i] = *(const u32x4*)(Bt + (size_t)(n0 + row) * ldb + k0 + kc * 8);
;     }
;   };
;   auto swrite = [&](int buf) {
; #pragma unroll
;     for (int i = 0; i < 4; i++) {
;       const int c = tid + i * 256, row = c >> 3, kc = c & 7;
;       u32x4 va;
;       if (AF32) {
;         va = (u32x4){pack2(rfa[2 * i][0], rfa[2 * i][1]), pack2(rfa[2 * i][2], rfa[2 * i][3]),
;                      pack2(rfa[2 * i + 1][0], rfa[2 * i + 1][1]), pack2(rfa[2 * i + 1][2], rfa[2 * i + 1][3])};
;       } else {
;         va = ra[i];
;       }
;       *(u32x4*)(sA + buf * 9216 + row * 72 + kc * 8) = va;
;       *(u32x4*)(sB + buf * 9216 + row * 72 + kc * 8) = rb[i];
;     }
;   };
;   gload(0);
;   swrite(0);
;   if (nk > 1) gload(1);
;   __syncthreads();
.LBB0_1309:
	s_ashr_i32 s0, s14, 31
	s_lshr_b32 s0, s0, 24
	s_add_i32 s0, s14, s0
	s_ashr_i32 s1, s0, 8
	s_and_b32 s0, s0, 0xffffff00
	s_lshl_b32 s16, s1, 5
	s_sub_i32 s15, s14, s0
	s_sub_i32 s0, 0x104, s16
	s_min_u32 s17, s0, 32
	v_cvt_f32_ubyte0_e32 v2, s17
	v_cvt_f32_i32_e32 v0, s15
	v_rcp_iflag_f32_e32 v3, v2
	s_ashr_i32 s0, s15, 30
	s_or_b32 s18, s0, 1
	s_waitcnt vmcnt(12)
	v_mov_b32_e32 v114, v157
	v_mul_f32_e32 v3, v0, v3
	v_trunc_f32_e32 v3, v3
	v_fma_f32 v0, -v3, v2, v0
	v_cvt_i32_f32_e32 v3, v3
	v_cmp_ge_f32_e64 s[0:1], |v0|, v2
	s_and_b64 s[0:1], s[0:1], exec
	s_cselect_b32 s0, s18, 0
	v_readfirstlane_b32 s1, v3
	s_add_i32 s0, s1, s0
	s_sext_i32_i16 s1, s0
	s_mul_i32 s0, s0, s17
	s_sub_i32 s0, s15, s0
	s_sext_i32_i16 s0, s0
	s_add_i32 s16, s16, s0
	s_lshl_b32 s16, s16, 7
	s_lshl_b32 s15, s1, 7
	v_ashrrev_i32_e32 v8, 3, v114
	v_add_u32_e32 v2, s16, v8
	v_ashrrev_i32_e32 v3, 31, v2
	v_lshlrev_b32_e32 v0, 3, v114
	v_add_u32_e32 v4, 0x100, v114
	v_lshlrev_b64 v[58:59], 11, v[2:3]
	v_and_b32_e32 v0, 56, v0
	v_ashrrev_i32_e32 v9, 3, v4
	v_lshl_add_u64 v[2:3], s[4:5], 0, v[58:59]
	v_lshlrev_b32_e32 v0, 1, v0
	v_add_u32_e32 v4, s16, v9
	v_add_u32_e32 v6, 0x200, v114
	v_lshl_add_u64 v[14:15], v[2:3], 0, v[0:1]
	v_add_u32_e32 v2, s15, v8
	v_ashrrev_i32_e32 v5, 31, v4
	v_ashrrev_i32_e32 v10, 3, v6
	v_ashrrev_i32_e32 v3, 31, v2
	v_lshlrev_b64 v[62:63], 11, v[4:5]
	v_add_u32_e32 v6, s16, v10
	v_lshlrev_b64 v[60:61], 11, v[2:3]
	v_lshl_add_u64 v[4:5], s[4:5], 0, v[62:63]
	v_ashrrev_i32_e32 v7, 31, v6
	v_lshl_add_u64 v[2:3], s[6:7], 0, v[60:61]
	v_lshl_add_u64 v[16:17], v[4:5], 0, v[0:1]
	v_add_u32_e32 v4, s15, v9
	v_lshlrev_b64 v[66:67], 11, v[6:7]
	v_lshl_add_u64 v[2:3], v[2:3], 0, v[0:1]
	v_ashrrev_i32_e32 v5, 31, v4
	v_lshl_add_u64 v[6:7], s[4:5], 0, v[66:67]
	global_load_dwordx4 v[30:33], v[2:3], off
	v_lshlrev_b64 v[64:65], 11, v[4:5]
	v_lshl_add_u64 v[68:69], v[6:7], 0, v[0:1]
	v_add_u32_e32 v6, s15, v10
	global_load_dwordx4 v[26:29], v[14:15], off
	global_load_dwordx4 v[34:37], v[16:17], off
	v_lshl_add_u64 v[4:5], s[6:7], 0, v[64:65]
	v_ashrrev_i32_e32 v7, 31, v6
	v_lshl_add_u64 v[4:5], v[4:5], 0, v[0:1]
	v_lshlrev_b64 v[70:71], 11, v[6:7]
	global_load_dwordx4 v[38:41], v[4:5], off
	v_lshl_add_u64 v[6:7], s[6:7], 0, v[70:71]
	global_load_dwordx4 v[42:45], v[68:69], off
	v_lshl_add_u64 v[18:19], v[6:7], 0, v[0:1]
	global_load_dwordx4 v[46:49], v[18:19], off
	v_add_u32_e32 v6, 0x300, v114
	v_ashrrev_i32_e32 v80, 3, v6
	v_add_u32_e32 v6, s16, v80
	v_ashrrev_i32_e32 v7, 31, v6
	v_lshlrev_b64 v[72:73], 11, v[6:7]
	v_lshl_add_u64 v[6:7], s[4:5], 0, v[72:73]
	v_lshl_add_u64 v[74:75], v[6:7], 0, v[0:1]
	v_add_u32_e32 v6, s15, v80
	v_ashrrev_i32_e32 v7, 31, v6
	v_lshlrev_b64 v[76:77], 11, v[6:7]
	v_lshl_add_u64 v[6:7], s[6:7], 0, v[76:77]
	v_lshl_add_u64 v[78:79], v[6:7], 0, v[0:1]
	global_load_dwordx4 v[50:53], v[74:75], off
	global_load_dwordx4 v[54:57], v[78:79], off
	s_waitcnt vmcnt(19)
	v_mul_lo_u32 v118, v8, s71
	v_mul_lo_u32 v119, v9, s71
	s_waitcnt vmcnt(18)
	v_mul_lo_u32 v123, v10, s71
	global_load_dwordx4 v[6:9], v[2:3], off offset:128
	global_load_dwordx4 v[10:13], v[4:5], off offset:128
	s_nop 0
	global_load_dwordx4 v[2:5], v[18:19], off offset:128
	global_load_dwordx4 v[22:25], v[14:15], off offset:128
	s_nop 0
	global_load_dwordx4 v[18:21], v[16:17], off offset:128
	s_nop 0
	global_load_dwordx4 v[14:17], v[68:69], off offset:128
	v_bfe_u32 v161, v157, 3, 4
	v_add_u32_e32 v161, 4, v161
	v_lshlrev_b32_e32 v161, 1, v161
	v_and_b32_e32 v161, 16, v161
	v_xor_b32_e32 v129, v0, v161
	v_lshl_add_u32 v122, v118, 1, v129
	v_lshl_add_u32 v121, v119, 1, v129
	v_lshl_add_u32 v120, v123, 1, v129
	v_and_b32_e32 v115, 15, v114
	s_waitcnt vmcnt(23)
	v_mul_lo_u32 v126, v80, s71
	v_bfe_u32 v116, v114, 4, 2
	v_lshl_add_u32 v124, v126, 1, v129
	s_mov_b32 s17, 0
	v_lshlrev_b32_e32 v125, 4, v116
	v_and_b32_e32 v161, 15, v157
	v_add_u32_e32 v161, 4, v161
	v_lshlrev_b32_e32 v161, 1, v161
	v_and_b32_e32 v161, 16, v161
	v_xor_b32_e32 v125, v125, v161
	s_mov_b64 s[0:1], 0
	s_waitcnt vmcnt(13)
	ds_write_b128 v122, v[30:33] offset:36864
	s_waitcnt vmcnt(12)
	ds_write_b128 v122, v[26:29]
	s_waitcnt vmcnt(11)
	ds_write_b128 v121, v[34:37]
	s_waitcnt vmcnt(10)
	ds_write_b128 v121, v[38:41] offset:36864
	s_waitcnt vmcnt(9)
	ds_write_b128 v120, v[42:45]
	s_waitcnt vmcnt(8)
	ds_write_b128 v120, v[46:49] offset:36864
	global_load_dwordx4 v[26:29], v[74:75], off offset:128
	global_load_dwordx4 v[30:33], v[78:79], off offset:128
	v_ashrrev_i32_e32 v34, 1, v114
	v_and_b32_e32 v117, 0xffffffc0, v34
	v_or_b32_e32 v34, v117, v115
	v_mul_lo_u32 v128, v34, s71
	v_lshlrev_b32_e32 v34, 4, v114
	v_and_b32_e32 v34, 0x70, v34
	v_and_b32_e32 v35, 0x4f, v114
	v_or_b32_e32 v76, v76, v34
	v_or_b32_e32 v72, v72, v34
	v_or_b32_e32 v70, v70, v34
	v_or_b32_e32 v66, v66, v34
	v_or_b32_e32 v64, v64, v34
	v_or_b32_e32 v62, v62, v34
	v_or_b32_e32 v60, v60, v34
	v_or_b32_e32 v58, v58, v34
	v_mov_b32_e32 v34, 0
	s_waitcnt vmcnt(9)
	ds_write_b128 v124, v[50:53]
	s_waitcnt vmcnt(8)
; DEV f32x4 mfma16(bf16x8 a, bf16x8 b, f32x4 c) { return __builtin_amdgcn_mfma_f32_16x16x32_bf16(a, b, c, 0, 0, 0); }
; template <int EPI, bool AF32>
; DEV void gemm_tile(const void* Ap, int lda, const u16* Bt, int ldb, int K, int m0, int n0, const Epi& ea, char* smem) {
;     ...
;   auto gload = [&](int kt) {
;     const int k0 = kt << 6;
; #pragma unroll
;     for (int i = 0; i < 4; i++) {
;       const int c = tid + i * 256, row = c >> 3, kc = c & 7;
;       if (AF32) {
;         const float* pa = (const float*)Ap + (size_t)(m0 + row) * lda + k0 + kc * 8;
;         rfa[2 * i] = *(const f32x4*)pa;
;         rfa[2 * i + 1] = *(const f32x4*)(pa + 4);
;       } else {
;         ra[i] = *(const u32x4*)((const u16*)Ap + (size_t)(m0 + row) * lda + k0 + kc * 8);
;       }
;       rb[i] = *(const u32x4*)(Bt + (size_t)(n0 + row) * ldb + k0 + kc * 8);
;     }
;   };
;   auto swrite = [&](int buf) {
; #pragma unroll
;     for (int i = 0; i < 4; i++) {
;       const int c = tid + i * 256, row = c >> 3, kc = c & 7;
;       u32x4 va;
;       if (AF32) {
;         va = (u32x4){pack2(rfa[2 * i][0], rfa[2 * i][1]), pack2(rfa[2 * i][2], rfa[2 * i][3]),
;                      pack2(rfa[2 * i + 1][0], rfa[2 * i + 1][1]), pack2(rfa[2 * i + 1][2], rfa[2 * i + 1][3])};
;       } else {
;         va = ra[i];
;       }
;       *(u32x4*)(sA + buf * 9216 + row * 72 + kc * 8) = va;
;       *(u32x4*)(sB + buf * 9216 + row * 72 + kc * 8) = rb[i];
;     }
;   };
;   gload(0);
;   swrite(0);
;   if (nk > 1) gload(1);
;   __syncthreads();
;   for (int kt = 0; kt < nk; kt++) {
;     const int buf = kt & 1;
;     if (kt + 1 < nk) swrite(buf ^ 1);
;     if (kt + 2 < nk) gload(kt + 2);
; #pragma unroll
;     for (int ks = 0; ks < 2; ks++) {
;       bf16x8 a[4], b[4];
; #pragma unroll
;       for (int m = 0; m < 4; m++) a[m] = *(const bf16x8*)(sA + buf * 9216 + (wr * 64 + m * 16 + fr) * 72 + ks * 32 + fq * 8);
; #pragma unroll
;       for (int n = 0; n < 4; n++) b[n] = *(const bf16x8*)(sB + buf * 9216 + (wc * 64 + n * 16 + fr) * 72 + ks * 32 + fq * 8);
;       __builtin_amdgcn_s_setprio(1);
; #pragma unroll
;       for (int m = 0; m < 4; m++)
; #pragma unroll
;         for (int n = 0; n < 4; n++) acc[m][n] = mfma16(a[m], b[n], acc[m][n]);
;       __builtin_amdgcn_s_setprio(0);
;     }
;     __syncthreads();
	ds_write_b128 v124, v[54:57] offset:36864
	v_mul_u32_u24_e32 v127, 0x48, v35
	v_lshl_add_u64 v[98:99], s[10:11], 0, v[76:77]
	v_lshl_add_u64 v[100:101], s[12:13], 0, v[72:73]
	v_lshl_add_u64 v[102:103], s[10:11], 0, v[70:71]
	v_lshl_add_u64 v[104:105], s[12:13], 0, v[66:67]
	v_lshl_add_u64 v[106:107], s[10:11], 0, v[64:65]
	v_lshl_add_u64 v[108:109], s[12:13], 0, v[62:63]
	v_lshl_add_u64 v[110:111], s[10:11], 0, v[60:61]
	v_lshl_add_u64 v[112:113], s[12:13], 0, v[58:59]
	global_load_dwordx4 v[222:225], v[112:113], off
	global_load_dwordx4 v[226:229], v[110:111], off
	global_load_dwordx4 v[230:233], v[108:109], off
	global_load_dwordx4 v[234:237], v[106:107], off
	global_load_dwordx4 v[238:241], v[104:105], off
	global_load_dwordx4 v[242:245], v[102:103], off
	global_load_dwordx4 v[246:249], v[100:101], off
	global_load_dwordx4 v[250:253], v[98:99], off
	v_mov_b32_e32 v35, v34
	v_mov_b32_e32 v36, v34
	v_mov_b32_e32 v37, v34
	v_mov_b32_e32 v38, v34
	v_mov_b32_e32 v39, v34
	v_mov_b32_e32 v40, v34
	v_mov_b32_e32 v41, v34
	v_mov_b32_e32 v42, v34
	v_mov_b32_e32 v43, v34
	v_mov_b32_e32 v44, v34
	v_mov_b32_e32 v45, v34
	v_mov_b32_e32 v46, v34
	v_mov_b32_e32 v47, v34
	v_mov_b32_e32 v48, v34
	v_mov_b32_e32 v49, v34
	v_mov_b32_e32 v50, v34
	v_mov_b32_e32 v51, v34
	v_mov_b32_e32 v52, v34
	v_mov_b32_e32 v53, v34
	v_mov_b32_e32 v54, v34
	v_mov_b32_e32 v55, v34
	v_mov_b32_e32 v56, v34
	v_mov_b32_e32 v57, v34
	v_mov_b32_e32 v58, v34
	v_mov_b32_e32 v59, v34
	v_mov_b32_e32 v60, v34
	v_mov_b32_e32 v61, v34
	v_mov_b32_e32 v62, v34
	v_mov_b32_e32 v63, v34
	v_mov_b32_e32 v64, v34
	v_mov_b32_e32 v65, v34
	v_mov_b32_e32 v66, v34
	v_mov_b32_e32 v67, v34
	v_mov_b32_e32 v68, v34
	v_mov_b32_e32 v69, v34
	v_mov_b32_e32 v70, v34
	v_mov_b32_e32 v71, v34
	v_mov_b32_e32 v72, v34
	v_mov_b32_e32 v73, v34
	v_mov_b32_e32 v74, v34
	v_mov_b32_e32 v75, v34
	v_mov_b32_e32 v76, v34
	v_mov_b32_e32 v77, v34
	v_mov_b32_e32 v78, v34
	v_mov_b32_e32 v79, v34
	v_mov_b32_e32 v80, v34
	v_mov_b32_e32 v81, v34
	v_mov_b32_e32 v82, v34
	v_mov_b32_e32 v83, v34
	v_mov_b32_e32 v84, v34
	v_mov_b32_e32 v85, v34
	v_mov_b32_e32 v86, v34
	v_mov_b32_e32 v87, v34
	v_mov_b32_e32 v88, v34
	v_mov_b32_e32 v89, v34
	v_mov_b32_e32 v90, v34
	v_mov_b32_e32 v91, v34
	v_mov_b32_e32 v92, v34
	v_mov_b32_e32 v93, v34
	v_mov_b32_e32 v94, v34
	v_mov_b32_e32 v95, v34
	v_mov_b32_e32 v96, v34
	v_mov_b32_e32 v97, v34
	s_waitcnt lgkmcnt(0)
	s_barrier
	v_lshl_add_u32 v161, v128, 1, v125
	v_lshl_add_u32 v129, v127, 1, v125
	s_mov_b32 s17, 0
	s_mov_b64 s[0:1], 0x100
.Lgk4_loop:
	v_lshl_add_u64 v[112:113], v[112:113], 0, s[0:1]
	v_lshl_add_u64 v[110:111], v[110:111], 0, s[0:1]
	v_lshl_add_u64 v[108:109], v[108:109], 0, s[0:1]
	v_lshl_add_u64 v[106:107], v[106:107], 0, s[0:1]
	v_lshl_add_u64 v[104:105], v[104:105], 0, s[0:1]
	v_lshl_add_u64 v[102:103], v[102:103], 0, s[0:1]
	v_lshl_add_u64 v[100:101], v[100:101], 0, s[0:1]
	v_lshl_add_u64 v[98:99], v[98:99], 0, s[0:1]
	ds_read_b128 v[130:133], v161
	ds_read_b128 v[134:137], v161 offset:2304
	ds_read_b128 v[138:141], v161 offset:4608
	ds_read_b128 v[142:145], v161 offset:6912
	ds_read_b128 v[146:149], v129 offset:36864
	ds_read_b128 v[150:153], v129 offset:39168
	ds_read_b128 v[162:165], v129 offset:41472
	ds_read_b128 v[166:169], v129 offset:43776
	s_setprio 1
	s_waitcnt lgkmcnt(3)
	v_mfma_f32_16x16x32_bf16 v[34:37], v[130:133], v[146:149], v[34:37]
	s_waitcnt lgkmcnt(2)
	v_mfma_f32_16x16x32_bf16 v[38:41], v[130:133], v[150:153], v[38:41]
	s_waitcnt lgkmcnt(1)
	v_mfma_f32_16x16x32_bf16 v[42:45], v[130:133], v[162:165], v[42:45]
	s_waitcnt lgkmcnt(0)
	v_mfma_f32_16x16x32_bf16 v[46:49], v[130:133], v[166:169], v[46:49]
	v_mfma_f32_16x16x32_bf16 v[50:53], v[134:137], v[146:149], v[50:53]
	v_mfma_f32_16x16x32_bf16 v[54:57], v[134:137], v[150:153], v[54:57]
	v_mfma_f32_16x16x32_bf16 v[58:61], v[134:137], v[162:165], v[58:61]
	v_mfma_f32_16x16x32_bf16 v[62:65], v[134:137], v[166:169], v[62:65]
	v_mfma_f32_16x16x32_bf16 v[66:69], v[138:141], v[146:149], v[66:69]
	v_mfma_f32_16x16x32_bf16 v[70:73], v[138:141], v[150:153], v[70:73]
	v_mfma_f32_16x16x32_bf16 v[74:77], v[138:141], v[162:165], v[74:77]
	v_mfma_f32_16x16x32_bf16 v[78:81], v[138:141], v[166:169], v[78:81]
	v_mfma_f32_16x16x32_bf16 v[82:85], v[142:145], v[146:149], v[82:85]
	v_mfma_f32_16x16x32_bf16 v[86:89], v[142:145], v[150:153], v[86:89]
	v_mfma_f32_16x16x32_bf16 v[90:93], v[142:145], v[162:165], v[90:93]
	v_mfma_f32_16x16x32_bf16 v[94:97], v[142:145], v[166:169], v[94:97]
	s_setprio 0
	ds_read_b128 v[130:133], v161 offset:64
	ds_read_b128 v[134:137], v161 offset:2368
	ds_read_b128 v[138:141], v161 offset:4672
	ds_read_b128 v[142:145], v161 offset:6976
	ds_read_b128 v[146:149], v129 offset:36928
	ds_read_b128 v[150:153], v129 offset:39232
	ds_read_b128 v[162:165], v129 offset:41536
	ds_read_b128 v[166:169], v129 offset:43840
	s_waitcnt vmcnt(8)
	ds_write_b128 v122, v[22:25] offset:18432
	ds_write_b128 v122, v[6:9] offset:55296
	ds_write_b128 v121, v[18:21] offset:18432
	ds_write_b128 v121, v[10:13] offset:55296
	ds_write_b128 v120, v[14:17] offset:18432
	ds_write_b128 v120, v[2:5] offset:55296
	ds_write_b128 v124, v[26:29] offset:18432
	ds_write_b128 v124, v[30:33] offset:55296
	global_load_dwordx4 v[22:25], v[112:113], off offset:-128
	global_load_dwordx4 v[6:9], v[110:111], off offset:-128
	global_load_dwordx4 v[18:21], v[108:109], off offset:-128
	global_load_dwordx4 v[10:13], v[106:107], off offset:-128
	global_load_dwordx4 v[14:17], v[104:105], off offset:-128
	global_load_dwordx4 v[2:5], v[102:103], off offset:-128
	global_load_dwordx4 v[26:29], v[100:101], off offset:-128
	global_load_dwordx4 v[30:33], v[98:99], off offset:-128
	s_setprio 1
	s_waitcnt lgkmcnt(11)
	v_mfma_f32_16x16x32_bf16 v[34:37], v[130:133], v[146:149], v[34:37]
	s_waitcnt lgkmcnt(10)
	v_mfma_f32_16x16x32_bf16 v[38:41], v[130:133], v[150:153], v[38:41]
	s_waitcnt lgkmcnt(9)
	v_mfma_f32_16x16x32_bf16 v[42:45], v[130:133], v[162:165], v[42:45]
	s_waitcnt lgkmcnt(8)
	v_mfma_f32_16x16x32_bf16 v[46:49], v[130:133], v[166:169], v[46:49]
	v_mfma_f32_16x16x32_bf16 v[50:53], v[134:137], v[146:149], v[50:53]
	v_mfma_f32_16x16x32_bf16 v[54:57], v[134:137], v[150:153], v[54:57]
	v_mfma_f32_16x16x32_bf16 v[58:61], v[134:137], v[162:165], v[58:61]
	v_mfma_f32_16x16x32_bf16 v[62:65], v[134:137], v[166:169], v[62:65]
	v_mfma_f32_16x16x32_bf16 v[66:69], v[138:141], v[146:149], v[66:69]
	v_mfma_f32_16x16x32_bf16 v[70:73], v[138:141], v[150:153], v[70:73]
	v_mfma_f32_16x16x32_bf16 v[74:77], v[138:141], v[162:165], v[74:77]
	v_mfma_f32_16x16x32_bf16 v[78:81], v[138:141], v[166:169], v[78:81]
	v_mfma_f32_16x16x32_bf16 v[82:85], v[142:145], v[146:149], v[82:85]
	v_mfma_f32_16x16x32_bf16 v[86:89], v[142:145], v[150:153], v[86:89]
	v_mfma_f32_16x16x32_bf16 v[90:93], v[142:145], v[162:165], v[90:93]
	v_mfma_f32_16x16x32_bf16 v[94:97], v[142:145], v[166:169], v[94:97]
	s_setprio 0
	s_waitcnt lgkmcnt(0)
	s_barrier
; DEV f32x4 mfma16(bf16x8 a, bf16x8 b, f32x4 c) { return __builtin_amdgcn_mfma_f32_16x16x32_bf16(a, b, c, 0, 0, 0); }
; template <int EPI, bool AF32>
; DEV void gemm_tile(const void* Ap, int lda, const u16* Bt, int ldb, int K, int m0, int n0, const Epi& ea, char* smem) {
;     ...
;   auto gload = [&](int kt) {
;     const int k0 = kt << 6;
; #pragma unroll
;     for (int i = 0; i < 4; i++) {
;       const int c = tid + i * 256, row = c >> 3, kc = c & 7;
;       if (AF32) {
;         const float* pa = (const float*)Ap + (size_t)(m0 + row) * lda + k0 + kc * 8;
;         rfa[2 * i] = *(const f32x4*)pa;
;         rfa[2 * i + 1] = *(const f32x4*)(pa + 4);
;       } else {
;         ra[i] = *(const u32x4*)((const u16*)Ap + (size_t)(m0 + row) * lda + k0 + kc * 8);
;       }
;       rb[i] = *(const u32x4*)(Bt + (size_t)(n0 + row) * ldb + k0 + kc * 8);
;     }
;   };
;   auto swrite = [&](int buf) {
; #pragma unroll
;     for (int i = 0; i < 4; i++) {
;       const int c = tid + i * 256, row = c >> 3, kc = c & 7;
;       u32x4 va;
;       if (AF32) {
;         va = (u32x4){pack2(rfa[2 * i][0], rfa[2 * i][1]), pack2(rfa[2 * i][2], rfa[2 * i][3]),
;                      pack2(rfa[2 * i + 1][0], rfa[2 * i + 1][1]), pack2(rfa[2 * i + 1][2], rfa[2 * i + 1][3])};
;       } else {
;         va = ra[i];
;       }
;       *(u32x4*)(sA + buf * 9216 + row * 72 + kc * 8) = va;
;       *(u32x4*)(sB + buf * 9216 + row * 72 + kc * 8) = rb[i];
;     }
;   };
;   gload(0);
;   swrite(0);
;   if (nk > 1) gload(1);
;   __syncthreads();
;   for (int kt = 0; kt < nk; kt++) {
;     const int buf = kt & 1;
;     if (kt + 1 < nk) swrite(buf ^ 1);
;     if (kt + 2 < nk) gload(kt + 2);
; #pragma unroll
;     for (int ks = 0; ks < 2; ks++) {
;       bf16x8 a[4], b[4];
; #pragma unroll
;       for (int m = 0; m < 4; m++) a[m] = *(const bf16x8*)(sA + buf * 9216 + (wr * 64 + m * 16 + fr) * 72 + ks * 32 + fq * 8);
; #pragma unroll
;       for (int n = 0; n < 4; n++) b[n] = *(const bf16x8*)(sB + buf * 9216 + (wc * 64 + n * 16 + fr) * 72 + ks * 32 + fq * 8);
;       __builtin_amdgcn_s_setprio(1);
; #pragma unroll
;       for (int m = 0; m < 4; m++)
; #pragma unroll
;         for (int n = 0; n < 4; n++) acc[m][n] = mfma16(a[m], b[n], acc[m][n]);
;       __builtin_amdgcn_s_setprio(0);
;     }
;     __syncthreads();
	ds_read_b128 v[130:133], v161 offset:18432
	ds_read_b128 v[134:137], v161 offset:20736
	ds_read_b128 v[138:141], v161 offset:23040
	ds_read_b128 v[142:145], v161 offset:25344
	ds_read_b128 v[146:149], v129 offset:55296
	ds_read_b128 v[150:153], v129 offset:57600
	ds_read_b128 v[162:165], v129 offset:59904
	ds_read_b128 v[166:169], v129 offset:62208
	s_setprio 1
	s_waitcnt lgkmcnt(3)
	v_mfma_f32_16x16x32_bf16 v[34:37], v[130:133], v[146:149], v[34:37]
	s_waitcnt lgkmcnt(2)
	v_mfma_f32_16x16x32_bf16 v[38:41], v[130:133], v[150:153], v[38:41]
	s_waitcnt lgkmcnt(1)
	v_mfma_f32_16x16x32_bf16 v[42:45], v[130:133], v[162:165], v[42:45]
	s_waitcnt lgkmcnt(0)
	v_mfma_f32_16x16x32_bf16 v[46:49], v[130:133], v[166:169], v[46:49]
	v_mfma_f32_16x16x32_bf16 v[50:53], v[134:137], v[146:149], v[50:53]
	v_mfma_f32_16x16x32_bf16 v[54:57], v[134:137], v[150:153], v[54:57]
	v_mfma_f32_16x16x32_bf16 v[58:61], v[134:137], v[162:165], v[58:61]
	v_mfma_f32_16x16x32_bf16 v[62:65], v[134:137], v[166:169], v[62:65]
	v_mfma_f32_16x16x32_bf16 v[66:69], v[138:141], v[146:149], v[66:69]
	v_mfma_f32_16x16x32_bf16 v[70:73], v[138:141], v[150:153], v[70:73]
	v_mfma_f32_16x16x32_bf16 v[74:77], v[138:141], v[162:165], v[74:77]
	v_mfma_f32_16x16x32_bf16 v[78:81], v[138:141], v[166:169], v[78:81]
	v_mfma_f32_16x16x32_bf16 v[82:85], v[142:145], v[146:149], v[82:85]
	v_mfma_f32_16x16x32_bf16 v[86:89], v[142:145], v[150:153], v[86:89]
	v_mfma_f32_16x16x32_bf16 v[90:93], v[142:145], v[162:165], v[90:93]
	v_mfma_f32_16x16x32_bf16 v[94:97], v[142:145], v[166:169], v[94:97]
	s_setprio 0
	ds_read_b128 v[130:133], v161 offset:18496
	ds_read_b128 v[134:137], v161 offset:20800
	ds_read_b128 v[138:141], v161 offset:23104
	ds_read_b128 v[142:145], v161 offset:25408
	ds_read_b128 v[146:149], v129 offset:55360
	ds_read_b128 v[150:153], v129 offset:57664
	ds_read_b128 v[162:165], v129 offset:59968
	ds_read_b128 v[166:169], v129 offset:62272
	s_waitcnt vmcnt(8)
	ds_write_b128 v122, v[222:225]
	ds_write_b128 v122, v[226:229] offset:36864
	ds_write_b128 v121, v[230:233]
	ds_write_b128 v121, v[234:237] offset:36864
	ds_write_b128 v120, v[238:241]
	ds_write_b128 v120, v[242:245] offset:36864
	ds_write_b128 v124, v[246:249]
	ds_write_b128 v124, v[250:253] offset:36864
	s_cmp_eq_u32 s17, 6
	s_cbranch_scc1 .Lgk4_nold
	global_load_dwordx4 v[222:225], v[112:113], off
	global_load_dwordx4 v[226:229], v[110:111], off
	global_load_dwordx4 v[230:233], v[108:109], off
	global_load_dwordx4 v[234:237], v[106:107], off
	global_load_dwordx4 v[238:241], v[104:105], off
	global_load_dwordx4 v[242:245], v[102:103], off
	global_load_dwordx4 v[246:249], v[100:101], off
	global_load_dwordx4 v[250:253], v[98:99], off
.Lgk4_nold:
	s_setprio 1
	s_waitcnt lgkmcnt(11)
	v_mfma_f32_16x16x32_bf16 v[34:37], v[130:133], v[146:149], v[34:37]
	s_waitcnt lgkmcnt(10)
	v_mfma_f32_16x16x32_bf16 v[38:41], v[130:133], v[150:153], v[38:41]
	s_waitcnt lgkmcnt(9)
	v_mfma_f32_16x16x32_bf16 v[42:45], v[130:133], v[162:165], v[42:45]
	s_waitcnt lgkmcnt(8)
	v_mfma_f32_16x16x32_bf16 v[46:49], v[130:133], v[166:169], v[46:49]
	v_mfma_f32_16x16x32_bf16 v[50:53], v[134:137], v[146:149], v[50:53]
	v_mfma_f32_16x16x32_bf16 v[54:57], v[134:137], v[150:153], v[54:57]
	v_mfma_f32_16x16x32_bf16 v[58:61], v[134:137], v[162:165], v[58:61]
	v_mfma_f32_16x16x32_bf16 v[62:65], v[134:137], v[166:169], v[62:65]
	v_mfma_f32_16x16x32_bf16 v[66:69], v[138:141], v[146:149], v[66:69]
	v_mfma_f32_16x16x32_bf16 v[70:73], v[138:141], v[150:153], v[70:73]
	v_mfma_f32_16x16x32_bf16 v[74:77], v[138:141], v[162:165], v[74:77]
	v_mfma_f32_16x16x32_bf16 v[78:81], v[138:141], v[166:169], v[78:81]
	v_mfma_f32_16x16x32_bf16 v[82:85], v[142:145], v[146:149], v[82:85]
	v_mfma_f32_16x16x32_bf16 v[86:89], v[142:145], v[150:153], v[86:89]
	v_mfma_f32_16x16x32_bf16 v[90:93], v[142:145], v[162:165], v[90:93]
	v_mfma_f32_16x16x32_bf16 v[94:97], v[142:145], v[166:169], v[94:97]
	s_setprio 0
	s_add_i32 s17, s17, 1
	s_cmp_lg_u32 s17, 7
	s_waitcnt lgkmcnt(0)
	s_barrier
	s_cbranch_scc1 .Lgk4_loop
	s_waitcnt vmcnt(7)
	ds_write_b128 v122, v[22:25] offset:18432
	s_waitcnt vmcnt(6)
	ds_write_b128 v122, v[6:9] offset:55296
	s_waitcnt vmcnt(5)
	ds_write_b128 v121, v[18:21] offset:18432
	s_waitcnt vmcnt(4)
	ds_write_b128 v121, v[10:13] offset:55296
	s_waitcnt vmcnt(3)
	ds_write_b128 v120, v[14:17] offset:18432
	s_waitcnt vmcnt(2)
	ds_write_b128 v120, v[2:5] offset:55296
	s_waitcnt vmcnt(1)
	ds_write_b128 v124, v[26:29] offset:18432
	s_waitcnt vmcnt(0)
	ds_write_b128 v124, v[30:33] offset:55296
	v_lshl_add_u32 v0, v128, 1, v125
	v_lshl_add_u32 v126, v127, 1, v125
	ds_read_b128 v[2:5], v0
	ds_read_b128 v[6:9], v0 offset:2304
	ds_read_b128 v[10:13], v0 offset:4608
	ds_read_b128 v[14:17], v0 offset:6912
	ds_read_b128 v[18:21], v126 offset:36864
	ds_read_b128 v[22:25], v126 offset:39168
	ds_read_b128 v[26:29], v126 offset:41472
	ds_read_b128 v[30:33], v126 offset:43776
	s_setprio 1
	s_waitcnt lgkmcnt(3)
	v_mfma_f32_16x16x32_bf16 v[34:37], v[2:5], v[18:21], v[34:37]
	s_waitcnt lgkmcnt(2)
	v_mfma_f32_16x16x32_bf16 v[38:41], v[2:5], v[22:25], v[38:41]
	s_waitcnt lgkmcnt(1)
	v_mfma_f32_16x16x32_bf16 v[42:45], v[2:5], v[26:29], v[42:45]
	s_waitcnt lgkmcnt(0)
; DEV f32x4 mfma16(bf16x8 a, bf16x8 b, f32x4 c) { return __builtin_amdgcn_mfma_f32_16x16x32_bf16(a, b, c, 0, 0, 0); }
; template <int EPI, bool AF32>
; DEV void gemm_tile(const void* Ap, int lda, const u16* Bt, int ldb, int K, int m0, int n0, const Epi& ea, char* smem) {
;     ...
; #pragma unroll
;     for (int ks = 0; ks < 2; ks++) {
;       bf16x8 a[4], b[4];
; #pragma unroll
;       for (int m = 0; m < 4; m++) a[m] = *(const bf16x8*)(sA + buf * 9216 + (wr * 64 + m * 16 + fr) * 72 + ks * 32 + fq * 8);
; #pragma unroll
;       for (int n = 0; n < 4; n++) b[n] = *(const bf16x8*)(sB + buf * 9216 + (wc * 64 + n * 16 + fr) * 72 + ks * 32 + fq * 8);
;       __builtin_amdgcn_s_setprio(1);
; #pragma unroll
;       for (int m = 0; m < 4; m++)
; #pragma unroll
;         for (int n = 0; n < 4; n++) acc[m][n] = mfma16(a[m], b[n], acc[m][n]);
;       __builtin_amdgcn_s_setprio(0);
;     }
;     __syncthreads();
	v_mfma_f32_16x16x32_bf16 v[2:5], v[2:5], v[30:33], v[46:49]
	v_mfma_f32_16x16x32_bf16 v[46:49], v[6:9], v[18:21], v[50:53]
	v_mfma_f32_16x16x32_bf16 v[50:53], v[6:9], v[22:25], v[54:57]
	v_mfma_f32_16x16x32_bf16 v[54:57], v[6:9], v[26:29], v[58:61]
	v_mfma_f32_16x16x32_bf16 v[6:9], v[6:9], v[30:33], v[62:65]
	v_mfma_f32_16x16x32_bf16 v[58:61], v[10:13], v[18:21], v[66:69]
	v_mfma_f32_16x16x32_bf16 v[62:65], v[10:13], v[22:25], v[70:73]
	v_mfma_f32_16x16x32_bf16 v[66:69], v[10:13], v[26:29], v[74:77]
	v_mfma_f32_16x16x32_bf16 v[10:13], v[10:13], v[30:33], v[78:81]
	v_mfma_f32_16x16x32_bf16 v[18:21], v[14:17], v[18:21], v[82:85]
	v_mfma_f32_16x16x32_bf16 v[22:25], v[14:17], v[22:25], v[86:89]
	v_mfma_f32_16x16x32_bf16 v[26:29], v[14:17], v[26:29], v[90:93]
	v_mfma_f32_16x16x32_bf16 v[14:17], v[14:17], v[30:33], v[94:97]
	s_setprio 0
	ds_read_b128 v[30:33], v0 offset:64
	ds_read_b128 v[70:73], v0 offset:2368
	ds_read_b128 v[74:77], v0 offset:4672
	ds_read_b128 v[78:81], v0 offset:6976
	ds_read_b128 v[82:85], v126 offset:36928
	ds_read_b128 v[86:89], v126 offset:39232
	ds_read_b128 v[90:93], v126 offset:41536
	ds_read_b128 v[94:97], v126 offset:43840
	s_setprio 1
	s_waitcnt lgkmcnt(3)
	v_mfma_f32_16x16x32_bf16 v[34:37], v[30:33], v[82:85], v[34:37]
	s_waitcnt lgkmcnt(2)
	v_mfma_f32_16x16x32_bf16 v[38:41], v[30:33], v[86:89], v[38:41]
	s_waitcnt lgkmcnt(1)
	v_mfma_f32_16x16x32_bf16 v[42:45], v[30:33], v[90:93], v[42:45]
	s_waitcnt lgkmcnt(0)
	v_mfma_f32_16x16x32_bf16 v[2:5], v[30:33], v[94:97], v[2:5]
	v_mfma_f32_16x16x32_bf16 v[30:33], v[70:73], v[82:85], v[46:49]
	v_mfma_f32_16x16x32_bf16 v[46:49], v[70:73], v[86:89], v[50:53]
	v_mfma_f32_16x16x32_bf16 v[50:53], v[70:73], v[90:93], v[54:57]
	v_mfma_f32_16x16x32_bf16 v[6:9], v[70:73], v[94:97], v[6:9]
	v_mfma_f32_16x16x32_bf16 v[54:57], v[74:77], v[82:85], v[58:61]
	v_mfma_f32_16x16x32_bf16 v[58:61], v[74:77], v[86:89], v[62:65]
	v_mfma_f32_16x16x32_bf16 v[62:65], v[74:77], v[90:93], v[66:69]
	v_mfma_f32_16x16x32_bf16 v[10:13], v[74:77], v[94:97], v[10:13]
	v_mfma_f32_16x16x32_bf16 v[18:21], v[78:81], v[82:85], v[18:21]
	v_mfma_f32_16x16x32_bf16 v[22:25], v[78:81], v[86:89], v[22:25]
	v_mfma_f32_16x16x32_bf16 v[26:29], v[78:81], v[90:93], v[26:29]
	v_mfma_f32_16x16x32_bf16 v[14:17], v[78:81], v[94:97], v[14:17]
	s_setprio 0
	s_barrier
	ds_read_b128 v[66:69], v0 offset:18432
	ds_read_b128 v[70:73], v0 offset:20736
	ds_read_b128 v[74:77], v0 offset:23040
	ds_read_b128 v[78:81], v0 offset:25344
	ds_read_b128 v[82:85], v126 offset:55296
	ds_read_b128 v[86:89], v126 offset:57600
	ds_read_b128 v[90:93], v126 offset:59904
	ds_read_b128 v[94:97], v126 offset:62208
	v_and_b32_e32 v114, 64, v114
	s_setprio 1
	s_waitcnt lgkmcnt(3)
	v_mfma_f32_16x16x32_bf16 v[34:37], v[66:69], v[82:85], v[34:37]
	s_waitcnt lgkmcnt(2)
	v_mfma_f32_16x16x32_bf16 v[38:41], v[66:69], v[86:89], v[38:41]
	s_waitcnt lgkmcnt(1)
	v_mfma_f32_16x16x32_bf16 v[42:45], v[66:69], v[90:93], v[42:45]
	s_waitcnt lgkmcnt(0)
	v_mfma_f32_16x16x32_bf16 v[2:5], v[66:69], v[94:97], v[2:5]
	v_mfma_f32_16x16x32_bf16 v[30:33], v[70:73], v[82:85], v[30:33]
	v_mfma_f32_16x16x32_bf16 v[66:69], v[70:73], v[86:89], v[46:49]
	v_mfma_f32_16x16x32_bf16 v[98:101], v[70:73], v[90:93], v[50:53]
	v_mfma_f32_16x16x32_bf16 v[6:9], v[70:73], v[94:97], v[6:9]
	v_mfma_f32_16x16x32_bf16 v[70:73], v[74:77], v[82:85], v[54:57]
	v_mfma_f32_16x16x32_bf16 v[102:105], v[74:77], v[86:89], v[58:61]
	v_mfma_f32_16x16x32_bf16 v[106:109], v[74:77], v[90:93], v[62:65]
	v_mfma_f32_16x16x32_bf16 v[10:13], v[74:77], v[94:97], v[10:13]
	v_mfma_f32_16x16x32_bf16 v[74:77], v[78:81], v[82:85], v[18:21]
	v_mfma_f32_16x16x32_bf16 v[82:85], v[78:81], v[86:89], v[22:25]
	v_mfma_f32_16x16x32_bf16 v[86:89], v[78:81], v[90:93], v[26:29]
	v_mfma_f32_16x16x32_bf16 v[78:81], v[78:81], v[94:97], v[14:17]
	s_setprio 0
	s_nop 1
	ds_read_b128 v[14:17], v0 offset:18496
	ds_read_b128 v[18:21], v0 offset:20800
	ds_read_b128 v[90:93], v0 offset:23104
	ds_read_b128 v[94:97], v0 offset:25408
	ds_read_b128 v[110:113], v126 offset:55360
	ds_read_b128 v[118:121], v126 offset:57664
	ds_read_b128 v[122:125], v126 offset:59968
	ds_read_b128 v[126:129], v126 offset:62272
	s_setprio 1
	s_waitcnt lgkmcnt(3)
	v_mfma_f32_16x16x32_bf16 v[62:65], v[14:17], v[110:113], v[34:37]
	s_waitcnt lgkmcnt(2)
	v_mfma_f32_16x16x32_bf16 v[58:61], v[14:17], v[118:121], v[38:41]
	s_waitcnt lgkmcnt(1)
	v_mfma_f32_16x16x32_bf16 v[54:57], v[14:17], v[122:125], v[42:45]
	s_waitcnt lgkmcnt(0)
; DEV f32x4 mfma16(bf16x8 a, bf16x8 b, f32x4 c) { return __builtin_amdgcn_mfma_f32_16x16x32_bf16(a, b, c, 0, 0, 0); }
; template <int EPI, bool AF32>
; DEV void gemm_tile(const void* Ap, int lda, const u16* Bt, int ldb, int K, int m0, int n0, const Epi& ea, char* smem) {
;     ...
; #pragma unroll
;     for (int ks = 0; ks < 2; ks++) {
;       bf16x8 a[4], b[4];
; #pragma unroll
;       for (int m = 0; m < 4; m++) a[m] = *(const bf16x8*)(sA + buf * 9216 + (wr * 64 + m * 16 + fr) * 72 + ks * 32 + fq * 8);
; #pragma unroll
;       for (int n = 0; n < 4; n++) b[n] = *(const bf16x8*)(sB + buf * 9216 + (wc * 64 + n * 16 + fr) * 72 + ks * 32 + fq * 8);
;       __builtin_amdgcn_s_setprio(1);
; #pragma unroll
;       for (int m = 0; m < 4; m++)
; #pragma unroll
;         for (int n = 0; n < 4; n++) acc[m][n] = mfma16(a[m], b[n], acc[m][n]);
;       __builtin_amdgcn_s_setprio(0);
;     }
;     __syncthreads();
;     ...
;       u16* C = (u16*)ea.p0;
;       const u16* G = (const u16*)ea.p1 + (EPI == EP_MERGE2 ? 1024 : 0);
;       u16 gv[4][4][4], cv[4][4][4];
; #pragma unroll
;       for (int m = 0; m < 4; m++)
; #pragma unroll
;         for (int j = 0; j < 4; j++)
; #pragma unroll
;           for (int n = 0; n < 4; n++) {
;             gv[m][j][n] = G[(size_t)(rbase + m * 16 + j) * 2048 + cbase + n * 16];
;             if (EPI == EP_MERGE2) cv[m][j][n] = C[(size_t)(rbase + m * 16 + j) * 1024 + cbase + n * 16];
;           }
	v_mfma_f32_16x16x32_bf16 v[50:53], v[14:17], v[126:129], v[2:5]
	v_mfma_f32_16x16x32_bf16 v[46:49], v[18:21], v[110:113], v[30:33]
	v_mfma_f32_16x16x32_bf16 v[42:45], v[18:21], v[118:121], v[66:69]
	v_mfma_f32_16x16x32_bf16 v[38:41], v[18:21], v[122:125], v[98:101]
	v_mfma_f32_16x16x32_bf16 v[34:37], v[18:21], v[126:129], v[6:9]
	v_mfma_f32_16x16x32_bf16 v[30:33], v[90:93], v[110:113], v[70:73]
	v_mfma_f32_16x16x32_bf16 v[26:29], v[90:93], v[118:121], v[102:105]
	v_mfma_f32_16x16x32_bf16 v[22:25], v[90:93], v[122:125], v[106:109]
	v_mfma_f32_16x16x32_bf16 v[18:21], v[90:93], v[126:129], v[10:13]
	v_mfma_f32_16x16x32_bf16 v[14:17], v[94:97], v[110:113], v[74:77]
	v_mfma_f32_16x16x32_bf16 v[10:13], v[94:97], v[118:121], v[82:85]
	v_mfma_f32_16x16x32_bf16 v[6:9], v[94:97], v[122:125], v[86:89]
	v_mfma_f32_16x16x32_bf16 v[2:5], v[94:97], v[126:129], v[78:81]
	s_setprio 0
	v_add_u32_e32 v0, s16, v117
	v_or3_b32 v68, v114, s15, v115
	v_lshl_or_b32 v66, v116, 2, v0
	v_ashrrev_i32_e32 v69, 31, v68
	v_lshlrev_b64 v[68:69], 1, v[68:69]
	v_ashrrev_i32_e32 v67, 31, v66
	v_lshl_add_u64 v[98:99], s[8:9], 0, v[68:69]
	v_lshl_add_u64 v[100:101], s[2:3], 0, v[68:69]
	v_lshlrev_b64 v[68:69], 12, v[66:67]
	v_lshl_add_u64 v[102:103], v[98:99], 0, v[68:69]
	v_lshlrev_b64 v[68:69], 11, v[66:67]
	v_lshl_add_u64 v[96:97], v[100:101], 0, v[68:69]
	v_or_b32_e32 v68, 1, v66
	v_ashrrev_i32_e32 v69, 31, v68
	v_lshlrev_b64 v[70:71], 12, v[68:69]
	v_lshlrev_b64 v[68:69], 11, v[68:69]
	v_lshl_add_u64 v[94:95], v[100:101], 0, v[68:69]
	v_or_b32_e32 v68, 2, v66
	v_ashrrev_i32_e32 v69, 31, v68
	v_lshl_add_u64 v[104:105], v[98:99], 0, v[70:71]
	v_lshlrev_b64 v[70:71], 12, v[68:69]
	v_lshlrev_b64 v[68:69], 11, v[68:69]
	v_lshl_add_u64 v[92:93], v[100:101], 0, v[68:69]
	v_or_b32_e32 v68, 3, v66
	v_ashrrev_i32_e32 v69, 31, v68
	v_lshl_add_u64 v[106:107], v[98:99], 0, v[70:71]
	v_lshlrev_b64 v[70:71], 12, v[68:69]
	v_lshlrev_b64 v[68:69], 11, v[68:69]
	v_lshl_add_u64 v[90:91], v[100:101], 0, v[68:69]
	v_or_b32_e32 v68, 16, v66
	v_ashrrev_i32_e32 v69, 31, v68
	v_lshl_add_u64 v[108:109], v[98:99], 0, v[70:71]
	v_lshlrev_b64 v[70:71], 12, v[68:69]
	v_lshlrev_b64 v[68:69], 11, v[68:69]
	v_lshl_add_u64 v[88:89], v[100:101], 0, v[68:69]
	v_or_b32_e32 v68, 17, v66
	v_ashrrev_i32_e32 v69, 31, v68
	v_lshl_add_u64 v[110:111], v[98:99], 0, v[70:71]
	v_lshlrev_b64 v[70:71], 12, v[68:69]
	v_lshlrev_b64 v[68:69], 11, v[68:69]
	v_lshl_add_u64 v[86:87], v[100:101], 0, v[68:69]
	v_or_b32_e32 v68, 18, v66
	v_ashrrev_i32_e32 v69, 31, v68
	v_lshl_add_u64 v[112:113], v[98:99], 0, v[70:71]
	v_lshlrev_b64 v[70:71], 12, v[68:69]
	v_lshlrev_b64 v[68:69], 11, v[68:69]
	v_lshl_add_u64 v[84:85], v[100:101], 0, v[68:69]
	v_or_b32_e32 v68, 19, v66
	v_ashrrev_i32_e32 v69, 31, v68
	v_lshl_add_u64 v[114:115], v[98:99], 0, v[70:71]
	v_lshlrev_b64 v[70:71], 12, v[68:69]
	v_lshlrev_b64 v[68:69], 11, v[68:69]
	v_lshl_add_u64 v[82:83], v[100:101], 0, v[68:69]
	v_or_b32_e32 v68, 32, v66
	v_ashrrev_i32_e32 v69, 31, v68
	v_lshl_add_u64 v[116:117], v[98:99], 0, v[70:71]
	v_lshlrev_b64 v[70:71], 12, v[68:69]
	v_lshlrev_b64 v[68:69], 11, v[68:69]
	v_lshl_add_u64 v[80:81], v[100:101], 0, v[68:69]
	v_or_b32_e32 v68, 33, v66
	v_ashrrev_i32_e32 v69, 31, v68
	v_lshl_add_u64 v[118:119], v[98:99], 0, v[70:71]
	v_lshlrev_b64 v[70:71], 12, v[68:69]
	v_lshlrev_b64 v[68:69], 11, v[68:69]
	v_lshl_add_u64 v[78:79], v[100:101], 0, v[68:69]
	v_or_b32_e32 v68, 34, v66
	v_ashrrev_i32_e32 v69, 31, v68
	v_lshl_add_u64 v[120:121], v[98:99], 0, v[70:71]
	v_lshlrev_b64 v[70:71], 12, v[68:69]
	v_lshlrev_b64 v[68:69], 11, v[68:69]
	v_lshl_add_u64 v[76:77], v[100:101], 0, v[68:69]
	v_or_b32_e32 v68, 35, v66
	v_ashrrev_i32_e32 v69, 31, v68
	v_lshl_add_u64 v[122:123], v[98:99], 0, v[70:71]
	v_lshlrev_b64 v[70:71], 12, v[68:69]
	v_lshlrev_b64 v[68:69], 11, v[68:69]
	v_lshl_add_u64 v[74:75], v[100:101], 0, v[68:69]
	v_or_b32_e32 v68, 48, v66
	v_ashrrev_i32_e32 v69, 31, v68
	v_lshl_add_u64 v[124:125], v[98:99], 0, v[70:71]
	v_lshlrev_b64 v[70:71], 12, v[68:69]
	v_lshlrev_b64 v[68:69], 11, v[68:69]
	v_lshl_add_u64 v[72:73], v[100:101], 0, v[68:69]
	v_or_b32_e32 v68, 49, v66
	v_ashrrev_i32_e32 v69, 31, v68
	v_lshl_add_u64 v[126:127], v[98:99], 0, v[70:71]
	v_lshlrev_b64 v[70:71], 12, v[68:69]
	v_lshlrev_b64 v[68:69], 11, v[68:69]
	v_lshl_add_u64 v[128:129], v[98:99], 0, v[70:71]
	v_lshl_add_u64 v[70:71], v[100:101], 0, v[68:69]
	v_or_b32_e32 v68, 50, v66
	v_or_b32_e32 v66, 51, v66
	v_ashrrev_i32_e32 v69, 31, v68
	v_ashrrev_i32_e32 v67, 31, v66
	v_lshlrev_b64 v[130:131], 12, v[68:69]
	v_lshlrev_b64 v[132:133], 12, v[66:67]
	v_lshl_add_u64 v[130:131], v[98:99], 0, v[130:131]
	v_lshlrev_b64 v[68:69], 11, v[68:69]
	v_lshl_add_u64 v[98:99], v[98:99], 0, v[132:133]
	v_lshlrev_b64 v[66:67], 11, v[66:67]
	s_barrier
; template <int EPI, bool AF32>
; DEV void gemm_tile(const void* Ap, int lda, const u16* Bt, int ldb, int K, int m0, int n0, const Epi& ea, char* smem) {
;     ...
;       u16 gv[4][4][4], cv[4][4][4];
; #pragma unroll
;       for (int m = 0; m < 4; m++)
; #pragma unroll
;         for (int j = 0; j < 4; j++)
; #pragma unroll
;           for (int n = 0; n < 4; n++) {
;             gv[m][j][n] = G[(size_t)(rbase + m * 16 + j) * 2048 + cbase + n * 16];
;             if (EPI == EP_MERGE2) cv[m][j][n] = C[(size_t)(rbase + m * 16 + j) * 1024 + cbase + n * 16];
;           }
	v_lshl_add_u64 v[68:69], v[100:101], 0, v[68:69]
	v_lshl_add_u64 v[66:67], v[100:101], 0, v[66:67]
	global_load_ushort v0, v[102:103], off
	global_load_ushort v100, v[102:103], off offset:32
	global_load_ushort v101, v[102:103], off offset:64
	s_nop 0
	global_load_ushort v102, v[102:103], off offset:96
	s_nop 0
	global_load_ushort v103, v[96:97], off
	global_load_ushort v132, v[96:97], off offset:32
	global_load_ushort v133, v[96:97], off offset:64
	global_load_ushort v134, v[96:97], off offset:96
	global_load_ushort v135, v[104:105], off
	global_load_ushort v136, v[104:105], off offset:32
	global_load_ushort v137, v[104:105], off offset:64
	s_nop 0
	global_load_ushort v104, v[104:105], off offset:96
	s_nop 0
	global_load_ushort v105, v[94:95], off
	global_load_ushort v138, v[94:95], off offset:32
	global_load_ushort v139, v[94:95], off offset:64
	global_load_ushort v140, v[94:95], off offset:96
	global_load_ushort v141, v[106:107], off
	global_load_ushort v142, v[106:107], off offset:32
	global_load_ushort v143, v[106:107], off offset:64
	s_nop 0
	global_load_ushort v106, v[106:107], off offset:96
	s_nop 0
	global_load_ushort v107, v[92:93], off
	global_load_ushort v144, v[92:93], off offset:32
	global_load_ushort v145, v[92:93], off offset:64
	global_load_ushort v146, v[92:93], off offset:96
	global_load_ushort v147, v[108:109], off
	global_load_ushort v148, v[108:109], off offset:32
	global_load_ushort v149, v[108:109], off offset:64
	s_nop 0
	global_load_ushort v108, v[108:109], off offset:96
	s_nop 0
	global_load_ushort v109, v[90:91], off
	global_load_ushort v150, v[90:91], off offset:32
	global_load_ushort v151, v[90:91], off offset:64
	global_load_ushort v152, v[90:91], off offset:96
	global_load_ushort v153, v[110:111], off
	global_load_ushort v161, v[110:111], off offset:32
	global_load_ushort v162, v[110:111], off offset:64
	s_nop 0
	global_load_ushort v110, v[110:111], off offset:96
	s_nop 0
	global_load_ushort v111, v[88:89], off
	global_load_ushort v163, v[88:89], off offset:32
	global_load_ushort v164, v[88:89], off offset:64
	global_load_ushort v165, v[88:89], off offset:96
	global_load_ushort v166, v[112:113], off
	global_load_ushort v167, v[112:113], off offset:32
	global_load_ushort v168, v[112:113], off offset:64
	s_nop 0
	global_load_ushort v112, v[112:113], off offset:96
	s_nop 0
	global_load_ushort v113, v[86:87], off
	global_load_ushort v169, v[86:87], off offset:32
	global_load_ushort v170, v[86:87], off offset:64
	global_load_ushort v171, v[86:87], off offset:96
	global_load_ushort v172, v[114:115], off
	global_load_ushort v173, v[114:115], off offset:32
	global_load_ushort v174, v[114:115], off offset:64
	s_nop 0
	global_load_ushort v114, v[114:115], off offset:96
	s_nop 0
	global_load_ushort v115, v[84:85], off
	global_load_ushort v175, v[84:85], off offset:32
	global_load_ushort v176, v[84:85], off offset:64
	global_load_ushort v177, v[84:85], off offset:96
	global_load_ushort v178, v[116:117], off
	global_load_ushort v179, v[116:117], off offset:32
	global_load_ushort v180, v[116:117], off offset:64
	s_nop 0
	global_load_ushort v116, v[116:117], off offset:96
	s_nop 0
	global_load_ushort v117, v[82:83], off
	global_load_ushort v181, v[82:83], off offset:32
	global_load_ushort v182, v[82:83], off offset:64
	global_load_ushort v183, v[82:83], off offset:96
	global_load_ushort v184, v[118:119], off
	global_load_ushort v185, v[118:119], off offset:32
	global_load_ushort v186, v[118:119], off offset:64
	s_nop 0
	global_load_ushort v118, v[118:119], off offset:96
	s_nop 0
	global_load_ushort v119, v[80:81], off
	global_load_ushort v187, v[80:81], off offset:32
	global_load_ushort v188, v[80:81], off offset:64
	global_load_ushort v189, v[80:81], off offset:96
	global_load_ushort v190, v[120:121], off
	global_load_ushort v191, v[120:121], off offset:32
	global_load_ushort v192, v[120:121], off offset:64
	s_nop 0
	global_load_ushort v120, v[120:121], off offset:96
	s_nop 0
	global_load_ushort v121, v[78:79], off
	global_load_ushort v193, v[78:79], off offset:32
	global_load_ushort v194, v[78:79], off offset:64
	global_load_ushort v195, v[78:79], off offset:96
	global_load_ushort v196, v[122:123], off
	global_load_ushort v197, v[122:123], off offset:32
	global_load_ushort v221, v[122:123], off offset:64
	s_nop 0
	global_load_ushort v122, v[122:123], off offset:96
	s_nop 0
	global_load_ushort v123, v[76:77], off
	global_load_ushort v222, v[76:77], off offset:32
	global_load_ushort v223, v[76:77], off offset:64
	global_load_ushort v224, v[76:77], off offset:96
	global_load_ushort v225, v[124:125], off
	global_load_ushort v226, v[124:125], off offset:32
	global_load_ushort v227, v[124:125], off offset:64
	s_nop 0
	global_load_ushort v124, v[124:125], off offset:96
	s_nop 0
	global_load_ushort v125, v[74:75], off
	global_load_ushort v228, v[74:75], off offset:32
	global_load_ushort v229, v[74:75], off offset:64
	global_load_ushort v230, v[74:75], off offset:96
	global_load_ushort v231, v[126:127], off
	global_load_ushort v232, v[126:127], off offset:32
	global_load_ushort v233, v[126:127], off offset:64
	s_nop 0
	global_load_ushort v126, v[126:127], off offset:96
	s_nop 0
	global_load_ushort v127, v[72:73], off
	global_load_ushort v234, v[72:73], off offset:32
	global_load_ushort v235, v[72:73], off offset:64
	global_load_ushort v236, v[72:73], off offset:96
	global_load_ushort v237, v[128:129], off
	global_load_ushort v238, v[128:129], off offset:32
	global_load_ushort v239, v[128:129], off offset:64
	s_nop 0
	global_load_ushort v128, v[128:129], off offset:96
	s_nop 0
	global_load_ushort v129, v[70:71], off
	global_load_ushort v240, v[70:71], off offset:32
	global_load_ushort v241, v[70:71], off offset:64
	global_load_ushort v242, v[70:71], off offset:96
	global_load_ushort v243, v[130:131], off
	global_load_ushort v244, v[130:131], off offset:32
	global_load_ushort v245, v[130:131], off offset:64
	s_nop 0
	global_load_ushort v130, v[130:131], off offset:96
	s_nop 0
	global_load_ushort v131, v[68:69], off
	global_load_ushort v246, v[68:69], off offset:32
	global_load_ushort v247, v[68:69], off offset:64
	global_load_ushort v248, v[68:69], off offset:96
	global_load_ushort v249, v[98:99], off
	global_load_ushort v250, v[98:99], off offset:32
	global_load_ushort v251, v[98:99], off offset:64
	s_nop 0
	global_load_ushort v98, v[98:99], off offset:96
	s_nop 0
	global_load_ushort v99, v[66:67], off
	global_load_ushort v252, v[66:67], off offset:32
	global_load_ushort v253, v[66:67], off offset:64
	global_load_ushort v201, v[66:67], off offset:96
	s_waitcnt vmcnt(62)
; DEV float bf2f(u16 h) { return __uint_as_float(((unsigned)h) << 16); }
; template <int EPI, bool AF32>
; DEV void gemm_tile(const void* Ap, int lda, const u16* Bt, int ldb, int K, int m0, int n0, const Epi& ea, char* smem) {
;     ...
; #pragma unroll
;       for (int m = 0; m < 4; m++)
; #pragma unroll
;         for (int j = 0; j < 4; j++)
; #pragma unroll
;           for (int n = 0; n < 4; n++) {
;             float v = bf2f(gv[m][j][n]) * acc[m][n][j];
;             if (EPI == EP_MERGE2) v += bf2f(cv[m][j][n]);
;             C[(size_t)(rbase + m * 16 + j) * 1024 + cbase + n * 16] = f2bf(v);
;           }
	v_lshlrev_b32_e32 v0, 16, v0
	v_lshlrev_b32_e32 v103, 16, v103
	v_fmac_f32_e32 v103, v62, v0
	v_cvt_pk_bf16_f32 v0, v103, s0
	global_store_short v[96:97], v0, off
	v_lshlrev_b32_e32 v0, 16, v100
	v_lshlrev_b32_e32 v62, 16, v132
	v_fmac_f32_e32 v62, v58, v0
	v_cvt_pk_bf16_f32 v0, v62, s0
	global_store_short v[96:97], v0, off offset:32
	v_lshlrev_b32_e32 v0, 16, v101
	v_lshlrev_b32_e32 v58, 16, v133
	v_fmac_f32_e32 v58, v54, v0
	v_cvt_pk_bf16_f32 v0, v58, s0
	global_store_short v[96:97], v0, off offset:64
	v_lshlrev_b32_e32 v0, 16, v102
	v_lshlrev_b32_e32 v54, 16, v134
	v_fmac_f32_e32 v54, v50, v0
	v_cvt_pk_bf16_f32 v0, v54, s0
	global_store_short v[96:97], v0, off offset:96
	v_lshlrev_b32_e32 v0, 16, v135
	v_lshlrev_b32_e32 v50, 16, v105
	v_fmac_f32_e32 v50, v63, v0
	v_cvt_pk_bf16_f32 v0, v50, s0
	global_store_short v[94:95], v0, off
	v_lshlrev_b32_e32 v0, 16, v136
	v_lshlrev_b32_e32 v50, 16, v138
	v_fmac_f32_e32 v50, v59, v0
	v_cvt_pk_bf16_f32 v0, v50, s0
	global_store_short v[94:95], v0, off offset:32
	v_lshlrev_b32_e32 v0, 16, v137
	v_lshlrev_b32_e32 v50, 16, v139
	v_fmac_f32_e32 v50, v55, v0
	v_cvt_pk_bf16_f32 v0, v50, s0
	global_store_short v[94:95], v0, off offset:64
	v_lshlrev_b32_e32 v0, 16, v104
	v_lshlrev_b32_e32 v50, 16, v140
	v_fmac_f32_e32 v50, v51, v0
	v_cvt_pk_bf16_f32 v0, v50, s0
	global_store_short v[94:95], v0, off offset:96
	v_lshlrev_b32_e32 v0, 16, v141
	v_lshlrev_b32_e32 v50, 16, v107
	v_fmac_f32_e32 v50, v64, v0
	v_cvt_pk_bf16_f32 v0, v50, s0
	global_store_short v[92:93], v0, off
	v_lshlrev_b32_e32 v0, 16, v142
	v_lshlrev_b32_e32 v50, 16, v144
	v_fmac_f32_e32 v50, v60, v0
	v_cvt_pk_bf16_f32 v0, v50, s0
	global_store_short v[92:93], v0, off offset:32
	v_lshlrev_b32_e32 v0, 16, v143
	v_lshlrev_b32_e32 v50, 16, v145
	v_fmac_f32_e32 v50, v56, v0
	v_cvt_pk_bf16_f32 v0, v50, s0
	global_store_short v[92:93], v0, off offset:64
	v_lshlrev_b32_e32 v0, 16, v106
	v_lshlrev_b32_e32 v50, 16, v146
	v_fmac_f32_e32 v50, v52, v0
	v_cvt_pk_bf16_f32 v0, v50, s0
	global_store_short v[92:93], v0, off offset:96
	v_lshlrev_b32_e32 v0, 16, v147
	v_lshlrev_b32_e32 v50, 16, v109
	v_fmac_f32_e32 v50, v65, v0
	v_cvt_pk_bf16_f32 v0, v50, s0
	global_store_short v[90:91], v0, off
	v_lshlrev_b32_e32 v0, 16, v148
	v_lshlrev_b32_e32 v50, 16, v150
	v_fmac_f32_e32 v50, v61, v0
	v_cvt_pk_bf16_f32 v0, v50, s0
	global_store_short v[90:91], v0, off offset:32
	v_lshlrev_b32_e32 v0, 16, v149
	v_lshlrev_b32_e32 v50, 16, v151
	v_fmac_f32_e32 v50, v57, v0
	v_cvt_pk_bf16_f32 v0, v50, s0
	global_store_short v[90:91], v0, off offset:64
	v_lshlrev_b32_e32 v0, 16, v108
	v_lshlrev_b32_e32 v50, 16, v152
	v_fmac_f32_e32 v50, v53, v0
	v_cvt_pk_bf16_f32 v0, v50, s0
	global_store_short v[90:91], v0, off offset:96
	v_lshlrev_b32_e32 v0, 16, v153
	v_lshlrev_b32_e32 v50, 16, v111
	v_fmac_f32_e32 v50, v46, v0
	v_cvt_pk_bf16_f32 v0, v50, s0
	global_store_short v[88:89], v0, off
	v_lshlrev_b32_e32 v0, 16, v161
	v_lshlrev_b32_e32 v46, 16, v163
	v_fmac_f32_e32 v46, v42, v0
	v_cvt_pk_bf16_f32 v0, v46, s0
	global_store_short v[88:89], v0, off offset:32
	v_lshlrev_b32_e32 v0, 16, v162
	v_lshlrev_b32_e32 v42, 16, v164
	v_fmac_f32_e32 v42, v38, v0
	v_cvt_pk_bf16_f32 v0, v42, s0
	global_store_short v[88:89], v0, off offset:64
	v_lshlrev_b32_e32 v0, 16, v110
	v_lshlrev_b32_e32 v38, 16, v165
	v_fmac_f32_e32 v38, v34, v0
	v_cvt_pk_bf16_f32 v0, v38, s0
	global_store_short v[88:89], v0, off offset:96
	v_lshlrev_b32_e32 v0, 16, v166
	v_lshlrev_b32_e32 v34, 16, v113
	v_fmac_f32_e32 v34, v47, v0
	v_cvt_pk_bf16_f32 v0, v34, s0
	global_store_short v[86:87], v0, off
	v_lshlrev_b32_e32 v0, 16, v167
	v_lshlrev_b32_e32 v34, 16, v169
	v_fmac_f32_e32 v34, v43, v0
	v_cvt_pk_bf16_f32 v0, v34, s0
	global_store_short v[86:87], v0, off offset:32
	v_lshlrev_b32_e32 v0, 16, v168
	v_lshlrev_b32_e32 v34, 16, v170
	v_fmac_f32_e32 v34, v39, v0
	v_cvt_pk_bf16_f32 v0, v34, s0
	global_store_short v[86:87], v0, off offset:64
	v_lshlrev_b32_e32 v0, 16, v112
	v_lshlrev_b32_e32 v34, 16, v171
	v_fmac_f32_e32 v34, v35, v0
	v_cvt_pk_bf16_f32 v0, v34, s0
	global_store_short v[86:87], v0, off offset:96
	v_lshlrev_b32_e32 v0, 16, v172
	v_lshlrev_b32_e32 v34, 16, v115
	v_fmac_f32_e32 v34, v48, v0
	v_cvt_pk_bf16_f32 v0, v34, s0
	global_store_short v[84:85], v0, off
	v_lshlrev_b32_e32 v0, 16, v173
	v_lshlrev_b32_e32 v34, 16, v175
	v_fmac_f32_e32 v34, v44, v0
	v_cvt_pk_bf16_f32 v0, v34, s0
	global_store_short v[84:85], v0, off offset:32
	v_lshlrev_b32_e32 v0, 16, v174
	v_lshlrev_b32_e32 v34, 16, v176
	v_fmac_f32_e32 v34, v40, v0
	v_cvt_pk_bf16_f32 v0, v34, s0
	global_store_short v[84:85], v0, off offset:64
	v_lshlrev_b32_e32 v0, 16, v114
	v_lshlrev_b32_e32 v34, 16, v177
	v_fmac_f32_e32 v34, v36, v0
	v_cvt_pk_bf16_f32 v0, v34, s0
	global_store_short v[84:85], v0, off offset:96
	v_lshlrev_b32_e32 v0, 16, v178
	v_lshlrev_b32_e32 v34, 16, v117
	v_fmac_f32_e32 v34, v49, v0
	v_cvt_pk_bf16_f32 v0, v34, s0
	global_store_short v[82:83], v0, off
	v_lshlrev_b32_e32 v0, 16, v179
	v_lshlrev_b32_e32 v34, 16, v181
	v_fmac_f32_e32 v34, v45, v0
	v_cvt_pk_bf16_f32 v0, v34, s0
	global_store_short v[82:83], v0, off offset:32
	v_lshlrev_b32_e32 v0, 16, v180
	v_lshlrev_b32_e32 v34, 16, v182
	v_fmac_f32_e32 v34, v41, v0
	v_cvt_pk_bf16_f32 v0, v34, s0
	global_store_short v[82:83], v0, off offset:64
	v_lshlrev_b32_e32 v0, 16, v116
	v_lshlrev_b32_e32 v34, 16, v183
	v_fmac_f32_e32 v34, v37, v0
	v_cvt_pk_bf16_f32 v0, v34, s0
	global_store_short v[82:83], v0, off offset:96
	v_lshlrev_b32_e32 v0, 16, v184
	s_waitcnt vmcnt(62)
; DEV float bf2f(u16 h) { return __uint_as_float(((unsigned)h) << 16); }
; template <int EPI, bool AF32>
; DEV void gemm_tile(const void* Ap, int lda, const u16* Bt, int ldb, int K, int m0, int n0, const Epi& ea, char* smem) {
;     ...
; #pragma unroll
;       for (int m = 0; m < 4; m++)
; #pragma unroll
;         for (int j = 0; j < 4; j++)
; #pragma unroll
;           for (int n = 0; n < 4; n++) {
;             float v = bf2f(gv[m][j][n]) * acc[m][n][j];
;             if (EPI == EP_MERGE2) v += bf2f(cv[m][j][n]);
;             C[(size_t)(rbase + m * 16 + j) * 1024 + cbase + n * 16] = f2bf(v);
;           }
	v_lshlrev_b32_e32 v34, 16, v119
	v_fmac_f32_e32 v34, v30, v0
	v_cvt_pk_bf16_f32 v0, v34, s0
	global_store_short v[80:81], v0, off
	v_lshlrev_b32_e32 v0, 16, v185
	v_lshlrev_b32_e32 v30, 16, v187
	v_fmac_f32_e32 v30, v26, v0
	v_cvt_pk_bf16_f32 v0, v30, s0
	global_store_short v[80:81], v0, off offset:32
	v_lshlrev_b32_e32 v0, 16, v186
	v_lshlrev_b32_e32 v26, 16, v188
	v_fmac_f32_e32 v26, v22, v0
	v_cvt_pk_bf16_f32 v0, v26, s0
	global_store_short v[80:81], v0, off offset:64
	v_lshlrev_b32_e32 v0, 16, v118
	v_lshlrev_b32_e32 v22, 16, v189
	v_fmac_f32_e32 v22, v18, v0
	v_cvt_pk_bf16_f32 v0, v22, s0
	global_store_short v[80:81], v0, off offset:96
	v_lshlrev_b32_e32 v0, 16, v190
	v_lshlrev_b32_e32 v18, 16, v121
	v_fmac_f32_e32 v18, v31, v0
	v_cvt_pk_bf16_f32 v0, v18, s0
	global_store_short v[78:79], v0, off
	v_lshlrev_b32_e32 v0, 16, v191
	v_lshlrev_b32_e32 v18, 16, v193
	v_fmac_f32_e32 v18, v27, v0
	v_cvt_pk_bf16_f32 v0, v18, s0
	global_store_short v[78:79], v0, off offset:32
	v_lshlrev_b32_e32 v0, 16, v192
	v_lshlrev_b32_e32 v18, 16, v194
	v_fmac_f32_e32 v18, v23, v0
	v_cvt_pk_bf16_f32 v0, v18, s0
	global_store_short v[78:79], v0, off offset:64
	v_lshlrev_b32_e32 v0, 16, v120
	v_lshlrev_b32_e32 v18, 16, v195
	v_fmac_f32_e32 v18, v19, v0
	v_cvt_pk_bf16_f32 v0, v18, s0
	global_store_short v[78:79], v0, off offset:96
	v_lshlrev_b32_e32 v0, 16, v196
	v_lshlrev_b32_e32 v18, 16, v123
	v_fmac_f32_e32 v18, v32, v0
	v_cvt_pk_bf16_f32 v0, v18, s0
	global_store_short v[76:77], v0, off
	v_lshlrev_b32_e32 v0, 16, v197
	v_lshlrev_b32_e32 v18, 16, v222
	v_fmac_f32_e32 v18, v28, v0
	v_cvt_pk_bf16_f32 v0, v18, s0
	global_store_short v[76:77], v0, off offset:32
	v_lshlrev_b32_e32 v0, 16, v221
	v_lshlrev_b32_e32 v18, 16, v223
	v_fmac_f32_e32 v18, v24, v0
	v_cvt_pk_bf16_f32 v0, v18, s0
	global_store_short v[76:77], v0, off offset:64
	v_lshlrev_b32_e32 v0, 16, v122
	v_lshlrev_b32_e32 v18, 16, v224
	v_fmac_f32_e32 v18, v20, v0
	v_cvt_pk_bf16_f32 v0, v18, s0
	global_store_short v[76:77], v0, off offset:96
	v_lshlrev_b32_e32 v0, 16, v225
	v_lshlrev_b32_e32 v18, 16, v125
	v_fmac_f32_e32 v18, v33, v0
	v_cvt_pk_bf16_f32 v0, v18, s0
	global_store_short v[74:75], v0, off
	v_lshlrev_b32_e32 v0, 16, v226
	v_lshlrev_b32_e32 v18, 16, v228
	v_fmac_f32_e32 v18, v29, v0
	v_cvt_pk_bf16_f32 v0, v18, s0
	global_store_short v[74:75], v0, off offset:32
	v_lshlrev_b32_e32 v0, 16, v227
	v_lshlrev_b32_e32 v18, 16, v229
	v_fmac_f32_e32 v18, v25, v0
	v_cvt_pk_bf16_f32 v0, v18, s0
	global_store_short v[74:75], v0, off offset:64
	v_lshlrev_b32_e32 v0, 16, v124
	v_lshlrev_b32_e32 v18, 16, v230
	v_fmac_f32_e32 v18, v21, v0
	v_cvt_pk_bf16_f32 v0, v18, s0
	global_store_short v[74:75], v0, off offset:96
	v_lshlrev_b32_e32 v0, 16, v231
	s_waitcnt vmcnt(62)
	v_lshlrev_b32_e32 v18, 16, v127
	v_fmac_f32_e32 v18, v14, v0
	v_cvt_pk_bf16_f32 v0, v18, s0
	global_store_short v[72:73], v0, off
	v_lshlrev_b32_e32 v0, 16, v232
	v_lshlrev_b32_e32 v14, 16, v234
	v_fmac_f32_e32 v14, v10, v0
	v_cvt_pk_bf16_f32 v0, v14, s0
	global_store_short v[72:73], v0, off offset:32
	v_lshlrev_b32_e32 v0, 16, v233
	v_lshlrev_b32_e32 v10, 16, v235
	v_fmac_f32_e32 v10, v6, v0
	v_cvt_pk_bf16_f32 v0, v10, s0
	global_store_short v[72:73], v0, off offset:64
	v_lshlrev_b32_e32 v0, 16, v126
	v_lshlrev_b32_e32 v6, 16, v236
	v_fmac_f32_e32 v6, v2, v0
	v_cvt_pk_bf16_f32 v0, v6, s0
	global_store_short v[72:73], v0, off offset:96
	v_lshlrev_b32_e32 v0, 16, v237
	v_lshlrev_b32_e32 v2, 16, v129
	v_fmac_f32_e32 v2, v15, v0
	v_cvt_pk_bf16_f32 v0, v2, s0
	global_store_short v[70:71], v0, off
	v_lshlrev_b32_e32 v0, 16, v238
	v_lshlrev_b32_e32 v2, 16, v240
	v_fmac_f32_e32 v2, v11, v0
	v_cvt_pk_bf16_f32 v0, v2, s0
	global_store_short v[70:71], v0, off offset:32
	v_lshlrev_b32_e32 v0, 16, v239
	v_lshlrev_b32_e32 v2, 16, v241
	v_fmac_f32_e32 v2, v7, v0
	v_cvt_pk_bf16_f32 v0, v2, s0
	global_store_short v[70:71], v0, off offset:64
	v_lshlrev_b32_e32 v0, 16, v128
	v_lshlrev_b32_e32 v2, 16, v242
	v_fmac_f32_e32 v2, v3, v0
	v_cvt_pk_bf16_f32 v0, v2, s0
	global_store_short v[70:71], v0, off offset:96
	v_lshlrev_b32_e32 v0, 16, v243
	s_waitcnt vmcnt(62)
	v_lshlrev_b32_e32 v2, 16, v131
	v_fmac_f32_e32 v2, v16, v0
	v_cvt_pk_bf16_f32 v0, v2, s0
	global_store_short v[68:69], v0, off
	v_lshlrev_b32_e32 v0, 16, v244
	v_lshlrev_b32_e32 v2, 16, v246
	v_fmac_f32_e32 v2, v12, v0
	v_cvt_pk_bf16_f32 v0, v2, s0
	global_store_short v[68:69], v0, off offset:32
	v_lshlrev_b32_e32 v0, 16, v245
	v_lshlrev_b32_e32 v2, 16, v247
	v_fmac_f32_e32 v2, v8, v0
	v_cvt_pk_bf16_f32 v0, v2, s0
	global_store_short v[68:69], v0, off offset:64
	v_lshlrev_b32_e32 v0, 16, v130
	v_lshlrev_b32_e32 v2, 16, v248
	v_fmac_f32_e32 v2, v4, v0
	v_cvt_pk_bf16_f32 v0, v2, s0
	global_store_short v[68:69], v0, off offset:96
	v_lshlrev_b32_e32 v0, 16, v249
	s_waitcnt vmcnt(62)
	v_lshlrev_b32_e32 v2, 16, v99
	v_fmac_f32_e32 v2, v17, v0
	v_cvt_pk_bf16_f32 v0, v2, s0
	global_store_short v[66:67], v0, off
	v_lshlrev_b32_e32 v0, 16, v250
	v_lshlrev_b32_e32 v2, 16, v252
	v_fmac_f32_e32 v2, v13, v0
	v_cvt_pk_bf16_f32 v0, v2, s0
	global_store_short v[66:67], v0, off offset:32
	v_lshlrev_b32_e32 v0, 16, v251
	s_waitcnt vmcnt(62)
	v_lshlrev_b32_e32 v2, 16, v253
	v_fmac_f32_e32 v2, v9, v0
	v_cvt_pk_bf16_f32 v0, v2, s0
	global_store_short v[66:67], v0, off offset:64
	v_lshlrev_b32_e32 v0, 16, v98
	v_lshlrev_b32_e32 v2, 16, v201
	v_fmac_f32_e32 v2, v5, v0
	v_cvt_pk_bf16_f32 v0, v2, s0
	v_readfirstlane_b32 s0, v198
	global_store_short v[66:67], v0, off offset:96
	s_add_i32 s14, s0, s14
	s_cmpk_lt_i32 s14, 0x820
	s_cbranch_scc1 .LBB0_1309
	v_mov_b32_e32 v201, 0x2723000

; template <int EPI, bool AF32>
; DEV void gemm_tile(const void* Ap, int lda, const u16* Bt, int ldb, int K, int m0, int n0, const Epi& ea, char* smem) {
;     ...
;   auto gload = [&](int kt) {
;     const int k0 = kt << 6;
; #pragma unroll
;     for (int i = 0; i < 4; i++) {
;       const int c = tid + i * 256, row = c >> 3, kc = c & 7;
;       if (AF32) {
;         const float* pa = (const float*)Ap + (size_t)(m0 + row) * lda + k0 + kc * 8;
;         rfa[2 * i] = *(const f32x4*)pa;
;         rfa[2 * i + 1] = *(const f32x4*)(pa + 4);
;       } else {
;         ra[i] = *(const u32x4*)((const u16*)Ap + (size_t)(m0 + row) * lda + k0 + kc * 8);
;       }
;       rb[i] = *(const u32x4*)(Bt + (size_t)(n0 + row) * ldb + k0 + kc * 8);
;     }
;   };
;   auto swrite = [&](int buf) {
; #pragma unroll
;     for (int i = 0; i < 4; i++) {
;       const int c = tid + i * 256, row = c >> 3, kc = c & 7;
;       u32x4 va;
;       if (AF32) {
;         va = (u32x4){pack2(rfa[2 * i][0], rfa[2 * i][1]), pack2(rfa[2 * i][2], rfa[2 * i][3]),
;                      pack2(rfa[2 * i + 1][0], rfa[2 * i + 1][1]), pack2(rfa[2 * i + 1][2], rfa[2 * i + 1][3])};
;       } else {
;         va = ra[i];
;       }
;       *(u32x4*)(sA + buf * 9216 + row * 72 + kc * 8) = va;
;       *(u32x4*)(sB + buf * 9216 + row * 72 + kc * 8) = rb[i];
;     }
;   };
;   gload(0);
;   swrite(0);
;   if (nk > 1) gload(1);
;   __syncthreads();
.LBB0_1352:
	s_ashr_i32 s10, s12, 31
	s_lshr_b32 s10, s10, 24
	s_add_i32 s10, s12, s10
	s_ashr_i32 s11, s10, 8
	s_and_b32 s10, s10, 0xffffff00
	s_lshl_b32 s14, s11, 5
	s_sub_i32 s13, s12, s10
	s_sub_i32 s10, 0x104, s14
	s_min_u32 s15, s10, 32
	v_cvt_f32_ubyte0_e32 v2, s15
	v_cvt_f32_i32_e32 v0, s13
	v_rcp_iflag_f32_e32 v3, v2
	s_ashr_i32 s10, s13, 30
	s_or_b32 s16, s10, 1
	s_waitcnt vmcnt(12)
	v_mov_b32_e32 v114, v157
	v_mul_f32_e32 v3, v0, v3
	v_trunc_f32_e32 v3, v3
	v_fma_f32 v0, -v3, v2, v0
	v_cvt_i32_f32_e32 v3, v3
	v_cmp_ge_f32_e64 s[10:11], |v0|, v2
	s_and_b64 s[10:11], s[10:11], exec
	s_cselect_b32 s10, s16, 0
	v_readfirstlane_b32 s11, v3
	s_add_i32 s10, s11, s10
	s_sext_i32_i16 s11, s10
	s_mul_i32 s10, s10, s15
	s_sub_i32 s10, s13, s10
	s_sext_i32_i16 s10, s10
	s_add_i32 s14, s14, s10
	s_lshl_b32 s14, s14, 7
	s_lshl_b32 s13, s11, 7
	v_ashrrev_i32_e32 v8, 3, v114
	v_add_u32_e32 v2, s14, v8
	v_ashrrev_i32_e32 v3, 31, v2
	v_lshlrev_b32_e32 v0, 3, v114
	v_add_u32_e32 v4, 0x100, v114
	v_lshlrev_b64 v[58:59], 11, v[2:3]
	v_and_b32_e32 v0, 56, v0
	v_ashrrev_i32_e32 v9, 3, v4
	v_lshl_add_u64 v[2:3], s[0:1], 0, v[58:59]
	v_lshlrev_b32_e32 v0, 1, v0
	v_add_u32_e32 v4, s14, v9
	v_add_u32_e32 v6, 0x200, v114
	v_lshl_add_u64 v[14:15], v[2:3], 0, v[0:1]
	v_add_u32_e32 v2, s13, v8
	v_ashrrev_i32_e32 v5, 31, v4
	v_ashrrev_i32_e32 v10, 3, v6
	v_ashrrev_i32_e32 v3, 31, v2
	v_lshlrev_b64 v[62:63], 11, v[4:5]
	v_add_u32_e32 v6, s14, v10
	v_lshlrev_b64 v[60:61], 11, v[2:3]
	v_lshl_add_u64 v[4:5], s[0:1], 0, v[62:63]
	v_ashrrev_i32_e32 v7, 31, v6
	v_lshl_add_u64 v[2:3], s[4:5], 0, v[60:61]
	v_lshl_add_u64 v[16:17], v[4:5], 0, v[0:1]
	v_add_u32_e32 v4, s13, v9
	v_lshlrev_b64 v[66:67], 11, v[6:7]
	v_lshl_add_u64 v[2:3], v[2:3], 0, v[0:1]
	v_ashrrev_i32_e32 v5, 31, v4
	v_lshl_add_u64 v[6:7], s[0:1], 0, v[66:67]
	global_load_dwordx4 v[30:33], v[2:3], off
	v_lshlrev_b64 v[64:65], 11, v[4:5]
	v_lshl_add_u64 v[68:69], v[6:7], 0, v[0:1]
	v_add_u32_e32 v6, s13, v10
	global_load_dwordx4 v[26:29], v[14:15], off
	global_load_dwordx4 v[34:37], v[16:17], off
	v_lshl_add_u64 v[4:5], s[4:5], 0, v[64:65]
	v_ashrrev_i32_e32 v7, 31, v6
	v_lshl_add_u64 v[4:5], v[4:5], 0, v[0:1]
	v_lshlrev_b64 v[70:71], 11, v[6:7]
	global_load_dwordx4 v[38:41], v[4:5], off
	v_lshl_add_u64 v[6:7], s[4:5], 0, v[70:71]
	global_load_dwordx4 v[42:45], v[68:69], off
	v_lshl_add_u64 v[18:19], v[6:7], 0, v[0:1]
	global_load_dwordx4 v[46:49], v[18:19], off
	v_add_u32_e32 v6, 0x300, v114
	v_ashrrev_i32_e32 v80, 3, v6
	v_add_u32_e32 v6, s14, v80
	v_ashrrev_i32_e32 v7, 31, v6
	v_lshlrev_b64 v[72:73], 11, v[6:7]
	v_lshl_add_u64 v[6:7], s[0:1], 0, v[72:73]
	v_lshl_add_u64 v[74:75], v[6:7], 0, v[0:1]
	v_add_u32_e32 v6, s13, v80
	v_ashrrev_i32_e32 v7, 31, v6
	v_lshlrev_b64 v[76:77], 11, v[6:7]
	v_lshl_add_u64 v[6:7], s[4:5], 0, v[76:77]
	v_lshl_add_u64 v[78:79], v[6:7], 0, v[0:1]
	global_load_dwordx4 v[50:53], v[74:75], off
	global_load_dwordx4 v[54:57], v[78:79], off
	s_waitcnt vmcnt(19)
	v_mul_lo_u32 v118, v8, s71
	v_mul_lo_u32 v119, v9, s71
	s_waitcnt vmcnt(18)
	v_mul_lo_u32 v123, v10, s71
	global_load_dwordx4 v[6:9], v[2:3], off offset:128
	global_load_dwordx4 v[10:13], v[4:5], off offset:128
	s_nop 0
	global_load_dwordx4 v[2:5], v[18:19], off offset:128
	global_load_dwordx4 v[22:25], v[14:15], off offset:128
	s_nop 0
	global_load_dwordx4 v[18:21], v[16:17], off offset:128
	s_nop 0
	global_load_dwordx4 v[14:17], v[68:69], off offset:128
	v_bfe_u32 v161, v157, 3, 4
	v_add_u32_e32 v161, 4, v161
	v_lshlrev_b32_e32 v161, 1, v161
	v_and_b32_e32 v161, 16, v161
	v_xor_b32_e32 v129, v0, v161
	v_lshl_add_u32 v122, v118, 1, v129
	v_lshl_add_u32 v121, v119, 1, v129
	v_lshl_add_u32 v120, v123, 1, v129
	v_and_b32_e32 v115, 15, v114
	s_waitcnt vmcnt(23)
	v_mul_lo_u32 v126, v80, s71
	v_bfe_u32 v116, v114, 4, 2
	v_lshl_add_u32 v124, v126, 1, v129
	s_mov_b32 s15, 0
	v_lshlrev_b32_e32 v125, 4, v116
	v_and_b32_e32 v161, 15, v157
	v_add_u32_e32 v161, 4, v161
	v_lshlrev_b32_e32 v161, 1, v161
	v_and_b32_e32 v161, 16, v161
	v_xor_b32_e32 v125, v125, v161
	s_mov_b64 s[10:11], 0
	s_waitcnt vmcnt(13)
	ds_write_b128 v122, v[30:33] offset:36864
	s_waitcnt vmcnt(12)
	ds_write_b128 v122, v[26:29]
	s_waitcnt vmcnt(11)
	ds_write_b128 v121, v[34:37]
	s_waitcnt vmcnt(10)
	ds_write_b128 v121, v[38:41] offset:36864
	s_waitcnt vmcnt(9)
	ds_write_b128 v120, v[42:45]
	s_waitcnt vmcnt(8)
	ds_write_b128 v120, v[46:49] offset:36864
	global_load_dwordx4 v[26:29], v[74:75], off offset:128
	global_load_dwordx4 v[30:33], v[78:79], off offset:128
	v_ashrrev_i32_e32 v34, 1, v114
	v_and_b32_e32 v117, 0xffffffc0, v34
	v_or_b32_e32 v34, v117, v115
	v_mul_lo_u32 v128, v34, s71
	v_lshlrev_b32_e32 v34, 4, v114
	v_and_b32_e32 v34, 0x70, v34
	v_and_b32_e32 v35, 0x4f, v114
	v_or_b32_e32 v76, v76, v34
	v_or_b32_e32 v72, v72, v34
	v_or_b32_e32 v70, v70, v34
	v_or_b32_e32 v66, v66, v34
	v_or_b32_e32 v64, v64, v34
	v_or_b32_e32 v62, v62, v34
	v_or_b32_e32 v60, v60, v34
	v_or_b32_e32 v58, v58, v34
	v_mov_b32_e32 v34, 0
	s_waitcnt vmcnt(9)
	ds_write_b128 v124, v[50:53]
	s_waitcnt vmcnt(8)
; DEV f32x4 mfma16(bf16x8 a, bf16x8 b, f32x4 c) { return __builtin_amdgcn_mfma_f32_16x16x32_bf16(a, b, c, 0, 0, 0); }
; template <int EPI, bool AF32>
; DEV void gemm_tile(const void* Ap, int lda, const u16* Bt, int ldb, int K, int m0, int n0, const Epi& ea, char* smem) {
;     ...
;   auto gload = [&](int kt) {
;     const int k0 = kt << 6;
; #pragma unroll
;     for (int i = 0; i < 4; i++) {
;       const int c = tid + i * 256, row = c >> 3, kc = c & 7;
;       if (AF32) {
;         const float* pa = (const float*)Ap + (size_t)(m0 + row) * lda + k0 + kc * 8;
;         rfa[2 * i] = *(const f32x4*)pa;
;         rfa[2 * i + 1] = *(const f32x4*)(pa + 4);
;       } else {
;         ra[i] = *(const u32x4*)((const u16*)Ap + (size_t)(m0 + row) * lda + k0 + kc * 8);
;       }
;       rb[i] = *(const u32x4*)(Bt + (size_t)(n0 + row) * ldb + k0 + kc * 8);
;     }
;   };
;   auto swrite = [&](int buf) {
; #pragma unroll
;     for (int i = 0; i < 4; i++) {
;       const int c = tid + i * 256, row = c >> 3, kc = c & 7;
;       u32x4 va;
;       if (AF32) {
;         va = (u32x4){pack2(rfa[2 * i][0], rfa[2 * i][1]), pack2(rfa[2 * i][2], rfa[2 * i][3]),
;                      pack2(rfa[2 * i + 1][0], rfa[2 * i + 1][1]), pack2(rfa[2 * i + 1][2], rfa[2 * i + 1][3])};
;       } else {
;         va = ra[i];
;       }
;       *(u32x4*)(sA + buf * 9216 + row * 72 + kc * 8) = va;
;       *(u32x4*)(sB + buf * 9216 + row * 72 + kc * 8) = rb[i];
;     }
;   };
;   gload(0);
;   swrite(0);
;   if (nk > 1) gload(1);
;   __syncthreads();
;   for (int kt = 0; kt < nk; kt++) {
;     const int buf = kt & 1;
;     if (kt + 1 < nk) swrite(buf ^ 1);
;     if (kt + 2 < nk) gload(kt + 2);
; #pragma unroll
;     for (int ks = 0; ks < 2; ks++) {
;       bf16x8 a[4], b[4];
; #pragma unroll
;       for (int m = 0; m < 4; m++) a[m] = *(const bf16x8*)(sA + buf * 9216 + (wr * 64 + m * 16 + fr) * 72 + ks * 32 + fq * 8);
; #pragma unroll
;       for (int n = 0; n < 4; n++) b[n] = *(const bf16x8*)(sB + buf * 9216 + (wc * 64 + n * 16 + fr) * 72 + ks * 32 + fq * 8);
;       __builtin_amdgcn_s_setprio(1);
; #pragma unroll
;       for (int m = 0; m < 4; m++)
; #pragma unroll
;         for (int n = 0; n < 4; n++) acc[m][n] = mfma16(a[m], b[n], acc[m][n]);
;       __builtin_amdgcn_s_setprio(0);
;     }
;     __syncthreads();
	ds_write_b128 v124, v[54:57] offset:36864
	v_mul_u32_u24_e32 v127, 0x48, v35
	v_lshl_add_u64 v[98:99], s[6:7], 0, v[76:77]
	v_lshl_add_u64 v[100:101], s[8:9], 0, v[72:73]
	v_lshl_add_u64 v[102:103], s[6:7], 0, v[70:71]
	v_lshl_add_u64 v[104:105], s[8:9], 0, v[66:67]
	v_lshl_add_u64 v[106:107], s[6:7], 0, v[64:65]
	v_lshl_add_u64 v[108:109], s[8:9], 0, v[62:63]
	v_lshl_add_u64 v[110:111], s[6:7], 0, v[60:61]
	v_lshl_add_u64 v[112:113], s[8:9], 0, v[58:59]
	global_load_dwordx4 v[222:225], v[112:113], off
	global_load_dwordx4 v[226:229], v[110:111], off
	global_load_dwordx4 v[230:233], v[108:109], off
	global_load_dwordx4 v[234:237], v[106:107], off
	global_load_dwordx4 v[238:241], v[104:105], off
	global_load_dwordx4 v[242:245], v[102:103], off
	global_load_dwordx4 v[246:249], v[100:101], off
	global_load_dwordx4 v[250:253], v[98:99], off
	v_mov_b32_e32 v35, v34
	v_mov_b32_e32 v36, v34
	v_mov_b32_e32 v37, v34
	v_mov_b32_e32 v38, v34
	v_mov_b32_e32 v39, v34
	v_mov_b32_e32 v40, v34
	v_mov_b32_e32 v41, v34
	v_mov_b32_e32 v42, v34
	v_mov_b32_e32 v43, v34
	v_mov_b32_e32 v44, v34
	v_mov_b32_e32 v45, v34
	v_mov_b32_e32 v46, v34
	v_mov_b32_e32 v47, v34
	v_mov_b32_e32 v48, v34
	v_mov_b32_e32 v49, v34
	v_mov_b32_e32 v50, v34
	v_mov_b32_e32 v51, v34
	v_mov_b32_e32 v52, v34
	v_mov_b32_e32 v53, v34
	v_mov_b32_e32 v54, v34
	v_mov_b32_e32 v55, v34
	v_mov_b32_e32 v56, v34
	v_mov_b32_e32 v57, v34
	v_mov_b32_e32 v58, v34
	v_mov_b32_e32 v59, v34
	v_mov_b32_e32 v60, v34
	v_mov_b32_e32 v61, v34
	v_mov_b32_e32 v62, v34
	v_mov_b32_e32 v63, v34
	v_mov_b32_e32 v64, v34
	v_mov_b32_e32 v65, v34
	v_mov_b32_e32 v66, v34
	v_mov_b32_e32 v67, v34
	v_mov_b32_e32 v68, v34
	v_mov_b32_e32 v69, v34
	v_mov_b32_e32 v70, v34
	v_mov_b32_e32 v71, v34
	v_mov_b32_e32 v72, v34
	v_mov_b32_e32 v73, v34
	v_mov_b32_e32 v74, v34
	v_mov_b32_e32 v75, v34
	v_mov_b32_e32 v76, v34
	v_mov_b32_e32 v77, v34
	v_mov_b32_e32 v78, v34
	v_mov_b32_e32 v79, v34
	v_mov_b32_e32 v80, v34
	v_mov_b32_e32 v81, v34
	v_mov_b32_e32 v82, v34
	v_mov_b32_e32 v83, v34
	v_mov_b32_e32 v84, v34
	v_mov_b32_e32 v85, v34
	v_mov_b32_e32 v86, v34
	v_mov_b32_e32 v87, v34
	v_mov_b32_e32 v88, v34
	v_mov_b32_e32 v89, v34
	v_mov_b32_e32 v90, v34
	v_mov_b32_e32 v91, v34
	v_mov_b32_e32 v92, v34
	v_mov_b32_e32 v93, v34
	v_mov_b32_e32 v94, v34
	v_mov_b32_e32 v95, v34
	v_mov_b32_e32 v96, v34
	v_mov_b32_e32 v97, v34
	s_waitcnt lgkmcnt(0)
	s_barrier
	v_lshl_add_u32 v161, v128, 1, v125
	v_lshl_add_u32 v129, v127, 1, v125
	s_mov_b32 s15, 0
	s_mov_b64 s[10:11], 0x100
.Lgk5_loop:
	v_lshl_add_u64 v[112:113], v[112:113], 0, s[10:11]
	v_lshl_add_u64 v[110:111], v[110:111], 0, s[10:11]
	v_lshl_add_u64 v[108:109], v[108:109], 0, s[10:11]
	v_lshl_add_u64 v[106:107], v[106:107], 0, s[10:11]
	v_lshl_add_u64 v[104:105], v[104:105], 0, s[10:11]
	v_lshl_add_u64 v[102:103], v[102:103], 0, s[10:11]
	v_lshl_add_u64 v[100:101], v[100:101], 0, s[10:11]
	v_lshl_add_u64 v[98:99], v[98:99], 0, s[10:11]
	ds_read_b128 v[130:133], v161
	ds_read_b128 v[134:137], v161 offset:2304
	ds_read_b128 v[138:141], v161 offset:4608
	ds_read_b128 v[142:145], v161 offset:6912
	ds_read_b128 v[146:149], v129 offset:36864
	ds_read_b128 v[150:153], v129 offset:39168
	ds_read_b128 v[162:165], v129 offset:41472
	ds_read_b128 v[166:169], v129 offset:43776
	s_setprio 1
	s_waitcnt lgkmcnt(3)
	v_mfma_f32_16x16x32_bf16 v[34:37], v[130:133], v[146:149], v[34:37]
	s_waitcnt lgkmcnt(2)
	v_mfma_f32_16x16x32_bf16 v[38:41], v[130:133], v[150:153], v[38:41]
	s_waitcnt lgkmcnt(1)
	v_mfma_f32_16x16x32_bf16 v[42:45], v[130:133], v[162:165], v[42:45]
	s_waitcnt lgkmcnt(0)
	v_mfma_f32_16x16x32_bf16 v[46:49], v[130:133], v[166:169], v[46:49]
	v_mfma_f32_16x16x32_bf16 v[50:53], v[134:137], v[146:149], v[50:53]
	v_mfma_f32_16x16x32_bf16 v[54:57], v[134:137], v[150:153], v[54:57]
	v_mfma_f32_16x16x32_bf16 v[58:61], v[134:137], v[162:165], v[58:61]
	v_mfma_f32_16x16x32_bf16 v[62:65], v[134:137], v[166:169], v[62:65]
	v_mfma_f32_16x16x32_bf16 v[66:69], v[138:141], v[146:149], v[66:69]
	v_mfma_f32_16x16x32_bf16 v[70:73], v[138:141], v[150:153], v[70:73]
	v_mfma_f32_16x16x32_bf16 v[74:77], v[138:141], v[162:165], v[74:77]
	v_mfma_f32_16x16x32_bf16 v[78:81], v[138:141], v[166:169], v[78:81]
	v_mfma_f32_16x16x32_bf16 v[82:85], v[142:145], v[146:149], v[82:85]
	v_mfma_f32_16x16x32_bf16 v[86:89], v[142:145], v[150:153], v[86:89]
	v_mfma_f32_16x16x32_bf16 v[90:93], v[142:145], v[162:165], v[90:93]
	v_mfma_f32_16x16x32_bf16 v[94:97], v[142:145], v[166:169], v[94:97]
	s_setprio 0
	ds_read_b128 v[130:133], v161 offset:64
	ds_read_b128 v[134:137], v161 offset:2368
	ds_read_b128 v[138:141], v161 offset:4672
	ds_read_b128 v[142:145], v161 offset:6976
	ds_read_b128 v[146:149], v129 offset:36928
	ds_read_b128 v[150:153], v129 offset:39232
	ds_read_b128 v[162:165], v129 offset:41536
	ds_read_b128 v[166:169], v129 offset:43840
	s_waitcnt vmcnt(8)
	ds_write_b128 v122, v[22:25] offset:18432
	ds_write_b128 v122, v[6:9] offset:55296
	ds_write_b128 v121, v[18:21] offset:18432
	ds_write_b128 v121, v[10:13] offset:55296
	ds_write_b128 v120, v[14:17] offset:18432
	ds_write_b128 v120, v[2:5] offset:55296
	ds_write_b128 v124, v[26:29] offset:18432
	ds_write_b128 v124, v[30:33] offset:55296
	global_load_dwordx4 v[22:25], v[112:113], off offset:-128
	global_load_dwordx4 v[6:9], v[110:111], off offset:-128
	global_load_dwordx4 v[18:21], v[108:109], off offset:-128
	global_load_dwordx4 v[10:13], v[106:107], off offset:-128
	global_load_dwordx4 v[14:17], v[104:105], off offset:-128
	global_load_dwordx4 v[2:5], v[102:103], off offset:-128
	global_load_dwordx4 v[26:29], v[100:101], off offset:-128
	global_load_dwordx4 v[30:33], v[98:99], off offset:-128
	s_setprio 1
	s_waitcnt lgkmcnt(11)
	v_mfma_f32_16x16x32_bf16 v[34:37], v[130:133], v[146:149], v[34:37]
	s_waitcnt lgkmcnt(10)
	v_mfma_f32_16x16x32_bf16 v[38:41], v[130:133], v[150:153], v[38:41]
	s_waitcnt lgkmcnt(9)
	v_mfma_f32_16x16x32_bf16 v[42:45], v[130:133], v[162:165], v[42:45]
	s_waitcnt lgkmcnt(8)
	v_mfma_f32_16x16x32_bf16 v[46:49], v[130:133], v[166:169], v[46:49]
	v_mfma_f32_16x16x32_bf16 v[50:53], v[134:137], v[146:149], v[50:53]
	v_mfma_f32_16x16x32_bf16 v[54:57], v[134:137], v[150:153], v[54:57]
	v_mfma_f32_16x16x32_bf16 v[58:61], v[134:137], v[162:165], v[58:61]
	v_mfma_f32_16x16x32_bf16 v[62:65], v[134:137], v[166:169], v[62:65]
	v_mfma_f32_16x16x32_bf16 v[66:69], v[138:141], v[146:149], v[66:69]
	v_mfma_f32_16x16x32_bf16 v[70:73], v[138:141], v[150:153], v[70:73]
	v_mfma_f32_16x16x32_bf16 v[74:77], v[138:141], v[162:165], v[74:77]
	v_mfma_f32_16x16x32_bf16 v[78:81], v[138:141], v[166:169], v[78:81]
	v_mfma_f32_16x16x32_bf16 v[82:85], v[142:145], v[146:149], v[82:85]
	v_mfma_f32_16x16x32_bf16 v[86:89], v[142:145], v[150:153], v[86:89]
	v_mfma_f32_16x16x32_bf16 v[90:93], v[142:145], v[162:165], v[90:93]
	v_mfma_f32_16x16x32_bf16 v[94:97], v[142:145], v[166:169], v[94:97]
	s_setprio 0
	s_waitcnt lgkmcnt(0)
	s_barrier
; DEV f32x4 mfma16(bf16x8 a, bf16x8 b, f32x4 c) { return __builtin_amdgcn_mfma_f32_16x16x32_bf16(a, b, c, 0, 0, 0); }
; template <int EPI, bool AF32>
; DEV void gemm_tile(const void* Ap, int lda, const u16* Bt, int ldb, int K, int m0, int n0, const Epi& ea, char* smem) {
;     ...
;   auto gload = [&](int kt) {
;     const int k0 = kt << 6;
; #pragma unroll
;     for (int i = 0; i < 4; i++) {
;       const int c = tid + i * 256, row = c >> 3, kc = c & 7;
;       if (AF32) {
;         const float* pa = (const float*)Ap + (size_t)(m0 + row) * lda + k0 + kc * 8;
;         rfa[2 * i] = *(const f32x4*)pa;
;         rfa[2 * i + 1] = *(const f32x4*)(pa + 4);
;       } else {
;         ra[i] = *(const u32x4*)((const u16*)Ap + (size_t)(m0 + row) * lda + k0 + kc * 8);
;       }
;       rb[i] = *(const u32x4*)(Bt + (size_t)(n0 + row) * ldb + k0 + kc * 8);
;     }
;   };
;   auto swrite = [&](int buf) {
; #pragma unroll
;     for (int i = 0; i < 4; i++) {
;       const int c = tid + i * 256, row = c >> 3, kc = c & 7;
;       u32x4 va;
;       if (AF32) {
;         va = (u32x4){pack2(rfa[2 * i][0], rfa[2 * i][1]), pack2(rfa[2 * i][2], rfa[2 * i][3]),
;                      pack2(rfa[2 * i + 1][0], rfa[2 * i + 1][1]), pack2(rfa[2 * i + 1][2], rfa[2 * i + 1][3])};
;       } else {
;         va = ra[i];
;       }
;       *(u32x4*)(sA + buf * 9216 + row * 72 + kc * 8) = va;
;       *(u32x4*)(sB + buf * 9216 + row * 72 + kc * 8) = rb[i];
;     }
;   };
;   gload(0);
;   swrite(0);
;   if (nk > 1) gload(1);
;   __syncthreads();
;   for (int kt = 0; kt < nk; kt++) {
;     const int buf = kt & 1;
;     if (kt + 1 < nk) swrite(buf ^ 1);
;     if (kt + 2 < nk) gload(kt + 2);
; #pragma unroll
;     for (int ks = 0; ks < 2; ks++) {
;       bf16x8 a[4], b[4];
; #pragma unroll
;       for (int m = 0; m < 4; m++) a[m] = *(const bf16x8*)(sA + buf * 9216 + (wr * 64 + m * 16 + fr) * 72 + ks * 32 + fq * 8);
; #pragma unroll
;       for (int n = 0; n < 4; n++) b[n] = *(const bf16x8*)(sB + buf * 9216 + (wc * 64 + n * 16 + fr) * 72 + ks * 32 + fq * 8);
;       __builtin_amdgcn_s_setprio(1);
; #pragma unroll
;       for (int m = 0; m < 4; m++)
; #pragma unroll
;         for (int n = 0; n < 4; n++) acc[m][n] = mfma16(a[m], b[n], acc[m][n]);
;       __builtin_amdgcn_s_setprio(0);
;     }
;     __syncthreads();
	ds_read_b128 v[130:133], v161 offset:18432
	ds_read_b128 v[134:137], v161 offset:20736
	ds_read_b128 v[138:141], v161 offset:23040
	ds_read_b128 v[142:145], v161 offset:25344
	ds_read_b128 v[146:149], v129 offset:55296
	ds_read_b128 v[150:153], v129 offset:57600
	ds_read_b128 v[162:165], v129 offset:59904
	ds_read_b128 v[166:169], v129 offset:62208
	s_setprio 1
	s_waitcnt lgkmcnt(3)
	v_mfma_f32_16x16x32_bf16 v[34:37], v[130:133], v[146:149], v[34:37]
	s_waitcnt lgkmcnt(2)
	v_mfma_f32_16x16x32_bf16 v[38:41], v[130:133], v[150:153], v[38:41]
	s_waitcnt lgkmcnt(1)
	v_mfma_f32_16x16x32_bf16 v[42:45], v[130:133], v[162:165], v[42:45]
	s_waitcnt lgkmcnt(0)
	v_mfma_f32_16x16x32_bf16 v[46:49], v[130:133], v[166:169], v[46:49]
	v_mfma_f32_16x16x32_bf16 v[50:53], v[134:137], v[146:149], v[50:53]
	v_mfma_f32_16x16x32_bf16 v[54:57], v[134:137], v[150:153], v[54:57]
	v_mfma_f32_16x16x32_bf16 v[58:61], v[134:137], v[162:165], v[58:61]
	v_mfma_f32_16x16x32_bf16 v[62:65], v[134:137], v[166:169], v[62:65]
	v_mfma_f32_16x16x32_bf16 v[66:69], v[138:141], v[146:149], v[66:69]
	v_mfma_f32_16x16x32_bf16 v[70:73], v[138:141], v[150:153], v[70:73]
	v_mfma_f32_16x16x32_bf16 v[74:77], v[138:141], v[162:165], v[74:77]
	v_mfma_f32_16x16x32_bf16 v[78:81], v[138:141], v[166:169], v[78:81]
	v_mfma_f32_16x16x32_bf16 v[82:85], v[142:145], v[146:149], v[82:85]
	v_mfma_f32_16x16x32_bf16 v[86:89], v[142:145], v[150:153], v[86:89]
	v_mfma_f32_16x16x32_bf16 v[90:93], v[142:145], v[162:165], v[90:93]
	v_mfma_f32_16x16x32_bf16 v[94:97], v[142:145], v[166:169], v[94:97]
	s_setprio 0
	ds_read_b128 v[130:133], v161 offset:18496
	ds_read_b128 v[134:137], v161 offset:20800
	ds_read_b128 v[138:141], v161 offset:23104
	ds_read_b128 v[142:145], v161 offset:25408
	ds_read_b128 v[146:149], v129 offset:55360
	ds_read_b128 v[150:153], v129 offset:57664
	ds_read_b128 v[162:165], v129 offset:59968
	ds_read_b128 v[166:169], v129 offset:62272
	s_waitcnt vmcnt(8)
	ds_write_b128 v122, v[222:225]
	ds_write_b128 v122, v[226:229] offset:36864
	ds_write_b128 v121, v[230:233]
	ds_write_b128 v121, v[234:237] offset:36864
	ds_write_b128 v120, v[238:241]
	ds_write_b128 v120, v[242:245] offset:36864
	ds_write_b128 v124, v[246:249]
	ds_write_b128 v124, v[250:253] offset:36864
	s_cmp_eq_u32 s15, 6
	s_cbranch_scc1 .Lgk5_nold
	global_load_dwordx4 v[222:225], v[112:113], off
	global_load_dwordx4 v[226:229], v[110:111], off
	global_load_dwordx4 v[230:233], v[108:109], off
	global_load_dwordx4 v[234:237], v[106:107], off
	global_load_dwordx4 v[238:241], v[104:105], off
	global_load_dwordx4 v[242:245], v[102:103], off
	global_load_dwordx4 v[246:249], v[100:101], off
	global_load_dwordx4 v[250:253], v[98:99], off
.Lgk5_nold:
	s_setprio 1
	s_waitcnt lgkmcnt(11)
	v_mfma_f32_16x16x32_bf16 v[34:37], v[130:133], v[146:149], v[34:37]
	s_waitcnt lgkmcnt(10)
	v_mfma_f32_16x16x32_bf16 v[38:41], v[130:133], v[150:153], v[38:41]
	s_waitcnt lgkmcnt(9)
	v_mfma_f32_16x16x32_bf16 v[42:45], v[130:133], v[162:165], v[42:45]
	s_waitcnt lgkmcnt(8)
	v_mfma_f32_16x16x32_bf16 v[46:49], v[130:133], v[166:169], v[46:49]
	v_mfma_f32_16x16x32_bf16 v[50:53], v[134:137], v[146:149], v[50:53]
	v_mfma_f32_16x16x32_bf16 v[54:57], v[134:137], v[150:153], v[54:57]
	v_mfma_f32_16x16x32_bf16 v[58:61], v[134:137], v[162:165], v[58:61]
	v_mfma_f32_16x16x32_bf16 v[62:65], v[134:137], v[166:169], v[62:65]
	v_mfma_f32_16x16x32_bf16 v[66:69], v[138:141], v[146:149], v[66:69]
	v_mfma_f32_16x16x32_bf16 v[70:73], v[138:141], v[150:153], v[70:73]
	v_mfma_f32_16x16x32_bf16 v[74:77], v[138:141], v[162:165], v[74:77]
	v_mfma_f32_16x16x32_bf16 v[78:81], v[138:141], v[166:169], v[78:81]
	v_mfma_f32_16x16x32_bf16 v[82:85], v[142:145], v[146:149], v[82:85]
	v_mfma_f32_16x16x32_bf16 v[86:89], v[142:145], v[150:153], v[86:89]
	v_mfma_f32_16x16x32_bf16 v[90:93], v[142:145], v[162:165], v[90:93]
	v_mfma_f32_16x16x32_bf16 v[94:97], v[142:145], v[166:169], v[94:97]
	s_setprio 0
	s_add_i32 s15, s15, 1
	s_cmp_lg_u32 s15, 7
	s_waitcnt lgkmcnt(0)
	s_barrier
	s_cbranch_scc1 .Lgk5_loop
	s_waitcnt vmcnt(7)
	ds_write_b128 v122, v[22:25] offset:18432
	s_waitcnt vmcnt(6)
	ds_write_b128 v122, v[6:9] offset:55296
	s_waitcnt vmcnt(5)
	ds_write_b128 v121, v[18:21] offset:18432
	s_waitcnt vmcnt(4)
	ds_write_b128 v121, v[10:13] offset:55296
	s_waitcnt vmcnt(3)
	ds_write_b128 v120, v[14:17] offset:18432
	s_waitcnt vmcnt(2)
	ds_write_b128 v120, v[2:5] offset:55296
	s_waitcnt vmcnt(1)
	ds_write_b128 v124, v[26:29] offset:18432
	s_waitcnt vmcnt(0)
	ds_write_b128 v124, v[30:33] offset:55296
	v_lshl_add_u32 v0, v128, 1, v125
	v_lshl_add_u32 v106, v127, 1, v125
	ds_read_b128 v[2:5], v0
	ds_read_b128 v[6:9], v0 offset:2304
	ds_read_b128 v[10:13], v0 offset:4608
	ds_read_b128 v[14:17], v0 offset:6912
	ds_read_b128 v[18:21], v106 offset:36864
	ds_read_b128 v[22:25], v106 offset:39168
	ds_read_b128 v[26:29], v106 offset:41472
	ds_read_b128 v[30:33], v106 offset:43776
	s_setprio 1
	s_waitcnt lgkmcnt(3)
	v_mfma_f32_16x16x32_bf16 v[34:37], v[2:5], v[18:21], v[34:37]
	s_waitcnt lgkmcnt(2)
	v_mfma_f32_16x16x32_bf16 v[38:41], v[2:5], v[22:25], v[38:41]
	s_waitcnt lgkmcnt(1)
	v_mfma_f32_16x16x32_bf16 v[42:45], v[2:5], v[26:29], v[42:45]
	s_waitcnt lgkmcnt(0)
; DEV f32x4 mfma16(bf16x8 a, bf16x8 b, f32x4 c) { return __builtin_amdgcn_mfma_f32_16x16x32_bf16(a, b, c, 0, 0, 0); }
; template <int EPI, bool AF32>
; DEV void gemm_tile(const void* Ap, int lda, const u16* Bt, int ldb, int K, int m0, int n0, const Epi& ea, char* smem) {
;     ...
; #pragma unroll
;     for (int ks = 0; ks < 2; ks++) {
;       bf16x8 a[4], b[4];
; #pragma unroll
;       for (int m = 0; m < 4; m++) a[m] = *(const bf16x8*)(sA + buf * 9216 + (wr * 64 + m * 16 + fr) * 72 + ks * 32 + fq * 8);
; #pragma unroll
;       for (int n = 0; n < 4; n++) b[n] = *(const bf16x8*)(sB + buf * 9216 + (wc * 64 + n * 16 + fr) * 72 + ks * 32 + fq * 8);
;       __builtin_amdgcn_s_setprio(1);
; #pragma unroll
;       for (int m = 0; m < 4; m++)
; #pragma unroll
;         for (int n = 0; n < 4; n++) acc[m][n] = mfma16(a[m], b[n], acc[m][n]);
;       __builtin_amdgcn_s_setprio(0);
;     }
;     __syncthreads();
	v_mfma_f32_16x16x32_bf16 v[2:5], v[2:5], v[30:33], v[46:49]
	v_mfma_f32_16x16x32_bf16 v[46:49], v[6:9], v[18:21], v[50:53]
	v_mfma_f32_16x16x32_bf16 v[50:53], v[6:9], v[22:25], v[54:57]
	v_mfma_f32_16x16x32_bf16 v[54:57], v[6:9], v[26:29], v[58:61]
	v_mfma_f32_16x16x32_bf16 v[6:9], v[6:9], v[30:33], v[62:65]
	v_mfma_f32_16x16x32_bf16 v[58:61], v[10:13], v[18:21], v[66:69]
	v_mfma_f32_16x16x32_bf16 v[62:65], v[10:13], v[22:25], v[70:73]
	v_mfma_f32_16x16x32_bf16 v[66:69], v[10:13], v[26:29], v[74:77]
	v_mfma_f32_16x16x32_bf16 v[10:13], v[10:13], v[30:33], v[78:81]
	v_mfma_f32_16x16x32_bf16 v[18:21], v[14:17], v[18:21], v[82:85]
	v_mfma_f32_16x16x32_bf16 v[22:25], v[14:17], v[22:25], v[86:89]
	v_mfma_f32_16x16x32_bf16 v[26:29], v[14:17], v[26:29], v[90:93]
	v_mfma_f32_16x16x32_bf16 v[14:17], v[14:17], v[30:33], v[94:97]
	s_setprio 0
	ds_read_b128 v[30:33], v0 offset:64
	ds_read_b128 v[70:73], v0 offset:2368
	ds_read_b128 v[74:77], v0 offset:4672
	ds_read_b128 v[78:81], v0 offset:6976
	ds_read_b128 v[82:85], v106 offset:36928
	ds_read_b128 v[86:89], v106 offset:39232
	ds_read_b128 v[90:93], v106 offset:41536
	ds_read_b128 v[94:97], v106 offset:43840
	s_setprio 1
	s_waitcnt lgkmcnt(3)
	v_mfma_f32_16x16x32_bf16 v[34:37], v[30:33], v[82:85], v[34:37]
	s_waitcnt lgkmcnt(2)
	v_mfma_f32_16x16x32_bf16 v[38:41], v[30:33], v[86:89], v[38:41]
	s_waitcnt lgkmcnt(1)
	v_mfma_f32_16x16x32_bf16 v[42:45], v[30:33], v[90:93], v[42:45]
	s_waitcnt lgkmcnt(0)
	v_mfma_f32_16x16x32_bf16 v[2:5], v[30:33], v[94:97], v[2:5]
	v_mfma_f32_16x16x32_bf16 v[30:33], v[70:73], v[82:85], v[46:49]
	v_mfma_f32_16x16x32_bf16 v[46:49], v[70:73], v[86:89], v[50:53]
	v_mfma_f32_16x16x32_bf16 v[50:53], v[70:73], v[90:93], v[54:57]
	v_mfma_f32_16x16x32_bf16 v[6:9], v[70:73], v[94:97], v[6:9]
	v_mfma_f32_16x16x32_bf16 v[54:57], v[74:77], v[82:85], v[58:61]
	v_mfma_f32_16x16x32_bf16 v[58:61], v[74:77], v[86:89], v[62:65]
	v_mfma_f32_16x16x32_bf16 v[62:65], v[74:77], v[90:93], v[66:69]
	v_mfma_f32_16x16x32_bf16 v[10:13], v[74:77], v[94:97], v[10:13]
	v_mfma_f32_16x16x32_bf16 v[18:21], v[78:81], v[82:85], v[18:21]
	v_mfma_f32_16x16x32_bf16 v[22:25], v[78:81], v[86:89], v[22:25]
	v_mfma_f32_16x16x32_bf16 v[26:29], v[78:81], v[90:93], v[26:29]
	v_mfma_f32_16x16x32_bf16 v[14:17], v[78:81], v[94:97], v[14:17]
	s_setprio 0
	s_barrier
	ds_read_b128 v[66:69], v0 offset:18432
	ds_read_b128 v[70:73], v0 offset:20736
	ds_read_b128 v[74:77], v0 offset:23040
	ds_read_b128 v[78:81], v0 offset:25344
	ds_read_b128 v[82:85], v106 offset:55296
	ds_read_b128 v[86:89], v106 offset:57600
	ds_read_b128 v[90:93], v106 offset:59904
	ds_read_b128 v[94:97], v106 offset:62208
	v_and_b32_e32 v114, 64, v114
	s_setprio 1
	s_waitcnt lgkmcnt(3)
	v_mfma_f32_16x16x32_bf16 v[34:37], v[66:69], v[82:85], v[34:37]
	s_waitcnt lgkmcnt(2)
	v_mfma_f32_16x16x32_bf16 v[38:41], v[66:69], v[86:89], v[38:41]
	s_waitcnt lgkmcnt(1)
	v_mfma_f32_16x16x32_bf16 v[42:45], v[66:69], v[90:93], v[42:45]
	s_waitcnt lgkmcnt(0)
	v_mfma_f32_16x16x32_bf16 v[2:5], v[66:69], v[94:97], v[2:5]
	v_mfma_f32_16x16x32_bf16 v[30:33], v[70:73], v[82:85], v[30:33]
	v_mfma_f32_16x16x32_bf16 v[66:69], v[70:73], v[86:89], v[46:49]
	v_mfma_f32_16x16x32_bf16 v[50:53], v[70:73], v[90:93], v[50:53]
	v_mfma_f32_16x16x32_bf16 v[6:9], v[70:73], v[94:97], v[6:9]
	v_mfma_f32_16x16x32_bf16 v[54:57], v[74:77], v[82:85], v[54:57]
	v_mfma_f32_16x16x32_bf16 v[58:61], v[74:77], v[86:89], v[58:61]
	v_mfma_f32_16x16x32_bf16 v[62:65], v[74:77], v[90:93], v[62:65]
	v_mfma_f32_16x16x32_bf16 v[10:13], v[74:77], v[94:97], v[10:13]
	v_mfma_f32_16x16x32_bf16 v[70:73], v[78:81], v[82:85], v[18:21]
	v_mfma_f32_16x16x32_bf16 v[74:77], v[78:81], v[86:89], v[22:25]
	v_mfma_f32_16x16x32_bf16 v[82:85], v[78:81], v[90:93], v[26:29]
	v_mfma_f32_16x16x32_bf16 v[78:81], v[78:81], v[94:97], v[14:17]
	s_setprio 0
	s_nop 1
	ds_read_b128 v[14:17], v0 offset:18496
	ds_read_b128 v[18:21], v0 offset:20800
	ds_read_b128 v[86:89], v0 offset:23104
	ds_read_b128 v[90:93], v0 offset:25408
	ds_read_b128 v[94:97], v106 offset:55360
	ds_read_b128 v[98:101], v106 offset:57664
	ds_read_b128 v[102:105], v106 offset:59968
	ds_read_b128 v[106:109], v106 offset:62272
	s_setprio 1
	s_waitcnt lgkmcnt(3)
	v_mfma_f32_16x16x32_bf16 v[110:113], v[14:17], v[94:97], v[34:37]
	s_waitcnt lgkmcnt(2)
	v_mfma_f32_16x16x32_bf16 v[118:121], v[14:17], v[98:101], v[38:41]
	s_waitcnt lgkmcnt(1)
	v_mfma_f32_16x16x32_bf16 v[122:125], v[14:17], v[102:105], v[42:45]
	s_waitcnt lgkmcnt(0)
; DEV f32x4 mfma16(bf16x8 a, bf16x8 b, f32x4 c) { return __builtin_amdgcn_mfma_f32_16x16x32_bf16(a, b, c, 0, 0, 0); }
; template <int EPI, bool AF32>
; DEV void gemm_tile(const void* Ap, int lda, const u16* Bt, int ldb, int K, int m0, int n0, const Epi& ea, char* smem) {
;     ...
; #pragma unroll
;     for (int ks = 0; ks < 2; ks++) {
;       bf16x8 a[4], b[4];
; #pragma unroll
;       for (int m = 0; m < 4; m++) a[m] = *(const bf16x8*)(sA + buf * 9216 + (wr * 64 + m * 16 + fr) * 72 + ks * 32 + fq * 8);
; #pragma unroll
;       for (int n = 0; n < 4; n++) b[n] = *(const bf16x8*)(sB + buf * 9216 + (wc * 64 + n * 16 + fr) * 72 + ks * 32 + fq * 8);
;       __builtin_amdgcn_s_setprio(1);
; #pragma unroll
;       for (int m = 0; m < 4; m++)
; #pragma unroll
;         for (int n = 0; n < 4; n++) acc[m][n] = mfma16(a[m], b[n], acc[m][n]);
;       __builtin_amdgcn_s_setprio(0);
;     }
;     __syncthreads();
;     ...
;   if (EPI == EP_RESB) {
;     const int rbase = m0 + wr * 64 + fq * 4, cbase = cb + fr;
;     float* C = (float*)ea.p0;
;     const u16* R = (const u16*)ea.p1;
;     u16 rv[4][4][4];
; #pragma unroll
;     for (int m = 0; m < 4; m++)
; #pragma unroll
;       for (int j = 0; j < 4; j++)
; #pragma unroll
;         for (int n = 0; n < 4; n++) rv[m][j][n] = R[(size_t)(rbase + m * 16 + j) * 1024 + cbase + n * 16];
;     __builtin_amdgcn_sched_barrier(0);
	v_mfma_f32_16x16x32_bf16 v[126:129], v[14:17], v[106:109], v[2:5]
	v_mfma_f32_16x16x32_bf16 v[46:49], v[18:21], v[94:97], v[30:33]
	v_mfma_f32_16x16x32_bf16 v[42:45], v[18:21], v[98:101], v[66:69]
	v_mfma_f32_16x16x32_bf16 v[38:41], v[18:21], v[102:105], v[50:53]
	v_mfma_f32_16x16x32_bf16 v[34:37], v[18:21], v[106:109], v[6:9]
	v_mfma_f32_16x16x32_bf16 v[30:33], v[86:89], v[94:97], v[54:57]
	v_mfma_f32_16x16x32_bf16 v[26:29], v[86:89], v[98:101], v[58:61]
	v_mfma_f32_16x16x32_bf16 v[22:25], v[86:89], v[102:105], v[62:65]
	v_mfma_f32_16x16x32_bf16 v[18:21], v[86:89], v[106:109], v[10:13]
	v_mfma_f32_16x16x32_bf16 v[14:17], v[90:93], v[94:97], v[70:73]
	v_mfma_f32_16x16x32_bf16 v[10:13], v[90:93], v[98:101], v[74:77]
	v_mfma_f32_16x16x32_bf16 v[6:9], v[90:93], v[102:105], v[82:85]
	v_mfma_f32_16x16x32_bf16 v[2:5], v[90:93], v[106:109], v[78:81]
	s_setprio 0
	v_add_u32_e32 v0, s14, v117
	v_lshl_or_b32 v60, v116, 2, v0
	v_or3_b32 v62, v114, s13, v115
	v_ashrrev_i32_e32 v63, 31, v62
	v_ashrrev_i32_e32 v61, 31, v60
	v_or_b32_e32 v68, 1, v60
	v_lshl_add_u64 v[64:65], v[62:63], 1, s[60:61]
	v_lshlrev_b64 v[50:51], 11, v[60:61]
	v_ashrrev_i32_e32 v69, 31, v68
	v_or_b32_e32 v72, 2, v60
	v_lshl_add_u64 v[66:67], v[64:65], 0, v[50:51]
	v_lshlrev_b64 v[50:51], 11, v[68:69]
	v_ashrrev_i32_e32 v73, 31, v72
	v_or_b32_e32 v76, 3, v60
	v_lshl_add_u64 v[70:71], v[64:65], 0, v[50:51]
	v_lshlrev_b64 v[50:51], 11, v[72:73]
	v_ashrrev_i32_e32 v77, 31, v76
	v_or_b32_e32 v80, 16, v60
	v_lshl_add_u64 v[74:75], v[64:65], 0, v[50:51]
	v_lshlrev_b64 v[50:51], 11, v[76:77]
	v_ashrrev_i32_e32 v81, 31, v80
	v_or_b32_e32 v84, 17, v60
	v_lshl_add_u64 v[78:79], v[64:65], 0, v[50:51]
	v_lshlrev_b64 v[50:51], 11, v[80:81]
	v_ashrrev_i32_e32 v85, 31, v84
	v_or_b32_e32 v88, 18, v60
	v_lshl_add_u64 v[82:83], v[64:65], 0, v[50:51]
	v_lshlrev_b64 v[50:51], 11, v[84:85]
	v_ashrrev_i32_e32 v89, 31, v88
	v_or_b32_e32 v92, 19, v60
	v_lshl_add_u64 v[86:87], v[64:65], 0, v[50:51]
	v_lshlrev_b64 v[50:51], 11, v[88:89]
	v_ashrrev_i32_e32 v93, 31, v92
	v_or_b32_e32 v96, 32, v60
	v_lshl_add_u64 v[90:91], v[64:65], 0, v[50:51]
	v_lshlrev_b64 v[50:51], 11, v[92:93]
	v_ashrrev_i32_e32 v97, 31, v96
	v_or_b32_e32 v100, 33, v60
	v_lshl_add_u64 v[94:95], v[64:65], 0, v[50:51]
	v_lshlrev_b64 v[50:51], 11, v[96:97]
	v_ashrrev_i32_e32 v101, 31, v100
	v_or_b32_e32 v104, 34, v60
	v_lshl_add_u64 v[98:99], v[64:65], 0, v[50:51]
	v_lshlrev_b64 v[50:51], 11, v[100:101]
	v_ashrrev_i32_e32 v105, 31, v104
	v_or_b32_e32 v58, 35, v60
	v_lshl_add_u64 v[102:103], v[64:65], 0, v[50:51]
	v_lshlrev_b64 v[50:51], 11, v[104:105]
	v_ashrrev_i32_e32 v59, 31, v58
	v_or_b32_e32 v56, 48, v60
	v_lshl_add_u64 v[106:107], v[64:65], 0, v[50:51]
	v_lshlrev_b64 v[50:51], 11, v[58:59]
	v_ashrrev_i32_e32 v57, 31, v56
	v_or_b32_e32 v54, 49, v60
	v_lshl_add_u64 v[108:109], v[64:65], 0, v[50:51]
	v_lshlrev_b64 v[50:51], 11, v[56:57]
	v_ashrrev_i32_e32 v55, 31, v54
	v_or_b32_e32 v52, 50, v60
	v_lshl_add_u64 v[114:115], v[64:65], 0, v[50:51]
	v_lshlrev_b64 v[50:51], 11, v[54:55]
	v_ashrrev_i32_e32 v53, 31, v52
	v_lshl_add_u64 v[116:117], v[64:65], 0, v[50:51]
	v_lshlrev_b64 v[50:51], 11, v[52:53]
	v_lshl_add_u64 v[130:131], v[64:65], 0, v[50:51]
	v_or_b32_e32 v50, 51, v60
	v_ashrrev_i32_e32 v51, 31, v50
	v_lshlrev_b64 v[132:133], 11, v[50:51]
	v_lshl_add_u64 v[64:65], v[64:65], 0, v[132:133]
	s_barrier
	global_load_ushort v0, v[66:67], off
	global_load_ushort v132, v[66:67], off offset:32
	global_load_ushort v133, v[66:67], off offset:64
	s_nop 0
	global_load_ushort v66, v[66:67], off offset:96
	s_nop 0
	global_load_ushort v67, v[70:71], off
	global_load_ushort v134, v[70:71], off offset:32
	global_load_ushort v135, v[70:71], off offset:64
	s_nop 0
	global_load_ushort v70, v[70:71], off offset:96
	s_nop 0
	global_load_ushort v71, v[74:75], off
	global_load_ushort v136, v[74:75], off offset:32
	global_load_ushort v137, v[74:75], off offset:64
	s_nop 0
	global_load_ushort v74, v[74:75], off offset:96
	s_nop 0
	global_load_ushort v75, v[78:79], off
	global_load_ushort v138, v[78:79], off offset:32
	global_load_ushort v139, v[78:79], off offset:64
	s_nop 0
	global_load_ushort v78, v[78:79], off offset:96
	s_nop 0
	global_load_ushort v79, v[82:83], off
	global_load_ushort v140, v[82:83], off offset:32
	global_load_ushort v141, v[82:83], off offset:64
	s_nop 0
	global_load_ushort v82, v[82:83], off offset:96
	s_nop 0
	global_load_ushort v83, v[86:87], off
	global_load_ushort v142, v[86:87], off offset:32
	global_load_ushort v143, v[86:87], off offset:64
	s_nop 0
	global_load_ushort v86, v[86:87], off offset:96
	s_nop 0
	global_load_ushort v87, v[90:91], off
	global_load_ushort v144, v[90:91], off offset:32
	global_load_ushort v145, v[90:91], off offset:64
	s_nop 0
	global_load_ushort v90, v[90:91], off offset:96
	s_nop 0
	global_load_ushort v91, v[94:95], off
	global_load_ushort v146, v[94:95], off offset:32
	global_load_ushort v147, v[94:95], off offset:64
	s_nop 0
	global_load_ushort v94, v[94:95], off offset:96
	s_nop 0
	global_load_ushort v95, v[98:99], off
	global_load_ushort v148, v[98:99], off offset:32
	global_load_ushort v149, v[98:99], off offset:64
	s_nop 0
	global_load_ushort v98, v[98:99], off offset:96
	s_nop 0
	global_load_ushort v99, v[102:103], off
	global_load_ushort v150, v[102:103], off offset:32
	global_load_ushort v151, v[102:103], off offset:64
	s_nop 0
	global_load_ushort v102, v[102:103], off offset:96
	s_nop 0
	global_load_ushort v103, v[106:107], off
	global_load_ushort v152, v[106:107], off offset:32
	global_load_ushort v153, v[106:107], off offset:64
	s_nop 0
	global_load_ushort v106, v[106:107], off offset:96
	s_nop 0
	global_load_ushort v107, v[108:109], off
	global_load_ushort v161, v[108:109], off offset:32
	global_load_ushort v162, v[108:109], off offset:64
	s_nop 0
	global_load_ushort v108, v[108:109], off offset:96
	s_nop 0
	global_load_ushort v109, v[114:115], off
	global_load_ushort v163, v[114:115], off offset:32
	global_load_ushort v164, v[114:115], off offset:64
	s_nop 0
	global_load_ushort v114, v[114:115], off offset:96
	s_nop 0
	global_load_ushort v115, v[116:117], off
	global_load_ushort v165, v[116:117], off offset:32
	global_load_ushort v166, v[116:117], off offset:64
	s_nop 0
	global_load_ushort v116, v[116:117], off offset:96
	s_nop 0
	global_load_ushort v117, v[130:131], off
	global_load_ushort v167, v[130:131], off offset:32
	global_load_ushort v168, v[130:131], off offset:64
	s_nop 0
	global_load_ushort v130, v[130:131], off offset:96
	s_nop 0
	global_load_ushort v131, v[64:65], off
	global_load_ushort v169, v[64:65], off offset:32
	global_load_ushort v170, v[64:65], off offset:64
	s_nop 0
	global_load_ushort v64, v[64:65], off offset:96
	v_lshl_add_u64 v[62:63], v[62:63], 2, s[2:3]
	v_lshlrev_b64 v[60:61], 12, v[60:61]
	s_waitcnt vmcnt(62)
; DEV float bf2f(u16 h) { return __uint_as_float(((unsigned)h) << 16); }
; template <int EPI, bool AF32>
; DEV void gemm_tile(const void* Ap, int lda, const u16* Bt, int ldb, int K, int m0, int n0, const Epi& ea, char* smem) {
;     ...
; #pragma unroll
;     for (int m = 0; m < 4; m++)
; #pragma unroll
;       for (int j = 0; j < 4; j++)
; #pragma unroll
;         for (int n = 0; n < 4; n++)
;           C[(size_t)(rbase + m * 16 + j) * 1024 + cbase + n * 16] = ALPHA_ * bf2f(rv[m][j][n]) + acc[m][n][j];
;     return;
	v_lshlrev_b32_e32 v0, 16, v0
	v_lshl_add_u64 v[60:61], v[62:63], 0, v[60:61]
	v_fmamk_f32 v0, v0, 0x3fb504f3, v110
	global_store_dword v[60:61], v0, off
	v_lshlrev_b32_e32 v0, 16, v132
	v_fmamk_f32 v0, v0, 0x3fb504f3, v118
	global_store_dword v[60:61], v0, off offset:64
	s_waitcnt vmcnt(62)
	v_lshlrev_b32_e32 v0, 16, v133
	v_fmamk_f32 v0, v0, 0x3fb504f3, v122
	global_store_dword v[60:61], v0, off offset:128
	v_lshlrev_b32_e32 v0, 16, v66
	v_fmamk_f32 v0, v0, 0x3fb504f3, v126
	global_store_dword v[60:61], v0, off offset:192
	v_lshlrev_b64 v[60:61], 12, v[68:69]
	s_waitcnt vmcnt(62)
	v_lshlrev_b32_e32 v0, 16, v67
	v_lshl_add_u64 v[60:61], v[62:63], 0, v[60:61]
	v_fmamk_f32 v0, v0, 0x3fb504f3, v111
	global_store_dword v[60:61], v0, off
	v_lshlrev_b32_e32 v0, 16, v134
	v_fmamk_f32 v0, v0, 0x3fb504f3, v119
	global_store_dword v[60:61], v0, off offset:64
	s_waitcnt vmcnt(62)
	v_lshlrev_b32_e32 v0, 16, v135
	v_fmamk_f32 v0, v0, 0x3fb504f3, v123
	global_store_dword v[60:61], v0, off offset:128
	v_lshlrev_b32_e32 v0, 16, v70
	v_fmamk_f32 v0, v0, 0x3fb504f3, v127
	global_store_dword v[60:61], v0, off offset:192
	v_lshlrev_b64 v[60:61], 12, v[72:73]
	s_waitcnt vmcnt(62)
	v_lshlrev_b32_e32 v0, 16, v71
	v_lshl_add_u64 v[60:61], v[62:63], 0, v[60:61]
	v_fmamk_f32 v0, v0, 0x3fb504f3, v112
	global_store_dword v[60:61], v0, off
	v_lshlrev_b32_e32 v0, 16, v136
	v_fmamk_f32 v0, v0, 0x3fb504f3, v120
	global_store_dword v[60:61], v0, off offset:64
	s_waitcnt vmcnt(62)
	v_lshlrev_b32_e32 v0, 16, v137
	v_fmamk_f32 v0, v0, 0x3fb504f3, v124
	global_store_dword v[60:61], v0, off offset:128
	v_lshlrev_b32_e32 v0, 16, v74
	v_fmamk_f32 v0, v0, 0x3fb504f3, v128
	global_store_dword v[60:61], v0, off offset:192
	s_waitcnt vmcnt(62)
	v_lshlrev_b32_e32 v0, 16, v75
	v_fmac_f32_e32 v113, 0x3fb504f3, v0
	v_lshlrev_b32_e32 v0, 16, v138
	v_fmac_f32_e32 v121, 0x3fb504f3, v0
	s_waitcnt vmcnt(61)
	v_lshlrev_b32_e32 v0, 16, v139
	v_lshlrev_b64 v[60:61], 12, v[76:77]
	v_fmac_f32_e32 v125, 0x3fb504f3, v0
	s_waitcnt vmcnt(60)
	v_lshlrev_b32_e32 v0, 16, v78
	v_lshl_add_u64 v[60:61], v[62:63], 0, v[60:61]
	v_fmac_f32_e32 v129, 0x3fb504f3, v0
	global_store_dword v[60:61], v113, off
	global_store_dword v[60:61], v121, off offset:64
	global_store_dword v[60:61], v125, off offset:128
	global_store_dword v[60:61], v129, off offset:192
	v_lshlrev_b64 v[60:61], 12, v[80:81]
	s_waitcnt vmcnt(62)
	v_lshlrev_b32_e32 v0, 16, v79
	v_lshl_add_u64 v[60:61], v[62:63], 0, v[60:61]
	v_fmamk_f32 v0, v0, 0x3fb504f3, v46
	global_store_dword v[60:61], v0, off
	v_lshlrev_b32_e32 v0, 16, v140
	v_fmamk_f32 v0, v0, 0x3fb504f3, v42
	global_store_dword v[60:61], v0, off offset:64
	s_waitcnt vmcnt(62)
	v_lshlrev_b32_e32 v0, 16, v141
	v_fmamk_f32 v0, v0, 0x3fb504f3, v38
	global_store_dword v[60:61], v0, off offset:128
	v_lshlrev_b32_e32 v0, 16, v82
	v_fmamk_f32 v0, v0, 0x3fb504f3, v34
	global_store_dword v[60:61], v0, off offset:192
	v_lshlrev_b64 v[60:61], 12, v[84:85]
	s_waitcnt vmcnt(62)
	v_lshlrev_b32_e32 v0, 16, v83
	v_lshl_add_u64 v[60:61], v[62:63], 0, v[60:61]
	v_fmamk_f32 v0, v0, 0x3fb504f3, v47
	global_store_dword v[60:61], v0, off
	v_lshlrev_b32_e32 v0, 16, v142
	v_fmamk_f32 v0, v0, 0x3fb504f3, v43
	global_store_dword v[60:61], v0, off offset:64
	s_waitcnt vmcnt(62)
	v_lshlrev_b32_e32 v0, 16, v143
	v_fmamk_f32 v0, v0, 0x3fb504f3, v39
	global_store_dword v[60:61], v0, off offset:128
	v_lshlrev_b32_e32 v0, 16, v86
	v_fmamk_f32 v0, v0, 0x3fb504f3, v35
	global_store_dword v[60:61], v0, off offset:192
	v_lshlrev_b64 v[34:35], 12, v[88:89]
	s_waitcnt vmcnt(62)
	v_lshlrev_b32_e32 v0, 16, v87
	v_lshl_add_u64 v[34:35], v[62:63], 0, v[34:35]
	v_fmamk_f32 v0, v0, 0x3fb504f3, v48
	global_store_dword v[34:35], v0, off
	v_lshlrev_b32_e32 v0, 16, v144
	v_fmamk_f32 v0, v0, 0x3fb504f3, v44
	global_store_dword v[34:35], v0, off offset:64
	s_waitcnt vmcnt(62)
	v_lshlrev_b32_e32 v0, 16, v145
	v_fmamk_f32 v0, v0, 0x3fb504f3, v40
	global_store_dword v[34:35], v0, off offset:128
	v_lshlrev_b32_e32 v0, 16, v90
	v_fmamk_f32 v0, v0, 0x3fb504f3, v36
	global_store_dword v[34:35], v0, off offset:192
	s_waitcnt vmcnt(62)
	v_lshlrev_b32_e32 v0, 16, v91
	v_fmac_f32_e32 v49, 0x3fb504f3, v0
	v_lshlrev_b32_e32 v0, 16, v146
	v_fmac_f32_e32 v45, 0x3fb504f3, v0
	s_waitcnt vmcnt(61)
	v_lshlrev_b32_e32 v0, 16, v147
	v_lshlrev_b64 v[34:35], 12, v[92:93]
	v_fmac_f32_e32 v41, 0x3fb504f3, v0
	s_waitcnt vmcnt(60)
	v_lshlrev_b32_e32 v0, 16, v94
	v_lshl_add_u64 v[34:35], v[62:63], 0, v[34:35]
	v_fmac_f32_e32 v37, 0x3fb504f3, v0
	global_store_dword v[34:35], v49, off
	global_store_dword v[34:35], v45, off offset:64
	global_store_dword v[34:35], v41, off offset:128
	global_store_dword v[34:35], v37, off offset:192
	v_lshlrev_b64 v[34:35], 12, v[96:97]
	s_waitcnt vmcnt(62)
; DEV float bf2f(u16 h) { return __uint_as_float(((unsigned)h) << 16); }
; template <int EPI, bool AF32>
; DEV void gemm_tile(const void* Ap, int lda, const u16* Bt, int ldb, int K, int m0, int n0, const Epi& ea, char* smem) {
;     ...
; #pragma unroll
;     for (int m = 0; m < 4; m++)
; #pragma unroll
;       for (int j = 0; j < 4; j++)
; #pragma unroll
;         for (int n = 0; n < 4; n++)
;           C[(size_t)(rbase + m * 16 + j) * 1024 + cbase + n * 16] = ALPHA_ * bf2f(rv[m][j][n]) + acc[m][n][j];
;     return;
	v_lshlrev_b32_e32 v0, 16, v95
	v_lshl_add_u64 v[34:35], v[62:63], 0, v[34:35]
	v_fmamk_f32 v0, v0, 0x3fb504f3, v30
	global_store_dword v[34:35], v0, off
	v_lshlrev_b32_e32 v0, 16, v148
	v_fmamk_f32 v0, v0, 0x3fb504f3, v26
	global_store_dword v[34:35], v0, off offset:64
	s_waitcnt vmcnt(62)
	v_lshlrev_b32_e32 v0, 16, v149
	v_fmamk_f32 v0, v0, 0x3fb504f3, v22
	global_store_dword v[34:35], v0, off offset:128
	v_lshlrev_b32_e32 v0, 16, v98
	v_fmamk_f32 v0, v0, 0x3fb504f3, v18
	global_store_dword v[34:35], v0, off offset:192
	v_lshlrev_b64 v[34:35], 12, v[100:101]
	s_waitcnt vmcnt(62)
	v_lshlrev_b32_e32 v0, 16, v99
	v_lshl_add_u64 v[34:35], v[62:63], 0, v[34:35]
	v_fmamk_f32 v0, v0, 0x3fb504f3, v31
	global_store_dword v[34:35], v0, off
	v_lshlrev_b32_e32 v0, 16, v150
	v_fmamk_f32 v0, v0, 0x3fb504f3, v27
	global_store_dword v[34:35], v0, off offset:64
	s_waitcnt vmcnt(62)
	v_lshlrev_b32_e32 v0, 16, v151
	v_fmamk_f32 v0, v0, 0x3fb504f3, v23
	global_store_dword v[34:35], v0, off offset:128
	v_lshlrev_b32_e32 v0, 16, v102
	v_fmamk_f32 v0, v0, 0x3fb504f3, v19
	global_store_dword v[34:35], v0, off offset:192
	v_lshlrev_b64 v[18:19], 12, v[104:105]
	s_waitcnt vmcnt(62)
	v_lshlrev_b32_e32 v0, 16, v103
	v_lshl_add_u64 v[18:19], v[62:63], 0, v[18:19]
	v_fmamk_f32 v0, v0, 0x3fb504f3, v32
	global_store_dword v[18:19], v0, off
	v_lshlrev_b32_e32 v0, 16, v152
	v_fmamk_f32 v0, v0, 0x3fb504f3, v28
	global_store_dword v[18:19], v0, off offset:64
	s_waitcnt vmcnt(62)
	v_lshlrev_b32_e32 v0, 16, v153
	v_fmamk_f32 v0, v0, 0x3fb504f3, v24
	global_store_dword v[18:19], v0, off offset:128
	v_lshlrev_b32_e32 v0, 16, v106
	v_fmamk_f32 v0, v0, 0x3fb504f3, v20
	global_store_dword v[18:19], v0, off offset:192
	s_waitcnt vmcnt(62)
	v_lshlrev_b32_e32 v0, 16, v107
	v_fmac_f32_e32 v33, 0x3fb504f3, v0
	v_lshlrev_b32_e32 v0, 16, v161
	v_fmac_f32_e32 v29, 0x3fb504f3, v0
	s_waitcnt vmcnt(61)
	v_lshlrev_b32_e32 v0, 16, v162
	v_lshlrev_b64 v[18:19], 12, v[58:59]
	v_fmac_f32_e32 v25, 0x3fb504f3, v0
	s_waitcnt vmcnt(60)
	v_lshlrev_b32_e32 v0, 16, v108
	v_lshl_add_u64 v[18:19], v[62:63], 0, v[18:19]
	v_fmac_f32_e32 v21, 0x3fb504f3, v0
	global_store_dword v[18:19], v33, off
	global_store_dword v[18:19], v29, off offset:64
	global_store_dword v[18:19], v25, off offset:128
	global_store_dword v[18:19], v21, off offset:192
	v_lshlrev_b64 v[18:19], 12, v[56:57]
	s_waitcnt vmcnt(62)
	v_lshlrev_b32_e32 v0, 16, v109
	v_lshl_add_u64 v[18:19], v[62:63], 0, v[18:19]
	v_fmamk_f32 v0, v0, 0x3fb504f3, v14
	global_store_dword v[18:19], v0, off
	v_lshlrev_b32_e32 v0, 16, v163
	v_fmamk_f32 v0, v0, 0x3fb504f3, v10
	global_store_dword v[18:19], v0, off offset:64
	s_waitcnt vmcnt(62)
	v_lshlrev_b32_e32 v0, 16, v164
	v_fmamk_f32 v0, v0, 0x3fb504f3, v6
	global_store_dword v[18:19], v0, off offset:128
	v_lshlrev_b32_e32 v0, 16, v114
	v_fmamk_f32 v0, v0, 0x3fb504f3, v2
	global_store_dword v[18:19], v0, off offset:192
	v_lshlrev_b64 v[18:19], 12, v[54:55]
	s_waitcnt vmcnt(62)
	v_lshlrev_b32_e32 v0, 16, v115
	v_lshl_add_u64 v[18:19], v[62:63], 0, v[18:19]
	v_fmamk_f32 v0, v0, 0x3fb504f3, v15
	global_store_dword v[18:19], v0, off
	v_lshlrev_b32_e32 v0, 16, v165
	v_fmamk_f32 v0, v0, 0x3fb504f3, v11
	global_store_dword v[18:19], v0, off offset:64
	s_waitcnt vmcnt(62)
	v_lshlrev_b32_e32 v0, 16, v166
	v_fmamk_f32 v0, v0, 0x3fb504f3, v7
	global_store_dword v[18:19], v0, off offset:128
	v_lshlrev_b32_e32 v0, 16, v116
	v_fmamk_f32 v0, v0, 0x3fb504f3, v3
	global_store_dword v[18:19], v0, off offset:192
	v_lshlrev_b64 v[2:3], 12, v[52:53]
	s_waitcnt vmcnt(62)
	v_lshlrev_b32_e32 v0, 16, v117
	v_lshl_add_u64 v[2:3], v[62:63], 0, v[2:3]
	v_fmamk_f32 v0, v0, 0x3fb504f3, v16
	global_store_dword v[2:3], v0, off
	v_lshlrev_b32_e32 v0, 16, v167
	v_fmamk_f32 v0, v0, 0x3fb504f3, v12
	global_store_dword v[2:3], v0, off offset:64
	s_waitcnt vmcnt(62)
	v_lshlrev_b32_e32 v0, 16, v168
	v_fmamk_f32 v0, v0, 0x3fb504f3, v8
	global_store_dword v[2:3], v0, off offset:128
	v_lshlrev_b32_e32 v0, 16, v130
	v_fmamk_f32 v0, v0, 0x3fb504f3, v4
	global_store_dword v[2:3], v0, off offset:192
	s_waitcnt vmcnt(62)
	v_lshlrev_b32_e32 v0, 16, v131
	v_fmac_f32_e32 v17, 0x3fb504f3, v0
	v_lshlrev_b32_e32 v0, 16, v169
	v_fmac_f32_e32 v13, 0x3fb504f3, v0
	s_waitcnt vmcnt(61)
	v_lshlrev_b32_e32 v0, 16, v170
	v_lshlrev_b64 v[2:3], 12, v[50:51]
	v_fmac_f32_e32 v9, 0x3fb504f3, v0
	s_waitcnt vmcnt(60)
	v_lshlrev_b32_e32 v0, 16, v64
	v_lshl_add_u64 v[2:3], v[62:63], 0, v[2:3]
	v_fmac_f32_e32 v5, 0x3fb504f3, v0
	v_readfirstlane_b32 s10, v198
	global_store_dword v[2:3], v17, off
	global_store_dword v[2:3], v13, off offset:64
	global_store_dword v[2:3], v9, off offset:128
	global_store_dword v[2:3], v5, off offset:192
	s_add_i32 s12, s10, s12
	s_cmpk_lt_i32 s12, 0x820
	s_cbranch_scc1 .LBB0_1352

; template <int EPI, bool AF32>
; DEV void gemm_tile(const void* Ap, int lda, const u16* Bt, int ldb, int K, int m0, int n0, const Epi& ea, char* smem) {
;     ...
;   auto gload = [&](int kt) {
;     const int k0 = kt << 6;
; #pragma unroll
;     for (int i = 0; i < 4; i++) {
;       const int c = tid + i * 256, row = c >> 3, kc = c & 7;
;       if (AF32) {
;         const float* pa = (const float*)Ap + (size_t)(m0 + row) * lda + k0 + kc * 8;
;         rfa[2 * i] = *(const f32x4*)pa;
;         rfa[2 * i + 1] = *(const f32x4*)(pa + 4);
;       } else {
;         ra[i] = *(const u32x4*)((const u16*)Ap + (size_t)(m0 + row) * lda + k0 + kc * 8);
;       }
;       rb[i] = *(const u32x4*)(Bt + (size_t)(n0 + row) * ldb + k0 + kc * 8);
;     }
;   };
;   auto swrite = [&](int buf) {
; #pragma unroll
;     for (int i = 0; i < 4; i++) {
;       const int c = tid + i * 256, row = c >> 3, kc = c & 7;
;       u32x4 va;
;       if (AF32) {
;         va = (u32x4){pack2(rfa[2 * i][0], rfa[2 * i][1]), pack2(rfa[2 * i][2], rfa[2 * i][3]),
;                      pack2(rfa[2 * i + 1][0], rfa[2 * i + 1][1]), pack2(rfa[2 * i + 1][2], rfa[2 * i + 1][3])};
;       } else {
;         va = ra[i];
;       }
;       *(u32x4*)(sA + buf * 9216 + row * 72 + kc * 8) = va;
;       *(u32x4*)(sB + buf * 9216 + row * 72 + kc * 8) = rb[i];
;     }
;   };
;   gload(0);
;   swrite(0);
;   if (nk > 1) gload(1);
;   __syncthreads();
.LBB0_1436:
	s_mul_hi_i32 s0, s12, 0x2e8ba2e9
	s_lshr_b32 s1, s0, 31
	s_ashr_i32 s0, s0, 8
	s_add_i32 s0, s0, s1
	s_lshl_b32 s14, s0, 5
	s_mul_i32 s1, s0, 0x580
	s_sub_i32 s0, 0x104, s14
	s_min_u32 s15, s0, 32
	s_sub_i32 s13, s12, s1
	v_cvt_f32_ubyte0_e32 v2, s15
	v_cvt_f32_i32_e32 v0, s13
	v_rcp_iflag_f32_e32 v3, v2
	s_ashr_i32 s0, s13, 30
	s_or_b32 s16, s0, 1
	s_waitcnt vmcnt(12)
	v_mov_b32_e32 v114, v157
	v_mul_f32_e32 v3, v0, v3
	v_trunc_f32_e32 v3, v3
	v_fma_f32 v0, -v3, v2, v0
	v_cvt_i32_f32_e32 v3, v3
	v_cmp_ge_f32_e64 s[0:1], |v0|, v2
	s_and_b64 s[0:1], s[0:1], exec
	s_cselect_b32 s0, s16, 0
	v_readfirstlane_b32 s1, v3
	s_add_i32 s0, s1, s0
	s_sext_i32_i16 s1, s0
	s_mul_i32 s0, s0, s15
	s_sub_i32 s0, s13, s0
	s_sext_i32_i16 s0, s0
	s_add_i32 s14, s14, s0
	s_lshl_b32 s13, s14, 7
	s_lshl_b32 s14, s1, 7
	v_ashrrev_i32_e32 v8, 3, v114
	v_add_u32_e32 v2, s13, v8
	v_ashrrev_i32_e32 v3, 31, v2
	v_lshlrev_b32_e32 v0, 3, v114
	v_add_u32_e32 v4, 0x100, v114
	v_lshlrev_b64 v[58:59], 11, v[2:3]
	v_and_b32_e32 v0, 56, v0
	v_ashrrev_i32_e32 v9, 3, v4
	v_lshl_add_u64 v[2:3], s[4:5], 0, v[58:59]
	v_lshlrev_b32_e32 v0, 1, v0
	v_add_u32_e32 v4, s13, v9
	v_add_u32_e32 v6, 0x200, v114
	v_lshl_add_u64 v[14:15], v[2:3], 0, v[0:1]
	v_add_u32_e32 v2, s14, v8
	v_ashrrev_i32_e32 v5, 31, v4
	v_ashrrev_i32_e32 v10, 3, v6
	v_ashrrev_i32_e32 v3, 31, v2
	v_lshlrev_b64 v[62:63], 11, v[4:5]
	v_add_u32_e32 v6, s13, v10
	v_lshlrev_b64 v[60:61], 11, v[2:3]
	v_lshl_add_u64 v[4:5], s[4:5], 0, v[62:63]
	v_ashrrev_i32_e32 v7, 31, v6
	v_lshl_add_u64 v[2:3], s[6:7], 0, v[60:61]
	v_lshl_add_u64 v[16:17], v[4:5], 0, v[0:1]
	v_add_u32_e32 v4, s14, v9
	v_lshlrev_b64 v[66:67], 11, v[6:7]
	v_lshl_add_u64 v[2:3], v[2:3], 0, v[0:1]
	v_ashrrev_i32_e32 v5, 31, v4
	v_lshl_add_u64 v[6:7], s[4:5], 0, v[66:67]
	global_load_dwordx4 v[30:33], v[2:3], off
	v_lshlrev_b64 v[64:65], 11, v[4:5]
	v_lshl_add_u64 v[68:69], v[6:7], 0, v[0:1]
	v_add_u32_e32 v6, s14, v10
	global_load_dwordx4 v[26:29], v[14:15], off
	global_load_dwordx4 v[34:37], v[16:17], off
	v_lshl_add_u64 v[4:5], s[6:7], 0, v[64:65]
	v_ashrrev_i32_e32 v7, 31, v6
	v_lshl_add_u64 v[4:5], v[4:5], 0, v[0:1]
	v_lshlrev_b64 v[70:71], 11, v[6:7]
	global_load_dwordx4 v[38:41], v[4:5], off
	v_lshl_add_u64 v[6:7], s[6:7], 0, v[70:71]
	global_load_dwordx4 v[42:45], v[68:69], off
	v_lshl_add_u64 v[18:19], v[6:7], 0, v[0:1]
	global_load_dwordx4 v[46:49], v[18:19], off
	v_add_u32_e32 v6, 0x300, v114
	v_ashrrev_i32_e32 v80, 3, v6
	v_add_u32_e32 v6, s13, v80
	v_ashrrev_i32_e32 v7, 31, v6
	v_lshlrev_b64 v[72:73], 11, v[6:7]
	v_lshl_add_u64 v[6:7], s[4:5], 0, v[72:73]
	v_lshl_add_u64 v[74:75], v[6:7], 0, v[0:1]
	v_add_u32_e32 v6, s14, v80
	v_ashrrev_i32_e32 v7, 31, v6
	v_lshlrev_b64 v[76:77], 11, v[6:7]
	v_lshl_add_u64 v[6:7], s[6:7], 0, v[76:77]
	v_lshl_add_u64 v[78:79], v[6:7], 0, v[0:1]
	global_load_dwordx4 v[50:53], v[74:75], off
	global_load_dwordx4 v[54:57], v[78:79], off
	s_waitcnt vmcnt(19)
	v_mul_lo_u32 v118, v8, s71
	v_mul_lo_u32 v119, v9, s71
	s_waitcnt vmcnt(18)
	v_mul_lo_u32 v123, v10, s71
	global_load_dwordx4 v[6:9], v[2:3], off offset:128
	global_load_dwordx4 v[10:13], v[4:5], off offset:128
	s_nop 0
	global_load_dwordx4 v[2:5], v[18:19], off offset:128
	global_load_dwordx4 v[22:25], v[14:15], off offset:128
	s_nop 0
	global_load_dwordx4 v[18:21], v[16:17], off offset:128
	s_nop 0
	global_load_dwordx4 v[14:17], v[68:69], off offset:128
	v_bfe_u32 v161, v157, 3, 4
	v_add_u32_e32 v161, 4, v161
	v_lshlrev_b32_e32 v161, 1, v161
	v_and_b32_e32 v161, 16, v161
	v_xor_b32_e32 v129, v0, v161
	v_lshl_add_u32 v122, v118, 1, v129
	v_lshl_add_u32 v121, v119, 1, v129
	v_lshl_add_u32 v120, v123, 1, v129
	v_and_b32_e32 v115, 15, v114
	s_waitcnt vmcnt(23)
	v_mul_lo_u32 v126, v80, s71
	v_bfe_u32 v116, v114, 4, 2
	v_lshl_add_u32 v124, v126, 1, v129
	s_mov_b32 s15, 0
	v_lshlrev_b32_e32 v125, 4, v116
	v_and_b32_e32 v161, 15, v157
	v_add_u32_e32 v161, 4, v161
	v_lshlrev_b32_e32 v161, 1, v161
	v_and_b32_e32 v161, 16, v161
	v_xor_b32_e32 v125, v125, v161
	s_mov_b64 s[0:1], 0
	s_waitcnt vmcnt(13)
	ds_write_b128 v122, v[30:33] offset:36864
	s_waitcnt vmcnt(12)
	ds_write_b128 v122, v[26:29]
	s_waitcnt vmcnt(11)
	ds_write_b128 v121, v[34:37]
	s_waitcnt vmcnt(10)
	ds_write_b128 v121, v[38:41] offset:36864
	s_waitcnt vmcnt(9)
	ds_write_b128 v120, v[42:45]
	s_waitcnt vmcnt(8)
	ds_write_b128 v120, v[46:49] offset:36864
	global_load_dwordx4 v[26:29], v[74:75], off offset:128
	global_load_dwordx4 v[30:33], v[78:79], off offset:128
	v_ashrrev_i32_e32 v34, 1, v114
	v_and_b32_e32 v117, 0xffffffc0, v34
	v_or_b32_e32 v34, v117, v115
	v_mul_lo_u32 v128, v34, s71
	v_lshlrev_b32_e32 v34, 4, v114
	v_and_b32_e32 v34, 0x70, v34
	v_and_b32_e32 v35, 0x4f, v114
	v_or_b32_e32 v76, v76, v34
	v_or_b32_e32 v72, v72, v34
	v_or_b32_e32 v70, v70, v34
	v_or_b32_e32 v66, v66, v34
	v_or_b32_e32 v64, v64, v34
	v_or_b32_e32 v62, v62, v34
	v_or_b32_e32 v60, v60, v34
	v_or_b32_e32 v58, v58, v34
	v_mov_b32_e32 v34, 0
	s_waitcnt vmcnt(9)
	ds_write_b128 v124, v[50:53]
	s_waitcnt vmcnt(8)
; DEV f32x4 mfma16(bf16x8 a, bf16x8 b, f32x4 c) { return __builtin_amdgcn_mfma_f32_16x16x32_bf16(a, b, c, 0, 0, 0); }
; template <int EPI, bool AF32>
; DEV void gemm_tile(const void* Ap, int lda, const u16* Bt, int ldb, int K, int m0, int n0, const Epi& ea, char* smem) {
;     ...
;   auto gload = [&](int kt) {
;     const int k0 = kt << 6;
; #pragma unroll
;     for (int i = 0; i < 4; i++) {
;       const int c = tid + i * 256, row = c >> 3, kc = c & 7;
;       if (AF32) {
;         const float* pa = (const float*)Ap + (size_t)(m0 + row) * lda + k0 + kc * 8;
;         rfa[2 * i] = *(const f32x4*)pa;
;         rfa[2 * i + 1] = *(const f32x4*)(pa + 4);
;       } else {
;         ra[i] = *(const u32x4*)((const u16*)Ap + (size_t)(m0 + row) * lda + k0 + kc * 8);
;       }
;       rb[i] = *(const u32x4*)(Bt + (size_t)(n0 + row) * ldb + k0 + kc * 8);
;     }
;   };
;   auto swrite = [&](int buf) {
; #pragma unroll
;     for (int i = 0; i < 4; i++) {
;       const int c = tid + i * 256, row = c >> 3, kc = c & 7;
;       u32x4 va;
;       if (AF32) {
;         va = (u32x4){pack2(rfa[2 * i][0], rfa[2 * i][1]), pack2(rfa[2 * i][2], rfa[2 * i][3]),
;                      pack2(rfa[2 * i + 1][0], rfa[2 * i + 1][1]), pack2(rfa[2 * i + 1][2], rfa[2 * i + 1][3])};
;       } else {
;         va = ra[i];
;       }
;       *(u32x4*)(sA + buf * 9216 + row * 72 + kc * 8) = va;
;       *(u32x4*)(sB + buf * 9216 + row * 72 + kc * 8) = rb[i];
;     }
;   };
;   gload(0);
;   swrite(0);
;   if (nk > 1) gload(1);
;   __syncthreads();
;   for (int kt = 0; kt < nk; kt++) {
;     const int buf = kt & 1;
;     if (kt + 1 < nk) swrite(buf ^ 1);
;     if (kt + 2 < nk) gload(kt + 2);
; #pragma unroll
;     for (int ks = 0; ks < 2; ks++) {
;       bf16x8 a[4], b[4];
; #pragma unroll
;       for (int m = 0; m < 4; m++) a[m] = *(const bf16x8*)(sA + buf * 9216 + (wr * 64 + m * 16 + fr) * 72 + ks * 32 + fq * 8);
; #pragma unroll
;       for (int n = 0; n < 4; n++) b[n] = *(const bf16x8*)(sB + buf * 9216 + (wc * 64 + n * 16 + fr) * 72 + ks * 32 + fq * 8);
;       __builtin_amdgcn_s_setprio(1);
; #pragma unroll
;       for (int m = 0; m < 4; m++)
; #pragma unroll
;         for (int n = 0; n < 4; n++) acc[m][n] = mfma16(a[m], b[n], acc[m][n]);
;       __builtin_amdgcn_s_setprio(0);
;     }
;     __syncthreads();
	ds_write_b128 v124, v[54:57] offset:36864
	v_mul_u32_u24_e32 v127, 0x48, v35
	v_lshl_add_u64 v[98:99], s[8:9], 0, v[76:77]
	v_lshl_add_u64 v[100:101], s[10:11], 0, v[72:73]
	v_lshl_add_u64 v[102:103], s[8:9], 0, v[70:71]
	v_lshl_add_u64 v[104:105], s[10:11], 0, v[66:67]
	v_lshl_add_u64 v[106:107], s[8:9], 0, v[64:65]
	v_lshl_add_u64 v[108:109], s[10:11], 0, v[62:63]
	v_lshl_add_u64 v[110:111], s[8:9], 0, v[60:61]
	v_lshl_add_u64 v[112:113], s[10:11], 0, v[58:59]
	global_load_dwordx4 v[222:225], v[112:113], off
	global_load_dwordx4 v[226:229], v[110:111], off
	global_load_dwordx4 v[230:233], v[108:109], off
	global_load_dwordx4 v[234:237], v[106:107], off
	global_load_dwordx4 v[238:241], v[104:105], off
	global_load_dwordx4 v[242:245], v[102:103], off
	global_load_dwordx4 v[246:249], v[100:101], off
	global_load_dwordx4 v[250:253], v[98:99], off
	v_mov_b32_e32 v35, v34
	v_mov_b32_e32 v36, v34
	v_mov_b32_e32 v37, v34
	v_mov_b32_e32 v38, v34
	v_mov_b32_e32 v39, v34
	v_mov_b32_e32 v40, v34
	v_mov_b32_e32 v41, v34
	v_mov_b32_e32 v42, v34
	v_mov_b32_e32 v43, v34
	v_mov_b32_e32 v44, v34
	v_mov_b32_e32 v45, v34
	v_mov_b32_e32 v46, v34
	v_mov_b32_e32 v47, v34
	v_mov_b32_e32 v48, v34
	v_mov_b32_e32 v49, v34
	v_mov_b32_e32 v50, v34
	v_mov_b32_e32 v51, v34
	v_mov_b32_e32 v52, v34
	v_mov_b32_e32 v53, v34
	v_mov_b32_e32 v54, v34
	v_mov_b32_e32 v55, v34
	v_mov_b32_e32 v56, v34
	v_mov_b32_e32 v57, v34
	v_mov_b32_e32 v58, v34
	v_mov_b32_e32 v59, v34
	v_mov_b32_e32 v60, v34
	v_mov_b32_e32 v61, v34
	v_mov_b32_e32 v62, v34
	v_mov_b32_e32 v63, v34
	v_mov_b32_e32 v64, v34
	v_mov_b32_e32 v65, v34
	v_mov_b32_e32 v66, v34
	v_mov_b32_e32 v67, v34
	v_mov_b32_e32 v68, v34
	v_mov_b32_e32 v69, v34
	v_mov_b32_e32 v70, v34
	v_mov_b32_e32 v71, v34
	v_mov_b32_e32 v72, v34
	v_mov_b32_e32 v73, v34
	v_mov_b32_e32 v74, v34
	v_mov_b32_e32 v75, v34
	v_mov_b32_e32 v76, v34
	v_mov_b32_e32 v77, v34
	v_mov_b32_e32 v78, v34
	v_mov_b32_e32 v79, v34
	v_mov_b32_e32 v80, v34
	v_mov_b32_e32 v81, v34
	v_mov_b32_e32 v82, v34
	v_mov_b32_e32 v83, v34
	v_mov_b32_e32 v84, v34
	v_mov_b32_e32 v85, v34
	v_mov_b32_e32 v86, v34
	v_mov_b32_e32 v87, v34
	v_mov_b32_e32 v88, v34
	v_mov_b32_e32 v89, v34
	v_mov_b32_e32 v90, v34
	v_mov_b32_e32 v91, v34
	v_mov_b32_e32 v92, v34
	v_mov_b32_e32 v93, v34
	v_mov_b32_e32 v94, v34
	v_mov_b32_e32 v95, v34
	v_mov_b32_e32 v96, v34
	v_mov_b32_e32 v97, v34
	s_waitcnt lgkmcnt(0)
	s_barrier
	v_lshl_add_u32 v161, v128, 1, v125
	v_lshl_add_u32 v129, v127, 1, v125
	s_mov_b32 s15, 0
	s_mov_b64 s[0:1], 0x100
.Lgk6_loop:
	v_lshl_add_u64 v[112:113], v[112:113], 0, s[0:1]
	v_lshl_add_u64 v[110:111], v[110:111], 0, s[0:1]
	v_lshl_add_u64 v[108:109], v[108:109], 0, s[0:1]
	v_lshl_add_u64 v[106:107], v[106:107], 0, s[0:1]
	v_lshl_add_u64 v[104:105], v[104:105], 0, s[0:1]
	v_lshl_add_u64 v[102:103], v[102:103], 0, s[0:1]
	v_lshl_add_u64 v[100:101], v[100:101], 0, s[0:1]
	v_lshl_add_u64 v[98:99], v[98:99], 0, s[0:1]
	ds_read_b128 v[130:133], v161
	ds_read_b128 v[134:137], v161 offset:2304
	ds_read_b128 v[138:141], v161 offset:4608
	ds_read_b128 v[142:145], v161 offset:6912
	ds_read_b128 v[146:149], v129 offset:36864
	ds_read_b128 v[150:153], v129 offset:39168
	ds_read_b128 v[162:165], v129 offset:41472
	ds_read_b128 v[166:169], v129 offset:43776
	s_setprio 1
	s_waitcnt lgkmcnt(3)
	v_mfma_f32_16x16x32_bf16 v[94:97], v[130:133], v[146:149], v[94:97]
	s_waitcnt lgkmcnt(2)
	v_mfma_f32_16x16x32_bf16 v[90:93], v[130:133], v[150:153], v[90:93]
	s_waitcnt lgkmcnt(1)
	v_mfma_f32_16x16x32_bf16 v[86:89], v[130:133], v[162:165], v[86:89]
	s_waitcnt lgkmcnt(0)
	v_mfma_f32_16x16x32_bf16 v[82:85], v[130:133], v[166:169], v[82:85]
	v_mfma_f32_16x16x32_bf16 v[78:81], v[134:137], v[146:149], v[78:81]
	v_mfma_f32_16x16x32_bf16 v[74:77], v[134:137], v[150:153], v[74:77]
	v_mfma_f32_16x16x32_bf16 v[70:73], v[134:137], v[162:165], v[70:73]
	v_mfma_f32_16x16x32_bf16 v[66:69], v[134:137], v[166:169], v[66:69]
	v_mfma_f32_16x16x32_bf16 v[62:65], v[138:141], v[146:149], v[62:65]
	v_mfma_f32_16x16x32_bf16 v[58:61], v[138:141], v[150:153], v[58:61]
	v_mfma_f32_16x16x32_bf16 v[54:57], v[138:141], v[162:165], v[54:57]
	v_mfma_f32_16x16x32_bf16 v[50:53], v[138:141], v[166:169], v[50:53]
	v_mfma_f32_16x16x32_bf16 v[46:49], v[142:145], v[146:149], v[46:49]
	v_mfma_f32_16x16x32_bf16 v[42:45], v[142:145], v[150:153], v[42:45]
	v_mfma_f32_16x16x32_bf16 v[38:41], v[142:145], v[162:165], v[38:41]
	v_mfma_f32_16x16x32_bf16 v[34:37], v[142:145], v[166:169], v[34:37]
	s_setprio 0
	ds_read_b128 v[130:133], v161 offset:64
	ds_read_b128 v[134:137], v161 offset:2368
	ds_read_b128 v[138:141], v161 offset:4672
	ds_read_b128 v[142:145], v161 offset:6976
	ds_read_b128 v[146:149], v129 offset:36928
	ds_read_b128 v[150:153], v129 offset:39232
	ds_read_b128 v[162:165], v129 offset:41536
	ds_read_b128 v[166:169], v129 offset:43840
	s_waitcnt vmcnt(8)
	ds_write_b128 v122, v[22:25] offset:18432
	ds_write_b128 v122, v[6:9] offset:55296
	ds_write_b128 v121, v[18:21] offset:18432
	ds_write_b128 v121, v[10:13] offset:55296
	ds_write_b128 v120, v[14:17] offset:18432
	ds_write_b128 v120, v[2:5] offset:55296
	ds_write_b128 v124, v[26:29] offset:18432
	ds_write_b128 v124, v[30:33] offset:55296
	global_load_dwordx4 v[22:25], v[112:113], off offset:-128
	global_load_dwordx4 v[6:9], v[110:111], off offset:-128
	global_load_dwordx4 v[18:21], v[108:109], off offset:-128
	global_load_dwordx4 v[10:13], v[106:107], off offset:-128
	global_load_dwordx4 v[14:17], v[104:105], off offset:-128
	global_load_dwordx4 v[2:5], v[102:103], off offset:-128
	global_load_dwordx4 v[26:29], v[100:101], off offset:-128
	global_load_dwordx4 v[30:33], v[98:99], off offset:-128
	s_setprio 1
	s_waitcnt lgkmcnt(11)
	v_mfma_f32_16x16x32_bf16 v[94:97], v[130:133], v[146:149], v[94:97]
	s_waitcnt lgkmcnt(10)
	v_mfma_f32_16x16x32_bf16 v[90:93], v[130:133], v[150:153], v[90:93]
	s_waitcnt lgkmcnt(9)
	v_mfma_f32_16x16x32_bf16 v[86:89], v[130:133], v[162:165], v[86:89]
	s_waitcnt lgkmcnt(8)
	v_mfma_f32_16x16x32_bf16 v[82:85], v[130:133], v[166:169], v[82:85]
	v_mfma_f32_16x16x32_bf16 v[78:81], v[134:137], v[146:149], v[78:81]
	v_mfma_f32_16x16x32_bf16 v[74:77], v[134:137], v[150:153], v[74:77]
	v_mfma_f32_16x16x32_bf16 v[70:73], v[134:137], v[162:165], v[70:73]
	v_mfma_f32_16x16x32_bf16 v[66:69], v[134:137], v[166:169], v[66:69]
	v_mfma_f32_16x16x32_bf16 v[62:65], v[138:141], v[146:149], v[62:65]
	v_mfma_f32_16x16x32_bf16 v[58:61], v[138:141], v[150:153], v[58:61]
	v_mfma_f32_16x16x32_bf16 v[54:57], v[138:141], v[162:165], v[54:57]
	v_mfma_f32_16x16x32_bf16 v[50:53], v[138:141], v[166:169], v[50:53]
	v_mfma_f32_16x16x32_bf16 v[46:49], v[142:145], v[146:149], v[46:49]
	v_mfma_f32_16x16x32_bf16 v[42:45], v[142:145], v[150:153], v[42:45]
	v_mfma_f32_16x16x32_bf16 v[38:41], v[142:145], v[162:165], v[38:41]
	v_mfma_f32_16x16x32_bf16 v[34:37], v[142:145], v[166:169], v[34:37]
	s_setprio 0
	s_waitcnt lgkmcnt(0)
	s_barrier
; DEV f32x4 mfma16(bf16x8 a, bf16x8 b, f32x4 c) { return __builtin_amdgcn_mfma_f32_16x16x32_bf16(a, b, c, 0, 0, 0); }
; template <int EPI, bool AF32>
; DEV void gemm_tile(const void* Ap, int lda, const u16* Bt, int ldb, int K, int m0, int n0, const Epi& ea, char* smem) {
;     ...
;   auto gload = [&](int kt) {
;     const int k0 = kt << 6;
; #pragma unroll
;     for (int i = 0; i < 4; i++) {
;       const int c = tid + i * 256, row = c >> 3, kc = c & 7;
;       if (AF32) {
;         const float* pa = (const float*)Ap + (size_t)(m0 + row) * lda + k0 + kc * 8;
;         rfa[2 * i] = *(const f32x4*)pa;
;         rfa[2 * i + 1] = *(const f32x4*)(pa + 4);
;       } else {
;         ra[i] = *(const u32x4*)((const u16*)Ap + (size_t)(m0 + row) * lda + k0 + kc * 8);
;       }
;       rb[i] = *(const u32x4*)(Bt + (size_t)(n0 + row) * ldb + k0 + kc * 8);
;     }
;   };
;   auto swrite = [&](int buf) {
; #pragma unroll
;     for (int i = 0; i < 4; i++) {
;       const int c = tid + i * 256, row = c >> 3, kc = c & 7;
;       u32x4 va;
;       if (AF32) {
;         va = (u32x4){pack2(rfa[2 * i][0], rfa[2 * i][1]), pack2(rfa[2 * i][2], rfa[2 * i][3]),
;                      pack2(rfa[2 * i + 1][0], rfa[2 * i + 1][1]), pack2(rfa[2 * i + 1][2], rfa[2 * i + 1][3])};
;       } else {
;         va = ra[i];
;       }
;       *(u32x4*)(sA + buf * 9216 + row * 72 + kc * 8) = va;
;       *(u32x4*)(sB + buf * 9216 + row * 72 + kc * 8) = rb[i];
;     }
;   };
;   gload(0);
;   swrite(0);
;   if (nk > 1) gload(1);
;   __syncthreads();
;   for (int kt = 0; kt < nk; kt++) {
;     const int buf = kt & 1;
;     if (kt + 1 < nk) swrite(buf ^ 1);
;     if (kt + 2 < nk) gload(kt + 2);
; #pragma unroll
;     for (int ks = 0; ks < 2; ks++) {
;       bf16x8 a[4], b[4];
; #pragma unroll
;       for (int m = 0; m < 4; m++) a[m] = *(const bf16x8*)(sA + buf * 9216 + (wr * 64 + m * 16 + fr) * 72 + ks * 32 + fq * 8);
; #pragma unroll
;       for (int n = 0; n < 4; n++) b[n] = *(const bf16x8*)(sB + buf * 9216 + (wc * 64 + n * 16 + fr) * 72 + ks * 32 + fq * 8);
;       __builtin_amdgcn_s_setprio(1);
; #pragma unroll
;       for (int m = 0; m < 4; m++)
; #pragma unroll
;         for (int n = 0; n < 4; n++) acc[m][n] = mfma16(a[m], b[n], acc[m][n]);
;       __builtin_amdgcn_s_setprio(0);
;     }
;     __syncthreads();
	ds_read_b128 v[130:133], v161 offset:18432
	ds_read_b128 v[134:137], v161 offset:20736
	ds_read_b128 v[138:141], v161 offset:23040
	ds_read_b128 v[142:145], v161 offset:25344
	ds_read_b128 v[146:149], v129 offset:55296
	ds_read_b128 v[150:153], v129 offset:57600
	ds_read_b128 v[162:165], v129 offset:59904
	ds_read_b128 v[166:169], v129 offset:62208
	s_setprio 1
	s_waitcnt lgkmcnt(3)
	v_mfma_f32_16x16x32_bf16 v[94:97], v[130:133], v[146:149], v[94:97]
	s_waitcnt lgkmcnt(2)
	v_mfma_f32_16x16x32_bf16 v[90:93], v[130:133], v[150:153], v[90:93]
	s_waitcnt lgkmcnt(1)
	v_mfma_f32_16x16x32_bf16 v[86:89], v[130:133], v[162:165], v[86:89]
	s_waitcnt lgkmcnt(0)
	v_mfma_f32_16x16x32_bf16 v[82:85], v[130:133], v[166:169], v[82:85]
	v_mfma_f32_16x16x32_bf16 v[78:81], v[134:137], v[146:149], v[78:81]
	v_mfma_f32_16x16x32_bf16 v[74:77], v[134:137], v[150:153], v[74:77]
	v_mfma_f32_16x16x32_bf16 v[70:73], v[134:137], v[162:165], v[70:73]
	v_mfma_f32_16x16x32_bf16 v[66:69], v[134:137], v[166:169], v[66:69]
	v_mfma_f32_16x16x32_bf16 v[62:65], v[138:141], v[146:149], v[62:65]
	v_mfma_f32_16x16x32_bf16 v[58:61], v[138:141], v[150:153], v[58:61]
	v_mfma_f32_16x16x32_bf16 v[54:57], v[138:141], v[162:165], v[54:57]
	v_mfma_f32_16x16x32_bf16 v[50:53], v[138:141], v[166:169], v[50:53]
	v_mfma_f32_16x16x32_bf16 v[46:49], v[142:145], v[146:149], v[46:49]
	v_mfma_f32_16x16x32_bf16 v[42:45], v[142:145], v[150:153], v[42:45]
	v_mfma_f32_16x16x32_bf16 v[38:41], v[142:145], v[162:165], v[38:41]
	v_mfma_f32_16x16x32_bf16 v[34:37], v[142:145], v[166:169], v[34:37]
	s_setprio 0
	ds_read_b128 v[130:133], v161 offset:18496
	ds_read_b128 v[134:137], v161 offset:20800
	ds_read_b128 v[138:141], v161 offset:23104
	ds_read_b128 v[142:145], v161 offset:25408
	ds_read_b128 v[146:149], v129 offset:55360
	ds_read_b128 v[150:153], v129 offset:57664
	ds_read_b128 v[162:165], v129 offset:59968
	ds_read_b128 v[166:169], v129 offset:62272
	s_waitcnt vmcnt(8)
	ds_write_b128 v122, v[222:225]
	ds_write_b128 v122, v[226:229] offset:36864
	ds_write_b128 v121, v[230:233]
	ds_write_b128 v121, v[234:237] offset:36864
	ds_write_b128 v120, v[238:241]
	ds_write_b128 v120, v[242:245] offset:36864
	ds_write_b128 v124, v[246:249]
	ds_write_b128 v124, v[250:253] offset:36864
	s_cmp_eq_u32 s15, 6
	s_cbranch_scc1 .Lgk6_nold
	global_load_dwordx4 v[222:225], v[112:113], off
	global_load_dwordx4 v[226:229], v[110:111], off
	global_load_dwordx4 v[230:233], v[108:109], off
	global_load_dwordx4 v[234:237], v[106:107], off
	global_load_dwordx4 v[238:241], v[104:105], off
	global_load_dwordx4 v[242:245], v[102:103], off
	global_load_dwordx4 v[246:249], v[100:101], off
	global_load_dwordx4 v[250:253], v[98:99], off
.Lgk6_nold:
	s_setprio 1
	s_waitcnt lgkmcnt(11)
	v_mfma_f32_16x16x32_bf16 v[94:97], v[130:133], v[146:149], v[94:97]
	s_waitcnt lgkmcnt(10)
	v_mfma_f32_16x16x32_bf16 v[90:93], v[130:133], v[150:153], v[90:93]
	s_waitcnt lgkmcnt(9)
	v_mfma_f32_16x16x32_bf16 v[86:89], v[130:133], v[162:165], v[86:89]
	s_waitcnt lgkmcnt(8)
	v_mfma_f32_16x16x32_bf16 v[82:85], v[130:133], v[166:169], v[82:85]
	v_mfma_f32_16x16x32_bf16 v[78:81], v[134:137], v[146:149], v[78:81]
	v_mfma_f32_16x16x32_bf16 v[74:77], v[134:137], v[150:153], v[74:77]
	v_mfma_f32_16x16x32_bf16 v[70:73], v[134:137], v[162:165], v[70:73]
	v_mfma_f32_16x16x32_bf16 v[66:69], v[134:137], v[166:169], v[66:69]
	v_mfma_f32_16x16x32_bf16 v[62:65], v[138:141], v[146:149], v[62:65]
	v_mfma_f32_16x16x32_bf16 v[58:61], v[138:141], v[150:153], v[58:61]
	v_mfma_f32_16x16x32_bf16 v[54:57], v[138:141], v[162:165], v[54:57]
	v_mfma_f32_16x16x32_bf16 v[50:53], v[138:141], v[166:169], v[50:53]
	v_mfma_f32_16x16x32_bf16 v[46:49], v[142:145], v[146:149], v[46:49]
	v_mfma_f32_16x16x32_bf16 v[42:45], v[142:145], v[150:153], v[42:45]
	v_mfma_f32_16x16x32_bf16 v[38:41], v[142:145], v[162:165], v[38:41]
	v_mfma_f32_16x16x32_bf16 v[34:37], v[142:145], v[166:169], v[34:37]
	s_setprio 0
	s_add_i32 s15, s15, 1
	s_cmp_lg_u32 s15, 7
	s_waitcnt lgkmcnt(0)
	s_barrier
	s_cbranch_scc1 .Lgk6_loop
	s_waitcnt vmcnt(7)
	ds_write_b128 v122, v[22:25] offset:18432
	s_waitcnt vmcnt(6)
	ds_write_b128 v122, v[6:9] offset:55296
	s_waitcnt vmcnt(5)
	ds_write_b128 v121, v[18:21] offset:18432
	s_waitcnt vmcnt(4)
	ds_write_b128 v121, v[10:13] offset:55296
	s_waitcnt vmcnt(3)
	ds_write_b128 v120, v[14:17] offset:18432
	s_waitcnt vmcnt(2)
	ds_write_b128 v120, v[2:5] offset:55296
	s_waitcnt vmcnt(1)
	ds_write_b128 v124, v[26:29] offset:18432
	s_waitcnt vmcnt(0)
	ds_write_b128 v124, v[30:33] offset:55296
	v_lshl_add_u32 v0, v128, 1, v125
	v_lshl_add_u32 v130, v127, 1, v125
	ds_read_b128 v[2:5], v0
	ds_read_b128 v[6:9], v0 offset:2304
	ds_read_b128 v[10:13], v0 offset:4608
	ds_read_b128 v[14:17], v0 offset:6912
	ds_read_b128 v[18:21], v130 offset:36864
	ds_read_b128 v[22:25], v130 offset:39168
	ds_read_b128 v[26:29], v130 offset:41472
	ds_read_b128 v[30:33], v130 offset:43776
	s_setprio 1
	s_waitcnt lgkmcnt(3)
	v_mfma_f32_16x16x32_bf16 v[94:97], v[2:5], v[18:21], v[94:97]
	s_waitcnt lgkmcnt(2)
	v_mfma_f32_16x16x32_bf16 v[90:93], v[2:5], v[22:25], v[90:93]
	s_waitcnt lgkmcnt(1)
	v_mfma_f32_16x16x32_bf16 v[86:89], v[2:5], v[26:29], v[86:89]
	s_waitcnt lgkmcnt(0)
; DEV float siluf(float x) { return x * __builtin_amdgcn_rcpf(1.f + __expf(-x)); }
; DEV f32x4 mfma16(bf16x8 a, bf16x8 b, f32x4 c) { return __builtin_amdgcn_mfma_f32_16x16x32_bf16(a, b, c, 0, 0, 0); }
; template <int EPI, bool AF32>
; DEV void gemm_tile(const void* Ap, int lda, const u16* Bt, int ldb, int K, int m0, int n0, const Epi& ea, char* smem) {
;     ...
; #pragma unroll
;     for (int ks = 0; ks < 2; ks++) {
;       bf16x8 a[4], b[4];
; #pragma unroll
;       for (int m = 0; m < 4; m++) a[m] = *(const bf16x8*)(sA + buf * 9216 + (wr * 64 + m * 16 + fr) * 72 + ks * 32 + fq * 8);
; #pragma unroll
;       for (int n = 0; n < 4; n++) b[n] = *(const bf16x8*)(sB + buf * 9216 + (wc * 64 + n * 16 + fr) * 72 + ks * 32 + fq * 8);
;       __builtin_amdgcn_s_setprio(1);
; #pragma unroll
;       for (int m = 0; m < 4; m++)
; #pragma unroll
;         for (int n = 0; n < 4; n++) acc[m][n] = mfma16(a[m], b[n], acc[m][n]);
;       __builtin_amdgcn_s_setprio(0);
;     }
;     __syncthreads();
;     ...
;       } else if (EPI == EP_SWIGLU) {
;         u16* C = (u16*)ea.p0;
;         const int jb = (cb >> 6) * 32;
; #pragma unroll
;         for (int n = 0; n < 2; n++)
;           __builtin_nontemporal_store(f2bf(siluf(acc[m][n][j]) * acc[m][n + 2][j]), &C[(size_t)row * 2816 + jb + n * 16 + fr]);
	v_mfma_f32_16x16x32_bf16 v[2:5], v[2:5], v[30:33], v[82:85]
	v_mfma_f32_16x16x32_bf16 v[78:81], v[6:9], v[18:21], v[78:81]
	v_mfma_f32_16x16x32_bf16 v[74:77], v[6:9], v[22:25], v[74:77]
	v_mfma_f32_16x16x32_bf16 v[70:73], v[6:9], v[26:29], v[70:73]
	v_mfma_f32_16x16x32_bf16 v[6:9], v[6:9], v[30:33], v[66:69]
	v_mfma_f32_16x16x32_bf16 v[62:65], v[10:13], v[18:21], v[62:65]
	v_mfma_f32_16x16x32_bf16 v[58:61], v[10:13], v[22:25], v[58:61]
	v_mfma_f32_16x16x32_bf16 v[54:57], v[10:13], v[26:29], v[54:57]
	v_mfma_f32_16x16x32_bf16 v[10:13], v[10:13], v[30:33], v[50:53]
	v_mfma_f32_16x16x32_bf16 v[18:21], v[14:17], v[18:21], v[46:49]
	v_mfma_f32_16x16x32_bf16 v[22:25], v[14:17], v[22:25], v[42:45]
	v_mfma_f32_16x16x32_bf16 v[26:29], v[14:17], v[26:29], v[38:41]
	v_mfma_f32_16x16x32_bf16 v[14:17], v[14:17], v[30:33], v[34:37]
	s_setprio 0
	ds_read_b128 v[30:33], v0 offset:64
	s_nop 0
	ds_read_b128 v[34:37], v0 offset:2368
	ds_read_b128 v[38:41], v0 offset:4672
	ds_read_b128 v[42:45], v0 offset:6976
	ds_read_b128 v[46:49], v130 offset:36928
	ds_read_b128 v[50:53], v130 offset:39232
	ds_read_b128 v[66:69], v130 offset:41536
	ds_read_b128 v[82:85], v130 offset:43840
	s_setprio 1
	s_waitcnt lgkmcnt(3)
	v_mfma_f32_16x16x32_bf16 v[94:97], v[30:33], v[46:49], v[94:97]
	s_waitcnt lgkmcnt(2)
	v_mfma_f32_16x16x32_bf16 v[90:93], v[30:33], v[50:53], v[90:93]
	s_waitcnt lgkmcnt(1)
	v_mfma_f32_16x16x32_bf16 v[86:89], v[30:33], v[66:69], v[86:89]
	s_waitcnt lgkmcnt(0)
	v_mfma_f32_16x16x32_bf16 v[2:5], v[30:33], v[82:85], v[2:5]
	v_mfma_f32_16x16x32_bf16 v[30:33], v[34:37], v[46:49], v[78:81]
	v_mfma_f32_16x16x32_bf16 v[74:77], v[34:37], v[50:53], v[74:77]
	v_mfma_f32_16x16x32_bf16 v[70:73], v[34:37], v[66:69], v[70:73]
	v_mfma_f32_16x16x32_bf16 v[6:9], v[34:37], v[82:85], v[6:9]
	v_mfma_f32_16x16x32_bf16 v[34:37], v[38:41], v[46:49], v[62:65]
	v_mfma_f32_16x16x32_bf16 v[58:61], v[38:41], v[50:53], v[58:61]
	v_mfma_f32_16x16x32_bf16 v[54:57], v[38:41], v[66:69], v[54:57]
	v_mfma_f32_16x16x32_bf16 v[10:13], v[38:41], v[82:85], v[10:13]
	v_mfma_f32_16x16x32_bf16 v[18:21], v[42:45], v[46:49], v[18:21]
	v_mfma_f32_16x16x32_bf16 v[22:25], v[42:45], v[50:53], v[22:25]
	v_mfma_f32_16x16x32_bf16 v[26:29], v[42:45], v[66:69], v[26:29]
	v_mfma_f32_16x16x32_bf16 v[14:17], v[42:45], v[82:85], v[14:17]
	s_setprio 0
	s_barrier
	ds_read_b128 v[38:41], v0 offset:18432
	ds_read_b128 v[42:45], v0 offset:20736
	ds_read_b128 v[46:49], v0 offset:23040
	ds_read_b128 v[50:53], v0 offset:25344
	ds_read_b128 v[62:65], v130 offset:55296
	ds_read_b128 v[66:69], v130 offset:57600
	ds_read_b128 v[78:81], v130 offset:59904
	ds_read_b128 v[82:85], v130 offset:62208
	s_setprio 1
	s_waitcnt lgkmcnt(3)
	v_mfma_f32_16x16x32_bf16 v[94:97], v[38:41], v[62:65], v[94:97]
	s_waitcnt lgkmcnt(2)
	v_mfma_f32_16x16x32_bf16 v[90:93], v[38:41], v[66:69], v[90:93]
	s_waitcnt lgkmcnt(1)
	v_mfma_f32_16x16x32_bf16 v[86:89], v[38:41], v[78:81], v[86:89]
	s_waitcnt lgkmcnt(0)
	v_mfma_f32_16x16x32_bf16 v[2:5], v[38:41], v[82:85], v[2:5]
	v_mfma_f32_16x16x32_bf16 v[30:33], v[42:45], v[62:65], v[30:33]
	v_mfma_f32_16x16x32_bf16 v[38:41], v[42:45], v[66:69], v[74:77]
	v_mfma_f32_16x16x32_bf16 v[70:73], v[42:45], v[78:81], v[70:73]
	v_mfma_f32_16x16x32_bf16 v[6:9], v[42:45], v[82:85], v[6:9]
	v_mfma_f32_16x16x32_bf16 v[74:77], v[46:49], v[62:65], v[34:37]
	v_mfma_f32_16x16x32_bf16 v[98:101], v[46:49], v[66:69], v[58:61]
	v_mfma_f32_16x16x32_bf16 v[102:105], v[46:49], v[78:81], v[54:57]
	v_mfma_f32_16x16x32_bf16 v[10:13], v[46:49], v[82:85], v[10:13]
	v_mfma_f32_16x16x32_bf16 v[106:109], v[50:53], v[62:65], v[18:21]
	v_mfma_f32_16x16x32_bf16 v[66:69], v[50:53], v[66:69], v[22:25]
	v_mfma_f32_16x16x32_bf16 v[78:81], v[50:53], v[78:81], v[26:29]
	v_mfma_f32_16x16x32_bf16 v[82:85], v[50:53], v[82:85], v[14:17]
	s_setprio 0
	s_nop 1
	ds_read_b128 v[14:17], v0 offset:18496
	ds_read_b128 v[18:21], v0 offset:20800
	ds_read_b128 v[22:25], v0 offset:23104
	ds_read_b128 v[110:113], v0 offset:25408
	ds_read_b128 v[118:121], v130 offset:55360
	ds_read_b128 v[122:125], v130 offset:57664
	ds_read_b128 v[126:129], v130 offset:59968
	ds_read_b128 v[130:133], v130 offset:62272
	s_setprio 1
	s_waitcnt lgkmcnt(3)
	v_mfma_f32_16x16x32_bf16 v[58:61], v[14:17], v[118:121], v[94:97]
	s_waitcnt lgkmcnt(2)
	v_mfma_f32_16x16x32_bf16 v[50:53], v[14:17], v[122:125], v[90:93]
	s_waitcnt lgkmcnt(1)
	v_mfma_f32_16x16x32_bf16 v[62:65], v[14:17], v[126:129], v[86:89]
	s_waitcnt lgkmcnt(0)
	v_mfma_f32_16x16x32_bf16 v[54:57], v[14:17], v[130:133], v[2:5]
	v_mfma_f32_16x16x32_bf16 v[42:45], v[18:21], v[118:121], v[30:33]
	v_mfma_f32_16x16x32_bf16 v[34:37], v[18:21], v[122:125], v[38:41]
	v_mfma_f32_16x16x32_bf16 v[46:49], v[18:21], v[126:129], v[70:73]
	v_mfma_f32_16x16x32_bf16 v[38:41], v[18:21], v[130:133], v[6:9]
	v_mfma_f32_16x16x32_bf16 v[26:29], v[22:25], v[118:121], v[74:77]
	v_mfma_f32_16x16x32_bf16 v[18:21], v[22:25], v[122:125], v[98:101]
	v_mfma_f32_16x16x32_bf16 v[30:33], v[22:25], v[126:129], v[102:105]
	v_mfma_f32_16x16x32_bf16 v[22:25], v[22:25], v[130:133], v[10:13]
	v_mfma_f32_16x16x32_bf16 v[10:13], v[110:113], v[118:121], v[106:109]
	v_mfma_f32_16x16x32_bf16 v[2:5], v[110:113], v[122:125], v[66:69]
	v_mfma_f32_16x16x32_bf16 v[14:17], v[110:113], v[126:129], v[78:81]
	v_mfma_f32_16x16x32_bf16 v[6:9], v[110:113], v[130:133], v[82:85]
	s_setprio 0
	v_and_or_b32 v0, v114, 64, s14
	v_add_u32_e32 v66, s13, v117
	v_lshl_or_b32 v68, v116, 2, v66
	v_ashrrev_i32_e32 v66, 1, v0
	v_ashrrev_i32_e32 v67, 31, v66
	v_lshl_add_u64 v[66:67], v[66:67], 1, s[2:3]
	v_lshlrev_b32_e32 v0, 1, v115
	v_lshl_add_u64 v[66:67], v[66:67], 0, v[0:1]
	v_mul_f32_e32 v0, 0xbfb8aa3b, v58
	v_exp_f32_e32 v0, v0
	v_mad_i64_i32 v[70:71], s[0:1], v68, s54, v[66:67]
	v_add_f32_e32 v0, 1.0, v0
	v_rcp_f32_e32 v0, v0
	s_barrier
; DEV float siluf(float x) { return x * __builtin_amdgcn_rcpf(1.f + __expf(-x)); }
; template <int EPI, bool AF32>
; DEV void gemm_tile(const void* Ap, int lda, const u16* Bt, int ldb, int K, int m0, int n0, const Epi& ea, char* smem) {
;     ...
;       } else if (EPI == EP_SWIGLU) {
;         u16* C = (u16*)ea.p0;
;         const int jb = (cb >> 6) * 32;
; #pragma unroll
;         for (int n = 0; n < 2; n++)
;           __builtin_nontemporal_store(f2bf(siluf(acc[m][n][j]) * acc[m][n + 2][j]), &C[(size_t)row * 2816 + jb + n * 16 + fr]);
	v_mul_f32_e32 v0, v58, v0
	v_mul_f32_e32 v0, v62, v0
	v_cvt_pk_bf16_f32 v0, v0, s0
	global_store_short v[70:71], v0, off nt
	v_mul_f32_e32 v0, 0xbfb8aa3b, v50
	v_exp_f32_e32 v0, v0
	s_nop 0
	v_add_f32_e32 v0, 1.0, v0
	v_rcp_f32_e32 v0, v0
	s_nop 0
	v_mul_f32_e32 v0, v50, v0
	v_mul_f32_e32 v0, v54, v0
	v_cvt_pk_bf16_f32 v0, v0, s0
	global_store_short v[70:71], v0, off offset:32 nt
	v_or_b32_e32 v0, 1, v68
	v_mad_i64_i32 v[70:71], s[0:1], v0, s54, v[66:67]
	v_mul_f32_e32 v0, 0xbfb8aa3b, v59
	v_exp_f32_e32 v0, v0
	s_nop 0
	v_add_f32_e32 v0, 1.0, v0
	v_rcp_f32_e32 v0, v0
	s_nop 0
	v_mul_f32_e32 v0, v59, v0
	v_mul_f32_e32 v0, v63, v0
	v_cvt_pk_bf16_f32 v0, v0, s0
	global_store_short v[70:71], v0, off nt
	v_mul_f32_e32 v0, 0xbfb8aa3b, v51
	v_exp_f32_e32 v0, v0
	s_nop 0
	v_add_f32_e32 v0, 1.0, v0
	v_rcp_f32_e32 v0, v0
	s_nop 0
	v_mul_f32_e32 v0, v51, v0
	v_mul_f32_e32 v0, v55, v0
	v_cvt_pk_bf16_f32 v0, v0, s0
	global_store_short v[70:71], v0, off offset:32 nt
	v_or_b32_e32 v0, 2, v68
	v_mad_i64_i32 v[50:51], s[0:1], v0, s54, v[66:67]
	v_mul_f32_e32 v0, 0xbfb8aa3b, v60
	v_exp_f32_e32 v0, v0
	s_nop 0
	v_add_f32_e32 v0, 1.0, v0
	v_rcp_f32_e32 v0, v0
	s_nop 0
	v_mul_f32_e32 v0, v60, v0
	v_mul_f32_e32 v0, v64, v0
	v_cvt_pk_bf16_f32 v0, v0, s0
	global_store_short v[50:51], v0, off nt
	v_mul_f32_e32 v0, 0xbfb8aa3b, v52
	v_exp_f32_e32 v0, v0
	s_nop 0
	v_add_f32_e32 v0, 1.0, v0
	v_rcp_f32_e32 v0, v0
	s_nop 0
	v_mul_f32_e32 v0, v52, v0
	v_mul_f32_e32 v0, v56, v0
	v_cvt_pk_bf16_f32 v0, v0, s0
	global_store_short v[50:51], v0, off offset:32 nt
	v_or_b32_e32 v0, 3, v68
	v_mad_i64_i32 v[50:51], s[0:1], v0, s54, v[66:67]
	v_mul_f32_e32 v0, 0xbfb8aa3b, v61
	v_exp_f32_e32 v0, v0
	s_nop 0
	v_add_f32_e32 v0, 1.0, v0
	v_rcp_f32_e32 v0, v0
	s_nop 0
	v_mul_f32_e32 v0, v61, v0
	v_mul_f32_e32 v0, v65, v0
	v_cvt_pk_bf16_f32 v0, v0, s0
	global_store_short v[50:51], v0, off nt
	v_mul_f32_e32 v0, 0xbfb8aa3b, v53
	v_exp_f32_e32 v0, v0
	s_nop 0
	v_add_f32_e32 v0, 1.0, v0
	v_rcp_f32_e32 v0, v0
	s_nop 0
	v_mul_f32_e32 v0, v53, v0
	v_mul_f32_e32 v0, v57, v0
	v_cvt_pk_bf16_f32 v0, v0, s0
	global_store_short v[50:51], v0, off offset:32 nt
	v_or_b32_e32 v0, 16, v68
	v_mad_i64_i32 v[50:51], s[0:1], v0, s54, v[66:67]
	v_mul_f32_e32 v0, 0xbfb8aa3b, v42
	v_exp_f32_e32 v0, v0
	s_nop 0
	v_add_f32_e32 v0, 1.0, v0
	v_rcp_f32_e32 v0, v0
	s_nop 0
	v_mul_f32_e32 v0, v42, v0
	v_mul_f32_e32 v0, v46, v0
	v_cvt_pk_bf16_f32 v0, v0, s0
	global_store_short v[50:51], v0, off nt
	v_mul_f32_e32 v0, 0xbfb8aa3b, v34
	v_exp_f32_e32 v0, v0
	s_nop 0
	v_add_f32_e32 v0, 1.0, v0
	v_rcp_f32_e32 v0, v0
	s_nop 0
	v_mul_f32_e32 v0, v34, v0
	v_mul_f32_e32 v0, v38, v0
	v_cvt_pk_bf16_f32 v0, v0, s0
	global_store_short v[50:51], v0, off offset:32 nt
	v_or_b32_e32 v0, 17, v68
	v_mad_i64_i32 v[50:51], s[0:1], v0, s54, v[66:67]
	v_mul_f32_e32 v0, 0xbfb8aa3b, v43
	v_exp_f32_e32 v0, v0
	s_nop 0
	v_add_f32_e32 v0, 1.0, v0
	v_rcp_f32_e32 v0, v0
	s_nop 0
	v_mul_f32_e32 v0, v43, v0
	v_mul_f32_e32 v0, v47, v0
	v_cvt_pk_bf16_f32 v0, v0, s0
	global_store_short v[50:51], v0, off nt
	v_mul_f32_e32 v0, 0xbfb8aa3b, v35
	v_exp_f32_e32 v0, v0
	s_nop 0
	v_add_f32_e32 v0, 1.0, v0
	v_rcp_f32_e32 v0, v0
	s_nop 0
	v_mul_f32_e32 v0, v35, v0
	v_mul_f32_e32 v0, v39, v0
	v_cvt_pk_bf16_f32 v0, v0, s0
	global_store_short v[50:51], v0, off offset:32 nt
	v_or_b32_e32 v0, 18, v68
	v_mad_i64_i32 v[34:35], s[0:1], v0, s54, v[66:67]
	v_mul_f32_e32 v0, 0xbfb8aa3b, v44
	v_exp_f32_e32 v0, v0
	s_nop 0
	v_add_f32_e32 v0, 1.0, v0
	v_rcp_f32_e32 v0, v0
	s_nop 0
	v_mul_f32_e32 v0, v44, v0
	v_mul_f32_e32 v0, v48, v0
	v_cvt_pk_bf16_f32 v0, v0, s0
	global_store_short v[34:35], v0, off nt
	v_mul_f32_e32 v0, 0xbfb8aa3b, v36
	v_exp_f32_e32 v0, v0
	s_nop 0
	v_add_f32_e32 v0, 1.0, v0
	v_rcp_f32_e32 v0, v0
	s_nop 0
	v_mul_f32_e32 v0, v36, v0
	v_mul_f32_e32 v0, v40, v0
	v_cvt_pk_bf16_f32 v0, v0, s0
	global_store_short v[34:35], v0, off offset:32 nt
	v_or_b32_e32 v0, 19, v68
	v_mad_i64_i32 v[34:35], s[0:1], v0, s54, v[66:67]
	v_mul_f32_e32 v0, 0xbfb8aa3b, v45
	v_exp_f32_e32 v0, v0
	s_nop 0
	v_add_f32_e32 v0, 1.0, v0
	v_rcp_f32_e32 v0, v0
	s_nop 0
	v_mul_f32_e32 v0, v45, v0
	v_mul_f32_e32 v0, v49, v0
	v_cvt_pk_bf16_f32 v0, v0, s0
	global_store_short v[34:35], v0, off nt
	v_mul_f32_e32 v0, 0xbfb8aa3b, v37
	v_exp_f32_e32 v0, v0
	s_nop 0
	v_add_f32_e32 v0, 1.0, v0
	v_rcp_f32_e32 v0, v0
	s_nop 0
	v_mul_f32_e32 v0, v37, v0
	v_mul_f32_e32 v0, v41, v0
	v_cvt_pk_bf16_f32 v0, v0, s0
	global_store_short v[34:35], v0, off offset:32 nt
	v_or_b32_e32 v0, 32, v68
	v_mad_i64_i32 v[34:35], s[0:1], v0, s54, v[66:67]
	v_mul_f32_e32 v0, 0xbfb8aa3b, v26
	v_exp_f32_e32 v0, v0
	s_nop 0
; DEV float siluf(float x) { return x * __builtin_amdgcn_rcpf(1.f + __expf(-x)); }
; template <int EPI, bool AF32>
; DEV void gemm_tile(const void* Ap, int lda, const u16* Bt, int ldb, int K, int m0, int n0, const Epi& ea, char* smem) {
;     ...
;       } else if (EPI == EP_SWIGLU) {
;         u16* C = (u16*)ea.p0;
;         const int jb = (cb >> 6) * 32;
; #pragma unroll
;         for (int n = 0; n < 2; n++)
;           __builtin_nontemporal_store(f2bf(siluf(acc[m][n][j]) * acc[m][n + 2][j]), &C[(size_t)row * 2816 + jb + n * 16 + fr]);
	v_add_f32_e32 v0, 1.0, v0
	v_rcp_f32_e32 v0, v0
	s_nop 0
	v_mul_f32_e32 v0, v26, v0
	v_mul_f32_e32 v0, v30, v0
	v_cvt_pk_bf16_f32 v0, v0, s0
	global_store_short v[34:35], v0, off nt
	v_mul_f32_e32 v0, 0xbfb8aa3b, v18
	v_exp_f32_e32 v0, v0
	s_nop 0
	v_add_f32_e32 v0, 1.0, v0
	v_rcp_f32_e32 v0, v0
	s_nop 0
	v_mul_f32_e32 v0, v18, v0
	v_mul_f32_e32 v0, v22, v0
	v_cvt_pk_bf16_f32 v0, v0, s0
	global_store_short v[34:35], v0, off offset:32 nt
	v_or_b32_e32 v0, 33, v68
	v_mad_i64_i32 v[34:35], s[0:1], v0, s54, v[66:67]
	v_mul_f32_e32 v0, 0xbfb8aa3b, v27
	v_exp_f32_e32 v0, v0
	s_nop 0
	v_add_f32_e32 v0, 1.0, v0
	v_rcp_f32_e32 v0, v0
	s_nop 0
	v_mul_f32_e32 v0, v27, v0
	v_mul_f32_e32 v0, v31, v0
	v_cvt_pk_bf16_f32 v0, v0, s0
	global_store_short v[34:35], v0, off nt
	v_mul_f32_e32 v0, 0xbfb8aa3b, v19
	v_exp_f32_e32 v0, v0
	s_nop 0
	v_add_f32_e32 v0, 1.0, v0
	v_rcp_f32_e32 v0, v0
	s_nop 0
	v_mul_f32_e32 v0, v19, v0
	v_mul_f32_e32 v0, v23, v0
	v_cvt_pk_bf16_f32 v0, v0, s0
	global_store_short v[34:35], v0, off offset:32 nt
	v_or_b32_e32 v0, 34, v68
	v_mad_i64_i32 v[18:19], s[0:1], v0, s54, v[66:67]
	v_mul_f32_e32 v0, 0xbfb8aa3b, v28
	v_exp_f32_e32 v0, v0
	s_nop 0
	v_add_f32_e32 v0, 1.0, v0
	v_rcp_f32_e32 v0, v0
	s_nop 0
	v_mul_f32_e32 v0, v28, v0
	v_mul_f32_e32 v0, v32, v0
	v_cvt_pk_bf16_f32 v0, v0, s0
	global_store_short v[18:19], v0, off nt
	v_mul_f32_e32 v0, 0xbfb8aa3b, v20
	v_exp_f32_e32 v0, v0
	s_nop 0
	v_add_f32_e32 v0, 1.0, v0
	v_rcp_f32_e32 v0, v0
	s_nop 0
	v_mul_f32_e32 v0, v20, v0
	v_mul_f32_e32 v0, v24, v0
	v_cvt_pk_bf16_f32 v0, v0, s0
	global_store_short v[18:19], v0, off offset:32 nt
	v_or_b32_e32 v0, 35, v68
	v_mad_i64_i32 v[18:19], s[0:1], v0, s54, v[66:67]
	v_mul_f32_e32 v0, 0xbfb8aa3b, v29
	v_exp_f32_e32 v0, v0
	s_nop 0
	v_add_f32_e32 v0, 1.0, v0
	v_rcp_f32_e32 v0, v0
	s_nop 0
	v_mul_f32_e32 v0, v29, v0
	v_mul_f32_e32 v0, v33, v0
	v_cvt_pk_bf16_f32 v0, v0, s0
	global_store_short v[18:19], v0, off nt
	v_mul_f32_e32 v0, 0xbfb8aa3b, v21
	v_exp_f32_e32 v0, v0
	s_nop 0
	v_add_f32_e32 v0, 1.0, v0
	v_rcp_f32_e32 v0, v0
	s_nop 0
	v_mul_f32_e32 v0, v21, v0
	v_mul_f32_e32 v0, v25, v0
	v_cvt_pk_bf16_f32 v0, v0, s0
	global_store_short v[18:19], v0, off offset:32 nt
	v_or_b32_e32 v0, 48, v68
	v_mad_i64_i32 v[18:19], s[0:1], v0, s54, v[66:67]
	v_mul_f32_e32 v0, 0xbfb8aa3b, v10
	v_exp_f32_e32 v0, v0
	s_nop 0
	v_add_f32_e32 v0, 1.0, v0
	v_rcp_f32_e32 v0, v0
	s_nop 0
	v_mul_f32_e32 v0, v10, v0
	v_mul_f32_e32 v0, v14, v0
	v_cvt_pk_bf16_f32 v0, v0, s0
	global_store_short v[18:19], v0, off nt
	v_mul_f32_e32 v0, 0xbfb8aa3b, v2
	v_exp_f32_e32 v0, v0
	s_nop 0
	v_add_f32_e32 v0, 1.0, v0
	v_rcp_f32_e32 v0, v0
	s_nop 0
	v_mul_f32_e32 v0, v2, v0
	v_mul_f32_e32 v0, v6, v0
	v_cvt_pk_bf16_f32 v0, v0, s0
	global_store_short v[18:19], v0, off offset:32 nt
	v_or_b32_e32 v0, 49, v68
	v_mad_i64_i32 v[18:19], s[0:1], v0, s54, v[66:67]
	v_mul_f32_e32 v0, 0xbfb8aa3b, v11
	v_exp_f32_e32 v0, v0
	s_nop 0
	v_add_f32_e32 v0, 1.0, v0
	v_rcp_f32_e32 v0, v0
	s_nop 0
	v_mul_f32_e32 v0, v11, v0
	v_mul_f32_e32 v0, v15, v0
	v_cvt_pk_bf16_f32 v0, v0, s0
	global_store_short v[18:19], v0, off nt
	v_mul_f32_e32 v0, 0xbfb8aa3b, v3
	v_exp_f32_e32 v0, v0
	s_nop 0
	v_add_f32_e32 v0, 1.0, v0
	v_rcp_f32_e32 v0, v0
	s_nop 0
	v_mul_f32_e32 v0, v3, v0
	v_mul_f32_e32 v0, v7, v0
	v_cvt_pk_bf16_f32 v0, v0, s0
	global_store_short v[18:19], v0, off offset:32 nt
	v_or_b32_e32 v0, 50, v68
	v_mad_i64_i32 v[2:3], s[0:1], v0, s54, v[66:67]
	v_mul_f32_e32 v0, 0xbfb8aa3b, v12
	v_exp_f32_e32 v0, v0
	s_nop 0
	v_add_f32_e32 v0, 1.0, v0
	v_rcp_f32_e32 v0, v0
	s_nop 0
	v_mul_f32_e32 v0, v12, v0
	v_mul_f32_e32 v0, v16, v0
	v_cvt_pk_bf16_f32 v0, v0, s0
	global_store_short v[2:3], v0, off nt
	v_mul_f32_e32 v0, 0xbfb8aa3b, v4
	v_exp_f32_e32 v0, v0
	s_nop 0
	v_add_f32_e32 v0, 1.0, v0
	v_rcp_f32_e32 v0, v0
	s_nop 0
	v_mul_f32_e32 v0, v4, v0
	v_mul_f32_e32 v0, v8, v0
	v_cvt_pk_bf16_f32 v0, v0, s0
	global_store_short v[2:3], v0, off offset:32 nt
	v_or_b32_e32 v0, 51, v68
	v_mad_i64_i32 v[2:3], s[0:1], v0, s54, v[66:67]
	v_mul_f32_e32 v0, 0xbfb8aa3b, v13
	v_exp_f32_e32 v0, v0
	s_nop 0
	v_add_f32_e32 v0, 1.0, v0
	v_rcp_f32_e32 v0, v0
	s_nop 0
	v_mul_f32_e32 v0, v13, v0
	v_mul_f32_e32 v0, v17, v0
	v_cvt_pk_bf16_f32 v0, v0, s0
	global_store_short v[2:3], v0, off nt
	v_mul_f32_e32 v0, 0xbfb8aa3b, v5
	v_exp_f32_e32 v0, v0
	s_nop 0
	v_add_f32_e32 v0, 1.0, v0
	v_rcp_f32_e32 v0, v0
	s_nop 0
	v_mul_f32_e32 v0, v5, v0
	v_mul_f32_e32 v0, v9, v0
	v_cvt_pk_bf16_f32 v0, v0, s0
	v_readfirstlane_b32 s0, v198
	global_store_short v[2:3], v0, off offset:32 nt
	s_add_i32 s12, s0, s12
	s_cmpk_lt_i32 s12, 0x2cb0
	s_cbranch_scc1 .LBB0_1436

; template <int EPI, bool AF32>
; DEV void gemm_tile(const void* Ap, int lda, const u16* Bt, int ldb, int K, int m0, int n0, const Epi& ea, char* smem) {
;     ...
;   auto gload = [&](int kt) {
;     const int k0 = kt << 6;
; #pragma unroll
;     for (int i = 0; i < 4; i++) {
;       const int c = tid + i * 256, row = c >> 3, kc = c & 7;
;       if (AF32) {
;         const float* pa = (const float*)Ap + (size_t)(m0 + row) * lda + k0 + kc * 8;
;         rfa[2 * i] = *(const f32x4*)pa;
;         rfa[2 * i + 1] = *(const f32x4*)(pa + 4);
;       } else {
;         ra[i] = *(const u32x4*)((const u16*)Ap + (size_t)(m0 + row) * lda + k0 + kc * 8);
;       }
;       rb[i] = *(const u32x4*)(Bt + (size_t)(n0 + row) * ldb + k0 + kc * 8);
;     }
;   };
;   auto swrite = [&](int buf) {
; #pragma unroll
;     for (int i = 0; i < 4; i++) {
;       const int c = tid + i * 256, row = c >> 3, kc = c & 7;
;       u32x4 va;
;       if (AF32) {
;         va = (u32x4){pack2(rfa[2 * i][0], rfa[2 * i][1]), pack2(rfa[2 * i][2], rfa[2 * i][3]),
;                      pack2(rfa[2 * i + 1][0], rfa[2 * i + 1][1]), pack2(rfa[2 * i + 1][2], rfa[2 * i + 1][3])};
;       } else {
;         va = ra[i];
;       }
;       *(u32x4*)(sA + buf * 9216 + row * 72 + kc * 8) = va;
;       *(u32x4*)(sB + buf * 9216 + row * 72 + kc * 8) = rb[i];
;     }
;   };
;   gload(0);
;   swrite(0);
;   if (nk > 1) gload(1);
;   __syncthreads();
.LBB0_1478:
	s_ashr_i32 s0, s14, 31
	s_lshr_b32 s0, s0, 24
	s_add_i32 s0, s14, s0
	s_ashr_i32 s1, s0, 8
	s_and_b32 s0, s0, 0xffffff00
	s_lshl_b32 s16, s1, 5
	s_sub_i32 s15, s14, s0
	s_sub_i32 s0, 0x104, s16
	s_min_u32 s17, s0, 32
	v_cvt_f32_ubyte0_e32 v2, s17
	v_cvt_f32_i32_e32 v0, s15
	v_rcp_iflag_f32_e32 v3, v2
	s_ashr_i32 s0, s15, 30
	s_or_b32 s18, s0, 1
	s_waitcnt vmcnt(12)
	v_mov_b32_e32 v116, v157
	v_mul_f32_e32 v3, v0, v3
	v_trunc_f32_e32 v3, v3
	v_fma_f32 v0, -v3, v2, v0
	v_cvt_i32_f32_e32 v3, v3
	v_cmp_ge_f32_e64 s[0:1], |v0|, v2
	s_and_b64 s[0:1], s[0:1], exec
	s_cselect_b32 s0, s18, 0
	v_readfirstlane_b32 s1, v3
	s_add_i32 s0, s1, s0
	s_sext_i32_i16 s1, s0
	s_mul_i32 s0, s0, s17
	s_sub_i32 s0, s15, s0
	s_sext_i32_i16 s0, s0
	s_add_i32 s16, s16, s0
	s_lshl_b32 s16, s16, 7
	v_mov_b64_e32 v[2:3], s[6:7]
	v_ashrrev_i32_e32 v54, 3, v116
	v_lshlrev_b32_e32 v0, 3, v116
	v_add_u32_e32 v62, s16, v54
	v_and_b32_e32 v0, 56, v0
	s_lshl_b32 s15, s1, 7
	v_mad_i64_i32 v[4:5], s[0:1], v62, s54, v[2:3]
	v_lshlrev_b32_e32 v0, 1, v0
	v_add_u32_e32 v18, 0x100, v116
	v_add_u32_e32 v26, 0x200, v116
	v_lshl_add_u64 v[6:7], v[4:5], 0, v[0:1]
	v_add_u32_e32 v55, s15, v54
	v_mov_b64_e32 v[4:5], s[8:9]
	v_ashrrev_i32_e32 v70, 3, v18
	v_ashrrev_i32_e32 v71, 3, v26
	v_mad_i64_i32 v[8:9], s[0:1], v55, s54, v[4:5]
	v_add_u32_e32 v64, s16, v70
	v_add_u32_e32 v56, s15, v70
	v_add_u32_e32 v66, s16, v71
	v_add_u32_e32 v58, s15, v71
	v_lshl_add_u64 v[8:9], v[8:9], 0, v[0:1]
	v_mad_i64_i32 v[18:19], s[0:1], v64, s54, v[2:3]
	v_mad_i64_i32 v[22:23], s[0:1], v56, s54, v[4:5]
	v_mad_i64_i32 v[26:27], s[0:1], v66, s54, v[2:3]
	v_mad_i64_i32 v[30:31], s[0:1], v58, s54, v[4:5]
	global_load_dwordx4 v[14:17], v[8:9], off
	v_lshl_add_u64 v[42:43], v[18:19], 0, v[0:1]
	v_lshl_add_u64 v[44:45], v[22:23], 0, v[0:1]
	v_lshl_add_u64 v[46:47], v[26:27], 0, v[0:1]
	v_lshl_add_u64 v[48:49], v[30:31], 0, v[0:1]
	global_load_dwordx4 v[10:13], v[6:7], off
	global_load_dwordx4 v[18:21], v[42:43], off
	global_load_dwordx4 v[22:25], v[44:45], off
	global_load_dwordx4 v[26:29], v[46:47], off
	global_load_dwordx4 v[30:33], v[48:49], off
	v_add_u32_e32 v34, 0x300, v116
	v_ashrrev_i32_e32 v72, 3, v34
	v_add_u32_e32 v68, s16, v72
	v_mad_i64_i32 v[2:3], s[0:1], v68, s54, v[2:3]
	v_lshl_add_u64 v[50:51], v[2:3], 0, v[0:1]
	global_load_dwordx4 v[34:37], v[50:51], off
	v_add_u32_e32 v60, s15, v72
	v_mad_i64_i32 v[2:3], s[0:1], v60, s54, v[4:5]
	s_waitcnt vmcnt(18)
	v_mul_lo_u32 v119, v54, s71
	v_lshl_add_u64 v[52:53], v[2:3], 0, v[0:1]
	v_bfe_u32 v161, v157, 3, 4
	v_add_u32_e32 v161, 4, v161
	v_lshlrev_b32_e32 v161, 1, v161
	v_and_b32_e32 v161, 16, v161
	v_xor_b32_e32 v129, v0, v161
	v_lshl_add_u32 v118, v119, 1, v129
	v_mul_lo_u32 v121, v70, s71
	s_waitcnt vmcnt(17)
	v_mul_lo_u32 v124, v71, s71
	global_load_dwordx4 v[38:41], v[52:53], off
	global_load_dwordx4 v[2:5], v[8:9], off offset:128
	v_lshl_add_u32 v120, v121, 1, v129
	global_load_dwordx4 v[6:9], v[6:7], off offset:128
	v_lshl_add_u32 v122, v124, 1, v129
	s_waitcnt vmcnt(19)
	v_mul_lo_u32 v126, v72, s71
	v_lshl_add_u32 v123, v126, 1, v129
	v_and_b32_e32 v114, 15, v116
	v_mad_i64_i32 v[54:55], s[0:1], v55, s54, 0
	v_mad_i64_i32 v[56:57], s[0:1], v56, s54, 0
	v_mad_i64_i32 v[58:59], s[0:1], v58, s54, 0
	v_mad_i64_i32 v[60:61], s[0:1], v60, s54, 0
	v_mad_i64_i32 v[62:63], s[0:1], v62, s54, 0
	v_mad_i64_i32 v[64:65], s[0:1], v64, s54, 0
	v_mad_i64_i32 v[66:67], s[0:1], v66, s54, 0
	v_mad_i64_i32 v[68:69], s[0:1], v68, s54, 0
	s_waitcnt vmcnt(9)
	ds_write_b128 v118, v[14:17] offset:36864
	s_waitcnt vmcnt(8)
	ds_write_b128 v118, v[10:13]
	global_load_dwordx4 v[10:13], v[42:43], off offset:128
	s_waitcnt vmcnt(8)
	ds_write_b128 v120, v[18:21]
	global_load_dwordx4 v[14:17], v[44:45], off offset:128
	s_waitcnt vmcnt(8)
	ds_write_b128 v120, v[22:25] offset:36864
	global_load_dwordx4 v[18:21], v[46:47], off offset:128
	s_waitcnt vmcnt(8)
	ds_write_b128 v122, v[26:29]
	global_load_dwordx4 v[22:25], v[48:49], off offset:128
	s_waitcnt vmcnt(8)
	ds_write_b128 v122, v[30:33] offset:36864
	global_load_dwordx4 v[26:29], v[50:51], off offset:128
	global_load_dwordx4 v[30:33], v[52:53], off offset:128
	v_bfe_u32 v115, v116, 4, 2
	s_waitcnt vmcnt(9)
	ds_write_b128 v123, v[34:37]
	v_ashrrev_i32_e32 v34, 1, v116
	v_and_b32_e32 v117, 0xffffffc0, v34
	v_or_b32_e32 v34, v117, v114
	v_mul_lo_u32 v128, v34, s71
	v_lshlrev_b32_e32 v34, 4, v116
	v_and_b32_e32 v34, 0x70, v34
	v_and_b32_e32 v35, 0x4f, v116
	v_or_b32_e32 v60, v60, v34
	v_or_b32_e32 v68, v68, v34
	v_or_b32_e32 v58, v58, v34
	v_or_b32_e32 v66, v66, v34
	v_or_b32_e32 v56, v56, v34
	v_or_b32_e32 v64, v64, v34
	v_or_b32_e32 v54, v54, v34
	v_or_b32_e32 v62, v62, v34
	v_mov_b32_e32 v34, 0
	s_mov_b32 s17, 0
	s_waitcnt vmcnt(8)
; DEV f32x4 mfma16(bf16x8 a, bf16x8 b, f32x4 c) { return __builtin_amdgcn_mfma_f32_16x16x32_bf16(a, b, c, 0, 0, 0); }
; template <int EPI, bool AF32>
; DEV void gemm_tile(const void* Ap, int lda, const u16* Bt, int ldb, int K, int m0, int n0, const Epi& ea, char* smem) {
;     ...
;   f32x4 acc[4][4];
; #pragma unroll
;   for (int m = 0; m < 4; m++)
; #pragma unroll
;     for (int n = 0; n < 4; n++) acc[m][n] = (f32x4){0.f, 0.f, 0.f, 0.f};
;     ...
;   for (int kt = 0; kt < nk; kt++) {
;     const int buf = kt & 1;
;     if (kt + 1 < nk) swrite(buf ^ 1);
;     if (kt + 2 < nk) gload(kt + 2);
; #pragma unroll
;     for (int ks = 0; ks < 2; ks++) {
;       bf16x8 a[4], b[4];
; #pragma unroll
;       for (int m = 0; m < 4; m++) a[m] = *(const bf16x8*)(sA + buf * 9216 + (wr * 64 + m * 16 + fr) * 72 + ks * 32 + fq * 8);
; #pragma unroll
;       for (int n = 0; n < 4; n++) b[n] = *(const bf16x8*)(sB + buf * 9216 + (wc * 64 + n * 16 + fr) * 72 + ks * 32 + fq * 8);
;       __builtin_amdgcn_s_setprio(1);
; #pragma unroll
;       for (int m = 0; m < 4; m++)
; #pragma unroll
;         for (int n = 0; n < 4; n++) acc[m][n] = mfma16(a[m], b[n], acc[m][n]);
;       __builtin_amdgcn_s_setprio(0);
;     }
;     __syncthreads();
	ds_write_b128 v123, v[38:41] offset:36864
	v_lshlrev_b32_e32 v125, 4, v115
	v_and_b32_e32 v161, 15, v157
	v_add_u32_e32 v161, 4, v161
	v_lshlrev_b32_e32 v161, 1, v161
	v_and_b32_e32 v161, 16, v161
	v_xor_b32_e32 v125, v125, v161
	v_mul_u32_u24_e32 v127, 0x48, v35
	v_lshl_add_u64 v[98:99], s[10:11], 0, v[60:61]
	v_lshl_add_u64 v[100:101], s[12:13], 0, v[68:69]
	v_lshl_add_u64 v[102:103], s[10:11], 0, v[58:59]
	v_lshl_add_u64 v[104:105], s[12:13], 0, v[66:67]
	v_lshl_add_u64 v[106:107], s[10:11], 0, v[56:57]
	v_lshl_add_u64 v[108:109], s[12:13], 0, v[64:65]
	v_lshl_add_u64 v[110:111], s[10:11], 0, v[54:55]
	v_lshl_add_u64 v[112:113], s[12:13], 0, v[62:63]
	global_load_dwordx4 v[222:225], v[112:113], off
	global_load_dwordx4 v[226:229], v[110:111], off
	global_load_dwordx4 v[230:233], v[108:109], off
	global_load_dwordx4 v[234:237], v[106:107], off
	global_load_dwordx4 v[238:241], v[104:105], off
	global_load_dwordx4 v[242:245], v[102:103], off
	global_load_dwordx4 v[246:249], v[100:101], off
	global_load_dwordx4 v[250:253], v[98:99], off
	s_mov_b64 s[0:1], 0
	v_mov_b32_e32 v35, v34
	v_mov_b32_e32 v36, v34
	v_mov_b32_e32 v37, v34
	v_mov_b32_e32 v38, v34
	v_mov_b32_e32 v39, v34
	v_mov_b32_e32 v40, v34
	v_mov_b32_e32 v41, v34
	v_mov_b32_e32 v42, v34
	v_mov_b32_e32 v43, v34
	v_mov_b32_e32 v44, v34
	v_mov_b32_e32 v45, v34
	v_mov_b32_e32 v46, v34
	v_mov_b32_e32 v47, v34
	v_mov_b32_e32 v48, v34
	v_mov_b32_e32 v49, v34
	v_mov_b32_e32 v50, v34
	v_mov_b32_e32 v51, v34
	v_mov_b32_e32 v52, v34
	v_mov_b32_e32 v53, v34
	v_mov_b32_e32 v54, v34
	v_mov_b32_e32 v55, v34
	v_mov_b32_e32 v56, v34
	v_mov_b32_e32 v57, v34
	v_mov_b32_e32 v58, v34
	v_mov_b32_e32 v59, v34
	v_mov_b32_e32 v60, v34
	v_mov_b32_e32 v61, v34
	v_mov_b32_e32 v62, v34
	v_mov_b32_e32 v63, v34
	v_mov_b32_e32 v64, v34
	v_mov_b32_e32 v65, v34
	v_mov_b32_e32 v66, v34
	v_mov_b32_e32 v67, v34
	v_mov_b32_e32 v68, v34
	v_mov_b32_e32 v69, v34
	v_mov_b32_e32 v70, v34
	v_mov_b32_e32 v71, v34
	v_mov_b32_e32 v72, v34
	v_mov_b32_e32 v73, v34
	v_mov_b32_e32 v74, v34
	v_mov_b32_e32 v75, v34
	v_mov_b32_e32 v76, v34
	v_mov_b32_e32 v77, v34
	v_mov_b32_e32 v78, v34
	v_mov_b32_e32 v79, v34
	v_mov_b32_e32 v80, v34
	v_mov_b32_e32 v81, v34
	v_mov_b32_e32 v82, v34
	v_mov_b32_e32 v83, v34
	v_mov_b32_e32 v84, v34
	v_mov_b32_e32 v85, v34
	v_mov_b32_e32 v86, v34
	v_mov_b32_e32 v87, v34
	v_mov_b32_e32 v88, v34
	v_mov_b32_e32 v89, v34
	v_mov_b32_e32 v90, v34
	v_mov_b32_e32 v91, v34
	v_mov_b32_e32 v92, v34
	v_mov_b32_e32 v93, v34
	v_mov_b32_e32 v94, v34
	v_mov_b32_e32 v95, v34
	v_mov_b32_e32 v96, v34
	v_mov_b32_e32 v97, v34
	s_waitcnt lgkmcnt(0)
	s_barrier
	v_lshl_add_u32 v161, v128, 1, v125
	v_lshl_add_u32 v129, v127, 1, v125
	s_mov_b32 s17, 0
	s_mov_b64 s[0:1], 0x100
.Lgk7_loop:
	v_lshl_add_u64 v[112:113], v[112:113], 0, s[0:1]
	v_lshl_add_u64 v[110:111], v[110:111], 0, s[0:1]
	v_lshl_add_u64 v[108:109], v[108:109], 0, s[0:1]
	v_lshl_add_u64 v[106:107], v[106:107], 0, s[0:1]
	v_lshl_add_u64 v[104:105], v[104:105], 0, s[0:1]
	v_lshl_add_u64 v[102:103], v[102:103], 0, s[0:1]
	v_lshl_add_u64 v[100:101], v[100:101], 0, s[0:1]
	v_lshl_add_u64 v[98:99], v[98:99], 0, s[0:1]
	ds_read_b128 v[130:133], v161
	ds_read_b128 v[134:137], v161 offset:2304
	ds_read_b128 v[138:141], v161 offset:4608
	ds_read_b128 v[142:145], v161 offset:6912
	ds_read_b128 v[146:149], v129 offset:36864
	ds_read_b128 v[150:153], v129 offset:39168
	ds_read_b128 v[162:165], v129 offset:41472
	ds_read_b128 v[166:169], v129 offset:43776
	s_setprio 1
	s_waitcnt lgkmcnt(3)
	v_mfma_f32_16x16x32_bf16 v[34:37], v[130:133], v[146:149], v[34:37]
	s_waitcnt lgkmcnt(2)
	v_mfma_f32_16x16x32_bf16 v[38:41], v[130:133], v[150:153], v[38:41]
	s_waitcnt lgkmcnt(1)
	v_mfma_f32_16x16x32_bf16 v[42:45], v[130:133], v[162:165], v[42:45]
	s_waitcnt lgkmcnt(0)
	v_mfma_f32_16x16x32_bf16 v[46:49], v[130:133], v[166:169], v[46:49]
	v_mfma_f32_16x16x32_bf16 v[50:53], v[134:137], v[146:149], v[50:53]
	v_mfma_f32_16x16x32_bf16 v[54:57], v[134:137], v[150:153], v[54:57]
	v_mfma_f32_16x16x32_bf16 v[58:61], v[134:137], v[162:165], v[58:61]
	v_mfma_f32_16x16x32_bf16 v[62:65], v[134:137], v[166:169], v[62:65]
	v_mfma_f32_16x16x32_bf16 v[66:69], v[138:141], v[146:149], v[66:69]
	v_mfma_f32_16x16x32_bf16 v[70:73], v[138:141], v[150:153], v[70:73]
	v_mfma_f32_16x16x32_bf16 v[74:77], v[138:141], v[162:165], v[74:77]
	v_mfma_f32_16x16x32_bf16 v[78:81], v[138:141], v[166:169], v[78:81]
	v_mfma_f32_16x16x32_bf16 v[82:85], v[142:145], v[146:149], v[82:85]
	v_mfma_f32_16x16x32_bf16 v[86:89], v[142:145], v[150:153], v[86:89]
	v_mfma_f32_16x16x32_bf16 v[90:93], v[142:145], v[162:165], v[90:93]
	v_mfma_f32_16x16x32_bf16 v[94:97], v[142:145], v[166:169], v[94:97]
	s_setprio 0
	ds_read_b128 v[130:133], v161 offset:64
	ds_read_b128 v[134:137], v161 offset:2368
	ds_read_b128 v[138:141], v161 offset:4672
	ds_read_b128 v[142:145], v161 offset:6976
	ds_read_b128 v[146:149], v129 offset:36928
	ds_read_b128 v[150:153], v129 offset:39232
	ds_read_b128 v[162:165], v129 offset:41536
	ds_read_b128 v[166:169], v129 offset:43840
	s_waitcnt vmcnt(8)
	ds_write_b128 v118, v[6:9] offset:18432
	ds_write_b128 v118, v[2:5] offset:55296
	ds_write_b128 v120, v[10:13] offset:18432
	ds_write_b128 v120, v[14:17] offset:55296
	ds_write_b128 v122, v[18:21] offset:18432
	ds_write_b128 v122, v[22:25] offset:55296
	ds_write_b128 v123, v[26:29] offset:18432
	ds_write_b128 v123, v[30:33] offset:55296
	global_load_dwordx4 v[6:9], v[112:113], off offset:-128
	global_load_dwordx4 v[2:5], v[110:111], off offset:-128
	global_load_dwordx4 v[10:13], v[108:109], off offset:-128
	global_load_dwordx4 v[14:17], v[106:107], off offset:-128
	global_load_dwordx4 v[18:21], v[104:105], off offset:-128
	global_load_dwordx4 v[22:25], v[102:103], off offset:-128
	global_load_dwordx4 v[26:29], v[100:101], off offset:-128
	global_load_dwordx4 v[30:33], v[98:99], off offset:-128
	s_setprio 1
	s_waitcnt lgkmcnt(11)
; DEV f32x4 mfma16(bf16x8 a, bf16x8 b, f32x4 c) { return __builtin_amdgcn_mfma_f32_16x16x32_bf16(a, b, c, 0, 0, 0); }
; template <int EPI, bool AF32>
; DEV void gemm_tile(const void* Ap, int lda, const u16* Bt, int ldb, int K, int m0, int n0, const Epi& ea, char* smem) {
;     ...
;   for (int kt = 0; kt < nk; kt++) {
;     const int buf = kt & 1;
;     if (kt + 1 < nk) swrite(buf ^ 1);
;     if (kt + 2 < nk) gload(kt + 2);
; #pragma unroll
;     for (int ks = 0; ks < 2; ks++) {
;       bf16x8 a[4], b[4];
; #pragma unroll
;       for (int m = 0; m < 4; m++) a[m] = *(const bf16x8*)(sA + buf * 9216 + (wr * 64 + m * 16 + fr) * 72 + ks * 32 + fq * 8);
; #pragma unroll
;       for (int n = 0; n < 4; n++) b[n] = *(const bf16x8*)(sB + buf * 9216 + (wc * 64 + n * 16 + fr) * 72 + ks * 32 + fq * 8);
;       __builtin_amdgcn_s_setprio(1);
; #pragma unroll
;       for (int m = 0; m < 4; m++)
; #pragma unroll
;         for (int n = 0; n < 4; n++) acc[m][n] = mfma16(a[m], b[n], acc[m][n]);
;       __builtin_amdgcn_s_setprio(0);
;     }
;     __syncthreads();
	v_mfma_f32_16x16x32_bf16 v[34:37], v[130:133], v[146:149], v[34:37]
	s_waitcnt lgkmcnt(10)
	v_mfma_f32_16x16x32_bf16 v[38:41], v[130:133], v[150:153], v[38:41]
	s_waitcnt lgkmcnt(9)
	v_mfma_f32_16x16x32_bf16 v[42:45], v[130:133], v[162:165], v[42:45]
	s_waitcnt lgkmcnt(8)
	v_mfma_f32_16x16x32_bf16 v[46:49], v[130:133], v[166:169], v[46:49]
	v_mfma_f32_16x16x32_bf16 v[50:53], v[134:137], v[146:149], v[50:53]
	v_mfma_f32_16x16x32_bf16 v[54:57], v[134:137], v[150:153], v[54:57]
	v_mfma_f32_16x16x32_bf16 v[58:61], v[134:137], v[162:165], v[58:61]
	v_mfma_f32_16x16x32_bf16 v[62:65], v[134:137], v[166:169], v[62:65]
	v_mfma_f32_16x16x32_bf16 v[66:69], v[138:141], v[146:149], v[66:69]
	v_mfma_f32_16x16x32_bf16 v[70:73], v[138:141], v[150:153], v[70:73]
	v_mfma_f32_16x16x32_bf16 v[74:77], v[138:141], v[162:165], v[74:77]
	v_mfma_f32_16x16x32_bf16 v[78:81], v[138:141], v[166:169], v[78:81]
	v_mfma_f32_16x16x32_bf16 v[82:85], v[142:145], v[146:149], v[82:85]
	v_mfma_f32_16x16x32_bf16 v[86:89], v[142:145], v[150:153], v[86:89]
	v_mfma_f32_16x16x32_bf16 v[90:93], v[142:145], v[162:165], v[90:93]
	v_mfma_f32_16x16x32_bf16 v[94:97], v[142:145], v[166:169], v[94:97]
	s_setprio 0
	s_waitcnt lgkmcnt(0)
	s_barrier
	ds_read_b128 v[130:133], v161 offset:18432
	ds_read_b128 v[134:137], v161 offset:20736
	ds_read_b128 v[138:141], v161 offset:23040
	ds_read_b128 v[142:145], v161 offset:25344
	ds_read_b128 v[146:149], v129 offset:55296
	ds_read_b128 v[150:153], v129 offset:57600
	ds_read_b128 v[162:165], v129 offset:59904
	ds_read_b128 v[166:169], v129 offset:62208
	s_setprio 1
	s_waitcnt lgkmcnt(3)
	v_mfma_f32_16x16x32_bf16 v[34:37], v[130:133], v[146:149], v[34:37]
	s_waitcnt lgkmcnt(2)
	v_mfma_f32_16x16x32_bf16 v[38:41], v[130:133], v[150:153], v[38:41]
	s_waitcnt lgkmcnt(1)
	v_mfma_f32_16x16x32_bf16 v[42:45], v[130:133], v[162:165], v[42:45]
	s_waitcnt lgkmcnt(0)
	v_mfma_f32_16x16x32_bf16 v[46:49], v[130:133], v[166:169], v[46:49]
	v_mfma_f32_16x16x32_bf16 v[50:53], v[134:137], v[146:149], v[50:53]
	v_mfma_f32_16x16x32_bf16 v[54:57], v[134:137], v[150:153], v[54:57]
	v_mfma_f32_16x16x32_bf16 v[58:61], v[134:137], v[162:165], v[58:61]
	v_mfma_f32_16x16x32_bf16 v[62:65], v[134:137], v[166:169], v[62:65]
	v_mfma_f32_16x16x32_bf16 v[66:69], v[138:141], v[146:149], v[66:69]
	v_mfma_f32_16x16x32_bf16 v[70:73], v[138:141], v[150:153], v[70:73]
	v_mfma_f32_16x16x32_bf16 v[74:77], v[138:141], v[162:165], v[74:77]
	v_mfma_f32_16x16x32_bf16 v[78:81], v[138:141], v[166:169], v[78:81]
	v_mfma_f32_16x16x32_bf16 v[82:85], v[142:145], v[146:149], v[82:85]
	v_mfma_f32_16x16x32_bf16 v[86:89], v[142:145], v[150:153], v[86:89]
	v_mfma_f32_16x16x32_bf16 v[90:93], v[142:145], v[162:165], v[90:93]
	v_mfma_f32_16x16x32_bf16 v[94:97], v[142:145], v[166:169], v[94:97]
	s_setprio 0
	ds_read_b128 v[130:133], v161 offset:18496
	ds_read_b128 v[134:137], v161 offset:20800
	ds_read_b128 v[138:141], v161 offset:23104
	ds_read_b128 v[142:145], v161 offset:25408
	ds_read_b128 v[146:149], v129 offset:55360
	ds_read_b128 v[150:153], v129 offset:57664
	ds_read_b128 v[162:165], v129 offset:59968
	ds_read_b128 v[166:169], v129 offset:62272
	s_waitcnt vmcnt(8)
	ds_write_b128 v118, v[222:225]
	ds_write_b128 v118, v[226:229] offset:36864
	ds_write_b128 v120, v[230:233]
	ds_write_b128 v120, v[234:237] offset:36864
	ds_write_b128 v122, v[238:241]
	ds_write_b128 v122, v[242:245] offset:36864
	ds_write_b128 v123, v[246:249]
	ds_write_b128 v123, v[250:253] offset:36864
	s_cmp_eq_u32 s17, 20
	s_cbranch_scc1 .Lgk7_nold
	global_load_dwordx4 v[222:225], v[112:113], off
	global_load_dwordx4 v[226:229], v[110:111], off
	global_load_dwordx4 v[230:233], v[108:109], off
	global_load_dwordx4 v[234:237], v[106:107], off
	global_load_dwordx4 v[238:241], v[104:105], off
	global_load_dwordx4 v[242:245], v[102:103], off
	global_load_dwordx4 v[246:249], v[100:101], off
	global_load_dwordx4 v[250:253], v[98:99], off
.Lgk7_nold:
	s_setprio 1
	s_waitcnt lgkmcnt(11)
	v_mfma_f32_16x16x32_bf16 v[34:37], v[130:133], v[146:149], v[34:37]
	s_waitcnt lgkmcnt(10)
	v_mfma_f32_16x16x32_bf16 v[38:41], v[130:133], v[150:153], v[38:41]
	s_waitcnt lgkmcnt(9)
	v_mfma_f32_16x16x32_bf16 v[42:45], v[130:133], v[162:165], v[42:45]
	s_waitcnt lgkmcnt(8)
	v_mfma_f32_16x16x32_bf16 v[46:49], v[130:133], v[166:169], v[46:49]
	v_mfma_f32_16x16x32_bf16 v[50:53], v[134:137], v[146:149], v[50:53]
	v_mfma_f32_16x16x32_bf16 v[54:57], v[134:137], v[150:153], v[54:57]
	v_mfma_f32_16x16x32_bf16 v[58:61], v[134:137], v[162:165], v[58:61]
	v_mfma_f32_16x16x32_bf16 v[62:65], v[134:137], v[166:169], v[62:65]
	v_mfma_f32_16x16x32_bf16 v[66:69], v[138:141], v[146:149], v[66:69]
	v_mfma_f32_16x16x32_bf16 v[70:73], v[138:141], v[150:153], v[70:73]
	v_mfma_f32_16x16x32_bf16 v[74:77], v[138:141], v[162:165], v[74:77]
	v_mfma_f32_16x16x32_bf16 v[78:81], v[138:141], v[166:169], v[78:81]
	v_mfma_f32_16x16x32_bf16 v[82:85], v[142:145], v[146:149], v[82:85]
	v_mfma_f32_16x16x32_bf16 v[86:89], v[142:145], v[150:153], v[86:89]
	v_mfma_f32_16x16x32_bf16 v[90:93], v[142:145], v[162:165], v[90:93]
	v_mfma_f32_16x16x32_bf16 v[94:97], v[142:145], v[166:169], v[94:97]
	s_setprio 0
	s_add_i32 s17, s17, 1
	s_cmp_lg_u32 s17, 21
	s_waitcnt lgkmcnt(0)
	s_barrier
	s_cbranch_scc1 .Lgk7_loop
; DEV f32x4 mfma16(bf16x8 a, bf16x8 b, f32x4 c) { return __builtin_amdgcn_mfma_f32_16x16x32_bf16(a, b, c, 0, 0, 0); }
; template <int EPI, bool AF32>
; DEV void gemm_tile(const void* Ap, int lda, const u16* Bt, int ldb, int K, int m0, int n0, const Epi& ea, char* smem) {
;     ...
;   for (int kt = 0; kt < nk; kt++) {
;     const int buf = kt & 1;
;     if (kt + 1 < nk) swrite(buf ^ 1);
;     if (kt + 2 < nk) gload(kt + 2);
; #pragma unroll
;     for (int ks = 0; ks < 2; ks++) {
;       bf16x8 a[4], b[4];
; #pragma unroll
;       for (int m = 0; m < 4; m++) a[m] = *(const bf16x8*)(sA + buf * 9216 + (wr * 64 + m * 16 + fr) * 72 + ks * 32 + fq * 8);
; #pragma unroll
;       for (int n = 0; n < 4; n++) b[n] = *(const bf16x8*)(sB + buf * 9216 + (wc * 64 + n * 16 + fr) * 72 + ks * 32 + fq * 8);
;       __builtin_amdgcn_s_setprio(1);
; #pragma unroll
;       for (int m = 0; m < 4; m++)
; #pragma unroll
;         for (int n = 0; n < 4; n++) acc[m][n] = mfma16(a[m], b[n], acc[m][n]);
;       __builtin_amdgcn_s_setprio(0);
;     }
;     __syncthreads();
;     ...
;     const int rbase = m0 + wr * 64 + fq * 4, cbase = cb + fr;
;     if (EPI == EP_RES) {
;       float* C = (float*)ea.p0;
;       const float* R = (const float*)ea.p1;
;       float rv[4][4][4];
; #pragma unroll
;       for (int m = 0; m < 4; m++)
; #pragma unroll
;         for (int j = 0; j < 4; j++)
; #pragma unroll
;           for (int n = 0; n < 4; n++) rv[m][j][n] = R[(size_t)(rbase + m * 16 + j) * 1024 + cbase + n * 16];
	s_waitcnt vmcnt(7)
	ds_write_b128 v118, v[6:9] offset:18432
	s_waitcnt vmcnt(6)
	ds_write_b128 v118, v[2:5] offset:55296
	s_waitcnt vmcnt(5)
	ds_write_b128 v120, v[10:13] offset:18432
	s_waitcnt vmcnt(4)
	ds_write_b128 v120, v[14:17] offset:55296
	s_waitcnt vmcnt(3)
	ds_write_b128 v122, v[18:21] offset:18432
	s_waitcnt vmcnt(2)
	ds_write_b128 v122, v[22:25] offset:55296
	s_waitcnt vmcnt(1)
	ds_write_b128 v123, v[26:29] offset:18432
	s_waitcnt vmcnt(0)
	ds_write_b128 v123, v[30:33] offset:55296
	v_lshl_add_u32 v0, v128, 1, v125
	v_lshl_add_u32 v126, v127, 1, v125
	ds_read_b128 v[2:5], v0
	ds_read_b128 v[6:9], v0 offset:2304
	ds_read_b128 v[10:13], v0 offset:4608
	ds_read_b128 v[14:17], v0 offset:6912
	ds_read_b128 v[18:21], v126 offset:36864
	ds_read_b128 v[22:25], v126 offset:39168
	ds_read_b128 v[26:29], v126 offset:41472
	ds_read_b128 v[30:33], v126 offset:43776
	s_setprio 1
	s_waitcnt lgkmcnt(3)
	v_mfma_f32_16x16x32_bf16 v[34:37], v[2:5], v[18:21], v[34:37]
	s_waitcnt lgkmcnt(2)
	v_mfma_f32_16x16x32_bf16 v[38:41], v[2:5], v[22:25], v[38:41]
	s_waitcnt lgkmcnt(1)
	v_mfma_f32_16x16x32_bf16 v[42:45], v[2:5], v[26:29], v[42:45]
	s_waitcnt lgkmcnt(0)
	v_mfma_f32_16x16x32_bf16 v[2:5], v[2:5], v[30:33], v[46:49]
	v_mfma_f32_16x16x32_bf16 v[46:49], v[6:9], v[18:21], v[50:53]
	v_mfma_f32_16x16x32_bf16 v[50:53], v[6:9], v[22:25], v[54:57]
	v_mfma_f32_16x16x32_bf16 v[54:57], v[6:9], v[26:29], v[58:61]
	v_mfma_f32_16x16x32_bf16 v[6:9], v[6:9], v[30:33], v[62:65]
	v_mfma_f32_16x16x32_bf16 v[58:61], v[10:13], v[18:21], v[66:69]
	v_mfma_f32_16x16x32_bf16 v[62:65], v[10:13], v[22:25], v[70:73]
	v_mfma_f32_16x16x32_bf16 v[66:69], v[10:13], v[26:29], v[74:77]
	v_mfma_f32_16x16x32_bf16 v[10:13], v[10:13], v[30:33], v[78:81]
	v_mfma_f32_16x16x32_bf16 v[18:21], v[14:17], v[18:21], v[82:85]
	v_mfma_f32_16x16x32_bf16 v[22:25], v[14:17], v[22:25], v[86:89]
	v_mfma_f32_16x16x32_bf16 v[26:29], v[14:17], v[26:29], v[90:93]
	v_mfma_f32_16x16x32_bf16 v[14:17], v[14:17], v[30:33], v[94:97]
	s_setprio 0
	ds_read_b128 v[30:33], v0 offset:64
	ds_read_b128 v[70:73], v0 offset:2368
	ds_read_b128 v[74:77], v0 offset:4672
	ds_read_b128 v[78:81], v0 offset:6976
	ds_read_b128 v[82:85], v126 offset:36928
	ds_read_b128 v[86:89], v126 offset:39232
	ds_read_b128 v[90:93], v126 offset:41536
	ds_read_b128 v[94:97], v126 offset:43840
	s_setprio 1
	s_waitcnt lgkmcnt(3)
	v_mfma_f32_16x16x32_bf16 v[34:37], v[30:33], v[82:85], v[34:37]
	s_waitcnt lgkmcnt(2)
	v_mfma_f32_16x16x32_bf16 v[38:41], v[30:33], v[86:89], v[38:41]
	s_waitcnt lgkmcnt(1)
	v_mfma_f32_16x16x32_bf16 v[42:45], v[30:33], v[90:93], v[42:45]
	s_waitcnt lgkmcnt(0)
	v_mfma_f32_16x16x32_bf16 v[2:5], v[30:33], v[94:97], v[2:5]
	v_mfma_f32_16x16x32_bf16 v[30:33], v[70:73], v[82:85], v[46:49]
	v_mfma_f32_16x16x32_bf16 v[46:49], v[70:73], v[86:89], v[50:53]
	v_mfma_f32_16x16x32_bf16 v[50:53], v[70:73], v[90:93], v[54:57]
	v_mfma_f32_16x16x32_bf16 v[6:9], v[70:73], v[94:97], v[6:9]
	v_mfma_f32_16x16x32_bf16 v[54:57], v[74:77], v[82:85], v[58:61]
	v_mfma_f32_16x16x32_bf16 v[58:61], v[74:77], v[86:89], v[62:65]
	v_mfma_f32_16x16x32_bf16 v[62:65], v[74:77], v[90:93], v[66:69]
	v_mfma_f32_16x16x32_bf16 v[10:13], v[74:77], v[94:97], v[10:13]
	v_mfma_f32_16x16x32_bf16 v[18:21], v[78:81], v[82:85], v[18:21]
	v_mfma_f32_16x16x32_bf16 v[22:25], v[78:81], v[86:89], v[22:25]
	v_mfma_f32_16x16x32_bf16 v[26:29], v[78:81], v[90:93], v[26:29]
	v_mfma_f32_16x16x32_bf16 v[14:17], v[78:81], v[94:97], v[14:17]
	s_setprio 0
	s_barrier
	ds_read_b128 v[66:69], v0 offset:18432
	ds_read_b128 v[70:73], v0 offset:20736
	ds_read_b128 v[74:77], v0 offset:23040
	ds_read_b128 v[78:81], v0 offset:25344
	ds_read_b128 v[82:85], v126 offset:55296
	ds_read_b128 v[86:89], v126 offset:57600
	ds_read_b128 v[90:93], v126 offset:59904
	ds_read_b128 v[94:97], v126 offset:62208
	v_and_b32_e32 v116, 64, v116
	s_setprio 1
	s_waitcnt lgkmcnt(3)
	v_mfma_f32_16x16x32_bf16 v[34:37], v[66:69], v[82:85], v[34:37]
	s_waitcnt lgkmcnt(2)
	v_mfma_f32_16x16x32_bf16 v[38:41], v[66:69], v[86:89], v[38:41]
	s_waitcnt lgkmcnt(1)
	v_mfma_f32_16x16x32_bf16 v[42:45], v[66:69], v[90:93], v[42:45]
	s_waitcnt lgkmcnt(0)
	v_mfma_f32_16x16x32_bf16 v[2:5], v[66:69], v[94:97], v[2:5]
	v_mfma_f32_16x16x32_bf16 v[30:33], v[70:73], v[82:85], v[30:33]
	v_mfma_f32_16x16x32_bf16 v[66:69], v[70:73], v[86:89], v[46:49]
	v_mfma_f32_16x16x32_bf16 v[98:101], v[70:73], v[90:93], v[50:53]
	v_mfma_f32_16x16x32_bf16 v[6:9], v[70:73], v[94:97], v[6:9]
	v_mfma_f32_16x16x32_bf16 v[70:73], v[74:77], v[82:85], v[54:57]
	v_mfma_f32_16x16x32_bf16 v[102:105], v[74:77], v[86:89], v[58:61]
	v_mfma_f32_16x16x32_bf16 v[106:109], v[74:77], v[90:93], v[62:65]
	v_mfma_f32_16x16x32_bf16 v[10:13], v[74:77], v[94:97], v[10:13]
	v_mfma_f32_16x16x32_bf16 v[74:77], v[78:81], v[82:85], v[18:21]
	v_mfma_f32_16x16x32_bf16 v[82:85], v[78:81], v[86:89], v[22:25]
	v_mfma_f32_16x16x32_bf16 v[86:89], v[78:81], v[90:93], v[26:29]
	v_mfma_f32_16x16x32_bf16 v[78:81], v[78:81], v[94:97], v[14:17]
	s_setprio 0
	s_nop 1
	ds_read_b128 v[14:17], v0 offset:18496
	ds_read_b128 v[18:21], v0 offset:20800
	ds_read_b128 v[90:93], v0 offset:23104
	ds_read_b128 v[94:97], v0 offset:25408
	ds_read_b128 v[110:113], v126 offset:55360
	ds_read_b128 v[118:121], v126 offset:57664
	ds_read_b128 v[122:125], v126 offset:59968
	ds_read_b128 v[126:129], v126 offset:62272
	s_setprio 1
	s_waitcnt lgkmcnt(3)
	v_mfma_f32_16x16x32_bf16 v[62:65], v[14:17], v[110:113], v[34:37]
	s_waitcnt lgkmcnt(2)
	v_mfma_f32_16x16x32_bf16 v[58:61], v[14:17], v[118:121], v[38:41]
	s_waitcnt lgkmcnt(1)
	v_mfma_f32_16x16x32_bf16 v[54:57], v[14:17], v[122:125], v[42:45]
	s_waitcnt lgkmcnt(0)
	v_mfma_f32_16x16x32_bf16 v[50:53], v[14:17], v[126:129], v[2:5]
	v_mfma_f32_16x16x32_bf16 v[46:49], v[18:21], v[110:113], v[30:33]
	v_mfma_f32_16x16x32_bf16 v[42:45], v[18:21], v[118:121], v[66:69]
	v_mfma_f32_16x16x32_bf16 v[38:41], v[18:21], v[122:125], v[98:101]
	v_mfma_f32_16x16x32_bf16 v[34:37], v[18:21], v[126:129], v[6:9]
	v_mfma_f32_16x16x32_bf16 v[30:33], v[90:93], v[110:113], v[70:73]
	v_mfma_f32_16x16x32_bf16 v[26:29], v[90:93], v[118:121], v[102:105]
	v_mfma_f32_16x16x32_bf16 v[22:25], v[90:93], v[122:125], v[106:109]
	v_mfma_f32_16x16x32_bf16 v[18:21], v[90:93], v[126:129], v[10:13]
	v_mfma_f32_16x16x32_bf16 v[14:17], v[94:97], v[110:113], v[74:77]
	v_mfma_f32_16x16x32_bf16 v[10:13], v[94:97], v[118:121], v[82:85]
	v_mfma_f32_16x16x32_bf16 v[6:9], v[94:97], v[122:125], v[86:89]
	v_mfma_f32_16x16x32_bf16 v[2:5], v[94:97], v[126:129], v[78:81]
	s_setprio 0
	v_add_u32_e32 v0, s16, v117
	v_or3_b32 v66, v116, s15, v114
	v_lshl_or_b32 v72, v115, 2, v0
	v_ashrrev_i32_e32 v67, 31, v66
	v_lshlrev_b64 v[66:67], 2, v[66:67]
	v_ashrrev_i32_e32 v73, 31, v72
	v_lshl_add_u64 v[74:75], s[4:5], 0, v[66:67]
	v_lshlrev_b64 v[68:69], 12, v[72:73]
	v_lshl_add_u64 v[70:71], v[74:75], 0, v[68:69]
	s_barrier
; template <int EPI, bool AF32>
; DEV void gemm_tile(const void* Ap, int lda, const u16* Bt, int ldb, int K, int m0, int n0, const Epi& ea, char* smem) {
;     ...
;     const int rbase = m0 + wr * 64 + fq * 4, cbase = cb + fr;
;     if (EPI == EP_RES) {
;       float* C = (float*)ea.p0;
;       const float* R = (const float*)ea.p1;
;       float rv[4][4][4];
; #pragma unroll
;       for (int m = 0; m < 4; m++)
; #pragma unroll
;         for (int j = 0; j < 4; j++)
; #pragma unroll
;           for (int n = 0; n < 4; n++) rv[m][j][n] = R[(size_t)(rbase + m * 16 + j) * 1024 + cbase + n * 16];
;       __builtin_amdgcn_sched_barrier(0);
; #pragma unroll
;       for (int m = 0; m < 4; m++)
; #pragma unroll
;         for (int j = 0; j < 4; j++)
; #pragma unroll
;           for (int n = 0; n < 4; n++)
;             C[(size_t)(rbase + m * 16 + j) * 1024 + cbase + n * 16] = ALPHA_ * rv[m][j][n] + acc[m][n][j];
	global_load_dword v0, v[70:71], off
	global_load_dword v104, v[70:71], off offset:64
	global_load_dword v105, v[70:71], off offset:128
	global_load_dword v106, v[70:71], off offset:192
	v_or_b32_e32 v70, 1, v72
	v_ashrrev_i32_e32 v71, 31, v70
	v_lshlrev_b64 v[70:71], 12, v[70:71]
	v_lshl_add_u64 v[76:77], v[74:75], 0, v[70:71]
	global_load_dword v107, v[76:77], off
	global_load_dword v108, v[76:77], off offset:64
	global_load_dword v109, v[76:77], off offset:128
	global_load_dword v110, v[76:77], off offset:192
	v_or_b32_e32 v76, 2, v72
	v_ashrrev_i32_e32 v77, 31, v76
	v_lshlrev_b64 v[76:77], 12, v[76:77]
	v_lshl_add_u64 v[78:79], v[74:75], 0, v[76:77]
	global_load_dword v111, v[78:79], off
	global_load_dword v112, v[78:79], off offset:64
	global_load_dword v113, v[78:79], off offset:128
	global_load_dword v114, v[78:79], off offset:192
	v_or_b32_e32 v78, 3, v72
	v_ashrrev_i32_e32 v79, 31, v78
	v_lshlrev_b64 v[78:79], 12, v[78:79]
	v_lshl_add_u64 v[80:81], v[74:75], 0, v[78:79]
	global_load_dword v115, v[80:81], off
	global_load_dword v116, v[80:81], off offset:64
	global_load_dword v117, v[80:81], off offset:128
	global_load_dword v118, v[80:81], off offset:192
	v_or_b32_e32 v80, 16, v72
	v_ashrrev_i32_e32 v81, 31, v80
	v_lshlrev_b64 v[80:81], 12, v[80:81]
	v_lshl_add_u64 v[82:83], v[74:75], 0, v[80:81]
	global_load_dword v119, v[82:83], off
	global_load_dword v120, v[82:83], off offset:64
	global_load_dword v121, v[82:83], off offset:128
	global_load_dword v122, v[82:83], off offset:192
	v_or_b32_e32 v82, 17, v72
	v_ashrrev_i32_e32 v83, 31, v82
	v_lshlrev_b64 v[82:83], 12, v[82:83]
	v_lshl_add_u64 v[84:85], v[74:75], 0, v[82:83]
	global_load_dword v123, v[84:85], off
	global_load_dword v124, v[84:85], off offset:64
	global_load_dword v125, v[84:85], off offset:128
	global_load_dword v126, v[84:85], off offset:192
	v_or_b32_e32 v84, 18, v72
	v_ashrrev_i32_e32 v85, 31, v84
	v_lshlrev_b64 v[84:85], 12, v[84:85]
	v_lshl_add_u64 v[86:87], v[74:75], 0, v[84:85]
	global_load_dword v127, v[86:87], off
	global_load_dword v128, v[86:87], off offset:64
	global_load_dword v129, v[86:87], off offset:128
	global_load_dword v130, v[86:87], off offset:192
	v_or_b32_e32 v86, 19, v72
	v_ashrrev_i32_e32 v87, 31, v86
	v_lshlrev_b64 v[86:87], 12, v[86:87]
	v_lshl_add_u64 v[88:89], v[74:75], 0, v[86:87]
	global_load_dword v131, v[88:89], off
	global_load_dword v132, v[88:89], off offset:64
	global_load_dword v133, v[88:89], off offset:128
	global_load_dword v134, v[88:89], off offset:192
	v_or_b32_e32 v88, 32, v72
	v_ashrrev_i32_e32 v89, 31, v88
	v_lshlrev_b64 v[88:89], 12, v[88:89]
	v_lshl_add_u64 v[90:91], v[74:75], 0, v[88:89]
	global_load_dword v135, v[90:91], off
	global_load_dword v136, v[90:91], off offset:64
	global_load_dword v137, v[90:91], off offset:128
	global_load_dword v138, v[90:91], off offset:192
	v_or_b32_e32 v90, 33, v72
	v_ashrrev_i32_e32 v91, 31, v90
	v_lshlrev_b64 v[90:91], 12, v[90:91]
	v_lshl_add_u64 v[92:93], v[74:75], 0, v[90:91]
	global_load_dword v139, v[92:93], off
	global_load_dword v140, v[92:93], off offset:64
	global_load_dword v141, v[92:93], off offset:128
	global_load_dword v142, v[92:93], off offset:192
	v_or_b32_e32 v92, 34, v72
	v_ashrrev_i32_e32 v93, 31, v92
	v_lshlrev_b64 v[92:93], 12, v[92:93]
	v_lshl_add_u64 v[94:95], v[74:75], 0, v[92:93]
	global_load_dword v143, v[94:95], off
	global_load_dword v144, v[94:95], off offset:64
	global_load_dword v145, v[94:95], off offset:128
	global_load_dword v146, v[94:95], off offset:192
	v_or_b32_e32 v94, 35, v72
	v_ashrrev_i32_e32 v95, 31, v94
	v_lshlrev_b64 v[94:95], 12, v[94:95]
	v_lshl_add_u64 v[96:97], v[74:75], 0, v[94:95]
	global_load_dword v147, v[96:97], off
	global_load_dword v148, v[96:97], off offset:64
	global_load_dword v149, v[96:97], off offset:128
	global_load_dword v150, v[96:97], off offset:192
	v_or_b32_e32 v96, 48, v72
	v_ashrrev_i32_e32 v97, 31, v96
	v_lshlrev_b64 v[96:97], 12, v[96:97]
	v_lshl_add_u64 v[98:99], v[74:75], 0, v[96:97]
	global_load_dword v151, v[98:99], off
	global_load_dword v152, v[98:99], off offset:64
	global_load_dword v153, v[98:99], off offset:128
	global_load_dword v161, v[98:99], off offset:192
	v_or_b32_e32 v98, 49, v72
	v_ashrrev_i32_e32 v99, 31, v98
	v_lshlrev_b64 v[98:99], 12, v[98:99]
	v_lshl_add_u64 v[100:101], v[74:75], 0, v[98:99]
	global_load_dword v162, v[100:101], off
	global_load_dword v163, v[100:101], off offset:64
	global_load_dword v164, v[100:101], off offset:128
	global_load_dword v165, v[100:101], off offset:192
	v_or_b32_e32 v100, 50, v72
	v_or_b32_e32 v72, 51, v72
	v_ashrrev_i32_e32 v101, 31, v100
	v_ashrrev_i32_e32 v73, 31, v72
	v_lshlrev_b64 v[100:101], 12, v[100:101]
	v_lshlrev_b64 v[72:73], 12, v[72:73]
	v_lshl_add_u64 v[102:103], v[74:75], 0, v[100:101]
	v_lshl_add_u64 v[74:75], v[74:75], 0, v[72:73]
	global_load_dword v166, v[102:103], off
	global_load_dword v167, v[102:103], off offset:64
	global_load_dword v168, v[102:103], off offset:128
	s_nop 0
	global_load_dword v102, v[102:103], off offset:192
	s_nop 0
	global_load_dword v103, v[74:75], off
	global_load_dword v169, v[74:75], off offset:64
	global_load_dword v170, v[74:75], off offset:128
	s_nop 0
	global_load_dword v74, v[74:75], off offset:192
	v_lshl_add_u64 v[66:67], s[2:3], 0, v[66:67]
	v_lshl_add_u64 v[68:69], v[66:67], 0, v[68:69]
	s_waitcnt vmcnt(62)
	v_fmamk_f32 v0, v0, 0x3fb504f3, v62
	global_store_dword v[68:69], v0, off
	v_fmamk_f32 v0, v104, 0x3fb504f3, v58
	global_store_dword v[68:69], v0, off offset:64
	s_waitcnt vmcnt(62)
; template <int EPI, bool AF32>
; DEV void gemm_tile(const void* Ap, int lda, const u16* Bt, int ldb, int K, int m0, int n0, const Epi& ea, char* smem) {
;     ...
; #pragma unroll
;       for (int m = 0; m < 4; m++)
; #pragma unroll
;         for (int j = 0; j < 4; j++)
; #pragma unroll
;           for (int n = 0; n < 4; n++)
;             C[(size_t)(rbase + m * 16 + j) * 1024 + cbase + n * 16] = ALPHA_ * rv[m][j][n] + acc[m][n][j];
	v_fmamk_f32 v0, v105, 0x3fb504f3, v54
	global_store_dword v[68:69], v0, off offset:128
	v_fmamk_f32 v0, v106, 0x3fb504f3, v50
	global_store_dword v[68:69], v0, off offset:192
	v_lshl_add_u64 v[68:69], v[66:67], 0, v[70:71]
	s_waitcnt vmcnt(62)
	v_fmamk_f32 v0, v107, 0x3fb504f3, v63
	global_store_dword v[68:69], v0, off
	v_fmamk_f32 v0, v108, 0x3fb504f3, v59
	global_store_dword v[68:69], v0, off offset:64
	s_waitcnt vmcnt(62)
	v_fmamk_f32 v0, v109, 0x3fb504f3, v55
	global_store_dword v[68:69], v0, off offset:128
	v_fmamk_f32 v0, v110, 0x3fb504f3, v51
	global_store_dword v[68:69], v0, off offset:192
	v_lshl_add_u64 v[50:51], v[66:67], 0, v[76:77]
	s_waitcnt vmcnt(62)
	v_fmamk_f32 v0, v111, 0x3fb504f3, v64
	global_store_dword v[50:51], v0, off
	v_fmamk_f32 v0, v112, 0x3fb504f3, v60
	global_store_dword v[50:51], v0, off offset:64
	s_waitcnt vmcnt(62)
	v_fmamk_f32 v0, v113, 0x3fb504f3, v56
	global_store_dword v[50:51], v0, off offset:128
	v_fmamk_f32 v0, v114, 0x3fb504f3, v52
	global_store_dword v[50:51], v0, off offset:192
	v_lshl_add_u64 v[50:51], v[66:67], 0, v[78:79]
	s_waitcnt vmcnt(62)
	v_fmac_f32_e32 v65, 0x3fb504f3, v115
	v_fmac_f32_e32 v61, 0x3fb504f3, v116
	s_waitcnt vmcnt(61)
	v_fmac_f32_e32 v57, 0x3fb504f3, v117
	s_waitcnt vmcnt(60)
	v_fmac_f32_e32 v53, 0x3fb504f3, v118
	global_store_dword v[50:51], v65, off
	global_store_dword v[50:51], v61, off offset:64
	global_store_dword v[50:51], v57, off offset:128
	global_store_dword v[50:51], v53, off offset:192
	v_lshl_add_u64 v[50:51], v[66:67], 0, v[80:81]
	s_waitcnt vmcnt(62)
	v_fmamk_f32 v0, v119, 0x3fb504f3, v46
	global_store_dword v[50:51], v0, off
	v_fmamk_f32 v0, v120, 0x3fb504f3, v42
	global_store_dword v[50:51], v0, off offset:64
	s_waitcnt vmcnt(62)
	v_fmamk_f32 v0, v121, 0x3fb504f3, v38
	global_store_dword v[50:51], v0, off offset:128
	v_fmamk_f32 v0, v122, 0x3fb504f3, v34
	global_store_dword v[50:51], v0, off offset:192
	v_lshl_add_u64 v[50:51], v[66:67], 0, v[82:83]
	s_waitcnt vmcnt(62)
	v_fmamk_f32 v0, v123, 0x3fb504f3, v47
	global_store_dword v[50:51], v0, off
	v_fmamk_f32 v0, v124, 0x3fb504f3, v43
	global_store_dword v[50:51], v0, off offset:64
	s_waitcnt vmcnt(62)
	v_fmamk_f32 v0, v125, 0x3fb504f3, v39
	global_store_dword v[50:51], v0, off offset:128
	v_fmamk_f32 v0, v126, 0x3fb504f3, v35
	global_store_dword v[50:51], v0, off offset:192
	v_lshl_add_u64 v[34:35], v[66:67], 0, v[84:85]
	s_waitcnt vmcnt(62)
	v_fmamk_f32 v0, v127, 0x3fb504f3, v48
	global_store_dword v[34:35], v0, off
	v_fmamk_f32 v0, v128, 0x3fb504f3, v44
	global_store_dword v[34:35], v0, off offset:64
	s_waitcnt vmcnt(62)
	v_fmamk_f32 v0, v129, 0x3fb504f3, v40
	global_store_dword v[34:35], v0, off offset:128
	v_fmamk_f32 v0, v130, 0x3fb504f3, v36
	global_store_dword v[34:35], v0, off offset:192
	v_lshl_add_u64 v[34:35], v[66:67], 0, v[86:87]
	s_waitcnt vmcnt(62)
	v_fmac_f32_e32 v49, 0x3fb504f3, v131
	v_fmac_f32_e32 v45, 0x3fb504f3, v132
	s_waitcnt vmcnt(61)
	v_fmac_f32_e32 v41, 0x3fb504f3, v133
	s_waitcnt vmcnt(60)
	v_fmac_f32_e32 v37, 0x3fb504f3, v134
	global_store_dword v[34:35], v49, off
	global_store_dword v[34:35], v45, off offset:64
	global_store_dword v[34:35], v41, off offset:128
	global_store_dword v[34:35], v37, off offset:192
	v_lshl_add_u64 v[34:35], v[66:67], 0, v[88:89]
	s_waitcnt vmcnt(62)
	v_fmamk_f32 v0, v135, 0x3fb504f3, v30
	global_store_dword v[34:35], v0, off
	v_fmamk_f32 v0, v136, 0x3fb504f3, v26
	global_store_dword v[34:35], v0, off offset:64
	s_waitcnt vmcnt(62)
	v_fmamk_f32 v0, v137, 0x3fb504f3, v22
	global_store_dword v[34:35], v0, off offset:128
	v_fmamk_f32 v0, v138, 0x3fb504f3, v18
	global_store_dword v[34:35], v0, off offset:192
	v_lshl_add_u64 v[34:35], v[66:67], 0, v[90:91]
	s_waitcnt vmcnt(62)
	v_fmamk_f32 v0, v139, 0x3fb504f3, v31
	global_store_dword v[34:35], v0, off
	v_fmamk_f32 v0, v140, 0x3fb504f3, v27
	global_store_dword v[34:35], v0, off offset:64
	s_waitcnt vmcnt(62)
	v_fmamk_f32 v0, v141, 0x3fb504f3, v23
	global_store_dword v[34:35], v0, off offset:128
	v_fmamk_f32 v0, v142, 0x3fb504f3, v19
	global_store_dword v[34:35], v0, off offset:192
	v_lshl_add_u64 v[18:19], v[66:67], 0, v[92:93]
	s_waitcnt vmcnt(62)
	v_fmamk_f32 v0, v143, 0x3fb504f3, v32
	global_store_dword v[18:19], v0, off
	v_fmamk_f32 v0, v144, 0x3fb504f3, v28
	global_store_dword v[18:19], v0, off offset:64
	s_waitcnt vmcnt(62)
	v_fmamk_f32 v0, v145, 0x3fb504f3, v24
	global_store_dword v[18:19], v0, off offset:128
	v_fmamk_f32 v0, v146, 0x3fb504f3, v20
	global_store_dword v[18:19], v0, off offset:192
	v_lshl_add_u64 v[18:19], v[66:67], 0, v[94:95]
	s_waitcnt vmcnt(62)
	v_fmac_f32_e32 v33, 0x3fb504f3, v147
	v_fmac_f32_e32 v29, 0x3fb504f3, v148
	s_waitcnt vmcnt(61)
	v_fmac_f32_e32 v25, 0x3fb504f3, v149
	s_waitcnt vmcnt(60)
	v_fmac_f32_e32 v21, 0x3fb504f3, v150
	global_store_dword v[18:19], v33, off
	global_store_dword v[18:19], v29, off offset:64
	global_store_dword v[18:19], v25, off offset:128
	global_store_dword v[18:19], v21, off offset:192
	v_lshl_add_u64 v[18:19], v[66:67], 0, v[96:97]
	s_waitcnt vmcnt(62)
	v_fmamk_f32 v0, v151, 0x3fb504f3, v14
	global_store_dword v[18:19], v0, off
	v_fmamk_f32 v0, v152, 0x3fb504f3, v10
	global_store_dword v[18:19], v0, off offset:64
	s_waitcnt vmcnt(62)
	v_fmamk_f32 v0, v153, 0x3fb504f3, v6
	global_store_dword v[18:19], v0, off offset:128
	v_fmamk_f32 v0, v161, 0x3fb504f3, v2
	global_store_dword v[18:19], v0, off offset:192
	v_lshl_add_u64 v[18:19], v[66:67], 0, v[98:99]
	s_waitcnt vmcnt(62)
	v_fmamk_f32 v0, v162, 0x3fb504f3, v15
	global_store_dword v[18:19], v0, off
	v_fmamk_f32 v0, v163, 0x3fb504f3, v11
	global_store_dword v[18:19], v0, off offset:64
	s_waitcnt vmcnt(62)
	v_fmamk_f32 v0, v164, 0x3fb504f3, v7
	global_store_dword v[18:19], v0, off offset:128
	v_fmamk_f32 v0, v165, 0x3fb504f3, v3
	global_store_dword v[18:19], v0, off offset:192
	v_lshl_add_u64 v[2:3], v[66:67], 0, v[100:101]
	s_waitcnt vmcnt(62)
	v_fmamk_f32 v0, v166, 0x3fb504f3, v16
	global_store_dword v[2:3], v0, off
	v_fmamk_f32 v0, v167, 0x3fb504f3, v12
	global_store_dword v[2:3], v0, off offset:64
	s_waitcnt vmcnt(62)
	v_fmamk_f32 v0, v168, 0x3fb504f3, v8
	global_store_dword v[2:3], v0, off offset:128
	v_fmamk_f32 v0, v102, 0x3fb504f3, v4
	global_store_dword v[2:3], v0, off offset:192
	v_lshl_add_u64 v[2:3], v[66:67], 0, v[72:73]
	s_waitcnt vmcnt(62)
	v_fmac_f32_e32 v17, 0x3fb504f3, v103
	v_fmac_f32_e32 v13, 0x3fb504f3, v169
	s_waitcnt vmcnt(61)
	v_fmac_f32_e32 v9, 0x3fb504f3, v170
	s_waitcnt vmcnt(60)
	v_fmac_f32_e32 v5, 0x3fb504f3, v74
	v_readfirstlane_b32 s0, v198
	global_store_dword v[2:3], v17, off
	global_store_dword v[2:3], v13, off offset:64
	global_store_dword v[2:3], v9, off offset:128
	global_store_dword v[2:3], v5, off offset:192
	s_add_i32 s14, s0, s14
	s_cmpk_lt_i32 s14, 0x820
	s_cbranch_scc1 .LBB0_1478
